# GEMM K-loops: first pass per unit peeled with C=0 (no accumulator zeroing), per-block s_setprio toggles dropped
# speedup vs baseline: 1.0696x; 1.0087x over previous
.LBB0_187:
	s_ashr_i32 s21, s20, 31
	s_lshl_b64 s[24:25], s[20:21], 19
	s_add_u32 s24, s48, s24
	s_addc_u32 s25, s49, s25
	s_and_b64 s[26:27], s[6:7], exec
	s_cselect_b32 s21, s25, s31
	s_cselect_b32 s63, s24, s30
	s_ashr_i32 s19, s18, 31
	s_lshl_b64 s[26:27], s[18:19], 19
	s_add_u32 s26, s35, s26
	s_addc_u32 s27, s50, s27
	s_and_b64 s[42:43], s[6:7], exec
	s_cselect_b32 s19, s27, s41
	s_cselect_b32 s64, s26, s40
	s_add_u32 s30, s30, 0x40080
	s_addc_u32 s31, s31, 0
	s_add_u32 s65, s40, 0x100
	s_addc_u32 s66, s41, 0
	s_mov_b32 s67, -2
	ds_read_b128 v[154:157], v149
	ds_read_b128 v[158:161], v149 offset:1024
	ds_read_b128 v[162:165], v149 offset:2048
	ds_read_b128 v[166:169], v149 offset:3072
	ds_read_b128 v[170:173], v150
	ds_read_b128 v[174:177], v150 offset:1024
	ds_read_b128 v[178:181], v150 offset:2048
	ds_read_b128 v[182:185], v150 offset:3072
	s_add_u32 s40, s30, 0xfffc0080
	s_addc_u32 s41, s31, -1
	s_cmp_eq_u32 s67, 12
	s_cselect_b32 s43, s21, s41
	s_cselect_b32 s42, s63, s40
	s_cselect_b32 s41, s19, s66
	s_cselect_b32 s40, s64, s65
	v_lshl_add_u64 v[144:145], s[30:31], 0, v[136:137]
	s_add_i32 m0, s29, 0xc000
	ds_read_b128 v[186:189], v151
	ds_read_b128 v[190:193], v151 offset:1024
	ds_read_b128 v[194:197], v151 offset:2048
	ds_read_b128 v[198:201], v151 offset:3072
	ds_read_b128 v[202:205], v151 offset:4096
	ds_read_b128 v[208:211], v151 offset:5120
	ds_read_b128 v[212:215], v151 offset:6144
	ds_read_b128 v[216:219], v151 offset:7168
	global_load_lds_dwordx4 v[144:145], off
	v_lshl_add_u64 v[144:145], s[30:31], 0, v[138:139]
	s_add_i32 m0, s29, 0xe000
	s_nop 0
	global_load_lds_dwordx4 v[144:145], off
	s_waitcnt vmcnt(8)
	s_waitcnt lgkmcnt(0)
	s_barrier
	s_setprio 1
	s_waitcnt lgkmcnt(0)
	v_mfma_f32_16x16x32_bf16 v[116:119], v[154:157], v[186:189], 0
	v_mfma_f32_16x16x32_bf16 v[112:115], v[162:165], v[186:189], 0
	v_mfma_f32_16x16x32_bf16 v[104:107], v[154:157], v[194:197], 0
	v_mfma_f32_16x16x32_bf16 v[100:103], v[162:165], v[194:197], 0
	v_mfma_f32_16x16x32_bf16 v[88:91], v[154:157], v[202:205], 0
	v_mfma_f32_16x16x32_bf16 v[84:87], v[162:165], v[202:205], 0
	v_mfma_f32_16x16x32_bf16 v[72:75], v[154:157], v[212:215], 0
	v_mfma_f32_16x16x32_bf16 v[68:71], v[162:165], v[212:215], 0
	v_mfma_f32_16x16x32_bf16 v[116:119], v[158:161], v[190:193], v[116:119]
	v_mfma_f32_16x16x32_bf16 v[112:115], v[166:169], v[190:193], v[112:115]
	v_mfma_f32_16x16x32_bf16 v[104:107], v[158:161], v[198:201], v[104:107]
	v_mfma_f32_16x16x32_bf16 v[100:103], v[166:169], v[198:201], v[100:103]
	v_mfma_f32_16x16x32_bf16 v[88:91], v[158:161], v[208:211], v[88:91]
	v_mfma_f32_16x16x32_bf16 v[84:87], v[166:169], v[208:211], v[84:87]
	v_mfma_f32_16x16x32_bf16 v[72:75], v[158:161], v[216:219], v[72:75]
	v_mfma_f32_16x16x32_bf16 v[68:71], v[166:169], v[216:219], v[68:71]
	s_setprio 0
	s_setprio 1
	v_mfma_f32_16x16x32_bf16 v[124:127], v[170:173], v[186:189], 0
	v_mfma_f32_16x16x32_bf16 v[120:123], v[178:181], v[186:189], 0
	v_mfma_f32_16x16x32_bf16 v[108:111], v[170:173], v[194:197], 0
	v_mfma_f32_16x16x32_bf16 v[96:99], v[178:181], v[194:197], 0
	v_mfma_f32_16x16x32_bf16 v[92:95], v[170:173], v[202:205], 0
	v_mfma_f32_16x16x32_bf16 v[80:83], v[178:181], v[202:205], 0
	v_mfma_f32_16x16x32_bf16 v[76:79], v[170:173], v[212:215], 0
	v_mfma_f32_16x16x32_bf16 v[64:67], v[178:181], v[212:215], 0
	v_mfma_f32_16x16x32_bf16 v[124:127], v[174:177], v[190:193], v[124:127]
	v_mfma_f32_16x16x32_bf16 v[120:123], v[182:185], v[190:193], v[120:123]
	v_mfma_f32_16x16x32_bf16 v[108:111], v[174:177], v[198:201], v[108:111]
	v_mfma_f32_16x16x32_bf16 v[96:99], v[182:185], v[198:201], v[96:99]
	v_mfma_f32_16x16x32_bf16 v[92:95], v[174:177], v[208:211], v[92:95]
	v_mfma_f32_16x16x32_bf16 v[80:83], v[182:185], v[208:211], v[80:83]
	v_mfma_f32_16x16x32_bf16 v[76:79], v[174:177], v[216:219], v[76:79]
	v_mfma_f32_16x16x32_bf16 v[64:67], v[182:185], v[216:219], v[64:67]
	s_setprio 0
	s_barrier
	s_add_i32 s68, s58, s51
	v_lshl_add_u64 v[144:145], s[40:41], 0, v[132:133]
	s_mov_b32 m0, s68
	ds_read_b128 v[186:189], v151 offset:16384
	ds_read_b128 v[190:193], v151 offset:17408
	ds_read_b128 v[194:197], v151 offset:18432
	ds_read_b128 v[198:201], v151 offset:19456
	ds_read_b128 v[202:205], v151 offset:20480
	ds_read_b128 v[208:211], v151 offset:21504
	ds_read_b128 v[212:215], v151 offset:22528
	ds_read_b128 v[216:219], v151 offset:23552
	global_load_lds_dwordx4 v[144:145], off
	s_add_i32 m0, s68, 0x2000
	s_add_u32 s68, s40, 0x40000
	v_lshl_add_u64 v[220:221], s[40:41], 0, v[128:129]
	s_addc_u32 s69, s41, 0
	s_add_i32 s70, s59, s51
	global_load_lds_dwordx4 v[220:221], off
	v_lshl_add_u64 v[222:223], s[68:69], 0, v[132:133]
	s_mov_b32 m0, s70
	v_lshl_add_u64 v[224:225], s[42:43], 0, v[130:131]
	global_load_lds_dwordx4 v[222:223], off
	v_lshl_add_u64 v[222:223], s[68:69], 0, v[128:129]
	s_add_i32 m0, s70, 0x2000
	s_nop 0
	global_load_lds_dwordx4 v[222:223], off
	v_lshl_add_u64 v[222:223], s[42:43], 0, v[134:135]
	s_mov_b32 m0, s29
	s_nop 0
	global_load_lds_dwordx4 v[222:223], off
	s_mov_b32 m0, s52
	s_nop 0
	global_load_lds_dwordx4 v[224:225], off
	s_waitcnt vmcnt(8)
	s_waitcnt lgkmcnt(0)
	s_barrier
	s_setprio 1
	s_waitcnt lgkmcnt(0)
	v_mfma_f32_16x16x32_bf16 v[56:59], v[154:157], v[186:189], 0
	v_mfma_f32_16x16x32_bf16 v[52:55], v[162:165], v[186:189], 0
	v_mfma_f32_16x16x32_bf16 v[40:43], v[154:157], v[194:197], 0
	v_mfma_f32_16x16x32_bf16 v[36:39], v[162:165], v[194:197], 0
	v_mfma_f32_16x16x32_bf16 v[24:27], v[154:157], v[202:205], 0
	v_mfma_f32_16x16x32_bf16 v[20:23], v[162:165], v[202:205], 0
	v_mfma_f32_16x16x32_bf16 v[8:11], v[154:157], v[212:215], 0
	v_mfma_f32_16x16x32_bf16 v[4:7], v[162:165], v[212:215], 0
	v_mfma_f32_16x16x32_bf16 v[56:59], v[158:161], v[190:193], v[56:59]
	v_mfma_f32_16x16x32_bf16 v[52:55], v[166:169], v[190:193], v[52:55]
	v_mfma_f32_16x16x32_bf16 v[40:43], v[158:161], v[198:201], v[40:43]
	v_mfma_f32_16x16x32_bf16 v[36:39], v[166:169], v[198:201], v[36:39]
	v_mfma_f32_16x16x32_bf16 v[24:27], v[158:161], v[208:211], v[24:27]
	v_mfma_f32_16x16x32_bf16 v[20:23], v[166:169], v[208:211], v[20:23]
	v_mfma_f32_16x16x32_bf16 v[8:11], v[158:161], v[216:219], v[8:11]
	v_mfma_f32_16x16x32_bf16 v[4:7], v[166:169], v[216:219], v[4:7]
	s_setprio 0
	s_setprio 1
	v_mfma_f32_16x16x32_bf16 v[60:63], v[170:173], v[186:189], 0
	v_mfma_f32_16x16x32_bf16 v[48:51], v[178:181], v[186:189], 0
	v_mfma_f32_16x16x32_bf16 v[44:47], v[170:173], v[194:197], 0
	v_mfma_f32_16x16x32_bf16 v[32:35], v[178:181], v[194:197], 0
	v_mfma_f32_16x16x32_bf16 v[28:31], v[170:173], v[202:205], 0
	v_mfma_f32_16x16x32_bf16 v[16:19], v[178:181], v[202:205], 0
	v_mfma_f32_16x16x32_bf16 v[12:15], v[170:173], v[212:215], 0
	v_mfma_f32_16x16x32_bf16 v[0:3], v[178:181], v[212:215], 0
	v_mfma_f32_16x16x32_bf16 v[60:63], v[174:177], v[190:193], v[60:63]
	v_mfma_f32_16x16x32_bf16 v[48:51], v[182:185], v[190:193], v[48:51]
	v_mfma_f32_16x16x32_bf16 v[44:47], v[174:177], v[198:201], v[44:47]
	v_mfma_f32_16x16x32_bf16 v[32:35], v[182:185], v[198:201], v[32:35]
	v_mfma_f32_16x16x32_bf16 v[28:31], v[174:177], v[208:211], v[28:31]
	v_mfma_f32_16x16x32_bf16 v[16:19], v[182:185], v[208:211], v[16:19]
	v_mfma_f32_16x16x32_bf16 v[12:15], v[174:177], v[216:219], v[12:15]
	v_mfma_f32_16x16x32_bf16 v[0:3], v[182:185], v[216:219], v[0:3]
	s_setprio 0
	s_barrier
	s_add_i32 s68, 0, 0x18000
	v_add_u32_e32 v153, s68, v147
	s_add_i32 s69, 0, 0x1c000
	ds_read_b128 v[154:157], v153
	ds_read_b128 v[158:161], v153 offset:1024
	ds_read_b128 v[162:165], v153 offset:2048
	ds_read_b128 v[166:169], v153 offset:3072
	v_add_u32_e32 v153, s69, v147
	ds_read_b128 v[170:173], v153
	ds_read_b128 v[174:177], v153 offset:1024
	ds_read_b128 v[178:181], v153 offset:2048
	ds_read_b128 v[182:185], v153 offset:3072
	s_add_u32 s42, s42, 0x40000
	s_addc_u32 s43, s43, 0
	s_mov_b32 m0, s53
	v_lshl_add_u64 v[226:227], s[42:43], 0, v[134:135]
	ds_read_b128 v[186:189], v151 offset:32768
	ds_read_b128 v[190:193], v151 offset:33792
	ds_read_b128 v[194:197], v151 offset:34816
	ds_read_b128 v[198:201], v151 offset:35840
	ds_read_b128 v[202:205], v151 offset:36864
	ds_read_b128 v[208:211], v151 offset:37888
	ds_read_b128 v[212:215], v151 offset:38912
	ds_read_b128 v[216:219], v151 offset:39936
	global_load_lds_dwordx4 v[226:227], off
	v_lshl_add_u64 v[226:227], s[42:43], 0, v[130:131]
	s_mov_b32 m0, s54
	s_nop 0
	global_load_lds_dwordx4 v[226:227], off
	s_waitcnt vmcnt(8)
	s_waitcnt lgkmcnt(0)
	s_barrier
	s_setprio 1
	s_waitcnt lgkmcnt(0)
	v_mfma_f32_16x16x32_bf16 v[116:119], v[154:157], v[186:189], v[116:119]
	v_mfma_f32_16x16x32_bf16 v[112:115], v[162:165], v[186:189], v[112:115]
	v_mfma_f32_16x16x32_bf16 v[104:107], v[154:157], v[194:197], v[104:107]
	v_mfma_f32_16x16x32_bf16 v[100:103], v[162:165], v[194:197], v[100:103]
	v_mfma_f32_16x16x32_bf16 v[88:91], v[154:157], v[202:205], v[88:91]
	v_mfma_f32_16x16x32_bf16 v[84:87], v[162:165], v[202:205], v[84:87]
	v_mfma_f32_16x16x32_bf16 v[72:75], v[154:157], v[212:215], v[72:75]
	v_mfma_f32_16x16x32_bf16 v[68:71], v[162:165], v[212:215], v[68:71]
	v_mfma_f32_16x16x32_bf16 v[116:119], v[158:161], v[190:193], v[116:119]
	v_mfma_f32_16x16x32_bf16 v[112:115], v[166:169], v[190:193], v[112:115]
	v_mfma_f32_16x16x32_bf16 v[104:107], v[158:161], v[198:201], v[104:107]
	v_mfma_f32_16x16x32_bf16 v[100:103], v[166:169], v[198:201], v[100:103]
	v_mfma_f32_16x16x32_bf16 v[88:91], v[158:161], v[208:211], v[88:91]
	v_mfma_f32_16x16x32_bf16 v[84:87], v[166:169], v[208:211], v[84:87]
	v_mfma_f32_16x16x32_bf16 v[72:75], v[158:161], v[216:219], v[72:75]
	v_mfma_f32_16x16x32_bf16 v[68:71], v[166:169], v[216:219], v[68:71]
	s_setprio 0
	s_setprio 1
	v_mfma_f32_16x16x32_bf16 v[124:127], v[170:173], v[186:189], v[124:127]
	v_mfma_f32_16x16x32_bf16 v[120:123], v[178:181], v[186:189], v[120:123]
	v_mfma_f32_16x16x32_bf16 v[108:111], v[170:173], v[194:197], v[108:111]
	v_mfma_f32_16x16x32_bf16 v[96:99], v[178:181], v[194:197], v[96:99]
	v_mfma_f32_16x16x32_bf16 v[92:95], v[170:173], v[202:205], v[92:95]
	v_mfma_f32_16x16x32_bf16 v[80:83], v[178:181], v[202:205], v[80:83]
	v_mfma_f32_16x16x32_bf16 v[76:79], v[170:173], v[212:215], v[76:79]
	v_mfma_f32_16x16x32_bf16 v[64:67], v[178:181], v[212:215], v[64:67]
	v_mfma_f32_16x16x32_bf16 v[124:127], v[174:177], v[190:193], v[124:127]
	v_mfma_f32_16x16x32_bf16 v[120:123], v[182:185], v[190:193], v[120:123]
	v_mfma_f32_16x16x32_bf16 v[108:111], v[174:177], v[198:201], v[108:111]
	v_mfma_f32_16x16x32_bf16 v[96:99], v[182:185], v[198:201], v[96:99]
	v_mfma_f32_16x16x32_bf16 v[92:95], v[174:177], v[208:211], v[92:95]
	v_mfma_f32_16x16x32_bf16 v[80:83], v[182:185], v[208:211], v[80:83]
	v_mfma_f32_16x16x32_bf16 v[76:79], v[174:177], v[216:219], v[76:79]
	v_mfma_f32_16x16x32_bf16 v[64:67], v[182:185], v[216:219], v[64:67]
	s_setprio 0
	s_barrier
	s_add_i32 s42, s68, s51
	v_lshl_add_u64 v[144:145], v[144:145], 0, s[12:13]
	s_mov_b32 m0, s42
	ds_read_b128 v[186:189], v151 offset:49152
	ds_read_b128 v[190:193], v151 offset:50176
	ds_read_b128 v[194:197], v151 offset:51200
	ds_read_b128 v[198:201], v151 offset:52224
	ds_read_b128 v[202:205], v151 offset:53248
	ds_read_b128 v[208:211], v151 offset:54272
	ds_read_b128 v[212:215], v151 offset:55296
	ds_read_b128 v[216:219], v151 offset:56320
	global_load_lds_dwordx4 v[144:145], off
	s_add_i32 m0, s42, 0x2000
	s_add_u32 s40, s40, 0x40080
	v_lshl_add_u64 v[144:145], v[220:221], 0, s[12:13]
	s_addc_u32 s41, s41, 0
	s_add_i32 s42, s69, s51
	global_load_lds_dwordx4 v[144:145], off
	v_lshl_add_u64 v[144:145], s[40:41], 0, v[132:133]
	s_mov_b32 m0, s42
	s_nop 0
	global_load_lds_dwordx4 v[144:145], off
	v_lshl_add_u64 v[144:145], s[40:41], 0, v[128:129]
	s_add_i32 m0, s42, 0x2000
	s_nop 0
	global_load_lds_dwordx4 v[144:145], off
	v_lshl_add_u64 v[144:145], v[222:223], 0, s[12:13]
	s_mov_b32 m0, s56
	s_nop 0
	global_load_lds_dwordx4 v[144:145], off
	v_lshl_add_u64 v[144:145], v[224:225], 0, s[12:13]
	s_mov_b32 m0, s57
	s_nop 0
	global_load_lds_dwordx4 v[144:145], off
	s_waitcnt vmcnt(8)
	s_waitcnt lgkmcnt(0)
	s_barrier
	s_setprio 1
	s_waitcnt lgkmcnt(0)
	v_mfma_f32_16x16x32_bf16 v[56:59], v[154:157], v[186:189], v[56:59]
	v_mfma_f32_16x16x32_bf16 v[52:55], v[162:165], v[186:189], v[52:55]
	v_mfma_f32_16x16x32_bf16 v[40:43], v[154:157], v[194:197], v[40:43]
	v_mfma_f32_16x16x32_bf16 v[36:39], v[162:165], v[194:197], v[36:39]
	v_mfma_f32_16x16x32_bf16 v[24:27], v[154:157], v[202:205], v[24:27]
	v_mfma_f32_16x16x32_bf16 v[20:23], v[162:165], v[202:205], v[20:23]
	v_mfma_f32_16x16x32_bf16 v[8:11], v[154:157], v[212:215], v[8:11]
	v_mfma_f32_16x16x32_bf16 v[4:7], v[162:165], v[212:215], v[4:7]
	v_mfma_f32_16x16x32_bf16 v[56:59], v[158:161], v[190:193], v[56:59]
	v_mfma_f32_16x16x32_bf16 v[52:55], v[166:169], v[190:193], v[52:55]
	v_mfma_f32_16x16x32_bf16 v[40:43], v[158:161], v[198:201], v[40:43]
	v_mfma_f32_16x16x32_bf16 v[36:39], v[166:169], v[198:201], v[36:39]
	v_mfma_f32_16x16x32_bf16 v[24:27], v[158:161], v[208:211], v[24:27]
	v_mfma_f32_16x16x32_bf16 v[20:23], v[166:169], v[208:211], v[20:23]
	v_mfma_f32_16x16x32_bf16 v[8:11], v[158:161], v[216:219], v[8:11]
	v_mfma_f32_16x16x32_bf16 v[4:7], v[166:169], v[216:219], v[4:7]
	s_setprio 0
	s_setprio 1
	v_mfma_f32_16x16x32_bf16 v[60:63], v[170:173], v[186:189], v[60:63]
	v_mfma_f32_16x16x32_bf16 v[48:51], v[178:181], v[186:189], v[48:51]
	v_mfma_f32_16x16x32_bf16 v[44:47], v[170:173], v[194:197], v[44:47]
	v_mfma_f32_16x16x32_bf16 v[32:35], v[178:181], v[194:197], v[32:35]
	v_mfma_f32_16x16x32_bf16 v[28:31], v[170:173], v[202:205], v[28:31]
	v_mfma_f32_16x16x32_bf16 v[16:19], v[178:181], v[202:205], v[16:19]
	v_mfma_f32_16x16x32_bf16 v[12:15], v[170:173], v[212:215], v[12:15]
	v_mfma_f32_16x16x32_bf16 v[0:3], v[178:181], v[212:215], v[0:3]
	v_mfma_f32_16x16x32_bf16 v[60:63], v[174:177], v[190:193], v[60:63]
	v_mfma_f32_16x16x32_bf16 v[48:51], v[182:185], v[190:193], v[48:51]
	v_mfma_f32_16x16x32_bf16 v[44:47], v[174:177], v[198:201], v[44:47]
	v_mfma_f32_16x16x32_bf16 v[32:35], v[182:185], v[198:201], v[32:35]
	v_mfma_f32_16x16x32_bf16 v[28:31], v[174:177], v[208:211], v[28:31]
	v_mfma_f32_16x16x32_bf16 v[16:19], v[182:185], v[208:211], v[16:19]
	v_mfma_f32_16x16x32_bf16 v[12:15], v[174:177], v[216:219], v[12:15]
	v_mfma_f32_16x16x32_bf16 v[0:3], v[182:185], v[216:219], v[0:3]
	s_setprio 0
	s_barrier
	s_add_i32 s67, s67, 2
	s_add_u32 s30, s30, 0x100
	s_addc_u32 s31, s31, 0
	s_add_u32 s65, s65, 0x100
	s_addc_u32 s66, s66, 0
	s_cmp_gt_u32 s67, 13
	s_cbranch_scc1 .Lpeel_done_4171
.LBB0_188:
	ds_read_b128 v[154:157], v149
	ds_read_b128 v[158:161], v149 offset:1024
	ds_read_b128 v[162:165], v149 offset:2048
	ds_read_b128 v[166:169], v149 offset:3072
	ds_read_b128 v[170:173], v150
	ds_read_b128 v[174:177], v150 offset:1024
	ds_read_b128 v[178:181], v150 offset:2048
	ds_read_b128 v[182:185], v150 offset:3072
	s_add_u32 s40, s30, 0xfffc0080
	s_addc_u32 s41, s31, -1
	s_cmp_eq_u32 s67, 12
	s_cselect_b32 s43, s21, s41
	s_cselect_b32 s42, s63, s40
	s_cselect_b32 s41, s19, s66
	s_cselect_b32 s40, s64, s65
	v_lshl_add_u64 v[144:145], s[30:31], 0, v[136:137]
	s_add_i32 m0, s29, 0xc000
	ds_read_b128 v[186:189], v151
	ds_read_b128 v[190:193], v151 offset:1024
	ds_read_b128 v[194:197], v151 offset:2048
	ds_read_b128 v[198:201], v151 offset:3072
	ds_read_b128 v[202:205], v151 offset:4096
	ds_read_b128 v[208:211], v151 offset:5120
	ds_read_b128 v[212:215], v151 offset:6144
	ds_read_b128 v[216:219], v151 offset:7168
	global_load_lds_dwordx4 v[144:145], off
	v_lshl_add_u64 v[144:145], s[30:31], 0, v[138:139]
	s_add_i32 m0, s29, 0xe000
	s_nop 0
	global_load_lds_dwordx4 v[144:145], off
	s_waitcnt vmcnt(8)
	s_waitcnt lgkmcnt(0)
	s_barrier
	s_waitcnt lgkmcnt(0)
	v_mfma_f32_16x16x32_bf16 v[116:119], v[154:157], v[186:189], v[116:119]
	v_mfma_f32_16x16x32_bf16 v[112:115], v[162:165], v[186:189], v[112:115]
	v_mfma_f32_16x16x32_bf16 v[104:107], v[154:157], v[194:197], v[104:107]
	v_mfma_f32_16x16x32_bf16 v[100:103], v[162:165], v[194:197], v[100:103]
	v_mfma_f32_16x16x32_bf16 v[88:91], v[154:157], v[202:205], v[88:91]
	v_mfma_f32_16x16x32_bf16 v[84:87], v[162:165], v[202:205], v[84:87]
	v_mfma_f32_16x16x32_bf16 v[72:75], v[154:157], v[212:215], v[72:75]
	v_mfma_f32_16x16x32_bf16 v[68:71], v[162:165], v[212:215], v[68:71]
	v_mfma_f32_16x16x32_bf16 v[116:119], v[158:161], v[190:193], v[116:119]
	v_mfma_f32_16x16x32_bf16 v[112:115], v[166:169], v[190:193], v[112:115]
	v_mfma_f32_16x16x32_bf16 v[104:107], v[158:161], v[198:201], v[104:107]
	v_mfma_f32_16x16x32_bf16 v[100:103], v[166:169], v[198:201], v[100:103]
	v_mfma_f32_16x16x32_bf16 v[88:91], v[158:161], v[208:211], v[88:91]
	v_mfma_f32_16x16x32_bf16 v[84:87], v[166:169], v[208:211], v[84:87]
	v_mfma_f32_16x16x32_bf16 v[72:75], v[158:161], v[216:219], v[72:75]
	v_mfma_f32_16x16x32_bf16 v[68:71], v[166:169], v[216:219], v[68:71]
	v_mfma_f32_16x16x32_bf16 v[124:127], v[170:173], v[186:189], v[124:127]
	v_mfma_f32_16x16x32_bf16 v[120:123], v[178:181], v[186:189], v[120:123]
	v_mfma_f32_16x16x32_bf16 v[108:111], v[170:173], v[194:197], v[108:111]
	v_mfma_f32_16x16x32_bf16 v[96:99], v[178:181], v[194:197], v[96:99]
	v_mfma_f32_16x16x32_bf16 v[92:95], v[170:173], v[202:205], v[92:95]
	v_mfma_f32_16x16x32_bf16 v[80:83], v[178:181], v[202:205], v[80:83]
	v_mfma_f32_16x16x32_bf16 v[76:79], v[170:173], v[212:215], v[76:79]
	v_mfma_f32_16x16x32_bf16 v[64:67], v[178:181], v[212:215], v[64:67]
	v_mfma_f32_16x16x32_bf16 v[124:127], v[174:177], v[190:193], v[124:127]
	v_mfma_f32_16x16x32_bf16 v[120:123], v[182:185], v[190:193], v[120:123]
	v_mfma_f32_16x16x32_bf16 v[108:111], v[174:177], v[198:201], v[108:111]
	v_mfma_f32_16x16x32_bf16 v[96:99], v[182:185], v[198:201], v[96:99]
	v_mfma_f32_16x16x32_bf16 v[92:95], v[174:177], v[208:211], v[92:95]
	v_mfma_f32_16x16x32_bf16 v[80:83], v[182:185], v[208:211], v[80:83]
	v_mfma_f32_16x16x32_bf16 v[76:79], v[174:177], v[216:219], v[76:79]
	v_mfma_f32_16x16x32_bf16 v[64:67], v[182:185], v[216:219], v[64:67]
	s_barrier
	s_add_i32 s68, s58, s51
	v_lshl_add_u64 v[144:145], s[40:41], 0, v[132:133]
	s_mov_b32 m0, s68
	ds_read_b128 v[186:189], v151 offset:16384
	ds_read_b128 v[190:193], v151 offset:17408
	ds_read_b128 v[194:197], v151 offset:18432
	ds_read_b128 v[198:201], v151 offset:19456
	ds_read_b128 v[202:205], v151 offset:20480
	ds_read_b128 v[208:211], v151 offset:21504
	ds_read_b128 v[212:215], v151 offset:22528
	ds_read_b128 v[216:219], v151 offset:23552
	global_load_lds_dwordx4 v[144:145], off
	s_add_i32 m0, s68, 0x2000
	s_add_u32 s68, s40, 0x40000
	v_lshl_add_u64 v[220:221], s[40:41], 0, v[128:129]
	s_addc_u32 s69, s41, 0
	s_add_i32 s70, s59, s51
	global_load_lds_dwordx4 v[220:221], off
	v_lshl_add_u64 v[222:223], s[68:69], 0, v[132:133]
	s_mov_b32 m0, s70
	v_lshl_add_u64 v[224:225], s[42:43], 0, v[130:131]
	global_load_lds_dwordx4 v[222:223], off
	v_lshl_add_u64 v[222:223], s[68:69], 0, v[128:129]
	s_add_i32 m0, s70, 0x2000
	s_nop 0
	global_load_lds_dwordx4 v[222:223], off
	v_lshl_add_u64 v[222:223], s[42:43], 0, v[134:135]
	s_mov_b32 m0, s29
	s_nop 0
	global_load_lds_dwordx4 v[222:223], off
	s_mov_b32 m0, s52
	s_nop 0
	global_load_lds_dwordx4 v[224:225], off
	s_waitcnt vmcnt(8)
	s_waitcnt lgkmcnt(0)
	s_barrier
	s_waitcnt lgkmcnt(0)
	v_mfma_f32_16x16x32_bf16 v[56:59], v[154:157], v[186:189], v[56:59]
	v_mfma_f32_16x16x32_bf16 v[52:55], v[162:165], v[186:189], v[52:55]
	v_mfma_f32_16x16x32_bf16 v[40:43], v[154:157], v[194:197], v[40:43]
	v_mfma_f32_16x16x32_bf16 v[36:39], v[162:165], v[194:197], v[36:39]
	v_mfma_f32_16x16x32_bf16 v[24:27], v[154:157], v[202:205], v[24:27]
	v_mfma_f32_16x16x32_bf16 v[20:23], v[162:165], v[202:205], v[20:23]
	v_mfma_f32_16x16x32_bf16 v[8:11], v[154:157], v[212:215], v[8:11]
	v_mfma_f32_16x16x32_bf16 v[4:7], v[162:165], v[212:215], v[4:7]
	v_mfma_f32_16x16x32_bf16 v[56:59], v[158:161], v[190:193], v[56:59]
	v_mfma_f32_16x16x32_bf16 v[52:55], v[166:169], v[190:193], v[52:55]
	v_mfma_f32_16x16x32_bf16 v[40:43], v[158:161], v[198:201], v[40:43]
	v_mfma_f32_16x16x32_bf16 v[36:39], v[166:169], v[198:201], v[36:39]
	v_mfma_f32_16x16x32_bf16 v[24:27], v[158:161], v[208:211], v[24:27]
	v_mfma_f32_16x16x32_bf16 v[20:23], v[166:169], v[208:211], v[20:23]
	v_mfma_f32_16x16x32_bf16 v[8:11], v[158:161], v[216:219], v[8:11]
	v_mfma_f32_16x16x32_bf16 v[4:7], v[166:169], v[216:219], v[4:7]
	v_mfma_f32_16x16x32_bf16 v[60:63], v[170:173], v[186:189], v[60:63]
	v_mfma_f32_16x16x32_bf16 v[48:51], v[178:181], v[186:189], v[48:51]
	v_mfma_f32_16x16x32_bf16 v[44:47], v[170:173], v[194:197], v[44:47]
	v_mfma_f32_16x16x32_bf16 v[32:35], v[178:181], v[194:197], v[32:35]
	v_mfma_f32_16x16x32_bf16 v[28:31], v[170:173], v[202:205], v[28:31]
	v_mfma_f32_16x16x32_bf16 v[16:19], v[178:181], v[202:205], v[16:19]
	v_mfma_f32_16x16x32_bf16 v[12:15], v[170:173], v[212:215], v[12:15]
	v_mfma_f32_16x16x32_bf16 v[0:3], v[178:181], v[212:215], v[0:3]
	v_mfma_f32_16x16x32_bf16 v[60:63], v[174:177], v[190:193], v[60:63]
	v_mfma_f32_16x16x32_bf16 v[48:51], v[182:185], v[190:193], v[48:51]
	v_mfma_f32_16x16x32_bf16 v[44:47], v[174:177], v[198:201], v[44:47]
	v_mfma_f32_16x16x32_bf16 v[32:35], v[182:185], v[198:201], v[32:35]
	v_mfma_f32_16x16x32_bf16 v[28:31], v[174:177], v[208:211], v[28:31]
	v_mfma_f32_16x16x32_bf16 v[16:19], v[182:185], v[208:211], v[16:19]
	v_mfma_f32_16x16x32_bf16 v[12:15], v[174:177], v[216:219], v[12:15]
	v_mfma_f32_16x16x32_bf16 v[0:3], v[182:185], v[216:219], v[0:3]
	s_barrier
	s_add_i32 s68, 0, 0x18000
	v_add_u32_e32 v153, s68, v147
	s_add_i32 s69, 0, 0x1c000
	ds_read_b128 v[154:157], v153
	ds_read_b128 v[158:161], v153 offset:1024
	ds_read_b128 v[162:165], v153 offset:2048
	ds_read_b128 v[166:169], v153 offset:3072
	v_add_u32_e32 v153, s69, v147
	ds_read_b128 v[170:173], v153
	ds_read_b128 v[174:177], v153 offset:1024
	ds_read_b128 v[178:181], v153 offset:2048
	ds_read_b128 v[182:185], v153 offset:3072
	s_add_u32 s42, s42, 0x40000
	s_addc_u32 s43, s43, 0
	s_mov_b32 m0, s53
	v_lshl_add_u64 v[226:227], s[42:43], 0, v[134:135]
	ds_read_b128 v[186:189], v151 offset:32768
	ds_read_b128 v[190:193], v151 offset:33792
	ds_read_b128 v[194:197], v151 offset:34816
	ds_read_b128 v[198:201], v151 offset:35840
	ds_read_b128 v[202:205], v151 offset:36864
	ds_read_b128 v[208:211], v151 offset:37888
	ds_read_b128 v[212:215], v151 offset:38912
	ds_read_b128 v[216:219], v151 offset:39936
	global_load_lds_dwordx4 v[226:227], off
	v_lshl_add_u64 v[226:227], s[42:43], 0, v[130:131]
	s_mov_b32 m0, s54
	s_nop 0
	global_load_lds_dwordx4 v[226:227], off
	s_waitcnt vmcnt(8)
	s_waitcnt lgkmcnt(0)
	s_barrier
	s_waitcnt lgkmcnt(0)
	v_mfma_f32_16x16x32_bf16 v[116:119], v[154:157], v[186:189], v[116:119]
	v_mfma_f32_16x16x32_bf16 v[112:115], v[162:165], v[186:189], v[112:115]
	v_mfma_f32_16x16x32_bf16 v[104:107], v[154:157], v[194:197], v[104:107]
	v_mfma_f32_16x16x32_bf16 v[100:103], v[162:165], v[194:197], v[100:103]
	v_mfma_f32_16x16x32_bf16 v[88:91], v[154:157], v[202:205], v[88:91]
	v_mfma_f32_16x16x32_bf16 v[84:87], v[162:165], v[202:205], v[84:87]
	v_mfma_f32_16x16x32_bf16 v[72:75], v[154:157], v[212:215], v[72:75]
	v_mfma_f32_16x16x32_bf16 v[68:71], v[162:165], v[212:215], v[68:71]
	v_mfma_f32_16x16x32_bf16 v[116:119], v[158:161], v[190:193], v[116:119]
	v_mfma_f32_16x16x32_bf16 v[112:115], v[166:169], v[190:193], v[112:115]
	v_mfma_f32_16x16x32_bf16 v[104:107], v[158:161], v[198:201], v[104:107]
	v_mfma_f32_16x16x32_bf16 v[100:103], v[166:169], v[198:201], v[100:103]
	v_mfma_f32_16x16x32_bf16 v[88:91], v[158:161], v[208:211], v[88:91]
	v_mfma_f32_16x16x32_bf16 v[84:87], v[166:169], v[208:211], v[84:87]
	v_mfma_f32_16x16x32_bf16 v[72:75], v[158:161], v[216:219], v[72:75]
	v_mfma_f32_16x16x32_bf16 v[68:71], v[166:169], v[216:219], v[68:71]
	v_mfma_f32_16x16x32_bf16 v[124:127], v[170:173], v[186:189], v[124:127]
	v_mfma_f32_16x16x32_bf16 v[120:123], v[178:181], v[186:189], v[120:123]
	v_mfma_f32_16x16x32_bf16 v[108:111], v[170:173], v[194:197], v[108:111]
	v_mfma_f32_16x16x32_bf16 v[96:99], v[178:181], v[194:197], v[96:99]
	v_mfma_f32_16x16x32_bf16 v[92:95], v[170:173], v[202:205], v[92:95]
	v_mfma_f32_16x16x32_bf16 v[80:83], v[178:181], v[202:205], v[80:83]
	v_mfma_f32_16x16x32_bf16 v[76:79], v[170:173], v[212:215], v[76:79]
	v_mfma_f32_16x16x32_bf16 v[64:67], v[178:181], v[212:215], v[64:67]
	v_mfma_f32_16x16x32_bf16 v[124:127], v[174:177], v[190:193], v[124:127]
	v_mfma_f32_16x16x32_bf16 v[120:123], v[182:185], v[190:193], v[120:123]
	v_mfma_f32_16x16x32_bf16 v[108:111], v[174:177], v[198:201], v[108:111]
	v_mfma_f32_16x16x32_bf16 v[96:99], v[182:185], v[198:201], v[96:99]
	v_mfma_f32_16x16x32_bf16 v[92:95], v[174:177], v[208:211], v[92:95]
	v_mfma_f32_16x16x32_bf16 v[80:83], v[182:185], v[208:211], v[80:83]
	v_mfma_f32_16x16x32_bf16 v[76:79], v[174:177], v[216:219], v[76:79]
	v_mfma_f32_16x16x32_bf16 v[64:67], v[182:185], v[216:219], v[64:67]
	s_barrier
	s_add_i32 s42, s68, s51
	v_lshl_add_u64 v[144:145], v[144:145], 0, s[12:13]
	s_mov_b32 m0, s42
	ds_read_b128 v[186:189], v151 offset:49152
	ds_read_b128 v[190:193], v151 offset:50176
	ds_read_b128 v[194:197], v151 offset:51200
	ds_read_b128 v[198:201], v151 offset:52224
	ds_read_b128 v[202:205], v151 offset:53248
	ds_read_b128 v[208:211], v151 offset:54272
	ds_read_b128 v[212:215], v151 offset:55296
	ds_read_b128 v[216:219], v151 offset:56320
	global_load_lds_dwordx4 v[144:145], off
	s_add_i32 m0, s42, 0x2000
	s_add_u32 s40, s40, 0x40080
	v_lshl_add_u64 v[144:145], v[220:221], 0, s[12:13]
	s_addc_u32 s41, s41, 0
	s_add_i32 s42, s69, s51
	global_load_lds_dwordx4 v[144:145], off
	v_lshl_add_u64 v[144:145], s[40:41], 0, v[132:133]
	s_mov_b32 m0, s42
	s_nop 0
	global_load_lds_dwordx4 v[144:145], off
	v_lshl_add_u64 v[144:145], s[40:41], 0, v[128:129]
	s_add_i32 m0, s42, 0x2000
	s_nop 0
	global_load_lds_dwordx4 v[144:145], off
	v_lshl_add_u64 v[144:145], v[222:223], 0, s[12:13]
	s_mov_b32 m0, s56
	s_nop 0
	global_load_lds_dwordx4 v[144:145], off
	v_lshl_add_u64 v[144:145], v[224:225], 0, s[12:13]
	s_mov_b32 m0, s57
	s_nop 0
	global_load_lds_dwordx4 v[144:145], off
	s_waitcnt vmcnt(8)
	s_waitcnt lgkmcnt(0)
	s_barrier
	s_waitcnt lgkmcnt(0)
	v_mfma_f32_16x16x32_bf16 v[56:59], v[154:157], v[186:189], v[56:59]
	v_mfma_f32_16x16x32_bf16 v[52:55], v[162:165], v[186:189], v[52:55]
	v_mfma_f32_16x16x32_bf16 v[40:43], v[154:157], v[194:197], v[40:43]
	v_mfma_f32_16x16x32_bf16 v[36:39], v[162:165], v[194:197], v[36:39]
	v_mfma_f32_16x16x32_bf16 v[24:27], v[154:157], v[202:205], v[24:27]
	v_mfma_f32_16x16x32_bf16 v[20:23], v[162:165], v[202:205], v[20:23]
	v_mfma_f32_16x16x32_bf16 v[8:11], v[154:157], v[212:215], v[8:11]
	v_mfma_f32_16x16x32_bf16 v[4:7], v[162:165], v[212:215], v[4:7]
	v_mfma_f32_16x16x32_bf16 v[56:59], v[158:161], v[190:193], v[56:59]
	v_mfma_f32_16x16x32_bf16 v[52:55], v[166:169], v[190:193], v[52:55]
	v_mfma_f32_16x16x32_bf16 v[40:43], v[158:161], v[198:201], v[40:43]
	v_mfma_f32_16x16x32_bf16 v[36:39], v[166:169], v[198:201], v[36:39]
	v_mfma_f32_16x16x32_bf16 v[24:27], v[158:161], v[208:211], v[24:27]
	v_mfma_f32_16x16x32_bf16 v[20:23], v[166:169], v[208:211], v[20:23]
	v_mfma_f32_16x16x32_bf16 v[8:11], v[158:161], v[216:219], v[8:11]
	v_mfma_f32_16x16x32_bf16 v[4:7], v[166:169], v[216:219], v[4:7]
	v_mfma_f32_16x16x32_bf16 v[60:63], v[170:173], v[186:189], v[60:63]
	v_mfma_f32_16x16x32_bf16 v[48:51], v[178:181], v[186:189], v[48:51]
	v_mfma_f32_16x16x32_bf16 v[44:47], v[170:173], v[194:197], v[44:47]
	v_mfma_f32_16x16x32_bf16 v[32:35], v[178:181], v[194:197], v[32:35]
	v_mfma_f32_16x16x32_bf16 v[28:31], v[170:173], v[202:205], v[28:31]
	v_mfma_f32_16x16x32_bf16 v[16:19], v[178:181], v[202:205], v[16:19]
	v_mfma_f32_16x16x32_bf16 v[12:15], v[170:173], v[212:215], v[12:15]
	v_mfma_f32_16x16x32_bf16 v[0:3], v[178:181], v[212:215], v[0:3]
	v_mfma_f32_16x16x32_bf16 v[60:63], v[174:177], v[190:193], v[60:63]
	v_mfma_f32_16x16x32_bf16 v[48:51], v[182:185], v[190:193], v[48:51]
	v_mfma_f32_16x16x32_bf16 v[44:47], v[174:177], v[198:201], v[44:47]
	v_mfma_f32_16x16x32_bf16 v[32:35], v[182:185], v[198:201], v[32:35]
	v_mfma_f32_16x16x32_bf16 v[28:31], v[174:177], v[208:211], v[28:31]
	v_mfma_f32_16x16x32_bf16 v[16:19], v[182:185], v[208:211], v[16:19]
	v_mfma_f32_16x16x32_bf16 v[12:15], v[174:177], v[216:219], v[12:15]
	v_mfma_f32_16x16x32_bf16 v[0:3], v[182:185], v[216:219], v[0:3]
	s_barrier
	s_add_i32 s67, s67, 2
	s_add_u32 s30, s30, 0x100
	s_addc_u32 s31, s31, 0
	s_add_u32 s65, s65, 0x100
	s_addc_u32 s66, s66, 0
	s_cmp_gt_u32 s67, 13
	s_cbranch_scc0 .LBB0_188
.Lpeel_done_4171:
	s_and_b64 vcc, exec, s[16:17]
	s_cbranch_vccz .LBB0_191
	s_barrier

.LBB0_270:
	s_add_u32 s77, s50, 0x100
	s_addc_u32 s78, s51, 0
	s_mov_b32 s79, -2
	s_waitcnt lgkmcnt(0)
	ds_read_b128 v[142:145], v153
	ds_read_b128 v[146:149], v153 offset:1024
	ds_read_b128 v[158:161], v153 offset:2048
	ds_read_b128 v[162:165], v153 offset:3072
	ds_read_b128 v[166:169], v154
	ds_read_b128 v[170:173], v154 offset:1024
	ds_read_b128 v[174:177], v154 offset:2048
	ds_read_b128 v[178:181], v154 offset:3072
	s_add_u32 s50, s42, 0x100
	s_addc_u32 s51, s43, 0
	s_cmp_eq_u32 s79, 40
	s_cselect_b32 s55, s13, s51
	s_cselect_b32 s54, s12, s50
	s_cselect_b32 s53, s41, s78
	s_cselect_b32 s52, s40, s77
	v_lshl_add_u64 v[216:217], s[42:43], 0, v[134:135]
	s_add_i32 m0, s59, 0xc000
	ds_read_b128 v[182:185], v155
	ds_read_b128 v[186:189], v155 offset:1024
	ds_read_b128 v[190:193], v155 offset:2048
	ds_read_b128 v[194:197], v155 offset:3072
	ds_read_b128 v[198:201], v155 offset:4096
	ds_read_b128 v[202:205], v155 offset:5120
	ds_read_b128 v[208:211], v155 offset:6144
	ds_read_b128 v[212:215], v155 offset:7168
	global_load_lds_dwordx4 v[216:217], off
	v_lshl_add_u64 v[216:217], s[42:43], 0, v[136:137]
	s_add_i32 m0, s59, 0xe000
	s_nop 0
	global_load_lds_dwordx4 v[216:217], off
	s_waitcnt vmcnt(8)
	s_waitcnt lgkmcnt(0)
	s_barrier
	s_setprio 1
	s_waitcnt lgkmcnt(0)
	v_mfma_f32_16x16x32_bf16 v[124:127], v[142:145], v[182:185], 0
	v_mfma_f32_16x16x32_bf16 v[120:123], v[158:161], v[182:185], 0
	v_mfma_f32_16x16x32_bf16 v[108:111], v[142:145], v[190:193], 0
	v_mfma_f32_16x16x32_bf16 v[104:107], v[158:161], v[190:193], 0
	v_mfma_f32_16x16x32_bf16 v[92:95], v[142:145], v[198:201], 0
	v_mfma_f32_16x16x32_bf16 v[88:91], v[158:161], v[198:201], 0
	v_mfma_f32_16x16x32_bf16 v[76:79], v[142:145], v[208:211], 0
	v_mfma_f32_16x16x32_bf16 v[72:75], v[158:161], v[208:211], 0
	v_mfma_f32_16x16x32_bf16 v[124:127], v[146:149], v[186:189], v[124:127]
	v_mfma_f32_16x16x32_bf16 v[120:123], v[162:165], v[186:189], v[120:123]
	v_mfma_f32_16x16x32_bf16 v[108:111], v[146:149], v[194:197], v[108:111]
	v_mfma_f32_16x16x32_bf16 v[104:107], v[162:165], v[194:197], v[104:107]
	v_mfma_f32_16x16x32_bf16 v[92:95], v[146:149], v[202:205], v[92:95]
	v_mfma_f32_16x16x32_bf16 v[88:91], v[162:165], v[202:205], v[88:91]
	v_mfma_f32_16x16x32_bf16 v[76:79], v[146:149], v[212:215], v[76:79]
	v_mfma_f32_16x16x32_bf16 v[72:75], v[162:165], v[212:215], v[72:75]
	s_setprio 0
	s_setprio 1
	v_mfma_f32_16x16x32_bf16 v[116:119], v[166:169], v[182:185], 0
	v_mfma_f32_16x16x32_bf16 v[112:115], v[174:177], v[182:185], 0
	v_mfma_f32_16x16x32_bf16 v[100:103], v[166:169], v[190:193], 0
	v_mfma_f32_16x16x32_bf16 v[96:99], v[174:177], v[190:193], 0
	v_mfma_f32_16x16x32_bf16 v[84:87], v[166:169], v[198:201], 0
	v_mfma_f32_16x16x32_bf16 v[80:83], v[174:177], v[198:201], 0
	v_mfma_f32_16x16x32_bf16 v[68:71], v[166:169], v[208:211], 0
	v_mfma_f32_16x16x32_bf16 v[64:67], v[174:177], v[208:211], 0
	v_mfma_f32_16x16x32_bf16 v[116:119], v[170:173], v[186:189], v[116:119]
	v_mfma_f32_16x16x32_bf16 v[112:115], v[178:181], v[186:189], v[112:115]
	v_mfma_f32_16x16x32_bf16 v[100:103], v[170:173], v[194:197], v[100:103]
	v_mfma_f32_16x16x32_bf16 v[96:99], v[178:181], v[194:197], v[96:99]
	v_mfma_f32_16x16x32_bf16 v[84:87], v[170:173], v[202:205], v[84:87]
	v_mfma_f32_16x16x32_bf16 v[80:83], v[178:181], v[202:205], v[80:83]
	v_mfma_f32_16x16x32_bf16 v[68:71], v[170:173], v[212:215], v[68:71]
	v_mfma_f32_16x16x32_bf16 v[64:67], v[178:181], v[212:215], v[64:67]
	s_setprio 0
	s_barrier
	s_add_i32 s42, s66, s58
	v_lshl_add_u64 v[216:217], s[52:53], 0, v[128:129]
	s_mov_b32 m0, s42
	ds_read_b128 v[182:185], v155 offset:16384
	ds_read_b128 v[186:189], v155 offset:17408
	ds_read_b128 v[190:193], v155 offset:18432
	ds_read_b128 v[194:197], v155 offset:19456
	ds_read_b128 v[198:201], v155 offset:20480
	ds_read_b128 v[202:205], v155 offset:21504
	ds_read_b128 v[208:211], v155 offset:22528
	ds_read_b128 v[212:215], v155 offset:23552
	global_load_lds_dwordx4 v[216:217], off
	s_add_i32 m0, s42, 0x2000
	s_add_u32 s42, s52, 0xb0000
	v_lshl_add_u64 v[218:219], s[52:53], 0, v[130:131]
	s_addc_u32 s43, s53, 0
	s_add_i32 s80, s67, s58
	global_load_lds_dwordx4 v[218:219], off
	v_lshl_add_u64 v[220:221], s[42:43], 0, v[128:129]
	s_mov_b32 m0, s80
	v_lshl_add_u64 v[222:223], s[54:55], 0, v[130:131]
	global_load_lds_dwordx4 v[220:221], off
	v_lshl_add_u64 v[220:221], s[42:43], 0, v[130:131]
	s_add_i32 m0, s80, 0x2000
	s_nop 0
	global_load_lds_dwordx4 v[220:221], off
	v_lshl_add_u64 v[220:221], s[54:55], 0, v[128:129]
	s_mov_b32 m0, s59
	s_nop 0
	global_load_lds_dwordx4 v[220:221], off
	s_mov_b32 m0, s60
	s_nop 0
	global_load_lds_dwordx4 v[222:223], off
	s_waitcnt vmcnt(8)
	s_waitcnt lgkmcnt(0)
	s_barrier
	s_setprio 1
	s_waitcnt lgkmcnt(0)
	v_mfma_f32_16x16x32_bf16 v[60:63], v[142:145], v[182:185], 0
	v_mfma_f32_16x16x32_bf16 v[56:59], v[158:161], v[182:185], 0
	v_mfma_f32_16x16x32_bf16 v[44:47], v[142:145], v[190:193], 0
	v_mfma_f32_16x16x32_bf16 v[40:43], v[158:161], v[190:193], 0
	v_mfma_f32_16x16x32_bf16 v[28:31], v[142:145], v[198:201], 0
	v_mfma_f32_16x16x32_bf16 v[24:27], v[158:161], v[198:201], 0
	v_mfma_f32_16x16x32_bf16 v[12:15], v[142:145], v[208:211], 0
	v_mfma_f32_16x16x32_bf16 v[8:11], v[158:161], v[208:211], 0
	v_mfma_f32_16x16x32_bf16 v[60:63], v[146:149], v[186:189], v[60:63]
	v_mfma_f32_16x16x32_bf16 v[56:59], v[162:165], v[186:189], v[56:59]
	v_mfma_f32_16x16x32_bf16 v[44:47], v[146:149], v[194:197], v[44:47]
	v_mfma_f32_16x16x32_bf16 v[40:43], v[162:165], v[194:197], v[40:43]
	v_mfma_f32_16x16x32_bf16 v[28:31], v[146:149], v[202:205], v[28:31]
	v_mfma_f32_16x16x32_bf16 v[24:27], v[162:165], v[202:205], v[24:27]
	v_mfma_f32_16x16x32_bf16 v[12:15], v[146:149], v[212:215], v[12:15]
	v_mfma_f32_16x16x32_bf16 v[8:11], v[162:165], v[212:215], v[8:11]
	s_setprio 0
	s_setprio 1
	v_mfma_f32_16x16x32_bf16 v[52:55], v[166:169], v[182:185], 0
	v_mfma_f32_16x16x32_bf16 v[48:51], v[174:177], v[182:185], 0
	v_mfma_f32_16x16x32_bf16 v[36:39], v[166:169], v[190:193], 0
	v_mfma_f32_16x16x32_bf16 v[32:35], v[174:177], v[190:193], 0
	v_mfma_f32_16x16x32_bf16 v[20:23], v[166:169], v[198:201], 0
	v_mfma_f32_16x16x32_bf16 v[16:19], v[174:177], v[198:201], 0
	v_mfma_f32_16x16x32_bf16 v[4:7], v[166:169], v[208:211], 0
	v_mfma_f32_16x16x32_bf16 v[0:3], v[174:177], v[208:211], 0
	v_mfma_f32_16x16x32_bf16 v[52:55], v[170:173], v[186:189], v[52:55]
	v_mfma_f32_16x16x32_bf16 v[48:51], v[178:181], v[186:189], v[48:51]
	v_mfma_f32_16x16x32_bf16 v[36:39], v[170:173], v[194:197], v[36:39]
	v_mfma_f32_16x16x32_bf16 v[32:35], v[178:181], v[194:197], v[32:35]
	v_mfma_f32_16x16x32_bf16 v[20:23], v[170:173], v[202:205], v[20:23]
	v_mfma_f32_16x16x32_bf16 v[16:19], v[178:181], v[202:205], v[16:19]
	v_mfma_f32_16x16x32_bf16 v[4:7], v[170:173], v[212:215], v[4:7]
	v_mfma_f32_16x16x32_bf16 v[0:3], v[178:181], v[212:215], v[0:3]
	s_setprio 0
	s_barrier
	s_add_i32 s80, 0, 0x18000
	v_add_u32_e32 v132, s80, v151
	s_add_i32 s81, 0, 0x1c000
	ds_read_b128 v[142:145], v132
	ds_read_b128 v[146:149], v132 offset:1024
	ds_read_b128 v[158:161], v132 offset:2048
	ds_read_b128 v[162:165], v132 offset:3072
	v_add_u32_e32 v132, s81, v151
	ds_read_b128 v[166:169], v132
	ds_read_b128 v[170:173], v132 offset:1024
	ds_read_b128 v[174:177], v132 offset:2048
	ds_read_b128 v[178:181], v132 offset:3072
	s_add_u32 s42, s54, 0xb0000
	s_addc_u32 s43, s55, 0
	s_mov_b32 m0, s61
	v_lshl_add_u64 v[224:225], s[42:43], 0, v[128:129]
	ds_read_b128 v[182:185], v155 offset:32768
	ds_read_b128 v[186:189], v155 offset:33792
	ds_read_b128 v[190:193], v155 offset:34816
	ds_read_b128 v[194:197], v155 offset:35840
	ds_read_b128 v[198:201], v155 offset:36864
	ds_read_b128 v[202:205], v155 offset:37888
	ds_read_b128 v[208:211], v155 offset:38912
	ds_read_b128 v[212:215], v155 offset:39936
	global_load_lds_dwordx4 v[224:225], off
	v_lshl_add_u64 v[224:225], s[42:43], 0, v[130:131]
	s_mov_b32 m0, s62
	s_nop 0
	global_load_lds_dwordx4 v[224:225], off
	s_waitcnt vmcnt(8)
	s_waitcnt lgkmcnt(0)
	s_barrier
	s_setprio 1
	s_waitcnt lgkmcnt(0)
	v_mfma_f32_16x16x32_bf16 v[124:127], v[142:145], v[182:185], v[124:127]
	v_mfma_f32_16x16x32_bf16 v[120:123], v[158:161], v[182:185], v[120:123]
	v_mfma_f32_16x16x32_bf16 v[108:111], v[142:145], v[190:193], v[108:111]
	v_mfma_f32_16x16x32_bf16 v[104:107], v[158:161], v[190:193], v[104:107]
	v_mfma_f32_16x16x32_bf16 v[92:95], v[142:145], v[198:201], v[92:95]
	v_mfma_f32_16x16x32_bf16 v[88:91], v[158:161], v[198:201], v[88:91]
	v_mfma_f32_16x16x32_bf16 v[76:79], v[142:145], v[208:211], v[76:79]
	v_mfma_f32_16x16x32_bf16 v[72:75], v[158:161], v[208:211], v[72:75]
	v_mfma_f32_16x16x32_bf16 v[124:127], v[146:149], v[186:189], v[124:127]
	v_mfma_f32_16x16x32_bf16 v[120:123], v[162:165], v[186:189], v[120:123]
	v_mfma_f32_16x16x32_bf16 v[108:111], v[146:149], v[194:197], v[108:111]
	v_mfma_f32_16x16x32_bf16 v[104:107], v[162:165], v[194:197], v[104:107]
	v_mfma_f32_16x16x32_bf16 v[92:95], v[146:149], v[202:205], v[92:95]
	v_mfma_f32_16x16x32_bf16 v[88:91], v[162:165], v[202:205], v[88:91]
	v_mfma_f32_16x16x32_bf16 v[76:79], v[146:149], v[212:215], v[76:79]
	v_mfma_f32_16x16x32_bf16 v[72:75], v[162:165], v[212:215], v[72:75]
	s_setprio 0
	s_setprio 1
	v_mfma_f32_16x16x32_bf16 v[116:119], v[166:169], v[182:185], v[116:119]
	v_mfma_f32_16x16x32_bf16 v[112:115], v[174:177], v[182:185], v[112:115]
	v_mfma_f32_16x16x32_bf16 v[100:103], v[166:169], v[190:193], v[100:103]
	v_mfma_f32_16x16x32_bf16 v[96:99], v[174:177], v[190:193], v[96:99]
	v_mfma_f32_16x16x32_bf16 v[84:87], v[166:169], v[198:201], v[84:87]
	v_mfma_f32_16x16x32_bf16 v[80:83], v[174:177], v[198:201], v[80:83]
	v_mfma_f32_16x16x32_bf16 v[68:71], v[166:169], v[208:211], v[68:71]
	v_mfma_f32_16x16x32_bf16 v[64:67], v[174:177], v[208:211], v[64:67]
	v_mfma_f32_16x16x32_bf16 v[116:119], v[170:173], v[186:189], v[116:119]
	v_mfma_f32_16x16x32_bf16 v[112:115], v[178:181], v[186:189], v[112:115]
	v_mfma_f32_16x16x32_bf16 v[100:103], v[170:173], v[194:197], v[100:103]
	v_mfma_f32_16x16x32_bf16 v[96:99], v[178:181], v[194:197], v[96:99]
	v_mfma_f32_16x16x32_bf16 v[84:87], v[170:173], v[202:205], v[84:87]
	v_mfma_f32_16x16x32_bf16 v[80:83], v[178:181], v[202:205], v[80:83]
	v_mfma_f32_16x16x32_bf16 v[68:71], v[170:173], v[212:215], v[68:71]
	v_mfma_f32_16x16x32_bf16 v[64:67], v[178:181], v[212:215], v[64:67]
	s_setprio 0
	s_barrier
	s_add_i32 s42, s80, s58
	v_lshl_add_u64 v[216:217], v[216:217], 0, s[28:29]
	s_mov_b32 m0, s42
	ds_read_b128 v[182:185], v155 offset:49152
	ds_read_b128 v[186:189], v155 offset:50176
	ds_read_b128 v[190:193], v155 offset:51200
	ds_read_b128 v[194:197], v155 offset:52224
	ds_read_b128 v[198:201], v155 offset:53248
	ds_read_b128 v[202:205], v155 offset:54272
	ds_read_b128 v[208:211], v155 offset:55296
	ds_read_b128 v[212:215], v155 offset:56320
	global_load_lds_dwordx4 v[216:217], off
	s_add_i32 m0, s42, 0x2000
	s_add_u32 s42, s52, 0xb0080
	v_lshl_add_u64 v[216:217], v[218:219], 0, s[28:29]
	s_addc_u32 s43, s53, 0
	s_add_i32 s52, s81, s58
	global_load_lds_dwordx4 v[216:217], off
	v_lshl_add_u64 v[216:217], s[42:43], 0, v[128:129]
	s_mov_b32 m0, s52
	s_nop 0
	global_load_lds_dwordx4 v[216:217], off
	v_lshl_add_u64 v[216:217], s[42:43], 0, v[130:131]
	s_add_i32 m0, s52, 0x2000
	s_nop 0
	global_load_lds_dwordx4 v[216:217], off
	v_lshl_add_u64 v[216:217], v[220:221], 0, s[28:29]
	s_mov_b32 m0, s64
	s_nop 0
	global_load_lds_dwordx4 v[216:217], off
	v_lshl_add_u64 v[216:217], v[222:223], 0, s[28:29]
	s_mov_b32 m0, s65
	s_nop 0
	global_load_lds_dwordx4 v[216:217], off
	s_waitcnt vmcnt(8)
	s_waitcnt lgkmcnt(0)
	s_barrier
	s_setprio 1
	s_waitcnt lgkmcnt(0)
	v_mfma_f32_16x16x32_bf16 v[60:63], v[142:145], v[182:185], v[60:63]
	v_mfma_f32_16x16x32_bf16 v[56:59], v[158:161], v[182:185], v[56:59]
	v_mfma_f32_16x16x32_bf16 v[44:47], v[142:145], v[190:193], v[44:47]
	v_mfma_f32_16x16x32_bf16 v[40:43], v[158:161], v[190:193], v[40:43]
	v_mfma_f32_16x16x32_bf16 v[28:31], v[142:145], v[198:201], v[28:31]
	v_mfma_f32_16x16x32_bf16 v[24:27], v[158:161], v[198:201], v[24:27]
	v_mfma_f32_16x16x32_bf16 v[12:15], v[142:145], v[208:211], v[12:15]
	v_mfma_f32_16x16x32_bf16 v[8:11], v[158:161], v[208:211], v[8:11]
	v_mfma_f32_16x16x32_bf16 v[60:63], v[146:149], v[186:189], v[60:63]
	v_mfma_f32_16x16x32_bf16 v[56:59], v[162:165], v[186:189], v[56:59]
	v_mfma_f32_16x16x32_bf16 v[44:47], v[146:149], v[194:197], v[44:47]
	v_mfma_f32_16x16x32_bf16 v[40:43], v[162:165], v[194:197], v[40:43]
	v_mfma_f32_16x16x32_bf16 v[28:31], v[146:149], v[202:205], v[28:31]
	v_mfma_f32_16x16x32_bf16 v[24:27], v[162:165], v[202:205], v[24:27]
	v_mfma_f32_16x16x32_bf16 v[12:15], v[146:149], v[212:215], v[12:15]
	v_mfma_f32_16x16x32_bf16 v[8:11], v[162:165], v[212:215], v[8:11]
	s_setprio 0
	s_setprio 1
	v_mfma_f32_16x16x32_bf16 v[52:55], v[166:169], v[182:185], v[52:55]
	v_mfma_f32_16x16x32_bf16 v[48:51], v[174:177], v[182:185], v[48:51]
	v_mfma_f32_16x16x32_bf16 v[36:39], v[166:169], v[190:193], v[36:39]
	v_mfma_f32_16x16x32_bf16 v[32:35], v[174:177], v[190:193], v[32:35]
	v_mfma_f32_16x16x32_bf16 v[20:23], v[166:169], v[198:201], v[20:23]
	v_mfma_f32_16x16x32_bf16 v[16:19], v[174:177], v[198:201], v[16:19]
	v_mfma_f32_16x16x32_bf16 v[4:7], v[166:169], v[208:211], v[4:7]
	v_mfma_f32_16x16x32_bf16 v[0:3], v[174:177], v[208:211], v[0:3]
	v_mfma_f32_16x16x32_bf16 v[52:55], v[170:173], v[186:189], v[52:55]
	v_mfma_f32_16x16x32_bf16 v[48:51], v[178:181], v[186:189], v[48:51]
	v_mfma_f32_16x16x32_bf16 v[36:39], v[170:173], v[194:197], v[36:39]
	v_mfma_f32_16x16x32_bf16 v[32:35], v[178:181], v[194:197], v[32:35]
	v_mfma_f32_16x16x32_bf16 v[20:23], v[170:173], v[202:205], v[20:23]
	v_mfma_f32_16x16x32_bf16 v[16:19], v[178:181], v[202:205], v[16:19]
	v_mfma_f32_16x16x32_bf16 v[4:7], v[170:173], v[212:215], v[4:7]
	v_mfma_f32_16x16x32_bf16 v[0:3], v[178:181], v[212:215], v[0:3]
	s_setprio 0
	s_barrier
	s_add_i32 s79, s79, 2
	s_add_u32 s77, s77, 0x100
	s_addc_u32 s78, s78, 0
	s_cmp_gt_u32 s79, 41
	s_mov_b64 s[42:43], s[50:51]
	s_cbranch_scc1 .Lpeel_done_6574
.LBB0_271:
	ds_read_b128 v[142:145], v153
	ds_read_b128 v[146:149], v153 offset:1024
	ds_read_b128 v[158:161], v153 offset:2048
	ds_read_b128 v[162:165], v153 offset:3072
	ds_read_b128 v[166:169], v154
	ds_read_b128 v[170:173], v154 offset:1024
	ds_read_b128 v[174:177], v154 offset:2048
	ds_read_b128 v[178:181], v154 offset:3072
	s_add_u32 s50, s42, 0x100
	s_addc_u32 s51, s43, 0
	s_cmp_eq_u32 s79, 40
	s_cselect_b32 s55, s13, s51
	s_cselect_b32 s54, s12, s50
	s_cselect_b32 s53, s41, s78
	s_cselect_b32 s52, s40, s77
	v_lshl_add_u64 v[216:217], s[42:43], 0, v[134:135]
	s_add_i32 m0, s59, 0xc000
	ds_read_b128 v[182:185], v155
	ds_read_b128 v[186:189], v155 offset:1024
	ds_read_b128 v[190:193], v155 offset:2048
	ds_read_b128 v[194:197], v155 offset:3072
	ds_read_b128 v[198:201], v155 offset:4096
	ds_read_b128 v[202:205], v155 offset:5120
	ds_read_b128 v[208:211], v155 offset:6144
	ds_read_b128 v[212:215], v155 offset:7168
	global_load_lds_dwordx4 v[216:217], off
	v_lshl_add_u64 v[216:217], s[42:43], 0, v[136:137]
	s_add_i32 m0, s59, 0xe000
	s_nop 0
	global_load_lds_dwordx4 v[216:217], off
	s_waitcnt vmcnt(8)
	s_waitcnt lgkmcnt(0)
	s_barrier
	s_waitcnt lgkmcnt(0)
	v_mfma_f32_16x16x32_bf16 v[124:127], v[142:145], v[182:185], v[124:127]
	v_mfma_f32_16x16x32_bf16 v[120:123], v[158:161], v[182:185], v[120:123]
	v_mfma_f32_16x16x32_bf16 v[108:111], v[142:145], v[190:193], v[108:111]
	v_mfma_f32_16x16x32_bf16 v[104:107], v[158:161], v[190:193], v[104:107]
	v_mfma_f32_16x16x32_bf16 v[92:95], v[142:145], v[198:201], v[92:95]
	v_mfma_f32_16x16x32_bf16 v[88:91], v[158:161], v[198:201], v[88:91]
	v_mfma_f32_16x16x32_bf16 v[76:79], v[142:145], v[208:211], v[76:79]
	v_mfma_f32_16x16x32_bf16 v[72:75], v[158:161], v[208:211], v[72:75]
	v_mfma_f32_16x16x32_bf16 v[124:127], v[146:149], v[186:189], v[124:127]
	v_mfma_f32_16x16x32_bf16 v[120:123], v[162:165], v[186:189], v[120:123]
	v_mfma_f32_16x16x32_bf16 v[108:111], v[146:149], v[194:197], v[108:111]
	v_mfma_f32_16x16x32_bf16 v[104:107], v[162:165], v[194:197], v[104:107]
	v_mfma_f32_16x16x32_bf16 v[92:95], v[146:149], v[202:205], v[92:95]
	v_mfma_f32_16x16x32_bf16 v[88:91], v[162:165], v[202:205], v[88:91]
	v_mfma_f32_16x16x32_bf16 v[76:79], v[146:149], v[212:215], v[76:79]
	v_mfma_f32_16x16x32_bf16 v[72:75], v[162:165], v[212:215], v[72:75]
	v_mfma_f32_16x16x32_bf16 v[116:119], v[166:169], v[182:185], v[116:119]
	v_mfma_f32_16x16x32_bf16 v[112:115], v[174:177], v[182:185], v[112:115]
	v_mfma_f32_16x16x32_bf16 v[100:103], v[166:169], v[190:193], v[100:103]
	v_mfma_f32_16x16x32_bf16 v[96:99], v[174:177], v[190:193], v[96:99]
	v_mfma_f32_16x16x32_bf16 v[84:87], v[166:169], v[198:201], v[84:87]
	v_mfma_f32_16x16x32_bf16 v[80:83], v[174:177], v[198:201], v[80:83]
	v_mfma_f32_16x16x32_bf16 v[68:71], v[166:169], v[208:211], v[68:71]
	v_mfma_f32_16x16x32_bf16 v[64:67], v[174:177], v[208:211], v[64:67]
	v_mfma_f32_16x16x32_bf16 v[116:119], v[170:173], v[186:189], v[116:119]
	v_mfma_f32_16x16x32_bf16 v[112:115], v[178:181], v[186:189], v[112:115]
	v_mfma_f32_16x16x32_bf16 v[100:103], v[170:173], v[194:197], v[100:103]
	v_mfma_f32_16x16x32_bf16 v[96:99], v[178:181], v[194:197], v[96:99]
	v_mfma_f32_16x16x32_bf16 v[84:87], v[170:173], v[202:205], v[84:87]
	v_mfma_f32_16x16x32_bf16 v[80:83], v[178:181], v[202:205], v[80:83]
	v_mfma_f32_16x16x32_bf16 v[68:71], v[170:173], v[212:215], v[68:71]
	v_mfma_f32_16x16x32_bf16 v[64:67], v[178:181], v[212:215], v[64:67]
	s_barrier
	s_add_i32 s42, s66, s58
	v_lshl_add_u64 v[216:217], s[52:53], 0, v[128:129]
	s_mov_b32 m0, s42
	ds_read_b128 v[182:185], v155 offset:16384
	ds_read_b128 v[186:189], v155 offset:17408
	ds_read_b128 v[190:193], v155 offset:18432
	ds_read_b128 v[194:197], v155 offset:19456
	ds_read_b128 v[198:201], v155 offset:20480
	ds_read_b128 v[202:205], v155 offset:21504
	ds_read_b128 v[208:211], v155 offset:22528
	ds_read_b128 v[212:215], v155 offset:23552
	global_load_lds_dwordx4 v[216:217], off
	s_add_i32 m0, s42, 0x2000
	s_add_u32 s42, s52, 0xb0000
	v_lshl_add_u64 v[218:219], s[52:53], 0, v[130:131]
	s_addc_u32 s43, s53, 0
	s_add_i32 s80, s67, s58
	global_load_lds_dwordx4 v[218:219], off
	v_lshl_add_u64 v[220:221], s[42:43], 0, v[128:129]
	s_mov_b32 m0, s80
	v_lshl_add_u64 v[222:223], s[54:55], 0, v[130:131]
	global_load_lds_dwordx4 v[220:221], off
	v_lshl_add_u64 v[220:221], s[42:43], 0, v[130:131]
	s_add_i32 m0, s80, 0x2000
	s_nop 0
	global_load_lds_dwordx4 v[220:221], off
	v_lshl_add_u64 v[220:221], s[54:55], 0, v[128:129]
	s_mov_b32 m0, s59
	s_nop 0
	global_load_lds_dwordx4 v[220:221], off
	s_mov_b32 m0, s60
	s_nop 0
	global_load_lds_dwordx4 v[222:223], off
	s_waitcnt vmcnt(8)
	s_waitcnt lgkmcnt(0)
	s_barrier
	s_waitcnt lgkmcnt(0)
	v_mfma_f32_16x16x32_bf16 v[60:63], v[142:145], v[182:185], v[60:63]
	v_mfma_f32_16x16x32_bf16 v[56:59], v[158:161], v[182:185], v[56:59]
	v_mfma_f32_16x16x32_bf16 v[44:47], v[142:145], v[190:193], v[44:47]
	v_mfma_f32_16x16x32_bf16 v[40:43], v[158:161], v[190:193], v[40:43]
	v_mfma_f32_16x16x32_bf16 v[28:31], v[142:145], v[198:201], v[28:31]
	v_mfma_f32_16x16x32_bf16 v[24:27], v[158:161], v[198:201], v[24:27]
	v_mfma_f32_16x16x32_bf16 v[12:15], v[142:145], v[208:211], v[12:15]
	v_mfma_f32_16x16x32_bf16 v[8:11], v[158:161], v[208:211], v[8:11]
	v_mfma_f32_16x16x32_bf16 v[60:63], v[146:149], v[186:189], v[60:63]
	v_mfma_f32_16x16x32_bf16 v[56:59], v[162:165], v[186:189], v[56:59]
	v_mfma_f32_16x16x32_bf16 v[44:47], v[146:149], v[194:197], v[44:47]
	v_mfma_f32_16x16x32_bf16 v[40:43], v[162:165], v[194:197], v[40:43]
	v_mfma_f32_16x16x32_bf16 v[28:31], v[146:149], v[202:205], v[28:31]
	v_mfma_f32_16x16x32_bf16 v[24:27], v[162:165], v[202:205], v[24:27]
	v_mfma_f32_16x16x32_bf16 v[12:15], v[146:149], v[212:215], v[12:15]
	v_mfma_f32_16x16x32_bf16 v[8:11], v[162:165], v[212:215], v[8:11]
	v_mfma_f32_16x16x32_bf16 v[52:55], v[166:169], v[182:185], v[52:55]
	v_mfma_f32_16x16x32_bf16 v[48:51], v[174:177], v[182:185], v[48:51]
	v_mfma_f32_16x16x32_bf16 v[36:39], v[166:169], v[190:193], v[36:39]
	v_mfma_f32_16x16x32_bf16 v[32:35], v[174:177], v[190:193], v[32:35]
	v_mfma_f32_16x16x32_bf16 v[20:23], v[166:169], v[198:201], v[20:23]
	v_mfma_f32_16x16x32_bf16 v[16:19], v[174:177], v[198:201], v[16:19]
	v_mfma_f32_16x16x32_bf16 v[4:7], v[166:169], v[208:211], v[4:7]
	v_mfma_f32_16x16x32_bf16 v[0:3], v[174:177], v[208:211], v[0:3]
	v_mfma_f32_16x16x32_bf16 v[52:55], v[170:173], v[186:189], v[52:55]
	v_mfma_f32_16x16x32_bf16 v[48:51], v[178:181], v[186:189], v[48:51]
	v_mfma_f32_16x16x32_bf16 v[36:39], v[170:173], v[194:197], v[36:39]
	v_mfma_f32_16x16x32_bf16 v[32:35], v[178:181], v[194:197], v[32:35]
	v_mfma_f32_16x16x32_bf16 v[20:23], v[170:173], v[202:205], v[20:23]
	v_mfma_f32_16x16x32_bf16 v[16:19], v[178:181], v[202:205], v[16:19]
	v_mfma_f32_16x16x32_bf16 v[4:7], v[170:173], v[212:215], v[4:7]
	v_mfma_f32_16x16x32_bf16 v[0:3], v[178:181], v[212:215], v[0:3]
	s_barrier
	s_add_i32 s80, 0, 0x18000
	v_add_u32_e32 v132, s80, v151
	s_add_i32 s81, 0, 0x1c000
	ds_read_b128 v[142:145], v132
	ds_read_b128 v[146:149], v132 offset:1024
	ds_read_b128 v[158:161], v132 offset:2048
	ds_read_b128 v[162:165], v132 offset:3072
	v_add_u32_e32 v132, s81, v151
	ds_read_b128 v[166:169], v132
	ds_read_b128 v[170:173], v132 offset:1024
	ds_read_b128 v[174:177], v132 offset:2048
	ds_read_b128 v[178:181], v132 offset:3072
	s_add_u32 s42, s54, 0xb0000
	s_addc_u32 s43, s55, 0
	s_mov_b32 m0, s61
	v_lshl_add_u64 v[224:225], s[42:43], 0, v[128:129]
	ds_read_b128 v[182:185], v155 offset:32768
	ds_read_b128 v[186:189], v155 offset:33792
	ds_read_b128 v[190:193], v155 offset:34816
	ds_read_b128 v[194:197], v155 offset:35840
	ds_read_b128 v[198:201], v155 offset:36864
	ds_read_b128 v[202:205], v155 offset:37888
	ds_read_b128 v[208:211], v155 offset:38912
	ds_read_b128 v[212:215], v155 offset:39936
	global_load_lds_dwordx4 v[224:225], off
	v_lshl_add_u64 v[224:225], s[42:43], 0, v[130:131]
	s_mov_b32 m0, s62
	s_nop 0
	global_load_lds_dwordx4 v[224:225], off
	s_waitcnt vmcnt(8)
	s_waitcnt lgkmcnt(0)
	s_barrier
	s_waitcnt lgkmcnt(0)
	v_mfma_f32_16x16x32_bf16 v[124:127], v[142:145], v[182:185], v[124:127]
	v_mfma_f32_16x16x32_bf16 v[120:123], v[158:161], v[182:185], v[120:123]
	v_mfma_f32_16x16x32_bf16 v[108:111], v[142:145], v[190:193], v[108:111]
	v_mfma_f32_16x16x32_bf16 v[104:107], v[158:161], v[190:193], v[104:107]
	v_mfma_f32_16x16x32_bf16 v[92:95], v[142:145], v[198:201], v[92:95]
	v_mfma_f32_16x16x32_bf16 v[88:91], v[158:161], v[198:201], v[88:91]
	v_mfma_f32_16x16x32_bf16 v[76:79], v[142:145], v[208:211], v[76:79]
	v_mfma_f32_16x16x32_bf16 v[72:75], v[158:161], v[208:211], v[72:75]
	v_mfma_f32_16x16x32_bf16 v[124:127], v[146:149], v[186:189], v[124:127]
	v_mfma_f32_16x16x32_bf16 v[120:123], v[162:165], v[186:189], v[120:123]
	v_mfma_f32_16x16x32_bf16 v[108:111], v[146:149], v[194:197], v[108:111]
	v_mfma_f32_16x16x32_bf16 v[104:107], v[162:165], v[194:197], v[104:107]
	v_mfma_f32_16x16x32_bf16 v[92:95], v[146:149], v[202:205], v[92:95]
	v_mfma_f32_16x16x32_bf16 v[88:91], v[162:165], v[202:205], v[88:91]
	v_mfma_f32_16x16x32_bf16 v[76:79], v[146:149], v[212:215], v[76:79]
	v_mfma_f32_16x16x32_bf16 v[72:75], v[162:165], v[212:215], v[72:75]
	v_mfma_f32_16x16x32_bf16 v[116:119], v[166:169], v[182:185], v[116:119]
	v_mfma_f32_16x16x32_bf16 v[112:115], v[174:177], v[182:185], v[112:115]
	v_mfma_f32_16x16x32_bf16 v[100:103], v[166:169], v[190:193], v[100:103]
	v_mfma_f32_16x16x32_bf16 v[96:99], v[174:177], v[190:193], v[96:99]
	v_mfma_f32_16x16x32_bf16 v[84:87], v[166:169], v[198:201], v[84:87]
	v_mfma_f32_16x16x32_bf16 v[80:83], v[174:177], v[198:201], v[80:83]
	v_mfma_f32_16x16x32_bf16 v[68:71], v[166:169], v[208:211], v[68:71]
	v_mfma_f32_16x16x32_bf16 v[64:67], v[174:177], v[208:211], v[64:67]
	v_mfma_f32_16x16x32_bf16 v[116:119], v[170:173], v[186:189], v[116:119]
	v_mfma_f32_16x16x32_bf16 v[112:115], v[178:181], v[186:189], v[112:115]
	v_mfma_f32_16x16x32_bf16 v[100:103], v[170:173], v[194:197], v[100:103]
	v_mfma_f32_16x16x32_bf16 v[96:99], v[178:181], v[194:197], v[96:99]
	v_mfma_f32_16x16x32_bf16 v[84:87], v[170:173], v[202:205], v[84:87]
	v_mfma_f32_16x16x32_bf16 v[80:83], v[178:181], v[202:205], v[80:83]
	v_mfma_f32_16x16x32_bf16 v[68:71], v[170:173], v[212:215], v[68:71]
	v_mfma_f32_16x16x32_bf16 v[64:67], v[178:181], v[212:215], v[64:67]
	s_barrier
	s_add_i32 s42, s80, s58
	v_lshl_add_u64 v[216:217], v[216:217], 0, s[28:29]
	s_mov_b32 m0, s42
	ds_read_b128 v[182:185], v155 offset:49152
	ds_read_b128 v[186:189], v155 offset:50176
	ds_read_b128 v[190:193], v155 offset:51200
	ds_read_b128 v[194:197], v155 offset:52224
	ds_read_b128 v[198:201], v155 offset:53248
	ds_read_b128 v[202:205], v155 offset:54272
	ds_read_b128 v[208:211], v155 offset:55296
	ds_read_b128 v[212:215], v155 offset:56320
	global_load_lds_dwordx4 v[216:217], off
	s_add_i32 m0, s42, 0x2000
	s_add_u32 s42, s52, 0xb0080
	v_lshl_add_u64 v[216:217], v[218:219], 0, s[28:29]
	s_addc_u32 s43, s53, 0
	s_add_i32 s52, s81, s58
	global_load_lds_dwordx4 v[216:217], off
	v_lshl_add_u64 v[216:217], s[42:43], 0, v[128:129]
	s_mov_b32 m0, s52
	s_nop 0
	global_load_lds_dwordx4 v[216:217], off
	v_lshl_add_u64 v[216:217], s[42:43], 0, v[130:131]
	s_add_i32 m0, s52, 0x2000
	s_nop 0
	global_load_lds_dwordx4 v[216:217], off
	v_lshl_add_u64 v[216:217], v[220:221], 0, s[28:29]
	s_mov_b32 m0, s64
	s_nop 0
	global_load_lds_dwordx4 v[216:217], off
	v_lshl_add_u64 v[216:217], v[222:223], 0, s[28:29]
	s_mov_b32 m0, s65
	s_nop 0
	global_load_lds_dwordx4 v[216:217], off
	s_waitcnt vmcnt(8)
	s_waitcnt lgkmcnt(0)
	s_barrier
	s_waitcnt lgkmcnt(0)
	v_mfma_f32_16x16x32_bf16 v[60:63], v[142:145], v[182:185], v[60:63]
	v_mfma_f32_16x16x32_bf16 v[56:59], v[158:161], v[182:185], v[56:59]
	v_mfma_f32_16x16x32_bf16 v[44:47], v[142:145], v[190:193], v[44:47]
	v_mfma_f32_16x16x32_bf16 v[40:43], v[158:161], v[190:193], v[40:43]
	v_mfma_f32_16x16x32_bf16 v[28:31], v[142:145], v[198:201], v[28:31]
	v_mfma_f32_16x16x32_bf16 v[24:27], v[158:161], v[198:201], v[24:27]
	v_mfma_f32_16x16x32_bf16 v[12:15], v[142:145], v[208:211], v[12:15]
	v_mfma_f32_16x16x32_bf16 v[8:11], v[158:161], v[208:211], v[8:11]
	v_mfma_f32_16x16x32_bf16 v[60:63], v[146:149], v[186:189], v[60:63]
	v_mfma_f32_16x16x32_bf16 v[56:59], v[162:165], v[186:189], v[56:59]
	v_mfma_f32_16x16x32_bf16 v[44:47], v[146:149], v[194:197], v[44:47]
	v_mfma_f32_16x16x32_bf16 v[40:43], v[162:165], v[194:197], v[40:43]
	v_mfma_f32_16x16x32_bf16 v[28:31], v[146:149], v[202:205], v[28:31]
	v_mfma_f32_16x16x32_bf16 v[24:27], v[162:165], v[202:205], v[24:27]
	v_mfma_f32_16x16x32_bf16 v[12:15], v[146:149], v[212:215], v[12:15]
	v_mfma_f32_16x16x32_bf16 v[8:11], v[162:165], v[212:215], v[8:11]
	v_mfma_f32_16x16x32_bf16 v[52:55], v[166:169], v[182:185], v[52:55]
	v_mfma_f32_16x16x32_bf16 v[48:51], v[174:177], v[182:185], v[48:51]
	v_mfma_f32_16x16x32_bf16 v[36:39], v[166:169], v[190:193], v[36:39]
	v_mfma_f32_16x16x32_bf16 v[32:35], v[174:177], v[190:193], v[32:35]
	v_mfma_f32_16x16x32_bf16 v[20:23], v[166:169], v[198:201], v[20:23]
	v_mfma_f32_16x16x32_bf16 v[16:19], v[174:177], v[198:201], v[16:19]
	v_mfma_f32_16x16x32_bf16 v[4:7], v[166:169], v[208:211], v[4:7]
	v_mfma_f32_16x16x32_bf16 v[0:3], v[174:177], v[208:211], v[0:3]
	v_mfma_f32_16x16x32_bf16 v[52:55], v[170:173], v[186:189], v[52:55]
	v_mfma_f32_16x16x32_bf16 v[48:51], v[178:181], v[186:189], v[48:51]
	v_mfma_f32_16x16x32_bf16 v[36:39], v[170:173], v[194:197], v[36:39]
	v_mfma_f32_16x16x32_bf16 v[32:35], v[178:181], v[194:197], v[32:35]
	v_mfma_f32_16x16x32_bf16 v[20:23], v[170:173], v[202:205], v[20:23]
	v_mfma_f32_16x16x32_bf16 v[16:19], v[178:181], v[202:205], v[16:19]
	v_mfma_f32_16x16x32_bf16 v[4:7], v[170:173], v[212:215], v[4:7]
	v_mfma_f32_16x16x32_bf16 v[0:3], v[178:181], v[212:215], v[0:3]
	s_barrier
	s_add_i32 s79, s79, 2
	s_add_u32 s77, s77, 0x100
	s_addc_u32 s78, s78, 0
	s_cmp_gt_u32 s79, 41
	s_mov_b64 s[42:43], s[50:51]
	s_cbranch_scc0 .LBB0_271
.Lpeel_done_6574:
	s_and_b64 vcc, exec, s[30:31]
	s_cbranch_vccz .LBB0_274
	s_barrier

.LBB0_339:
	s_ashr_i32 s31, s30, 31
	s_lshl_b64 s[40:41], s[30:31], 19
	s_add_u32 s40, s54, s40
	s_addc_u32 s41, s55, s41
	s_and_b64 s[42:43], s[8:9], exec
	s_cselect_b32 s31, s41, s11
	s_cselect_b32 s76, s40, s10
	s_ashr_i32 s29, s28, 31
	s_lshl_b64 s[42:43], s[28:29], 19
	s_add_u32 s42, s56, s42
	s_addc_u32 s43, s57, s43
	s_and_b64 s[52:53], s[8:9], exec
	s_cselect_b32 s29, s43, s51
	s_cselect_b32 s77, s42, s50
	s_add_u32 s10, s10, 0x40080
	s_addc_u32 s11, s11, 0
	s_add_u32 s78, s50, 0x100
	s_addc_u32 s79, s51, 0
	s_mov_b32 s80, -2
	ds_read_b128 v[142:145], v151
	ds_read_b128 v[156:159], v151 offset:1024
	ds_read_b128 v[160:163], v151 offset:2048
	ds_read_b128 v[164:167], v151 offset:3072
	ds_read_b128 v[168:171], v152
	ds_read_b128 v[172:175], v152 offset:1024
	ds_read_b128 v[176:179], v152 offset:2048
	ds_read_b128 v[180:183], v152 offset:3072
	s_add_u32 s50, s10, 0xfffc0080
	s_addc_u32 s51, s11, -1
	s_cmp_eq_u32 s80, 12
	s_cselect_b32 s53, s31, s51
	s_cselect_b32 s52, s76, s50
	s_cselect_b32 s51, s29, s79
	s_cselect_b32 s50, s77, s78
	v_lshl_add_u64 v[146:147], s[10:11], 0, v[134:135]
	s_add_i32 m0, s59, 0xc000
	ds_read_b128 v[184:187], v153
	ds_read_b128 v[188:191], v153 offset:1024
	ds_read_b128 v[192:195], v153 offset:2048
	ds_read_b128 v[196:199], v153 offset:3072
	ds_read_b128 v[200:203], v153 offset:4096
	ds_read_b128 v[208:211], v153 offset:5120
	ds_read_b128 v[212:215], v153 offset:6144
	ds_read_b128 v[216:219], v153 offset:7168
	global_load_lds_dwordx4 v[146:147], off
	v_lshl_add_u64 v[146:147], s[10:11], 0, v[136:137]
	s_add_i32 m0, s59, 0xe000
	s_nop 0
	global_load_lds_dwordx4 v[146:147], off
	s_waitcnt vmcnt(8)
	s_waitcnt lgkmcnt(0)
	s_barrier
	s_setprio 1
	s_waitcnt lgkmcnt(0)
	v_mfma_f32_16x16x32_bf16 v[124:127], v[142:145], v[184:187], 0
	v_mfma_f32_16x16x32_bf16 v[120:123], v[160:163], v[184:187], 0
	v_mfma_f32_16x16x32_bf16 v[108:111], v[142:145], v[192:195], 0
	v_mfma_f32_16x16x32_bf16 v[104:107], v[160:163], v[192:195], 0
	v_mfma_f32_16x16x32_bf16 v[92:95], v[142:145], v[200:203], 0
	v_mfma_f32_16x16x32_bf16 v[88:91], v[160:163], v[200:203], 0
	v_mfma_f32_16x16x32_bf16 v[76:79], v[142:145], v[212:215], 0
	v_mfma_f32_16x16x32_bf16 v[72:75], v[160:163], v[212:215], 0
	v_mfma_f32_16x16x32_bf16 v[124:127], v[156:159], v[188:191], v[124:127]
	v_mfma_f32_16x16x32_bf16 v[120:123], v[164:167], v[188:191], v[120:123]
	v_mfma_f32_16x16x32_bf16 v[108:111], v[156:159], v[196:199], v[108:111]
	v_mfma_f32_16x16x32_bf16 v[104:107], v[164:167], v[196:199], v[104:107]
	v_mfma_f32_16x16x32_bf16 v[92:95], v[156:159], v[208:211], v[92:95]
	v_mfma_f32_16x16x32_bf16 v[88:91], v[164:167], v[208:211], v[88:91]
	v_mfma_f32_16x16x32_bf16 v[76:79], v[156:159], v[216:219], v[76:79]
	v_mfma_f32_16x16x32_bf16 v[72:75], v[164:167], v[216:219], v[72:75]
	s_setprio 0
	s_setprio 1
	v_mfma_f32_16x16x32_bf16 v[116:119], v[168:171], v[184:187], 0
	v_mfma_f32_16x16x32_bf16 v[112:115], v[176:179], v[184:187], 0
	v_mfma_f32_16x16x32_bf16 v[100:103], v[168:171], v[192:195], 0
	v_mfma_f32_16x16x32_bf16 v[96:99], v[176:179], v[192:195], 0
	v_mfma_f32_16x16x32_bf16 v[84:87], v[168:171], v[200:203], 0
	v_mfma_f32_16x16x32_bf16 v[80:83], v[176:179], v[200:203], 0
	v_mfma_f32_16x16x32_bf16 v[68:71], v[168:171], v[212:215], 0
	v_mfma_f32_16x16x32_bf16 v[64:67], v[176:179], v[212:215], 0
	v_mfma_f32_16x16x32_bf16 v[116:119], v[172:175], v[188:191], v[116:119]
	v_mfma_f32_16x16x32_bf16 v[112:115], v[180:183], v[188:191], v[112:115]
	v_mfma_f32_16x16x32_bf16 v[100:103], v[172:175], v[196:199], v[100:103]
	v_mfma_f32_16x16x32_bf16 v[96:99], v[180:183], v[196:199], v[96:99]
	v_mfma_f32_16x16x32_bf16 v[84:87], v[172:175], v[208:211], v[84:87]
	v_mfma_f32_16x16x32_bf16 v[80:83], v[180:183], v[208:211], v[80:83]
	v_mfma_f32_16x16x32_bf16 v[68:71], v[172:175], v[216:219], v[68:71]
	v_mfma_f32_16x16x32_bf16 v[64:67], v[180:183], v[216:219], v[64:67]
	s_setprio 0
	s_barrier
	s_add_i32 s81, s68, s58
	v_lshl_add_u64 v[146:147], s[50:51], 0, v[130:131]
	s_mov_b32 m0, s81
	ds_read_b128 v[184:187], v153 offset:16384
	ds_read_b128 v[188:191], v153 offset:17408
	ds_read_b128 v[192:195], v153 offset:18432
	ds_read_b128 v[196:199], v153 offset:19456
	ds_read_b128 v[200:203], v153 offset:20480
	ds_read_b128 v[208:211], v153 offset:21504
	ds_read_b128 v[212:215], v153 offset:22528
	ds_read_b128 v[216:219], v153 offset:23552
	global_load_lds_dwordx4 v[146:147], off
	s_add_i32 m0, s81, 0x2000
	s_add_u32 s82, s50, 0x40000
	v_lshl_add_u64 v[204:205], s[50:51], 0, v[128:129]
	s_addc_u32 s83, s51, 0
	s_add_i32 s81, s69, s58
	global_load_lds_dwordx4 v[204:205], off
	v_lshl_add_u64 v[220:221], s[82:83], 0, v[130:131]
	s_mov_b32 m0, s81
	v_lshl_add_u64 v[222:223], s[52:53], 0, v[128:129]
	global_load_lds_dwordx4 v[220:221], off
	v_lshl_add_u64 v[220:221], s[82:83], 0, v[128:129]
	s_add_i32 m0, s81, 0x2000
	s_nop 0
	global_load_lds_dwordx4 v[220:221], off
	v_lshl_add_u64 v[220:221], s[52:53], 0, v[130:131]
	s_mov_b32 m0, s59
	s_nop 0
	global_load_lds_dwordx4 v[220:221], off
	s_mov_b32 m0, s60
	s_nop 0
	global_load_lds_dwordx4 v[222:223], off
	s_waitcnt vmcnt(8)
	s_waitcnt lgkmcnt(0)
	s_barrier
	s_setprio 1
	s_waitcnt lgkmcnt(0)
	v_mfma_f32_16x16x32_bf16 v[60:63], v[142:145], v[184:187], 0
	v_mfma_f32_16x16x32_bf16 v[56:59], v[160:163], v[184:187], 0
	v_mfma_f32_16x16x32_bf16 v[44:47], v[142:145], v[192:195], 0
	v_mfma_f32_16x16x32_bf16 v[40:43], v[160:163], v[192:195], 0
	v_mfma_f32_16x16x32_bf16 v[28:31], v[142:145], v[200:203], 0
	v_mfma_f32_16x16x32_bf16 v[24:27], v[160:163], v[200:203], 0
	v_mfma_f32_16x16x32_bf16 v[12:15], v[142:145], v[212:215], 0
	v_mfma_f32_16x16x32_bf16 v[8:11], v[160:163], v[212:215], 0
	v_mfma_f32_16x16x32_bf16 v[60:63], v[156:159], v[188:191], v[60:63]
	v_mfma_f32_16x16x32_bf16 v[56:59], v[164:167], v[188:191], v[56:59]
	v_mfma_f32_16x16x32_bf16 v[44:47], v[156:159], v[196:199], v[44:47]
	v_mfma_f32_16x16x32_bf16 v[40:43], v[164:167], v[196:199], v[40:43]
	v_mfma_f32_16x16x32_bf16 v[28:31], v[156:159], v[208:211], v[28:31]
	v_mfma_f32_16x16x32_bf16 v[24:27], v[164:167], v[208:211], v[24:27]
	v_mfma_f32_16x16x32_bf16 v[12:15], v[156:159], v[216:219], v[12:15]
	v_mfma_f32_16x16x32_bf16 v[8:11], v[164:167], v[216:219], v[8:11]
	s_setprio 0
	s_setprio 1
	v_mfma_f32_16x16x32_bf16 v[52:55], v[168:171], v[184:187], 0
	v_mfma_f32_16x16x32_bf16 v[48:51], v[176:179], v[184:187], 0
	v_mfma_f32_16x16x32_bf16 v[36:39], v[168:171], v[192:195], 0
	v_mfma_f32_16x16x32_bf16 v[32:35], v[176:179], v[192:195], 0
	v_mfma_f32_16x16x32_bf16 v[20:23], v[168:171], v[200:203], 0
	v_mfma_f32_16x16x32_bf16 v[16:19], v[176:179], v[200:203], 0
	v_mfma_f32_16x16x32_bf16 v[4:7], v[168:171], v[212:215], 0
	v_mfma_f32_16x16x32_bf16 v[0:3], v[176:179], v[212:215], 0
	v_mfma_f32_16x16x32_bf16 v[52:55], v[172:175], v[188:191], v[52:55]
	v_mfma_f32_16x16x32_bf16 v[48:51], v[180:183], v[188:191], v[48:51]
	v_mfma_f32_16x16x32_bf16 v[36:39], v[172:175], v[196:199], v[36:39]
	v_mfma_f32_16x16x32_bf16 v[32:35], v[180:183], v[196:199], v[32:35]
	v_mfma_f32_16x16x32_bf16 v[20:23], v[172:175], v[208:211], v[20:23]
	v_mfma_f32_16x16x32_bf16 v[16:19], v[180:183], v[208:211], v[16:19]
	v_mfma_f32_16x16x32_bf16 v[4:7], v[172:175], v[216:219], v[4:7]
	v_mfma_f32_16x16x32_bf16 v[0:3], v[180:183], v[216:219], v[0:3]
	s_setprio 0
	s_barrier
	s_add_i32 s81, 0, 0x18000
	v_add_u32_e32 v132, s81, v149
	s_add_i32 s82, 0, 0x1c000
	ds_read_b128 v[142:145], v132
	ds_read_b128 v[156:159], v132 offset:1024
	ds_read_b128 v[160:163], v132 offset:2048
	ds_read_b128 v[164:167], v132 offset:3072
	v_add_u32_e32 v132, s82, v149
	ds_read_b128 v[168:171], v132
	ds_read_b128 v[172:175], v132 offset:1024
	ds_read_b128 v[176:179], v132 offset:2048
	ds_read_b128 v[180:183], v132 offset:3072
	s_add_u32 s52, s52, 0x40000
	s_addc_u32 s53, s53, 0
	s_mov_b32 m0, s61
	v_lshl_add_u64 v[224:225], s[52:53], 0, v[130:131]
	ds_read_b128 v[184:187], v153 offset:32768
	ds_read_b128 v[188:191], v153 offset:33792
	ds_read_b128 v[192:195], v153 offset:34816
	ds_read_b128 v[196:199], v153 offset:35840
	ds_read_b128 v[200:203], v153 offset:36864
	ds_read_b128 v[208:211], v153 offset:37888
	ds_read_b128 v[212:215], v153 offset:38912
	ds_read_b128 v[216:219], v153 offset:39936
	global_load_lds_dwordx4 v[224:225], off
	v_lshl_add_u64 v[224:225], s[52:53], 0, v[128:129]
	s_mov_b32 m0, s62
	s_nop 0
	global_load_lds_dwordx4 v[224:225], off
	s_waitcnt vmcnt(8)
	s_waitcnt lgkmcnt(0)
	s_barrier
	s_setprio 1
	s_waitcnt lgkmcnt(0)
	v_mfma_f32_16x16x32_bf16 v[124:127], v[142:145], v[184:187], v[124:127]
	v_mfma_f32_16x16x32_bf16 v[120:123], v[160:163], v[184:187], v[120:123]
	v_mfma_f32_16x16x32_bf16 v[108:111], v[142:145], v[192:195], v[108:111]
	v_mfma_f32_16x16x32_bf16 v[104:107], v[160:163], v[192:195], v[104:107]
	v_mfma_f32_16x16x32_bf16 v[92:95], v[142:145], v[200:203], v[92:95]
	v_mfma_f32_16x16x32_bf16 v[88:91], v[160:163], v[200:203], v[88:91]
	v_mfma_f32_16x16x32_bf16 v[76:79], v[142:145], v[212:215], v[76:79]
	v_mfma_f32_16x16x32_bf16 v[72:75], v[160:163], v[212:215], v[72:75]
	v_mfma_f32_16x16x32_bf16 v[124:127], v[156:159], v[188:191], v[124:127]
	v_mfma_f32_16x16x32_bf16 v[120:123], v[164:167], v[188:191], v[120:123]
	v_mfma_f32_16x16x32_bf16 v[108:111], v[156:159], v[196:199], v[108:111]
	v_mfma_f32_16x16x32_bf16 v[104:107], v[164:167], v[196:199], v[104:107]
	v_mfma_f32_16x16x32_bf16 v[92:95], v[156:159], v[208:211], v[92:95]
	v_mfma_f32_16x16x32_bf16 v[88:91], v[164:167], v[208:211], v[88:91]
	v_mfma_f32_16x16x32_bf16 v[76:79], v[156:159], v[216:219], v[76:79]
	v_mfma_f32_16x16x32_bf16 v[72:75], v[164:167], v[216:219], v[72:75]
	s_setprio 0
	s_setprio 1
	v_mfma_f32_16x16x32_bf16 v[116:119], v[168:171], v[184:187], v[116:119]
	v_mfma_f32_16x16x32_bf16 v[112:115], v[176:179], v[184:187], v[112:115]
	v_mfma_f32_16x16x32_bf16 v[100:103], v[168:171], v[192:195], v[100:103]
	v_mfma_f32_16x16x32_bf16 v[96:99], v[176:179], v[192:195], v[96:99]
	v_mfma_f32_16x16x32_bf16 v[84:87], v[168:171], v[200:203], v[84:87]
	v_mfma_f32_16x16x32_bf16 v[80:83], v[176:179], v[200:203], v[80:83]
	v_mfma_f32_16x16x32_bf16 v[68:71], v[168:171], v[212:215], v[68:71]
	v_mfma_f32_16x16x32_bf16 v[64:67], v[176:179], v[212:215], v[64:67]
	v_mfma_f32_16x16x32_bf16 v[116:119], v[172:175], v[188:191], v[116:119]
	v_mfma_f32_16x16x32_bf16 v[112:115], v[180:183], v[188:191], v[112:115]
	v_mfma_f32_16x16x32_bf16 v[100:103], v[172:175], v[196:199], v[100:103]
	v_mfma_f32_16x16x32_bf16 v[96:99], v[180:183], v[196:199], v[96:99]
	v_mfma_f32_16x16x32_bf16 v[84:87], v[172:175], v[208:211], v[84:87]
	v_mfma_f32_16x16x32_bf16 v[80:83], v[180:183], v[208:211], v[80:83]
	v_mfma_f32_16x16x32_bf16 v[68:71], v[172:175], v[216:219], v[68:71]
	v_mfma_f32_16x16x32_bf16 v[64:67], v[180:183], v[216:219], v[64:67]
	s_setprio 0
	s_barrier
	s_add_i32 s52, s81, s58
	v_lshl_add_u64 v[146:147], v[146:147], 0, s[24:25]
	s_mov_b32 m0, s52
	ds_read_b128 v[184:187], v153 offset:49152
	ds_read_b128 v[188:191], v153 offset:50176
	ds_read_b128 v[192:195], v153 offset:51200
	ds_read_b128 v[196:199], v153 offset:52224
	ds_read_b128 v[200:203], v153 offset:53248
	ds_read_b128 v[208:211], v153 offset:54272
	ds_read_b128 v[212:215], v153 offset:55296
	ds_read_b128 v[216:219], v153 offset:56320
	global_load_lds_dwordx4 v[146:147], off
	s_add_i32 m0, s52, 0x2000
	s_add_u32 s50, s50, 0x40080
	v_lshl_add_u64 v[146:147], v[204:205], 0, s[24:25]
	s_addc_u32 s51, s51, 0
	s_add_i32 s52, s82, s58
	global_load_lds_dwordx4 v[146:147], off
	v_lshl_add_u64 v[146:147], s[50:51], 0, v[130:131]
	s_mov_b32 m0, s52
	s_nop 0
	global_load_lds_dwordx4 v[146:147], off
	v_lshl_add_u64 v[146:147], s[50:51], 0, v[128:129]
	s_add_i32 m0, s52, 0x2000
	s_nop 0
	global_load_lds_dwordx4 v[146:147], off
	v_lshl_add_u64 v[146:147], v[220:221], 0, s[24:25]
	s_mov_b32 m0, s65
	s_nop 0
	global_load_lds_dwordx4 v[146:147], off
	v_lshl_add_u64 v[146:147], v[222:223], 0, s[24:25]
	s_mov_b32 m0, s66
	s_nop 0
	global_load_lds_dwordx4 v[146:147], off
	s_waitcnt vmcnt(8)
	s_waitcnt lgkmcnt(0)
	s_barrier
	s_setprio 1
	s_waitcnt lgkmcnt(0)
	v_mfma_f32_16x16x32_bf16 v[60:63], v[142:145], v[184:187], v[60:63]
	v_mfma_f32_16x16x32_bf16 v[56:59], v[160:163], v[184:187], v[56:59]
	v_mfma_f32_16x16x32_bf16 v[44:47], v[142:145], v[192:195], v[44:47]
	v_mfma_f32_16x16x32_bf16 v[40:43], v[160:163], v[192:195], v[40:43]
	v_mfma_f32_16x16x32_bf16 v[28:31], v[142:145], v[200:203], v[28:31]
	v_mfma_f32_16x16x32_bf16 v[24:27], v[160:163], v[200:203], v[24:27]
	v_mfma_f32_16x16x32_bf16 v[12:15], v[142:145], v[212:215], v[12:15]
	v_mfma_f32_16x16x32_bf16 v[8:11], v[160:163], v[212:215], v[8:11]
	v_mfma_f32_16x16x32_bf16 v[60:63], v[156:159], v[188:191], v[60:63]
	v_mfma_f32_16x16x32_bf16 v[56:59], v[164:167], v[188:191], v[56:59]
	v_mfma_f32_16x16x32_bf16 v[44:47], v[156:159], v[196:199], v[44:47]
	v_mfma_f32_16x16x32_bf16 v[40:43], v[164:167], v[196:199], v[40:43]
	v_mfma_f32_16x16x32_bf16 v[28:31], v[156:159], v[208:211], v[28:31]
	v_mfma_f32_16x16x32_bf16 v[24:27], v[164:167], v[208:211], v[24:27]
	v_mfma_f32_16x16x32_bf16 v[12:15], v[156:159], v[216:219], v[12:15]
	v_mfma_f32_16x16x32_bf16 v[8:11], v[164:167], v[216:219], v[8:11]
	s_setprio 0
	s_setprio 1
	v_mfma_f32_16x16x32_bf16 v[52:55], v[168:171], v[184:187], v[52:55]
	v_mfma_f32_16x16x32_bf16 v[48:51], v[176:179], v[184:187], v[48:51]
	v_mfma_f32_16x16x32_bf16 v[36:39], v[168:171], v[192:195], v[36:39]
	v_mfma_f32_16x16x32_bf16 v[32:35], v[176:179], v[192:195], v[32:35]
	v_mfma_f32_16x16x32_bf16 v[20:23], v[168:171], v[200:203], v[20:23]
	v_mfma_f32_16x16x32_bf16 v[16:19], v[176:179], v[200:203], v[16:19]
	v_mfma_f32_16x16x32_bf16 v[4:7], v[168:171], v[212:215], v[4:7]
	v_mfma_f32_16x16x32_bf16 v[0:3], v[176:179], v[212:215], v[0:3]
	v_mfma_f32_16x16x32_bf16 v[52:55], v[172:175], v[188:191], v[52:55]
	v_mfma_f32_16x16x32_bf16 v[48:51], v[180:183], v[188:191], v[48:51]
	v_mfma_f32_16x16x32_bf16 v[36:39], v[172:175], v[196:199], v[36:39]
	v_mfma_f32_16x16x32_bf16 v[32:35], v[180:183], v[196:199], v[32:35]
	v_mfma_f32_16x16x32_bf16 v[20:23], v[172:175], v[208:211], v[20:23]
	v_mfma_f32_16x16x32_bf16 v[16:19], v[180:183], v[208:211], v[16:19]
	v_mfma_f32_16x16x32_bf16 v[4:7], v[172:175], v[216:219], v[4:7]
	v_mfma_f32_16x16x32_bf16 v[0:3], v[180:183], v[216:219], v[0:3]
	s_setprio 0
	s_barrier
	s_add_i32 s80, s80, 2
	s_add_u32 s10, s10, 0x100
	s_addc_u32 s11, s11, 0
	s_add_u32 s78, s78, 0x100
	s_addc_u32 s79, s79, 0
	s_cmp_gt_u32 s80, 13
	s_cbranch_scc1 .Lpeel_done_8286
.LBB0_340:
	ds_read_b128 v[142:145], v151
	ds_read_b128 v[156:159], v151 offset:1024
	ds_read_b128 v[160:163], v151 offset:2048
	ds_read_b128 v[164:167], v151 offset:3072
	ds_read_b128 v[168:171], v152
	ds_read_b128 v[172:175], v152 offset:1024
	ds_read_b128 v[176:179], v152 offset:2048
	ds_read_b128 v[180:183], v152 offset:3072
	s_add_u32 s50, s10, 0xfffc0080
	s_addc_u32 s51, s11, -1
	s_cmp_eq_u32 s80, 12
	s_cselect_b32 s53, s31, s51
	s_cselect_b32 s52, s76, s50
	s_cselect_b32 s51, s29, s79
	s_cselect_b32 s50, s77, s78
	v_lshl_add_u64 v[146:147], s[10:11], 0, v[134:135]
	s_add_i32 m0, s59, 0xc000
	ds_read_b128 v[184:187], v153
	ds_read_b128 v[188:191], v153 offset:1024
	ds_read_b128 v[192:195], v153 offset:2048
	ds_read_b128 v[196:199], v153 offset:3072
	ds_read_b128 v[200:203], v153 offset:4096
	ds_read_b128 v[208:211], v153 offset:5120
	ds_read_b128 v[212:215], v153 offset:6144
	ds_read_b128 v[216:219], v153 offset:7168
	global_load_lds_dwordx4 v[146:147], off
	v_lshl_add_u64 v[146:147], s[10:11], 0, v[136:137]
	s_add_i32 m0, s59, 0xe000
	s_nop 0
	global_load_lds_dwordx4 v[146:147], off
	s_waitcnt vmcnt(8)
	s_waitcnt lgkmcnt(0)
	s_barrier
	s_waitcnt lgkmcnt(0)
	v_mfma_f32_16x16x32_bf16 v[124:127], v[142:145], v[184:187], v[124:127]
	v_mfma_f32_16x16x32_bf16 v[120:123], v[160:163], v[184:187], v[120:123]
	v_mfma_f32_16x16x32_bf16 v[108:111], v[142:145], v[192:195], v[108:111]
	v_mfma_f32_16x16x32_bf16 v[104:107], v[160:163], v[192:195], v[104:107]
	v_mfma_f32_16x16x32_bf16 v[92:95], v[142:145], v[200:203], v[92:95]
	v_mfma_f32_16x16x32_bf16 v[88:91], v[160:163], v[200:203], v[88:91]
	v_mfma_f32_16x16x32_bf16 v[76:79], v[142:145], v[212:215], v[76:79]
	v_mfma_f32_16x16x32_bf16 v[72:75], v[160:163], v[212:215], v[72:75]
	v_mfma_f32_16x16x32_bf16 v[124:127], v[156:159], v[188:191], v[124:127]
	v_mfma_f32_16x16x32_bf16 v[120:123], v[164:167], v[188:191], v[120:123]
	v_mfma_f32_16x16x32_bf16 v[108:111], v[156:159], v[196:199], v[108:111]
	v_mfma_f32_16x16x32_bf16 v[104:107], v[164:167], v[196:199], v[104:107]
	v_mfma_f32_16x16x32_bf16 v[92:95], v[156:159], v[208:211], v[92:95]
	v_mfma_f32_16x16x32_bf16 v[88:91], v[164:167], v[208:211], v[88:91]
	v_mfma_f32_16x16x32_bf16 v[76:79], v[156:159], v[216:219], v[76:79]
	v_mfma_f32_16x16x32_bf16 v[72:75], v[164:167], v[216:219], v[72:75]
	v_mfma_f32_16x16x32_bf16 v[116:119], v[168:171], v[184:187], v[116:119]
	v_mfma_f32_16x16x32_bf16 v[112:115], v[176:179], v[184:187], v[112:115]
	v_mfma_f32_16x16x32_bf16 v[100:103], v[168:171], v[192:195], v[100:103]
	v_mfma_f32_16x16x32_bf16 v[96:99], v[176:179], v[192:195], v[96:99]
	v_mfma_f32_16x16x32_bf16 v[84:87], v[168:171], v[200:203], v[84:87]
	v_mfma_f32_16x16x32_bf16 v[80:83], v[176:179], v[200:203], v[80:83]
	v_mfma_f32_16x16x32_bf16 v[68:71], v[168:171], v[212:215], v[68:71]
	v_mfma_f32_16x16x32_bf16 v[64:67], v[176:179], v[212:215], v[64:67]
	v_mfma_f32_16x16x32_bf16 v[116:119], v[172:175], v[188:191], v[116:119]
	v_mfma_f32_16x16x32_bf16 v[112:115], v[180:183], v[188:191], v[112:115]
	v_mfma_f32_16x16x32_bf16 v[100:103], v[172:175], v[196:199], v[100:103]
	v_mfma_f32_16x16x32_bf16 v[96:99], v[180:183], v[196:199], v[96:99]
	v_mfma_f32_16x16x32_bf16 v[84:87], v[172:175], v[208:211], v[84:87]
	v_mfma_f32_16x16x32_bf16 v[80:83], v[180:183], v[208:211], v[80:83]
	v_mfma_f32_16x16x32_bf16 v[68:71], v[172:175], v[216:219], v[68:71]
	v_mfma_f32_16x16x32_bf16 v[64:67], v[180:183], v[216:219], v[64:67]
	s_barrier
	s_add_i32 s81, s68, s58
	v_lshl_add_u64 v[146:147], s[50:51], 0, v[130:131]
	s_mov_b32 m0, s81
	ds_read_b128 v[184:187], v153 offset:16384
	ds_read_b128 v[188:191], v153 offset:17408
	ds_read_b128 v[192:195], v153 offset:18432
	ds_read_b128 v[196:199], v153 offset:19456
	ds_read_b128 v[200:203], v153 offset:20480
	ds_read_b128 v[208:211], v153 offset:21504
	ds_read_b128 v[212:215], v153 offset:22528
	ds_read_b128 v[216:219], v153 offset:23552
	global_load_lds_dwordx4 v[146:147], off
	s_add_i32 m0, s81, 0x2000
	s_add_u32 s82, s50, 0x40000
	v_lshl_add_u64 v[204:205], s[50:51], 0, v[128:129]
	s_addc_u32 s83, s51, 0
	s_add_i32 s81, s69, s58
	global_load_lds_dwordx4 v[204:205], off
	v_lshl_add_u64 v[220:221], s[82:83], 0, v[130:131]
	s_mov_b32 m0, s81
	v_lshl_add_u64 v[222:223], s[52:53], 0, v[128:129]
	global_load_lds_dwordx4 v[220:221], off
	v_lshl_add_u64 v[220:221], s[82:83], 0, v[128:129]
	s_add_i32 m0, s81, 0x2000
	s_nop 0
	global_load_lds_dwordx4 v[220:221], off
	v_lshl_add_u64 v[220:221], s[52:53], 0, v[130:131]
	s_mov_b32 m0, s59
	s_nop 0
	global_load_lds_dwordx4 v[220:221], off
	s_mov_b32 m0, s60
	s_nop 0
	global_load_lds_dwordx4 v[222:223], off
	s_waitcnt vmcnt(8)
	s_waitcnt lgkmcnt(0)
	s_barrier
	s_waitcnt lgkmcnt(0)
	v_mfma_f32_16x16x32_bf16 v[60:63], v[142:145], v[184:187], v[60:63]
	v_mfma_f32_16x16x32_bf16 v[56:59], v[160:163], v[184:187], v[56:59]
	v_mfma_f32_16x16x32_bf16 v[44:47], v[142:145], v[192:195], v[44:47]
	v_mfma_f32_16x16x32_bf16 v[40:43], v[160:163], v[192:195], v[40:43]
	v_mfma_f32_16x16x32_bf16 v[28:31], v[142:145], v[200:203], v[28:31]
	v_mfma_f32_16x16x32_bf16 v[24:27], v[160:163], v[200:203], v[24:27]
	v_mfma_f32_16x16x32_bf16 v[12:15], v[142:145], v[212:215], v[12:15]
	v_mfma_f32_16x16x32_bf16 v[8:11], v[160:163], v[212:215], v[8:11]
	v_mfma_f32_16x16x32_bf16 v[60:63], v[156:159], v[188:191], v[60:63]
	v_mfma_f32_16x16x32_bf16 v[56:59], v[164:167], v[188:191], v[56:59]
	v_mfma_f32_16x16x32_bf16 v[44:47], v[156:159], v[196:199], v[44:47]
	v_mfma_f32_16x16x32_bf16 v[40:43], v[164:167], v[196:199], v[40:43]
	v_mfma_f32_16x16x32_bf16 v[28:31], v[156:159], v[208:211], v[28:31]
	v_mfma_f32_16x16x32_bf16 v[24:27], v[164:167], v[208:211], v[24:27]
	v_mfma_f32_16x16x32_bf16 v[12:15], v[156:159], v[216:219], v[12:15]
	v_mfma_f32_16x16x32_bf16 v[8:11], v[164:167], v[216:219], v[8:11]
	v_mfma_f32_16x16x32_bf16 v[52:55], v[168:171], v[184:187], v[52:55]
	v_mfma_f32_16x16x32_bf16 v[48:51], v[176:179], v[184:187], v[48:51]
	v_mfma_f32_16x16x32_bf16 v[36:39], v[168:171], v[192:195], v[36:39]
	v_mfma_f32_16x16x32_bf16 v[32:35], v[176:179], v[192:195], v[32:35]
	v_mfma_f32_16x16x32_bf16 v[20:23], v[168:171], v[200:203], v[20:23]
	v_mfma_f32_16x16x32_bf16 v[16:19], v[176:179], v[200:203], v[16:19]
	v_mfma_f32_16x16x32_bf16 v[4:7], v[168:171], v[212:215], v[4:7]
	v_mfma_f32_16x16x32_bf16 v[0:3], v[176:179], v[212:215], v[0:3]
	v_mfma_f32_16x16x32_bf16 v[52:55], v[172:175], v[188:191], v[52:55]
	v_mfma_f32_16x16x32_bf16 v[48:51], v[180:183], v[188:191], v[48:51]
	v_mfma_f32_16x16x32_bf16 v[36:39], v[172:175], v[196:199], v[36:39]
	v_mfma_f32_16x16x32_bf16 v[32:35], v[180:183], v[196:199], v[32:35]
	v_mfma_f32_16x16x32_bf16 v[20:23], v[172:175], v[208:211], v[20:23]
	v_mfma_f32_16x16x32_bf16 v[16:19], v[180:183], v[208:211], v[16:19]
	v_mfma_f32_16x16x32_bf16 v[4:7], v[172:175], v[216:219], v[4:7]
	v_mfma_f32_16x16x32_bf16 v[0:3], v[180:183], v[216:219], v[0:3]
	s_barrier
	s_add_i32 s81, 0, 0x18000
	v_add_u32_e32 v132, s81, v149
	s_add_i32 s82, 0, 0x1c000
	ds_read_b128 v[142:145], v132
	ds_read_b128 v[156:159], v132 offset:1024
	ds_read_b128 v[160:163], v132 offset:2048
	ds_read_b128 v[164:167], v132 offset:3072
	v_add_u32_e32 v132, s82, v149
	ds_read_b128 v[168:171], v132
	ds_read_b128 v[172:175], v132 offset:1024
	ds_read_b128 v[176:179], v132 offset:2048
	ds_read_b128 v[180:183], v132 offset:3072
	s_add_u32 s52, s52, 0x40000
	s_addc_u32 s53, s53, 0
	s_mov_b32 m0, s61
	v_lshl_add_u64 v[224:225], s[52:53], 0, v[130:131]
	ds_read_b128 v[184:187], v153 offset:32768
	ds_read_b128 v[188:191], v153 offset:33792
	ds_read_b128 v[192:195], v153 offset:34816
	ds_read_b128 v[196:199], v153 offset:35840
	ds_read_b128 v[200:203], v153 offset:36864
	ds_read_b128 v[208:211], v153 offset:37888
	ds_read_b128 v[212:215], v153 offset:38912
	ds_read_b128 v[216:219], v153 offset:39936
	global_load_lds_dwordx4 v[224:225], off
	v_lshl_add_u64 v[224:225], s[52:53], 0, v[128:129]
	s_mov_b32 m0, s62
	s_nop 0
	global_load_lds_dwordx4 v[224:225], off
	s_waitcnt vmcnt(8)
	s_waitcnt lgkmcnt(0)
	s_barrier
	s_waitcnt lgkmcnt(0)
	v_mfma_f32_16x16x32_bf16 v[124:127], v[142:145], v[184:187], v[124:127]
	v_mfma_f32_16x16x32_bf16 v[120:123], v[160:163], v[184:187], v[120:123]
	v_mfma_f32_16x16x32_bf16 v[108:111], v[142:145], v[192:195], v[108:111]
	v_mfma_f32_16x16x32_bf16 v[104:107], v[160:163], v[192:195], v[104:107]
	v_mfma_f32_16x16x32_bf16 v[92:95], v[142:145], v[200:203], v[92:95]
	v_mfma_f32_16x16x32_bf16 v[88:91], v[160:163], v[200:203], v[88:91]
	v_mfma_f32_16x16x32_bf16 v[76:79], v[142:145], v[212:215], v[76:79]
	v_mfma_f32_16x16x32_bf16 v[72:75], v[160:163], v[212:215], v[72:75]
	v_mfma_f32_16x16x32_bf16 v[124:127], v[156:159], v[188:191], v[124:127]
	v_mfma_f32_16x16x32_bf16 v[120:123], v[164:167], v[188:191], v[120:123]
	v_mfma_f32_16x16x32_bf16 v[108:111], v[156:159], v[196:199], v[108:111]
	v_mfma_f32_16x16x32_bf16 v[104:107], v[164:167], v[196:199], v[104:107]
	v_mfma_f32_16x16x32_bf16 v[92:95], v[156:159], v[208:211], v[92:95]
	v_mfma_f32_16x16x32_bf16 v[88:91], v[164:167], v[208:211], v[88:91]
	v_mfma_f32_16x16x32_bf16 v[76:79], v[156:159], v[216:219], v[76:79]
	v_mfma_f32_16x16x32_bf16 v[72:75], v[164:167], v[216:219], v[72:75]
	v_mfma_f32_16x16x32_bf16 v[116:119], v[168:171], v[184:187], v[116:119]
	v_mfma_f32_16x16x32_bf16 v[112:115], v[176:179], v[184:187], v[112:115]
	v_mfma_f32_16x16x32_bf16 v[100:103], v[168:171], v[192:195], v[100:103]
	v_mfma_f32_16x16x32_bf16 v[96:99], v[176:179], v[192:195], v[96:99]
	v_mfma_f32_16x16x32_bf16 v[84:87], v[168:171], v[200:203], v[84:87]
	v_mfma_f32_16x16x32_bf16 v[80:83], v[176:179], v[200:203], v[80:83]
	v_mfma_f32_16x16x32_bf16 v[68:71], v[168:171], v[212:215], v[68:71]
	v_mfma_f32_16x16x32_bf16 v[64:67], v[176:179], v[212:215], v[64:67]
	v_mfma_f32_16x16x32_bf16 v[116:119], v[172:175], v[188:191], v[116:119]
	v_mfma_f32_16x16x32_bf16 v[112:115], v[180:183], v[188:191], v[112:115]
	v_mfma_f32_16x16x32_bf16 v[100:103], v[172:175], v[196:199], v[100:103]
	v_mfma_f32_16x16x32_bf16 v[96:99], v[180:183], v[196:199], v[96:99]
	v_mfma_f32_16x16x32_bf16 v[84:87], v[172:175], v[208:211], v[84:87]
	v_mfma_f32_16x16x32_bf16 v[80:83], v[180:183], v[208:211], v[80:83]
	v_mfma_f32_16x16x32_bf16 v[68:71], v[172:175], v[216:219], v[68:71]
	v_mfma_f32_16x16x32_bf16 v[64:67], v[180:183], v[216:219], v[64:67]
	s_barrier
	s_add_i32 s52, s81, s58
	v_lshl_add_u64 v[146:147], v[146:147], 0, s[24:25]
	s_mov_b32 m0, s52
	ds_read_b128 v[184:187], v153 offset:49152
	ds_read_b128 v[188:191], v153 offset:50176
	ds_read_b128 v[192:195], v153 offset:51200
	ds_read_b128 v[196:199], v153 offset:52224
	ds_read_b128 v[200:203], v153 offset:53248
	ds_read_b128 v[208:211], v153 offset:54272
	ds_read_b128 v[212:215], v153 offset:55296
	ds_read_b128 v[216:219], v153 offset:56320
	global_load_lds_dwordx4 v[146:147], off
	s_add_i32 m0, s52, 0x2000
	s_add_u32 s50, s50, 0x40080
	v_lshl_add_u64 v[146:147], v[204:205], 0, s[24:25]
	s_addc_u32 s51, s51, 0
	s_add_i32 s52, s82, s58
	global_load_lds_dwordx4 v[146:147], off
	v_lshl_add_u64 v[146:147], s[50:51], 0, v[130:131]
	s_mov_b32 m0, s52
	s_nop 0
	global_load_lds_dwordx4 v[146:147], off
	v_lshl_add_u64 v[146:147], s[50:51], 0, v[128:129]
	s_add_i32 m0, s52, 0x2000
	s_nop 0
	global_load_lds_dwordx4 v[146:147], off
	v_lshl_add_u64 v[146:147], v[220:221], 0, s[24:25]
	s_mov_b32 m0, s65
	s_nop 0
	global_load_lds_dwordx4 v[146:147], off
	v_lshl_add_u64 v[146:147], v[222:223], 0, s[24:25]
	s_mov_b32 m0, s66
	s_nop 0
	global_load_lds_dwordx4 v[146:147], off
	s_waitcnt vmcnt(8)
	s_waitcnt lgkmcnt(0)
	s_barrier
	s_waitcnt lgkmcnt(0)
	v_mfma_f32_16x16x32_bf16 v[60:63], v[142:145], v[184:187], v[60:63]
	v_mfma_f32_16x16x32_bf16 v[56:59], v[160:163], v[184:187], v[56:59]
	v_mfma_f32_16x16x32_bf16 v[44:47], v[142:145], v[192:195], v[44:47]
	v_mfma_f32_16x16x32_bf16 v[40:43], v[160:163], v[192:195], v[40:43]
	v_mfma_f32_16x16x32_bf16 v[28:31], v[142:145], v[200:203], v[28:31]
	v_mfma_f32_16x16x32_bf16 v[24:27], v[160:163], v[200:203], v[24:27]
	v_mfma_f32_16x16x32_bf16 v[12:15], v[142:145], v[212:215], v[12:15]
	v_mfma_f32_16x16x32_bf16 v[8:11], v[160:163], v[212:215], v[8:11]
	v_mfma_f32_16x16x32_bf16 v[60:63], v[156:159], v[188:191], v[60:63]
	v_mfma_f32_16x16x32_bf16 v[56:59], v[164:167], v[188:191], v[56:59]
	v_mfma_f32_16x16x32_bf16 v[44:47], v[156:159], v[196:199], v[44:47]
	v_mfma_f32_16x16x32_bf16 v[40:43], v[164:167], v[196:199], v[40:43]
	v_mfma_f32_16x16x32_bf16 v[28:31], v[156:159], v[208:211], v[28:31]
	v_mfma_f32_16x16x32_bf16 v[24:27], v[164:167], v[208:211], v[24:27]
	v_mfma_f32_16x16x32_bf16 v[12:15], v[156:159], v[216:219], v[12:15]
	v_mfma_f32_16x16x32_bf16 v[8:11], v[164:167], v[216:219], v[8:11]
	v_mfma_f32_16x16x32_bf16 v[52:55], v[168:171], v[184:187], v[52:55]
	v_mfma_f32_16x16x32_bf16 v[48:51], v[176:179], v[184:187], v[48:51]
	v_mfma_f32_16x16x32_bf16 v[36:39], v[168:171], v[192:195], v[36:39]
	v_mfma_f32_16x16x32_bf16 v[32:35], v[176:179], v[192:195], v[32:35]
	v_mfma_f32_16x16x32_bf16 v[20:23], v[168:171], v[200:203], v[20:23]
	v_mfma_f32_16x16x32_bf16 v[16:19], v[176:179], v[200:203], v[16:19]
	v_mfma_f32_16x16x32_bf16 v[4:7], v[168:171], v[212:215], v[4:7]
	v_mfma_f32_16x16x32_bf16 v[0:3], v[176:179], v[212:215], v[0:3]
	v_mfma_f32_16x16x32_bf16 v[52:55], v[172:175], v[188:191], v[52:55]
	v_mfma_f32_16x16x32_bf16 v[48:51], v[180:183], v[188:191], v[48:51]
	v_mfma_f32_16x16x32_bf16 v[36:39], v[172:175], v[196:199], v[36:39]
	v_mfma_f32_16x16x32_bf16 v[32:35], v[180:183], v[196:199], v[32:35]
	v_mfma_f32_16x16x32_bf16 v[20:23], v[172:175], v[208:211], v[20:23]
	v_mfma_f32_16x16x32_bf16 v[16:19], v[180:183], v[208:211], v[16:19]
	v_mfma_f32_16x16x32_bf16 v[4:7], v[172:175], v[216:219], v[4:7]
	v_mfma_f32_16x16x32_bf16 v[0:3], v[180:183], v[216:219], v[0:3]
	s_barrier
	s_add_i32 s80, s80, 2
	s_add_u32 s10, s10, 0x100
	s_addc_u32 s11, s11, 0
	s_add_u32 s78, s78, 0x100
	s_addc_u32 s79, s79, 0
	s_cmp_gt_u32 s80, 13
	s_cbranch_scc0 .LBB0_340
.Lpeel_done_8286:
	s_and_b64 vcc, exec, s[26:27]
	s_cbranch_vccz .LBB0_343
	s_barrier

.LBB0_415:
	s_ashr_i32 s27, s26, 31
	s_lshl_b64 s[28:29], s[26:27], 19
	s_add_u32 s28, s48, s28
	s_addc_u32 s29, s49, s29
	s_and_b64 s[30:31], s[10:11], exec
	s_cselect_b32 s27, s29, s41
	s_cselect_b32 s66, s28, s40
	s_ashr_i32 s25, s24, 31
	s_lshl_b64 s[30:31], s[24:25], 19
	s_add_u32 s30, s52, s30
	s_addc_u32 s31, s53, s31
	s_and_b64 s[50:51], s[10:11], exec
	s_cselect_b32 s25, s31, s43
	s_cselect_b32 s67, s30, s42
	s_add_u32 s40, s40, 0x40080
	s_addc_u32 s41, s41, 0
	s_add_u32 s68, s42, 0x100
	s_addc_u32 s69, s43, 0
	s_mov_b32 s70, -2
	ds_read_b128 v[146:149], v154
	ds_read_b128 v[158:161], v154 offset:1024
	ds_read_b128 v[162:165], v154 offset:2048
	ds_read_b128 v[166:169], v154 offset:3072
	ds_read_b128 v[170:173], v155
	ds_read_b128 v[174:177], v155 offset:1024
	ds_read_b128 v[178:181], v155 offset:2048
	ds_read_b128 v[182:185], v155 offset:3072
	s_add_u32 s42, s40, 0xfffc0080
	s_addc_u32 s43, s41, -1
	s_cmp_eq_u32 s70, 12
	s_cselect_b32 s51, s27, s43
	s_cselect_b32 s50, s66, s42
	s_cselect_b32 s43, s25, s69
	s_cselect_b32 s42, s67, s68
	v_lshl_add_u64 v[150:151], s[40:41], 0, v[138:139]
	s_add_i32 m0, s55, 0xc000
	ds_read_b128 v[186:189], v156
	ds_read_b128 v[190:193], v156 offset:1024
	ds_read_b128 v[194:197], v156 offset:2048
	ds_read_b128 v[198:201], v156 offset:3072
	ds_read_b128 v[202:205], v156 offset:4096
	ds_read_b128 v[208:211], v156 offset:5120
	ds_read_b128 v[212:215], v156 offset:6144
	ds_read_b128 v[216:219], v156 offset:7168
	global_load_lds_dwordx4 v[150:151], off
	v_lshl_add_u64 v[150:151], s[40:41], 0, v[140:141]
	s_add_i32 m0, s55, 0xe000
	s_nop 0
	global_load_lds_dwordx4 v[150:151], off
	s_waitcnt vmcnt(8)
	s_waitcnt lgkmcnt(0)
	s_barrier
	s_setprio 1
	s_waitcnt lgkmcnt(0)
	v_mfma_f32_16x16x32_bf16 v[124:127], v[146:149], v[186:189], 0
	v_mfma_f32_16x16x32_bf16 v[120:123], v[162:165], v[186:189], 0
	v_mfma_f32_16x16x32_bf16 v[108:111], v[146:149], v[194:197], 0
	v_mfma_f32_16x16x32_bf16 v[104:107], v[162:165], v[194:197], 0
	v_mfma_f32_16x16x32_bf16 v[92:95], v[146:149], v[202:205], 0
	v_mfma_f32_16x16x32_bf16 v[88:91], v[162:165], v[202:205], 0
	v_mfma_f32_16x16x32_bf16 v[76:79], v[146:149], v[212:215], 0
	v_mfma_f32_16x16x32_bf16 v[72:75], v[162:165], v[212:215], 0
	v_mfma_f32_16x16x32_bf16 v[124:127], v[158:161], v[190:193], v[124:127]
	v_mfma_f32_16x16x32_bf16 v[120:123], v[166:169], v[190:193], v[120:123]
	v_mfma_f32_16x16x32_bf16 v[108:111], v[158:161], v[198:201], v[108:111]
	v_mfma_f32_16x16x32_bf16 v[104:107], v[166:169], v[198:201], v[104:107]
	v_mfma_f32_16x16x32_bf16 v[92:95], v[158:161], v[208:211], v[92:95]
	v_mfma_f32_16x16x32_bf16 v[88:91], v[166:169], v[208:211], v[88:91]
	v_mfma_f32_16x16x32_bf16 v[76:79], v[158:161], v[216:219], v[76:79]
	v_mfma_f32_16x16x32_bf16 v[72:75], v[166:169], v[216:219], v[72:75]
	s_setprio 0
	s_setprio 1
	v_mfma_f32_16x16x32_bf16 v[116:119], v[170:173], v[186:189], 0
	v_mfma_f32_16x16x32_bf16 v[112:115], v[178:181], v[186:189], 0
	v_mfma_f32_16x16x32_bf16 v[100:103], v[170:173], v[194:197], 0
	v_mfma_f32_16x16x32_bf16 v[96:99], v[178:181], v[194:197], 0
	v_mfma_f32_16x16x32_bf16 v[84:87], v[170:173], v[202:205], 0
	v_mfma_f32_16x16x32_bf16 v[80:83], v[178:181], v[202:205], 0
	v_mfma_f32_16x16x32_bf16 v[68:71], v[170:173], v[212:215], 0
	v_mfma_f32_16x16x32_bf16 v[64:67], v[178:181], v[212:215], 0
	v_mfma_f32_16x16x32_bf16 v[116:119], v[174:177], v[190:193], v[116:119]
	v_mfma_f32_16x16x32_bf16 v[112:115], v[182:185], v[190:193], v[112:115]
	v_mfma_f32_16x16x32_bf16 v[100:103], v[174:177], v[198:201], v[100:103]
	v_mfma_f32_16x16x32_bf16 v[96:99], v[182:185], v[198:201], v[96:99]
	v_mfma_f32_16x16x32_bf16 v[84:87], v[174:177], v[208:211], v[84:87]
	v_mfma_f32_16x16x32_bf16 v[80:83], v[182:185], v[208:211], v[80:83]
	v_mfma_f32_16x16x32_bf16 v[68:71], v[174:177], v[216:219], v[68:71]
	v_mfma_f32_16x16x32_bf16 v[64:67], v[182:185], v[216:219], v[64:67]
	s_setprio 0
	s_barrier
	s_add_i32 s71, s62, s54
	v_lshl_add_u64 v[150:151], s[42:43], 0, v[132:133]
	s_mov_b32 m0, s71
	ds_read_b128 v[186:189], v156 offset:16384
	ds_read_b128 v[190:193], v156 offset:17408
	ds_read_b128 v[194:197], v156 offset:18432
	ds_read_b128 v[198:201], v156 offset:19456
	ds_read_b128 v[202:205], v156 offset:20480
	ds_read_b128 v[208:211], v156 offset:21504
	ds_read_b128 v[212:215], v156 offset:22528
	ds_read_b128 v[216:219], v156 offset:23552
	global_load_lds_dwordx4 v[150:151], off
	s_add_i32 m0, s71, 0x2000
	s_add_u32 s72, s42, 0x40000
	v_lshl_add_u64 v[220:221], s[42:43], 0, v[136:137]
	s_addc_u32 s73, s43, 0
	s_add_i32 s71, s63, s54
	global_load_lds_dwordx4 v[220:221], off
	v_lshl_add_u64 v[222:223], s[72:73], 0, v[132:133]
	s_mov_b32 m0, s71
	v_lshl_add_u64 v[224:225], s[50:51], 0, v[134:135]
	global_load_lds_dwordx4 v[222:223], off
	v_lshl_add_u64 v[222:223], s[72:73], 0, v[136:137]
	s_add_i32 m0, s71, 0x2000
	s_nop 0
	global_load_lds_dwordx4 v[222:223], off
	v_lshl_add_u64 v[222:223], s[50:51], 0, v[130:131]
	s_mov_b32 m0, s55
	s_nop 0
	global_load_lds_dwordx4 v[222:223], off
	s_mov_b32 m0, s56
	s_nop 0
	global_load_lds_dwordx4 v[224:225], off
	s_waitcnt vmcnt(8)
	s_waitcnt lgkmcnt(0)
	s_barrier
	s_setprio 1
	s_waitcnt lgkmcnt(0)
	v_mfma_f32_16x16x32_bf16 v[60:63], v[146:149], v[186:189], 0
	v_mfma_f32_16x16x32_bf16 v[56:59], v[162:165], v[186:189], 0
	v_mfma_f32_16x16x32_bf16 v[44:47], v[146:149], v[194:197], 0
	v_mfma_f32_16x16x32_bf16 v[40:43], v[162:165], v[194:197], 0
	v_mfma_f32_16x16x32_bf16 v[28:31], v[146:149], v[202:205], 0
	v_mfma_f32_16x16x32_bf16 v[24:27], v[162:165], v[202:205], 0
	v_mfma_f32_16x16x32_bf16 v[12:15], v[146:149], v[212:215], 0
	v_mfma_f32_16x16x32_bf16 v[8:11], v[162:165], v[212:215], 0
	v_mfma_f32_16x16x32_bf16 v[60:63], v[158:161], v[190:193], v[60:63]
	v_mfma_f32_16x16x32_bf16 v[56:59], v[166:169], v[190:193], v[56:59]
	v_mfma_f32_16x16x32_bf16 v[44:47], v[158:161], v[198:201], v[44:47]
	v_mfma_f32_16x16x32_bf16 v[40:43], v[166:169], v[198:201], v[40:43]
	v_mfma_f32_16x16x32_bf16 v[28:31], v[158:161], v[208:211], v[28:31]
	v_mfma_f32_16x16x32_bf16 v[24:27], v[166:169], v[208:211], v[24:27]
	v_mfma_f32_16x16x32_bf16 v[12:15], v[158:161], v[216:219], v[12:15]
	v_mfma_f32_16x16x32_bf16 v[8:11], v[166:169], v[216:219], v[8:11]
	s_setprio 0
	s_setprio 1
	v_mfma_f32_16x16x32_bf16 v[52:55], v[170:173], v[186:189], 0
	v_mfma_f32_16x16x32_bf16 v[48:51], v[178:181], v[186:189], 0
	v_mfma_f32_16x16x32_bf16 v[36:39], v[170:173], v[194:197], 0
	v_mfma_f32_16x16x32_bf16 v[32:35], v[178:181], v[194:197], 0
	v_mfma_f32_16x16x32_bf16 v[20:23], v[170:173], v[202:205], 0
	v_mfma_f32_16x16x32_bf16 v[16:19], v[178:181], v[202:205], 0
	v_mfma_f32_16x16x32_bf16 v[4:7], v[170:173], v[212:215], 0
	v_mfma_f32_16x16x32_bf16 v[0:3], v[178:181], v[212:215], 0
	v_mfma_f32_16x16x32_bf16 v[52:55], v[174:177], v[190:193], v[52:55]
	v_mfma_f32_16x16x32_bf16 v[48:51], v[182:185], v[190:193], v[48:51]
	v_mfma_f32_16x16x32_bf16 v[36:39], v[174:177], v[198:201], v[36:39]
	v_mfma_f32_16x16x32_bf16 v[32:35], v[182:185], v[198:201], v[32:35]
	v_mfma_f32_16x16x32_bf16 v[20:23], v[174:177], v[208:211], v[20:23]
	v_mfma_f32_16x16x32_bf16 v[16:19], v[182:185], v[208:211], v[16:19]
	v_mfma_f32_16x16x32_bf16 v[4:7], v[174:177], v[216:219], v[4:7]
	v_mfma_f32_16x16x32_bf16 v[0:3], v[182:185], v[216:219], v[0:3]
	s_setprio 0
	s_barrier
	s_add_i32 s71, 0, 0x18000
	s_add_i32 s72, 0, 0x1c000
	v_add_u32_e32 v166, s71, v152
	v_add_u32_e32 v182, s72, v152
	ds_read_b128 v[146:149], v166
	ds_read_b128 v[158:161], v166 offset:1024
	ds_read_b128 v[162:165], v166 offset:2048
	ds_read_b128 v[166:169], v166 offset:3072
	ds_read_b128 v[170:173], v182
	ds_read_b128 v[174:177], v182 offset:1024
	ds_read_b128 v[178:181], v182 offset:2048
	ds_read_b128 v[182:185], v182 offset:3072
	s_add_u32 s50, s50, 0x40000
	s_addc_u32 s51, s51, 0
	s_mov_b32 m0, s57
	v_lshl_add_u64 v[226:227], s[50:51], 0, v[130:131]
	ds_read_b128 v[186:189], v156 offset:32768
	ds_read_b128 v[190:193], v156 offset:33792
	ds_read_b128 v[194:197], v156 offset:34816
	ds_read_b128 v[198:201], v156 offset:35840
	ds_read_b128 v[202:205], v156 offset:36864
	ds_read_b128 v[208:211], v156 offset:37888
	ds_read_b128 v[212:215], v156 offset:38912
	ds_read_b128 v[216:219], v156 offset:39936
	global_load_lds_dwordx4 v[226:227], off
	v_lshl_add_u64 v[226:227], s[50:51], 0, v[134:135]
	s_mov_b32 m0, s58
	s_nop 0
	global_load_lds_dwordx4 v[226:227], off
	s_waitcnt vmcnt(8)
	s_waitcnt lgkmcnt(0)
	s_barrier
	s_setprio 1
	s_waitcnt lgkmcnt(0)
	v_mfma_f32_16x16x32_bf16 v[124:127], v[146:149], v[186:189], v[124:127]
	v_mfma_f32_16x16x32_bf16 v[120:123], v[162:165], v[186:189], v[120:123]
	v_mfma_f32_16x16x32_bf16 v[108:111], v[146:149], v[194:197], v[108:111]
	v_mfma_f32_16x16x32_bf16 v[104:107], v[162:165], v[194:197], v[104:107]
	v_mfma_f32_16x16x32_bf16 v[92:95], v[146:149], v[202:205], v[92:95]
	v_mfma_f32_16x16x32_bf16 v[88:91], v[162:165], v[202:205], v[88:91]
	v_mfma_f32_16x16x32_bf16 v[76:79], v[146:149], v[212:215], v[76:79]
	v_mfma_f32_16x16x32_bf16 v[72:75], v[162:165], v[212:215], v[72:75]
	v_mfma_f32_16x16x32_bf16 v[124:127], v[158:161], v[190:193], v[124:127]
	v_mfma_f32_16x16x32_bf16 v[120:123], v[166:169], v[190:193], v[120:123]
	v_mfma_f32_16x16x32_bf16 v[108:111], v[158:161], v[198:201], v[108:111]
	v_mfma_f32_16x16x32_bf16 v[104:107], v[166:169], v[198:201], v[104:107]
	v_mfma_f32_16x16x32_bf16 v[92:95], v[158:161], v[208:211], v[92:95]
	v_mfma_f32_16x16x32_bf16 v[88:91], v[166:169], v[208:211], v[88:91]
	v_mfma_f32_16x16x32_bf16 v[76:79], v[158:161], v[216:219], v[76:79]
	v_mfma_f32_16x16x32_bf16 v[72:75], v[166:169], v[216:219], v[72:75]
	s_setprio 0
	s_setprio 1
	v_mfma_f32_16x16x32_bf16 v[116:119], v[170:173], v[186:189], v[116:119]
	v_mfma_f32_16x16x32_bf16 v[112:115], v[178:181], v[186:189], v[112:115]
	v_mfma_f32_16x16x32_bf16 v[100:103], v[170:173], v[194:197], v[100:103]
	v_mfma_f32_16x16x32_bf16 v[96:99], v[178:181], v[194:197], v[96:99]
	v_mfma_f32_16x16x32_bf16 v[84:87], v[170:173], v[202:205], v[84:87]
	v_mfma_f32_16x16x32_bf16 v[80:83], v[178:181], v[202:205], v[80:83]
	v_mfma_f32_16x16x32_bf16 v[68:71], v[170:173], v[212:215], v[68:71]
	v_mfma_f32_16x16x32_bf16 v[64:67], v[178:181], v[212:215], v[64:67]
	v_mfma_f32_16x16x32_bf16 v[116:119], v[174:177], v[190:193], v[116:119]
	v_mfma_f32_16x16x32_bf16 v[112:115], v[182:185], v[190:193], v[112:115]
	v_mfma_f32_16x16x32_bf16 v[100:103], v[174:177], v[198:201], v[100:103]
	v_mfma_f32_16x16x32_bf16 v[96:99], v[182:185], v[198:201], v[96:99]
	v_mfma_f32_16x16x32_bf16 v[84:87], v[174:177], v[208:211], v[84:87]
	v_mfma_f32_16x16x32_bf16 v[80:83], v[182:185], v[208:211], v[80:83]
	v_mfma_f32_16x16x32_bf16 v[68:71], v[174:177], v[216:219], v[68:71]
	v_mfma_f32_16x16x32_bf16 v[64:67], v[182:185], v[216:219], v[64:67]
	s_setprio 0
	s_barrier
	s_add_i32 s50, s71, s54
	v_lshl_add_u64 v[150:151], v[150:151], 0, s[16:17]
	s_mov_b32 m0, s50
	ds_read_b128 v[186:189], v156 offset:49152
	ds_read_b128 v[190:193], v156 offset:50176
	ds_read_b128 v[194:197], v156 offset:51200
	ds_read_b128 v[198:201], v156 offset:52224
	ds_read_b128 v[202:205], v156 offset:53248
	ds_read_b128 v[208:211], v156 offset:54272
	ds_read_b128 v[212:215], v156 offset:55296
	ds_read_b128 v[216:219], v156 offset:56320
	global_load_lds_dwordx4 v[150:151], off
	s_add_i32 m0, s50, 0x2000
	s_add_u32 s42, s42, 0x40080
	v_lshl_add_u64 v[150:151], v[220:221], 0, s[16:17]
	s_addc_u32 s43, s43, 0
	s_add_i32 s50, s72, s54
	global_load_lds_dwordx4 v[150:151], off
	v_lshl_add_u64 v[150:151], s[42:43], 0, v[132:133]
	s_mov_b32 m0, s50
	s_nop 0
	global_load_lds_dwordx4 v[150:151], off
	v_lshl_add_u64 v[150:151], s[42:43], 0, v[136:137]
	s_add_i32 m0, s50, 0x2000
	s_nop 0
	global_load_lds_dwordx4 v[150:151], off
	v_lshl_add_u64 v[150:151], v[222:223], 0, s[16:17]
	s_mov_b32 m0, s60
	s_nop 0
	global_load_lds_dwordx4 v[150:151], off
	v_lshl_add_u64 v[150:151], v[224:225], 0, s[16:17]
	s_mov_b32 m0, s61
	s_nop 0
	global_load_lds_dwordx4 v[150:151], off
	s_waitcnt vmcnt(8)
	s_waitcnt lgkmcnt(0)
	s_barrier
	s_setprio 1
	s_waitcnt lgkmcnt(0)
	v_mfma_f32_16x16x32_bf16 v[60:63], v[146:149], v[186:189], v[60:63]
	v_mfma_f32_16x16x32_bf16 v[56:59], v[162:165], v[186:189], v[56:59]
	v_mfma_f32_16x16x32_bf16 v[44:47], v[146:149], v[194:197], v[44:47]
	v_mfma_f32_16x16x32_bf16 v[40:43], v[162:165], v[194:197], v[40:43]
	v_mfma_f32_16x16x32_bf16 v[28:31], v[146:149], v[202:205], v[28:31]
	v_mfma_f32_16x16x32_bf16 v[24:27], v[162:165], v[202:205], v[24:27]
	v_mfma_f32_16x16x32_bf16 v[12:15], v[146:149], v[212:215], v[12:15]
	v_mfma_f32_16x16x32_bf16 v[8:11], v[162:165], v[212:215], v[8:11]
	v_mfma_f32_16x16x32_bf16 v[60:63], v[158:161], v[190:193], v[60:63]
	v_mfma_f32_16x16x32_bf16 v[56:59], v[166:169], v[190:193], v[56:59]
	v_mfma_f32_16x16x32_bf16 v[44:47], v[158:161], v[198:201], v[44:47]
	v_mfma_f32_16x16x32_bf16 v[40:43], v[166:169], v[198:201], v[40:43]
	v_mfma_f32_16x16x32_bf16 v[28:31], v[158:161], v[208:211], v[28:31]
	v_mfma_f32_16x16x32_bf16 v[24:27], v[166:169], v[208:211], v[24:27]
	v_mfma_f32_16x16x32_bf16 v[12:15], v[158:161], v[216:219], v[12:15]
	v_mfma_f32_16x16x32_bf16 v[8:11], v[166:169], v[216:219], v[8:11]
	s_setprio 0
	s_setprio 1
	v_mfma_f32_16x16x32_bf16 v[52:55], v[170:173], v[186:189], v[52:55]
	v_mfma_f32_16x16x32_bf16 v[48:51], v[178:181], v[186:189], v[48:51]
	v_mfma_f32_16x16x32_bf16 v[36:39], v[170:173], v[194:197], v[36:39]
	v_mfma_f32_16x16x32_bf16 v[32:35], v[178:181], v[194:197], v[32:35]
	v_mfma_f32_16x16x32_bf16 v[20:23], v[170:173], v[202:205], v[20:23]
	v_mfma_f32_16x16x32_bf16 v[16:19], v[178:181], v[202:205], v[16:19]
	v_mfma_f32_16x16x32_bf16 v[4:7], v[170:173], v[212:215], v[4:7]
	v_mfma_f32_16x16x32_bf16 v[0:3], v[178:181], v[212:215], v[0:3]
	v_mfma_f32_16x16x32_bf16 v[52:55], v[174:177], v[190:193], v[52:55]
	v_mfma_f32_16x16x32_bf16 v[48:51], v[182:185], v[190:193], v[48:51]
	v_mfma_f32_16x16x32_bf16 v[36:39], v[174:177], v[198:201], v[36:39]
	v_mfma_f32_16x16x32_bf16 v[32:35], v[182:185], v[198:201], v[32:35]
	v_mfma_f32_16x16x32_bf16 v[20:23], v[174:177], v[208:211], v[20:23]
	v_mfma_f32_16x16x32_bf16 v[16:19], v[182:185], v[208:211], v[16:19]
	v_mfma_f32_16x16x32_bf16 v[4:7], v[174:177], v[216:219], v[4:7]
	v_mfma_f32_16x16x32_bf16 v[0:3], v[182:185], v[216:219], v[0:3]
	s_setprio 0
	s_barrier
	s_add_i32 s70, s70, 2
	s_add_u32 s40, s40, 0x100
	s_addc_u32 s41, s41, 0
	s_add_u32 s68, s68, 0x100
	s_addc_u32 s69, s69, 0
	s_cmp_gt_u32 s70, 13
	s_cbranch_scc1 .Lpeel_done_10170
.LBB0_416:
	ds_read_b128 v[146:149], v154
	ds_read_b128 v[158:161], v154 offset:1024
	ds_read_b128 v[162:165], v154 offset:2048
	ds_read_b128 v[166:169], v154 offset:3072
	ds_read_b128 v[170:173], v155
	ds_read_b128 v[174:177], v155 offset:1024
	ds_read_b128 v[178:181], v155 offset:2048
	ds_read_b128 v[182:185], v155 offset:3072
	s_add_u32 s42, s40, 0xfffc0080
	s_addc_u32 s43, s41, -1
	s_cmp_eq_u32 s70, 12
	s_cselect_b32 s51, s27, s43
	s_cselect_b32 s50, s66, s42
	s_cselect_b32 s43, s25, s69
	s_cselect_b32 s42, s67, s68
	v_lshl_add_u64 v[150:151], s[40:41], 0, v[138:139]
	s_add_i32 m0, s55, 0xc000
	ds_read_b128 v[186:189], v156
	ds_read_b128 v[190:193], v156 offset:1024
	ds_read_b128 v[194:197], v156 offset:2048
	ds_read_b128 v[198:201], v156 offset:3072
	ds_read_b128 v[202:205], v156 offset:4096
	ds_read_b128 v[208:211], v156 offset:5120
	ds_read_b128 v[212:215], v156 offset:6144
	ds_read_b128 v[216:219], v156 offset:7168
	global_load_lds_dwordx4 v[150:151], off
	v_lshl_add_u64 v[150:151], s[40:41], 0, v[140:141]
	s_add_i32 m0, s55, 0xe000
	s_nop 0
	global_load_lds_dwordx4 v[150:151], off
	s_waitcnt vmcnt(8)
	s_waitcnt lgkmcnt(0)
	s_barrier
	s_waitcnt lgkmcnt(0)
	v_mfma_f32_16x16x32_bf16 v[124:127], v[146:149], v[186:189], v[124:127]
	v_mfma_f32_16x16x32_bf16 v[120:123], v[162:165], v[186:189], v[120:123]
	v_mfma_f32_16x16x32_bf16 v[108:111], v[146:149], v[194:197], v[108:111]
	v_mfma_f32_16x16x32_bf16 v[104:107], v[162:165], v[194:197], v[104:107]
	v_mfma_f32_16x16x32_bf16 v[92:95], v[146:149], v[202:205], v[92:95]
	v_mfma_f32_16x16x32_bf16 v[88:91], v[162:165], v[202:205], v[88:91]
	v_mfma_f32_16x16x32_bf16 v[76:79], v[146:149], v[212:215], v[76:79]
	v_mfma_f32_16x16x32_bf16 v[72:75], v[162:165], v[212:215], v[72:75]
	v_mfma_f32_16x16x32_bf16 v[124:127], v[158:161], v[190:193], v[124:127]
	v_mfma_f32_16x16x32_bf16 v[120:123], v[166:169], v[190:193], v[120:123]
	v_mfma_f32_16x16x32_bf16 v[108:111], v[158:161], v[198:201], v[108:111]
	v_mfma_f32_16x16x32_bf16 v[104:107], v[166:169], v[198:201], v[104:107]
	v_mfma_f32_16x16x32_bf16 v[92:95], v[158:161], v[208:211], v[92:95]
	v_mfma_f32_16x16x32_bf16 v[88:91], v[166:169], v[208:211], v[88:91]
	v_mfma_f32_16x16x32_bf16 v[76:79], v[158:161], v[216:219], v[76:79]
	v_mfma_f32_16x16x32_bf16 v[72:75], v[166:169], v[216:219], v[72:75]
	v_mfma_f32_16x16x32_bf16 v[116:119], v[170:173], v[186:189], v[116:119]
	v_mfma_f32_16x16x32_bf16 v[112:115], v[178:181], v[186:189], v[112:115]
	v_mfma_f32_16x16x32_bf16 v[100:103], v[170:173], v[194:197], v[100:103]
	v_mfma_f32_16x16x32_bf16 v[96:99], v[178:181], v[194:197], v[96:99]
	v_mfma_f32_16x16x32_bf16 v[84:87], v[170:173], v[202:205], v[84:87]
	v_mfma_f32_16x16x32_bf16 v[80:83], v[178:181], v[202:205], v[80:83]
	v_mfma_f32_16x16x32_bf16 v[68:71], v[170:173], v[212:215], v[68:71]
	v_mfma_f32_16x16x32_bf16 v[64:67], v[178:181], v[212:215], v[64:67]
	v_mfma_f32_16x16x32_bf16 v[116:119], v[174:177], v[190:193], v[116:119]
	v_mfma_f32_16x16x32_bf16 v[112:115], v[182:185], v[190:193], v[112:115]
	v_mfma_f32_16x16x32_bf16 v[100:103], v[174:177], v[198:201], v[100:103]
	v_mfma_f32_16x16x32_bf16 v[96:99], v[182:185], v[198:201], v[96:99]
	v_mfma_f32_16x16x32_bf16 v[84:87], v[174:177], v[208:211], v[84:87]
	v_mfma_f32_16x16x32_bf16 v[80:83], v[182:185], v[208:211], v[80:83]
	v_mfma_f32_16x16x32_bf16 v[68:71], v[174:177], v[216:219], v[68:71]
	v_mfma_f32_16x16x32_bf16 v[64:67], v[182:185], v[216:219], v[64:67]
	s_barrier
	s_add_i32 s71, s62, s54
	v_lshl_add_u64 v[150:151], s[42:43], 0, v[132:133]
	s_mov_b32 m0, s71
	ds_read_b128 v[186:189], v156 offset:16384
	ds_read_b128 v[190:193], v156 offset:17408
	ds_read_b128 v[194:197], v156 offset:18432
	ds_read_b128 v[198:201], v156 offset:19456
	ds_read_b128 v[202:205], v156 offset:20480
	ds_read_b128 v[208:211], v156 offset:21504
	ds_read_b128 v[212:215], v156 offset:22528
	ds_read_b128 v[216:219], v156 offset:23552
	global_load_lds_dwordx4 v[150:151], off
	s_add_i32 m0, s71, 0x2000
	s_add_u32 s72, s42, 0x40000
	v_lshl_add_u64 v[220:221], s[42:43], 0, v[136:137]
	s_addc_u32 s73, s43, 0
	s_add_i32 s71, s63, s54
	global_load_lds_dwordx4 v[220:221], off
	v_lshl_add_u64 v[222:223], s[72:73], 0, v[132:133]
	s_mov_b32 m0, s71
	v_lshl_add_u64 v[224:225], s[50:51], 0, v[134:135]
	global_load_lds_dwordx4 v[222:223], off
	v_lshl_add_u64 v[222:223], s[72:73], 0, v[136:137]
	s_add_i32 m0, s71, 0x2000
	s_nop 0
	global_load_lds_dwordx4 v[222:223], off
	v_lshl_add_u64 v[222:223], s[50:51], 0, v[130:131]
	s_mov_b32 m0, s55
	s_nop 0
	global_load_lds_dwordx4 v[222:223], off
	s_mov_b32 m0, s56
	s_nop 0
	global_load_lds_dwordx4 v[224:225], off
	s_waitcnt vmcnt(8)
	s_waitcnt lgkmcnt(0)
	s_barrier
	s_waitcnt lgkmcnt(0)
	v_mfma_f32_16x16x32_bf16 v[60:63], v[146:149], v[186:189], v[60:63]
	v_mfma_f32_16x16x32_bf16 v[56:59], v[162:165], v[186:189], v[56:59]
	v_mfma_f32_16x16x32_bf16 v[44:47], v[146:149], v[194:197], v[44:47]
	v_mfma_f32_16x16x32_bf16 v[40:43], v[162:165], v[194:197], v[40:43]
	v_mfma_f32_16x16x32_bf16 v[28:31], v[146:149], v[202:205], v[28:31]
	v_mfma_f32_16x16x32_bf16 v[24:27], v[162:165], v[202:205], v[24:27]
	v_mfma_f32_16x16x32_bf16 v[12:15], v[146:149], v[212:215], v[12:15]
	v_mfma_f32_16x16x32_bf16 v[8:11], v[162:165], v[212:215], v[8:11]
	v_mfma_f32_16x16x32_bf16 v[60:63], v[158:161], v[190:193], v[60:63]
	v_mfma_f32_16x16x32_bf16 v[56:59], v[166:169], v[190:193], v[56:59]
	v_mfma_f32_16x16x32_bf16 v[44:47], v[158:161], v[198:201], v[44:47]
	v_mfma_f32_16x16x32_bf16 v[40:43], v[166:169], v[198:201], v[40:43]
	v_mfma_f32_16x16x32_bf16 v[28:31], v[158:161], v[208:211], v[28:31]
	v_mfma_f32_16x16x32_bf16 v[24:27], v[166:169], v[208:211], v[24:27]
	v_mfma_f32_16x16x32_bf16 v[12:15], v[158:161], v[216:219], v[12:15]
	v_mfma_f32_16x16x32_bf16 v[8:11], v[166:169], v[216:219], v[8:11]
	v_mfma_f32_16x16x32_bf16 v[52:55], v[170:173], v[186:189], v[52:55]
	v_mfma_f32_16x16x32_bf16 v[48:51], v[178:181], v[186:189], v[48:51]
	v_mfma_f32_16x16x32_bf16 v[36:39], v[170:173], v[194:197], v[36:39]
	v_mfma_f32_16x16x32_bf16 v[32:35], v[178:181], v[194:197], v[32:35]
	v_mfma_f32_16x16x32_bf16 v[20:23], v[170:173], v[202:205], v[20:23]
	v_mfma_f32_16x16x32_bf16 v[16:19], v[178:181], v[202:205], v[16:19]
	v_mfma_f32_16x16x32_bf16 v[4:7], v[170:173], v[212:215], v[4:7]
	v_mfma_f32_16x16x32_bf16 v[0:3], v[178:181], v[212:215], v[0:3]
	v_mfma_f32_16x16x32_bf16 v[52:55], v[174:177], v[190:193], v[52:55]
	v_mfma_f32_16x16x32_bf16 v[48:51], v[182:185], v[190:193], v[48:51]
	v_mfma_f32_16x16x32_bf16 v[36:39], v[174:177], v[198:201], v[36:39]
	v_mfma_f32_16x16x32_bf16 v[32:35], v[182:185], v[198:201], v[32:35]
	v_mfma_f32_16x16x32_bf16 v[20:23], v[174:177], v[208:211], v[20:23]
	v_mfma_f32_16x16x32_bf16 v[16:19], v[182:185], v[208:211], v[16:19]
	v_mfma_f32_16x16x32_bf16 v[4:7], v[174:177], v[216:219], v[4:7]
	v_mfma_f32_16x16x32_bf16 v[0:3], v[182:185], v[216:219], v[0:3]
	s_barrier
	s_add_i32 s71, 0, 0x18000
	s_add_i32 s72, 0, 0x1c000
	v_add_u32_e32 v166, s71, v152
	v_add_u32_e32 v182, s72, v152
	ds_read_b128 v[146:149], v166
	ds_read_b128 v[158:161], v166 offset:1024
	ds_read_b128 v[162:165], v166 offset:2048
	ds_read_b128 v[166:169], v166 offset:3072
	ds_read_b128 v[170:173], v182
	ds_read_b128 v[174:177], v182 offset:1024
	ds_read_b128 v[178:181], v182 offset:2048
	ds_read_b128 v[182:185], v182 offset:3072
	s_add_u32 s50, s50, 0x40000
	s_addc_u32 s51, s51, 0
	s_mov_b32 m0, s57
	v_lshl_add_u64 v[226:227], s[50:51], 0, v[130:131]
	ds_read_b128 v[186:189], v156 offset:32768
	ds_read_b128 v[190:193], v156 offset:33792
	ds_read_b128 v[194:197], v156 offset:34816
	ds_read_b128 v[198:201], v156 offset:35840
	ds_read_b128 v[202:205], v156 offset:36864
	ds_read_b128 v[208:211], v156 offset:37888
	ds_read_b128 v[212:215], v156 offset:38912
	ds_read_b128 v[216:219], v156 offset:39936
	global_load_lds_dwordx4 v[226:227], off
	v_lshl_add_u64 v[226:227], s[50:51], 0, v[134:135]
	s_mov_b32 m0, s58
	s_nop 0
	global_load_lds_dwordx4 v[226:227], off
	s_waitcnt vmcnt(8)
	s_waitcnt lgkmcnt(0)
	s_barrier
	s_waitcnt lgkmcnt(0)
	v_mfma_f32_16x16x32_bf16 v[124:127], v[146:149], v[186:189], v[124:127]
	v_mfma_f32_16x16x32_bf16 v[120:123], v[162:165], v[186:189], v[120:123]
	v_mfma_f32_16x16x32_bf16 v[108:111], v[146:149], v[194:197], v[108:111]
	v_mfma_f32_16x16x32_bf16 v[104:107], v[162:165], v[194:197], v[104:107]
	v_mfma_f32_16x16x32_bf16 v[92:95], v[146:149], v[202:205], v[92:95]
	v_mfma_f32_16x16x32_bf16 v[88:91], v[162:165], v[202:205], v[88:91]
	v_mfma_f32_16x16x32_bf16 v[76:79], v[146:149], v[212:215], v[76:79]
	v_mfma_f32_16x16x32_bf16 v[72:75], v[162:165], v[212:215], v[72:75]
	v_mfma_f32_16x16x32_bf16 v[124:127], v[158:161], v[190:193], v[124:127]
	v_mfma_f32_16x16x32_bf16 v[120:123], v[166:169], v[190:193], v[120:123]
	v_mfma_f32_16x16x32_bf16 v[108:111], v[158:161], v[198:201], v[108:111]
	v_mfma_f32_16x16x32_bf16 v[104:107], v[166:169], v[198:201], v[104:107]
	v_mfma_f32_16x16x32_bf16 v[92:95], v[158:161], v[208:211], v[92:95]
	v_mfma_f32_16x16x32_bf16 v[88:91], v[166:169], v[208:211], v[88:91]
	v_mfma_f32_16x16x32_bf16 v[76:79], v[158:161], v[216:219], v[76:79]
	v_mfma_f32_16x16x32_bf16 v[72:75], v[166:169], v[216:219], v[72:75]
	v_mfma_f32_16x16x32_bf16 v[116:119], v[170:173], v[186:189], v[116:119]
	v_mfma_f32_16x16x32_bf16 v[112:115], v[178:181], v[186:189], v[112:115]
	v_mfma_f32_16x16x32_bf16 v[100:103], v[170:173], v[194:197], v[100:103]
	v_mfma_f32_16x16x32_bf16 v[96:99], v[178:181], v[194:197], v[96:99]
	v_mfma_f32_16x16x32_bf16 v[84:87], v[170:173], v[202:205], v[84:87]
	v_mfma_f32_16x16x32_bf16 v[80:83], v[178:181], v[202:205], v[80:83]
	v_mfma_f32_16x16x32_bf16 v[68:71], v[170:173], v[212:215], v[68:71]
	v_mfma_f32_16x16x32_bf16 v[64:67], v[178:181], v[212:215], v[64:67]
	v_mfma_f32_16x16x32_bf16 v[116:119], v[174:177], v[190:193], v[116:119]
	v_mfma_f32_16x16x32_bf16 v[112:115], v[182:185], v[190:193], v[112:115]
	v_mfma_f32_16x16x32_bf16 v[100:103], v[174:177], v[198:201], v[100:103]
	v_mfma_f32_16x16x32_bf16 v[96:99], v[182:185], v[198:201], v[96:99]
	v_mfma_f32_16x16x32_bf16 v[84:87], v[174:177], v[208:211], v[84:87]
	v_mfma_f32_16x16x32_bf16 v[80:83], v[182:185], v[208:211], v[80:83]
	v_mfma_f32_16x16x32_bf16 v[68:71], v[174:177], v[216:219], v[68:71]
	v_mfma_f32_16x16x32_bf16 v[64:67], v[182:185], v[216:219], v[64:67]
	s_barrier
	s_add_i32 s50, s71, s54
	v_lshl_add_u64 v[150:151], v[150:151], 0, s[16:17]
	s_mov_b32 m0, s50
	ds_read_b128 v[186:189], v156 offset:49152
	ds_read_b128 v[190:193], v156 offset:50176
	ds_read_b128 v[194:197], v156 offset:51200
	ds_read_b128 v[198:201], v156 offset:52224
	ds_read_b128 v[202:205], v156 offset:53248
	ds_read_b128 v[208:211], v156 offset:54272
	ds_read_b128 v[212:215], v156 offset:55296
	ds_read_b128 v[216:219], v156 offset:56320
	global_load_lds_dwordx4 v[150:151], off
	s_add_i32 m0, s50, 0x2000
	s_add_u32 s42, s42, 0x40080
	v_lshl_add_u64 v[150:151], v[220:221], 0, s[16:17]
	s_addc_u32 s43, s43, 0
	s_add_i32 s50, s72, s54
	global_load_lds_dwordx4 v[150:151], off
	v_lshl_add_u64 v[150:151], s[42:43], 0, v[132:133]
	s_mov_b32 m0, s50
	s_nop 0
	global_load_lds_dwordx4 v[150:151], off
	v_lshl_add_u64 v[150:151], s[42:43], 0, v[136:137]
	s_add_i32 m0, s50, 0x2000
	s_nop 0
	global_load_lds_dwordx4 v[150:151], off
	v_lshl_add_u64 v[150:151], v[222:223], 0, s[16:17]
	s_mov_b32 m0, s60
	s_nop 0
	global_load_lds_dwordx4 v[150:151], off
	v_lshl_add_u64 v[150:151], v[224:225], 0, s[16:17]
	s_mov_b32 m0, s61
	s_nop 0
	global_load_lds_dwordx4 v[150:151], off
	s_waitcnt vmcnt(8)
	s_waitcnt lgkmcnt(0)
	s_barrier
	s_waitcnt lgkmcnt(0)
	v_mfma_f32_16x16x32_bf16 v[60:63], v[146:149], v[186:189], v[60:63]
	v_mfma_f32_16x16x32_bf16 v[56:59], v[162:165], v[186:189], v[56:59]
	v_mfma_f32_16x16x32_bf16 v[44:47], v[146:149], v[194:197], v[44:47]
	v_mfma_f32_16x16x32_bf16 v[40:43], v[162:165], v[194:197], v[40:43]
	v_mfma_f32_16x16x32_bf16 v[28:31], v[146:149], v[202:205], v[28:31]
	v_mfma_f32_16x16x32_bf16 v[24:27], v[162:165], v[202:205], v[24:27]
	v_mfma_f32_16x16x32_bf16 v[12:15], v[146:149], v[212:215], v[12:15]
	v_mfma_f32_16x16x32_bf16 v[8:11], v[162:165], v[212:215], v[8:11]
	v_mfma_f32_16x16x32_bf16 v[60:63], v[158:161], v[190:193], v[60:63]
	v_mfma_f32_16x16x32_bf16 v[56:59], v[166:169], v[190:193], v[56:59]
	v_mfma_f32_16x16x32_bf16 v[44:47], v[158:161], v[198:201], v[44:47]
	v_mfma_f32_16x16x32_bf16 v[40:43], v[166:169], v[198:201], v[40:43]
	v_mfma_f32_16x16x32_bf16 v[28:31], v[158:161], v[208:211], v[28:31]
	v_mfma_f32_16x16x32_bf16 v[24:27], v[166:169], v[208:211], v[24:27]
	v_mfma_f32_16x16x32_bf16 v[12:15], v[158:161], v[216:219], v[12:15]
	v_mfma_f32_16x16x32_bf16 v[8:11], v[166:169], v[216:219], v[8:11]
	v_mfma_f32_16x16x32_bf16 v[52:55], v[170:173], v[186:189], v[52:55]
	v_mfma_f32_16x16x32_bf16 v[48:51], v[178:181], v[186:189], v[48:51]
	v_mfma_f32_16x16x32_bf16 v[36:39], v[170:173], v[194:197], v[36:39]
	v_mfma_f32_16x16x32_bf16 v[32:35], v[178:181], v[194:197], v[32:35]
	v_mfma_f32_16x16x32_bf16 v[20:23], v[170:173], v[202:205], v[20:23]
	v_mfma_f32_16x16x32_bf16 v[16:19], v[178:181], v[202:205], v[16:19]
	v_mfma_f32_16x16x32_bf16 v[4:7], v[170:173], v[212:215], v[4:7]
	v_mfma_f32_16x16x32_bf16 v[0:3], v[178:181], v[212:215], v[0:3]
	v_mfma_f32_16x16x32_bf16 v[52:55], v[174:177], v[190:193], v[52:55]
	v_mfma_f32_16x16x32_bf16 v[48:51], v[182:185], v[190:193], v[48:51]
	v_mfma_f32_16x16x32_bf16 v[36:39], v[174:177], v[198:201], v[36:39]
	v_mfma_f32_16x16x32_bf16 v[32:35], v[182:185], v[198:201], v[32:35]
	v_mfma_f32_16x16x32_bf16 v[20:23], v[174:177], v[208:211], v[20:23]
	v_mfma_f32_16x16x32_bf16 v[16:19], v[182:185], v[208:211], v[16:19]
	v_mfma_f32_16x16x32_bf16 v[4:7], v[174:177], v[216:219], v[4:7]
	v_mfma_f32_16x16x32_bf16 v[0:3], v[182:185], v[216:219], v[0:3]
	s_barrier
	s_add_i32 s70, s70, 2
	s_add_u32 s40, s40, 0x100
	s_addc_u32 s41, s41, 0
	s_add_u32 s68, s68, 0x100
	s_addc_u32 s69, s69, 0
	s_cmp_gt_u32 s70, 13
	s_cbranch_scc0 .LBB0_416
.Lpeel_done_10170:
	s_and_b64 vcc, exec, s[18:19]
	s_cbranch_vccz .LBB0_419
	s_barrier

.LBB0_900:
	s_ashr_i32 s25, s24, 31
	s_lshl_b64 s[28:29], s[24:25], 18
	s_add_u32 s28, s35, s28
	s_addc_u32 s29, s50, s29
	s_and_b64 s[12:13], s[12:13], exec
	s_cselect_b32 s25, s29, s41
	s_cselect_b32 s65, s28, s40
	s_add_u32 s66, s40, 0x100
	s_addc_u32 s67, s41, 0
	s_mov_b32 s68, -2
	ds_read_b128 v[128:131], v159
	ds_read_b128 v[148:151], v159 offset:1024
	ds_read_b128 v[152:155], v159 offset:2048
	ds_read_b128 v[162:165], v159 offset:3072
	ds_read_b128 v[166:169], v160
	ds_read_b128 v[170:173], v160 offset:1024
	ds_read_b128 v[174:177], v160 offset:2048
	ds_read_b128 v[178:181], v160 offset:3072
	s_add_u32 s12, s30, 0x100
	s_addc_u32 s13, s31, 0
	s_cmp_eq_u32 s68, 4
	s_cselect_b32 s43, s27, s13
	s_cselect_b32 s42, s26, s12
	s_cselect_b32 s41, s25, s67
	s_cselect_b32 s40, s65, s66
	v_lshl_add_u64 v[218:219], s[30:31], 0, v[140:141]
	s_add_i32 m0, s52, 0xc000
	ds_read_b128 v[182:185], v161
	ds_read_b128 v[186:189], v161 offset:1024
	ds_read_b128 v[190:193], v161 offset:2048
	ds_read_b128 v[194:197], v161 offset:3072
	ds_read_b128 v[198:201], v161 offset:4096
	ds_read_b128 v[202:205], v161 offset:5120
	ds_read_b128 v[210:213], v161 offset:6144
	ds_read_b128 v[214:217], v161 offset:7168
	global_load_lds_dwordx4 v[218:219], off
	v_lshl_add_u64 v[218:219], s[30:31], 0, v[142:143]
	s_add_i32 m0, s52, 0xe000
	s_nop 0
	global_load_lds_dwordx4 v[218:219], off
	s_waitcnt vmcnt(8)
	s_waitcnt lgkmcnt(0)
	s_barrier
	s_setprio 1
	s_waitcnt lgkmcnt(0)
	v_mfma_f32_16x16x32_bf16 v[124:127], v[128:131], v[182:185], 0
	v_mfma_f32_16x16x32_bf16 v[120:123], v[152:155], v[182:185], 0
	v_mfma_f32_16x16x32_bf16 v[108:111], v[128:131], v[190:193], 0
	v_mfma_f32_16x16x32_bf16 v[104:107], v[152:155], v[190:193], 0
	v_mfma_f32_16x16x32_bf16 v[92:95], v[128:131], v[198:201], 0
	v_mfma_f32_16x16x32_bf16 v[88:91], v[152:155], v[198:201], 0
	v_mfma_f32_16x16x32_bf16 v[76:79], v[128:131], v[210:213], 0
	v_mfma_f32_16x16x32_bf16 v[72:75], v[152:155], v[210:213], 0
	v_mfma_f32_16x16x32_bf16 v[124:127], v[148:151], v[186:189], v[124:127]
	v_mfma_f32_16x16x32_bf16 v[120:123], v[162:165], v[186:189], v[120:123]
	v_mfma_f32_16x16x32_bf16 v[108:111], v[148:151], v[194:197], v[108:111]
	v_mfma_f32_16x16x32_bf16 v[104:107], v[162:165], v[194:197], v[104:107]
	v_mfma_f32_16x16x32_bf16 v[92:95], v[148:151], v[202:205], v[92:95]
	v_mfma_f32_16x16x32_bf16 v[88:91], v[162:165], v[202:205], v[88:91]
	v_mfma_f32_16x16x32_bf16 v[76:79], v[148:151], v[214:217], v[76:79]
	v_mfma_f32_16x16x32_bf16 v[72:75], v[162:165], v[214:217], v[72:75]
	s_setprio 0
	s_setprio 1
	v_mfma_f32_16x16x32_bf16 v[116:119], v[166:169], v[182:185], 0
	v_mfma_f32_16x16x32_bf16 v[112:115], v[174:177], v[182:185], 0
	v_mfma_f32_16x16x32_bf16 v[100:103], v[166:169], v[190:193], 0
	v_mfma_f32_16x16x32_bf16 v[96:99], v[174:177], v[190:193], 0
	v_mfma_f32_16x16x32_bf16 v[84:87], v[166:169], v[198:201], 0
	v_mfma_f32_16x16x32_bf16 v[80:83], v[174:177], v[198:201], 0
	v_mfma_f32_16x16x32_bf16 v[68:71], v[166:169], v[210:213], 0
	v_mfma_f32_16x16x32_bf16 v[64:67], v[174:177], v[210:213], 0
	v_mfma_f32_16x16x32_bf16 v[116:119], v[170:173], v[186:189], v[116:119]
	v_mfma_f32_16x16x32_bf16 v[112:115], v[178:181], v[186:189], v[112:115]
	v_mfma_f32_16x16x32_bf16 v[100:103], v[170:173], v[194:197], v[100:103]
	v_mfma_f32_16x16x32_bf16 v[96:99], v[178:181], v[194:197], v[96:99]
	v_mfma_f32_16x16x32_bf16 v[84:87], v[170:173], v[202:205], v[84:87]
	v_mfma_f32_16x16x32_bf16 v[80:83], v[178:181], v[202:205], v[80:83]
	v_mfma_f32_16x16x32_bf16 v[68:71], v[170:173], v[214:217], v[68:71]
	v_mfma_f32_16x16x32_bf16 v[64:67], v[178:181], v[214:217], v[64:67]
	s_setprio 0
	s_barrier
	s_add_i32 s30, s59, s51
	v_lshl_add_u64 v[218:219], s[40:41], 0, v[134:135]
	s_mov_b32 m0, s30
	ds_read_b128 v[182:185], v161 offset:16384
	ds_read_b128 v[186:189], v161 offset:17408
	ds_read_b128 v[190:193], v161 offset:18432
	ds_read_b128 v[194:197], v161 offset:19456
	ds_read_b128 v[198:201], v161 offset:20480
	ds_read_b128 v[202:205], v161 offset:21504
	ds_read_b128 v[210:213], v161 offset:22528
	ds_read_b128 v[214:217], v161 offset:23552
	global_load_lds_dwordx4 v[218:219], off
	s_add_i32 m0, s30, 0x2000
	s_add_u32 s30, s40, 0x20000
	v_lshl_add_u64 v[220:221], s[40:41], 0, v[138:139]
	s_addc_u32 s31, s41, 0
	s_add_i32 s69, s60, s51
	global_load_lds_dwordx4 v[220:221], off
	v_lshl_add_u64 v[222:223], s[30:31], 0, v[134:135]
	s_mov_b32 m0, s69
	v_lshl_add_u64 v[224:225], s[42:43], 0, v[136:137]
	global_load_lds_dwordx4 v[222:223], off
	v_lshl_add_u64 v[222:223], s[30:31], 0, v[138:139]
	s_add_i32 m0, s69, 0x2000
	s_nop 0
	global_load_lds_dwordx4 v[222:223], off
	v_lshl_add_u64 v[222:223], s[42:43], 0, v[132:133]
	s_mov_b32 m0, s52
	s_nop 0
	global_load_lds_dwordx4 v[222:223], off
	s_mov_b32 m0, s53
	s_nop 0
	global_load_lds_dwordx4 v[224:225], off
	s_waitcnt vmcnt(8)
	s_waitcnt lgkmcnt(0)
	s_barrier
	s_setprio 1
	s_waitcnt lgkmcnt(0)
	v_mfma_f32_16x16x32_bf16 v[60:63], v[128:131], v[182:185], 0
	v_mfma_f32_16x16x32_bf16 v[56:59], v[152:155], v[182:185], 0
	v_mfma_f32_16x16x32_bf16 v[44:47], v[128:131], v[190:193], 0
	v_mfma_f32_16x16x32_bf16 v[40:43], v[152:155], v[190:193], 0
	v_mfma_f32_16x16x32_bf16 v[28:31], v[128:131], v[198:201], 0
	v_mfma_f32_16x16x32_bf16 v[24:27], v[152:155], v[198:201], 0
	v_mfma_f32_16x16x32_bf16 v[12:15], v[128:131], v[210:213], 0
	v_mfma_f32_16x16x32_bf16 v[8:11], v[152:155], v[210:213], 0
	v_mfma_f32_16x16x32_bf16 v[60:63], v[148:151], v[186:189], v[60:63]
	v_mfma_f32_16x16x32_bf16 v[56:59], v[162:165], v[186:189], v[56:59]
	v_mfma_f32_16x16x32_bf16 v[44:47], v[148:151], v[194:197], v[44:47]
	v_mfma_f32_16x16x32_bf16 v[40:43], v[162:165], v[194:197], v[40:43]
	v_mfma_f32_16x16x32_bf16 v[28:31], v[148:151], v[202:205], v[28:31]
	v_mfma_f32_16x16x32_bf16 v[24:27], v[162:165], v[202:205], v[24:27]
	v_mfma_f32_16x16x32_bf16 v[12:15], v[148:151], v[214:217], v[12:15]
	v_mfma_f32_16x16x32_bf16 v[8:11], v[162:165], v[214:217], v[8:11]
	s_setprio 0
	s_setprio 1
	v_mfma_f32_16x16x32_bf16 v[52:55], v[166:169], v[182:185], 0
	v_mfma_f32_16x16x32_bf16 v[48:51], v[174:177], v[182:185], 0
	v_mfma_f32_16x16x32_bf16 v[36:39], v[166:169], v[190:193], 0
	v_mfma_f32_16x16x32_bf16 v[32:35], v[174:177], v[190:193], 0
	v_mfma_f32_16x16x32_bf16 v[20:23], v[166:169], v[198:201], 0
	v_mfma_f32_16x16x32_bf16 v[16:19], v[174:177], v[198:201], 0
	v_mfma_f32_16x16x32_bf16 v[4:7], v[166:169], v[210:213], 0
	v_mfma_f32_16x16x32_bf16 v[0:3], v[174:177], v[210:213], 0
	v_mfma_f32_16x16x32_bf16 v[52:55], v[170:173], v[186:189], v[52:55]
	v_mfma_f32_16x16x32_bf16 v[48:51], v[178:181], v[186:189], v[48:51]
	v_mfma_f32_16x16x32_bf16 v[36:39], v[170:173], v[194:197], v[36:39]
	v_mfma_f32_16x16x32_bf16 v[32:35], v[178:181], v[194:197], v[32:35]
	v_mfma_f32_16x16x32_bf16 v[20:23], v[170:173], v[202:205], v[20:23]
	v_mfma_f32_16x16x32_bf16 v[16:19], v[178:181], v[202:205], v[16:19]
	v_mfma_f32_16x16x32_bf16 v[4:7], v[170:173], v[214:217], v[4:7]
	v_mfma_f32_16x16x32_bf16 v[0:3], v[178:181], v[214:217], v[0:3]
	s_setprio 0
	s_barrier
	s_add_i32 s69, 0, 0x18000
	s_add_i32 s70, 0, 0x1c000
	v_add_u32_e32 v162, s69, v157
	v_add_u32_e32 v178, s70, v157
	ds_read_b128 v[128:131], v162
	ds_read_b128 v[148:151], v162 offset:1024
	ds_read_b128 v[152:155], v162 offset:2048
	ds_read_b128 v[162:165], v162 offset:3072
	ds_read_b128 v[166:169], v178
	ds_read_b128 v[170:173], v178 offset:1024
	ds_read_b128 v[174:177], v178 offset:2048
	ds_read_b128 v[178:181], v178 offset:3072
	s_add_u32 s30, s42, 0x160000
	s_addc_u32 s31, s43, 0
	s_mov_b32 m0, s54
	v_lshl_add_u64 v[226:227], s[30:31], 0, v[132:133]
	ds_read_b128 v[182:185], v161 offset:32768
	ds_read_b128 v[186:189], v161 offset:33792
	ds_read_b128 v[190:193], v161 offset:34816
	ds_read_b128 v[194:197], v161 offset:35840
	ds_read_b128 v[198:201], v161 offset:36864
	ds_read_b128 v[202:205], v161 offset:37888
	ds_read_b128 v[210:213], v161 offset:38912
	ds_read_b128 v[214:217], v161 offset:39936
	global_load_lds_dwordx4 v[226:227], off
	v_lshl_add_u64 v[226:227], s[30:31], 0, v[136:137]
	s_mov_b32 m0, s55
	s_nop 0
	global_load_lds_dwordx4 v[226:227], off
	s_waitcnt vmcnt(8)
	s_waitcnt lgkmcnt(0)
	s_barrier
	s_setprio 1
	s_waitcnt lgkmcnt(0)
	v_mfma_f32_16x16x32_bf16 v[124:127], v[128:131], v[182:185], v[124:127]
	v_mfma_f32_16x16x32_bf16 v[120:123], v[152:155], v[182:185], v[120:123]
	v_mfma_f32_16x16x32_bf16 v[108:111], v[128:131], v[190:193], v[108:111]
	v_mfma_f32_16x16x32_bf16 v[104:107], v[152:155], v[190:193], v[104:107]
	v_mfma_f32_16x16x32_bf16 v[92:95], v[128:131], v[198:201], v[92:95]
	v_mfma_f32_16x16x32_bf16 v[88:91], v[152:155], v[198:201], v[88:91]
	v_mfma_f32_16x16x32_bf16 v[76:79], v[128:131], v[210:213], v[76:79]
	v_mfma_f32_16x16x32_bf16 v[72:75], v[152:155], v[210:213], v[72:75]
	v_mfma_f32_16x16x32_bf16 v[124:127], v[148:151], v[186:189], v[124:127]
	v_mfma_f32_16x16x32_bf16 v[120:123], v[162:165], v[186:189], v[120:123]
	v_mfma_f32_16x16x32_bf16 v[108:111], v[148:151], v[194:197], v[108:111]
	v_mfma_f32_16x16x32_bf16 v[104:107], v[162:165], v[194:197], v[104:107]
	v_mfma_f32_16x16x32_bf16 v[92:95], v[148:151], v[202:205], v[92:95]
	v_mfma_f32_16x16x32_bf16 v[88:91], v[162:165], v[202:205], v[88:91]
	v_mfma_f32_16x16x32_bf16 v[76:79], v[148:151], v[214:217], v[76:79]
	v_mfma_f32_16x16x32_bf16 v[72:75], v[162:165], v[214:217], v[72:75]
	s_setprio 0
	s_setprio 1
	v_mfma_f32_16x16x32_bf16 v[116:119], v[166:169], v[182:185], v[116:119]
	v_mfma_f32_16x16x32_bf16 v[112:115], v[174:177], v[182:185], v[112:115]
	v_mfma_f32_16x16x32_bf16 v[100:103], v[166:169], v[190:193], v[100:103]
	v_mfma_f32_16x16x32_bf16 v[96:99], v[174:177], v[190:193], v[96:99]
	v_mfma_f32_16x16x32_bf16 v[84:87], v[166:169], v[198:201], v[84:87]
	v_mfma_f32_16x16x32_bf16 v[80:83], v[174:177], v[198:201], v[80:83]
	v_mfma_f32_16x16x32_bf16 v[68:71], v[166:169], v[210:213], v[68:71]
	v_mfma_f32_16x16x32_bf16 v[64:67], v[174:177], v[210:213], v[64:67]
	v_mfma_f32_16x16x32_bf16 v[116:119], v[170:173], v[186:189], v[116:119]
	v_mfma_f32_16x16x32_bf16 v[112:115], v[178:181], v[186:189], v[112:115]
	v_mfma_f32_16x16x32_bf16 v[100:103], v[170:173], v[194:197], v[100:103]
	v_mfma_f32_16x16x32_bf16 v[96:99], v[178:181], v[194:197], v[96:99]
	v_mfma_f32_16x16x32_bf16 v[84:87], v[170:173], v[202:205], v[84:87]
	v_mfma_f32_16x16x32_bf16 v[80:83], v[178:181], v[202:205], v[80:83]
	v_mfma_f32_16x16x32_bf16 v[68:71], v[170:173], v[214:217], v[68:71]
	v_mfma_f32_16x16x32_bf16 v[64:67], v[178:181], v[214:217], v[64:67]
	s_setprio 0
	s_barrier
	s_add_i32 s30, s69, s51
	v_lshl_add_u64 v[218:219], v[218:219], 0, s[16:17]
	s_mov_b32 m0, s30
	ds_read_b128 v[182:185], v161 offset:49152
	ds_read_b128 v[186:189], v161 offset:50176
	ds_read_b128 v[190:193], v161 offset:51200
	ds_read_b128 v[194:197], v161 offset:52224
	ds_read_b128 v[198:201], v161 offset:53248
	ds_read_b128 v[202:205], v161 offset:54272
	ds_read_b128 v[210:213], v161 offset:55296
	ds_read_b128 v[214:217], v161 offset:56320
	global_load_lds_dwordx4 v[218:219], off
	s_add_i32 m0, s30, 0x2000
	s_add_u32 s30, s40, 0x20080
	v_lshl_add_u64 v[218:219], v[220:221], 0, s[16:17]
	s_addc_u32 s31, s41, 0
	s_add_i32 s40, s70, s51
	global_load_lds_dwordx4 v[218:219], off
	v_lshl_add_u64 v[218:219], s[30:31], 0, v[134:135]
	s_mov_b32 m0, s40
	s_nop 0
	global_load_lds_dwordx4 v[218:219], off
	v_lshl_add_u64 v[218:219], s[30:31], 0, v[138:139]
	s_add_i32 m0, s40, 0x2000
	s_nop 0
	global_load_lds_dwordx4 v[218:219], off
	v_lshl_add_u64 v[218:219], v[222:223], 0, s[16:17]
	s_mov_b32 m0, s57
	s_nop 0
	global_load_lds_dwordx4 v[218:219], off
	v_lshl_add_u64 v[218:219], v[224:225], 0, s[16:17]
	s_mov_b32 m0, s58
	s_nop 0
	global_load_lds_dwordx4 v[218:219], off
	s_waitcnt vmcnt(8)
	s_waitcnt lgkmcnt(0)
	s_barrier
	s_setprio 1
	s_waitcnt lgkmcnt(0)
	v_mfma_f32_16x16x32_bf16 v[60:63], v[128:131], v[182:185], v[60:63]
	v_mfma_f32_16x16x32_bf16 v[56:59], v[152:155], v[182:185], v[56:59]
	v_mfma_f32_16x16x32_bf16 v[44:47], v[128:131], v[190:193], v[44:47]
	v_mfma_f32_16x16x32_bf16 v[40:43], v[152:155], v[190:193], v[40:43]
	v_mfma_f32_16x16x32_bf16 v[28:31], v[128:131], v[198:201], v[28:31]
	v_mfma_f32_16x16x32_bf16 v[24:27], v[152:155], v[198:201], v[24:27]
	v_mfma_f32_16x16x32_bf16 v[12:15], v[128:131], v[210:213], v[12:15]
	v_mfma_f32_16x16x32_bf16 v[8:11], v[152:155], v[210:213], v[8:11]
	v_mfma_f32_16x16x32_bf16 v[60:63], v[148:151], v[186:189], v[60:63]
	v_mfma_f32_16x16x32_bf16 v[56:59], v[162:165], v[186:189], v[56:59]
	v_mfma_f32_16x16x32_bf16 v[44:47], v[148:151], v[194:197], v[44:47]
	v_mfma_f32_16x16x32_bf16 v[40:43], v[162:165], v[194:197], v[40:43]
	v_mfma_f32_16x16x32_bf16 v[28:31], v[148:151], v[202:205], v[28:31]
	v_mfma_f32_16x16x32_bf16 v[24:27], v[162:165], v[202:205], v[24:27]
	v_mfma_f32_16x16x32_bf16 v[12:15], v[148:151], v[214:217], v[12:15]
	v_mfma_f32_16x16x32_bf16 v[8:11], v[162:165], v[214:217], v[8:11]
	s_setprio 0
	s_setprio 1
	v_mfma_f32_16x16x32_bf16 v[52:55], v[166:169], v[182:185], v[52:55]
	v_mfma_f32_16x16x32_bf16 v[48:51], v[174:177], v[182:185], v[48:51]
	v_mfma_f32_16x16x32_bf16 v[36:39], v[166:169], v[190:193], v[36:39]
	v_mfma_f32_16x16x32_bf16 v[32:35], v[174:177], v[190:193], v[32:35]
	v_mfma_f32_16x16x32_bf16 v[20:23], v[166:169], v[198:201], v[20:23]
	v_mfma_f32_16x16x32_bf16 v[16:19], v[174:177], v[198:201], v[16:19]
	v_mfma_f32_16x16x32_bf16 v[4:7], v[166:169], v[210:213], v[4:7]
	v_mfma_f32_16x16x32_bf16 v[0:3], v[174:177], v[210:213], v[0:3]
	v_mfma_f32_16x16x32_bf16 v[52:55], v[170:173], v[186:189], v[52:55]
	v_mfma_f32_16x16x32_bf16 v[48:51], v[178:181], v[186:189], v[48:51]
	v_mfma_f32_16x16x32_bf16 v[36:39], v[170:173], v[194:197], v[36:39]
	v_mfma_f32_16x16x32_bf16 v[32:35], v[178:181], v[194:197], v[32:35]
	v_mfma_f32_16x16x32_bf16 v[20:23], v[170:173], v[202:205], v[20:23]
	v_mfma_f32_16x16x32_bf16 v[16:19], v[178:181], v[202:205], v[16:19]
	v_mfma_f32_16x16x32_bf16 v[4:7], v[170:173], v[214:217], v[4:7]
	v_mfma_f32_16x16x32_bf16 v[0:3], v[178:181], v[214:217], v[0:3]
	s_setprio 0
	s_barrier
	s_add_i32 s68, s68, 2
	s_add_u32 s66, s66, 0x100
	s_addc_u32 s67, s67, 0
	s_cmp_gt_u32 s68, 5
	s_mov_b64 s[30:31], s[12:13]
	s_cbranch_scc1 .Lpeel_done_25342
.LBB0_901:
	ds_read_b128 v[128:131], v159
	ds_read_b128 v[148:151], v159 offset:1024
	ds_read_b128 v[152:155], v159 offset:2048
	ds_read_b128 v[162:165], v159 offset:3072
	ds_read_b128 v[166:169], v160
	ds_read_b128 v[170:173], v160 offset:1024
	ds_read_b128 v[174:177], v160 offset:2048
	ds_read_b128 v[178:181], v160 offset:3072
	s_add_u32 s12, s30, 0x100
	s_addc_u32 s13, s31, 0
	s_cmp_eq_u32 s68, 4
	s_cselect_b32 s43, s27, s13
	s_cselect_b32 s42, s26, s12
	s_cselect_b32 s41, s25, s67
	s_cselect_b32 s40, s65, s66
	v_lshl_add_u64 v[218:219], s[30:31], 0, v[140:141]
	s_add_i32 m0, s52, 0xc000
	ds_read_b128 v[182:185], v161
	ds_read_b128 v[186:189], v161 offset:1024
	ds_read_b128 v[190:193], v161 offset:2048
	ds_read_b128 v[194:197], v161 offset:3072
	ds_read_b128 v[198:201], v161 offset:4096
	ds_read_b128 v[202:205], v161 offset:5120
	ds_read_b128 v[210:213], v161 offset:6144
	ds_read_b128 v[214:217], v161 offset:7168
	global_load_lds_dwordx4 v[218:219], off
	v_lshl_add_u64 v[218:219], s[30:31], 0, v[142:143]
	s_add_i32 m0, s52, 0xe000
	s_nop 0
	global_load_lds_dwordx4 v[218:219], off
	s_waitcnt vmcnt(8)
	s_waitcnt lgkmcnt(0)
	s_barrier
	s_waitcnt lgkmcnt(0)
	v_mfma_f32_16x16x32_bf16 v[124:127], v[128:131], v[182:185], v[124:127]
	v_mfma_f32_16x16x32_bf16 v[120:123], v[152:155], v[182:185], v[120:123]
	v_mfma_f32_16x16x32_bf16 v[108:111], v[128:131], v[190:193], v[108:111]
	v_mfma_f32_16x16x32_bf16 v[104:107], v[152:155], v[190:193], v[104:107]
	v_mfma_f32_16x16x32_bf16 v[92:95], v[128:131], v[198:201], v[92:95]
	v_mfma_f32_16x16x32_bf16 v[88:91], v[152:155], v[198:201], v[88:91]
	v_mfma_f32_16x16x32_bf16 v[76:79], v[128:131], v[210:213], v[76:79]
	v_mfma_f32_16x16x32_bf16 v[72:75], v[152:155], v[210:213], v[72:75]
	v_mfma_f32_16x16x32_bf16 v[124:127], v[148:151], v[186:189], v[124:127]
	v_mfma_f32_16x16x32_bf16 v[120:123], v[162:165], v[186:189], v[120:123]
	v_mfma_f32_16x16x32_bf16 v[108:111], v[148:151], v[194:197], v[108:111]
	v_mfma_f32_16x16x32_bf16 v[104:107], v[162:165], v[194:197], v[104:107]
	v_mfma_f32_16x16x32_bf16 v[92:95], v[148:151], v[202:205], v[92:95]
	v_mfma_f32_16x16x32_bf16 v[88:91], v[162:165], v[202:205], v[88:91]
	v_mfma_f32_16x16x32_bf16 v[76:79], v[148:151], v[214:217], v[76:79]
	v_mfma_f32_16x16x32_bf16 v[72:75], v[162:165], v[214:217], v[72:75]
	v_mfma_f32_16x16x32_bf16 v[116:119], v[166:169], v[182:185], v[116:119]
	v_mfma_f32_16x16x32_bf16 v[112:115], v[174:177], v[182:185], v[112:115]
	v_mfma_f32_16x16x32_bf16 v[100:103], v[166:169], v[190:193], v[100:103]
	v_mfma_f32_16x16x32_bf16 v[96:99], v[174:177], v[190:193], v[96:99]
	v_mfma_f32_16x16x32_bf16 v[84:87], v[166:169], v[198:201], v[84:87]
	v_mfma_f32_16x16x32_bf16 v[80:83], v[174:177], v[198:201], v[80:83]
	v_mfma_f32_16x16x32_bf16 v[68:71], v[166:169], v[210:213], v[68:71]
	v_mfma_f32_16x16x32_bf16 v[64:67], v[174:177], v[210:213], v[64:67]
	v_mfma_f32_16x16x32_bf16 v[116:119], v[170:173], v[186:189], v[116:119]
	v_mfma_f32_16x16x32_bf16 v[112:115], v[178:181], v[186:189], v[112:115]
	v_mfma_f32_16x16x32_bf16 v[100:103], v[170:173], v[194:197], v[100:103]
	v_mfma_f32_16x16x32_bf16 v[96:99], v[178:181], v[194:197], v[96:99]
	v_mfma_f32_16x16x32_bf16 v[84:87], v[170:173], v[202:205], v[84:87]
	v_mfma_f32_16x16x32_bf16 v[80:83], v[178:181], v[202:205], v[80:83]
	v_mfma_f32_16x16x32_bf16 v[68:71], v[170:173], v[214:217], v[68:71]
	v_mfma_f32_16x16x32_bf16 v[64:67], v[178:181], v[214:217], v[64:67]
	s_barrier
	s_add_i32 s30, s59, s51
	v_lshl_add_u64 v[218:219], s[40:41], 0, v[134:135]
	s_mov_b32 m0, s30
	ds_read_b128 v[182:185], v161 offset:16384
	ds_read_b128 v[186:189], v161 offset:17408
	ds_read_b128 v[190:193], v161 offset:18432
	ds_read_b128 v[194:197], v161 offset:19456
	ds_read_b128 v[198:201], v161 offset:20480
	ds_read_b128 v[202:205], v161 offset:21504
	ds_read_b128 v[210:213], v161 offset:22528
	ds_read_b128 v[214:217], v161 offset:23552
	global_load_lds_dwordx4 v[218:219], off
	s_add_i32 m0, s30, 0x2000
	s_add_u32 s30, s40, 0x20000
	v_lshl_add_u64 v[220:221], s[40:41], 0, v[138:139]
	s_addc_u32 s31, s41, 0
	s_add_i32 s69, s60, s51
	global_load_lds_dwordx4 v[220:221], off
	v_lshl_add_u64 v[222:223], s[30:31], 0, v[134:135]
	s_mov_b32 m0, s69
	v_lshl_add_u64 v[224:225], s[42:43], 0, v[136:137]
	global_load_lds_dwordx4 v[222:223], off
	v_lshl_add_u64 v[222:223], s[30:31], 0, v[138:139]
	s_add_i32 m0, s69, 0x2000
	s_nop 0
	global_load_lds_dwordx4 v[222:223], off
	v_lshl_add_u64 v[222:223], s[42:43], 0, v[132:133]
	s_mov_b32 m0, s52
	s_nop 0
	global_load_lds_dwordx4 v[222:223], off
	s_mov_b32 m0, s53
	s_nop 0
	global_load_lds_dwordx4 v[224:225], off
	s_waitcnt vmcnt(8)
	s_waitcnt lgkmcnt(0)
	s_barrier
	s_waitcnt lgkmcnt(0)
	v_mfma_f32_16x16x32_bf16 v[60:63], v[128:131], v[182:185], v[60:63]
	v_mfma_f32_16x16x32_bf16 v[56:59], v[152:155], v[182:185], v[56:59]
	v_mfma_f32_16x16x32_bf16 v[44:47], v[128:131], v[190:193], v[44:47]
	v_mfma_f32_16x16x32_bf16 v[40:43], v[152:155], v[190:193], v[40:43]
	v_mfma_f32_16x16x32_bf16 v[28:31], v[128:131], v[198:201], v[28:31]
	v_mfma_f32_16x16x32_bf16 v[24:27], v[152:155], v[198:201], v[24:27]
	v_mfma_f32_16x16x32_bf16 v[12:15], v[128:131], v[210:213], v[12:15]
	v_mfma_f32_16x16x32_bf16 v[8:11], v[152:155], v[210:213], v[8:11]
	v_mfma_f32_16x16x32_bf16 v[60:63], v[148:151], v[186:189], v[60:63]
	v_mfma_f32_16x16x32_bf16 v[56:59], v[162:165], v[186:189], v[56:59]
	v_mfma_f32_16x16x32_bf16 v[44:47], v[148:151], v[194:197], v[44:47]
	v_mfma_f32_16x16x32_bf16 v[40:43], v[162:165], v[194:197], v[40:43]
	v_mfma_f32_16x16x32_bf16 v[28:31], v[148:151], v[202:205], v[28:31]
	v_mfma_f32_16x16x32_bf16 v[24:27], v[162:165], v[202:205], v[24:27]
	v_mfma_f32_16x16x32_bf16 v[12:15], v[148:151], v[214:217], v[12:15]
	v_mfma_f32_16x16x32_bf16 v[8:11], v[162:165], v[214:217], v[8:11]
	v_mfma_f32_16x16x32_bf16 v[52:55], v[166:169], v[182:185], v[52:55]
	v_mfma_f32_16x16x32_bf16 v[48:51], v[174:177], v[182:185], v[48:51]
	v_mfma_f32_16x16x32_bf16 v[36:39], v[166:169], v[190:193], v[36:39]
	v_mfma_f32_16x16x32_bf16 v[32:35], v[174:177], v[190:193], v[32:35]
	v_mfma_f32_16x16x32_bf16 v[20:23], v[166:169], v[198:201], v[20:23]
	v_mfma_f32_16x16x32_bf16 v[16:19], v[174:177], v[198:201], v[16:19]
	v_mfma_f32_16x16x32_bf16 v[4:7], v[166:169], v[210:213], v[4:7]
	v_mfma_f32_16x16x32_bf16 v[0:3], v[174:177], v[210:213], v[0:3]
	v_mfma_f32_16x16x32_bf16 v[52:55], v[170:173], v[186:189], v[52:55]
	v_mfma_f32_16x16x32_bf16 v[48:51], v[178:181], v[186:189], v[48:51]
	v_mfma_f32_16x16x32_bf16 v[36:39], v[170:173], v[194:197], v[36:39]
	v_mfma_f32_16x16x32_bf16 v[32:35], v[178:181], v[194:197], v[32:35]
	v_mfma_f32_16x16x32_bf16 v[20:23], v[170:173], v[202:205], v[20:23]
	v_mfma_f32_16x16x32_bf16 v[16:19], v[178:181], v[202:205], v[16:19]
	v_mfma_f32_16x16x32_bf16 v[4:7], v[170:173], v[214:217], v[4:7]
	v_mfma_f32_16x16x32_bf16 v[0:3], v[178:181], v[214:217], v[0:3]
	s_barrier
	s_add_i32 s69, 0, 0x18000
	s_add_i32 s70, 0, 0x1c000
	v_add_u32_e32 v162, s69, v157
	v_add_u32_e32 v178, s70, v157
	ds_read_b128 v[128:131], v162
	ds_read_b128 v[148:151], v162 offset:1024
	ds_read_b128 v[152:155], v162 offset:2048
	ds_read_b128 v[162:165], v162 offset:3072
	ds_read_b128 v[166:169], v178
	ds_read_b128 v[170:173], v178 offset:1024
	ds_read_b128 v[174:177], v178 offset:2048
	ds_read_b128 v[178:181], v178 offset:3072
	s_add_u32 s30, s42, 0x160000
	s_addc_u32 s31, s43, 0
	s_mov_b32 m0, s54
	v_lshl_add_u64 v[226:227], s[30:31], 0, v[132:133]
	ds_read_b128 v[182:185], v161 offset:32768
	ds_read_b128 v[186:189], v161 offset:33792
	ds_read_b128 v[190:193], v161 offset:34816
	ds_read_b128 v[194:197], v161 offset:35840
	ds_read_b128 v[198:201], v161 offset:36864
	ds_read_b128 v[202:205], v161 offset:37888
	ds_read_b128 v[210:213], v161 offset:38912
	ds_read_b128 v[214:217], v161 offset:39936
	global_load_lds_dwordx4 v[226:227], off
	v_lshl_add_u64 v[226:227], s[30:31], 0, v[136:137]
	s_mov_b32 m0, s55
	s_nop 0
	global_load_lds_dwordx4 v[226:227], off
	s_waitcnt vmcnt(8)
	s_waitcnt lgkmcnt(0)
	s_barrier
	s_waitcnt lgkmcnt(0)
	v_mfma_f32_16x16x32_bf16 v[124:127], v[128:131], v[182:185], v[124:127]
	v_mfma_f32_16x16x32_bf16 v[120:123], v[152:155], v[182:185], v[120:123]
	v_mfma_f32_16x16x32_bf16 v[108:111], v[128:131], v[190:193], v[108:111]
	v_mfma_f32_16x16x32_bf16 v[104:107], v[152:155], v[190:193], v[104:107]
	v_mfma_f32_16x16x32_bf16 v[92:95], v[128:131], v[198:201], v[92:95]
	v_mfma_f32_16x16x32_bf16 v[88:91], v[152:155], v[198:201], v[88:91]
	v_mfma_f32_16x16x32_bf16 v[76:79], v[128:131], v[210:213], v[76:79]
	v_mfma_f32_16x16x32_bf16 v[72:75], v[152:155], v[210:213], v[72:75]
	v_mfma_f32_16x16x32_bf16 v[124:127], v[148:151], v[186:189], v[124:127]
	v_mfma_f32_16x16x32_bf16 v[120:123], v[162:165], v[186:189], v[120:123]
	v_mfma_f32_16x16x32_bf16 v[108:111], v[148:151], v[194:197], v[108:111]
	v_mfma_f32_16x16x32_bf16 v[104:107], v[162:165], v[194:197], v[104:107]
	v_mfma_f32_16x16x32_bf16 v[92:95], v[148:151], v[202:205], v[92:95]
	v_mfma_f32_16x16x32_bf16 v[88:91], v[162:165], v[202:205], v[88:91]
	v_mfma_f32_16x16x32_bf16 v[76:79], v[148:151], v[214:217], v[76:79]
	v_mfma_f32_16x16x32_bf16 v[72:75], v[162:165], v[214:217], v[72:75]
	v_mfma_f32_16x16x32_bf16 v[116:119], v[166:169], v[182:185], v[116:119]
	v_mfma_f32_16x16x32_bf16 v[112:115], v[174:177], v[182:185], v[112:115]
	v_mfma_f32_16x16x32_bf16 v[100:103], v[166:169], v[190:193], v[100:103]
	v_mfma_f32_16x16x32_bf16 v[96:99], v[174:177], v[190:193], v[96:99]
	v_mfma_f32_16x16x32_bf16 v[84:87], v[166:169], v[198:201], v[84:87]
	v_mfma_f32_16x16x32_bf16 v[80:83], v[174:177], v[198:201], v[80:83]
	v_mfma_f32_16x16x32_bf16 v[68:71], v[166:169], v[210:213], v[68:71]
	v_mfma_f32_16x16x32_bf16 v[64:67], v[174:177], v[210:213], v[64:67]
	v_mfma_f32_16x16x32_bf16 v[116:119], v[170:173], v[186:189], v[116:119]
	v_mfma_f32_16x16x32_bf16 v[112:115], v[178:181], v[186:189], v[112:115]
	v_mfma_f32_16x16x32_bf16 v[100:103], v[170:173], v[194:197], v[100:103]
	v_mfma_f32_16x16x32_bf16 v[96:99], v[178:181], v[194:197], v[96:99]
	v_mfma_f32_16x16x32_bf16 v[84:87], v[170:173], v[202:205], v[84:87]
	v_mfma_f32_16x16x32_bf16 v[80:83], v[178:181], v[202:205], v[80:83]
	v_mfma_f32_16x16x32_bf16 v[68:71], v[170:173], v[214:217], v[68:71]
	v_mfma_f32_16x16x32_bf16 v[64:67], v[178:181], v[214:217], v[64:67]
	s_barrier
	s_add_i32 s30, s69, s51
	v_lshl_add_u64 v[218:219], v[218:219], 0, s[16:17]
	s_mov_b32 m0, s30
	ds_read_b128 v[182:185], v161 offset:49152
	ds_read_b128 v[186:189], v161 offset:50176
	ds_read_b128 v[190:193], v161 offset:51200
	ds_read_b128 v[194:197], v161 offset:52224
	ds_read_b128 v[198:201], v161 offset:53248
	ds_read_b128 v[202:205], v161 offset:54272
	ds_read_b128 v[210:213], v161 offset:55296
	ds_read_b128 v[214:217], v161 offset:56320
	global_load_lds_dwordx4 v[218:219], off
	s_add_i32 m0, s30, 0x2000
	s_add_u32 s30, s40, 0x20080
	v_lshl_add_u64 v[218:219], v[220:221], 0, s[16:17]
	s_addc_u32 s31, s41, 0
	s_add_i32 s40, s70, s51
	global_load_lds_dwordx4 v[218:219], off
	v_lshl_add_u64 v[218:219], s[30:31], 0, v[134:135]
	s_mov_b32 m0, s40
	s_nop 0
	global_load_lds_dwordx4 v[218:219], off
	v_lshl_add_u64 v[218:219], s[30:31], 0, v[138:139]
	s_add_i32 m0, s40, 0x2000
	s_nop 0
	global_load_lds_dwordx4 v[218:219], off
	v_lshl_add_u64 v[218:219], v[222:223], 0, s[16:17]
	s_mov_b32 m0, s57
	s_nop 0
	global_load_lds_dwordx4 v[218:219], off
	v_lshl_add_u64 v[218:219], v[224:225], 0, s[16:17]
	s_mov_b32 m0, s58
	s_nop 0
	global_load_lds_dwordx4 v[218:219], off
	s_waitcnt vmcnt(8)
	s_waitcnt lgkmcnt(0)
	s_barrier
	s_waitcnt lgkmcnt(0)
	v_mfma_f32_16x16x32_bf16 v[60:63], v[128:131], v[182:185], v[60:63]
	v_mfma_f32_16x16x32_bf16 v[56:59], v[152:155], v[182:185], v[56:59]
	v_mfma_f32_16x16x32_bf16 v[44:47], v[128:131], v[190:193], v[44:47]
	v_mfma_f32_16x16x32_bf16 v[40:43], v[152:155], v[190:193], v[40:43]
	v_mfma_f32_16x16x32_bf16 v[28:31], v[128:131], v[198:201], v[28:31]
	v_mfma_f32_16x16x32_bf16 v[24:27], v[152:155], v[198:201], v[24:27]
	v_mfma_f32_16x16x32_bf16 v[12:15], v[128:131], v[210:213], v[12:15]
	v_mfma_f32_16x16x32_bf16 v[8:11], v[152:155], v[210:213], v[8:11]
	v_mfma_f32_16x16x32_bf16 v[60:63], v[148:151], v[186:189], v[60:63]
	v_mfma_f32_16x16x32_bf16 v[56:59], v[162:165], v[186:189], v[56:59]
	v_mfma_f32_16x16x32_bf16 v[44:47], v[148:151], v[194:197], v[44:47]
	v_mfma_f32_16x16x32_bf16 v[40:43], v[162:165], v[194:197], v[40:43]
	v_mfma_f32_16x16x32_bf16 v[28:31], v[148:151], v[202:205], v[28:31]
	v_mfma_f32_16x16x32_bf16 v[24:27], v[162:165], v[202:205], v[24:27]
	v_mfma_f32_16x16x32_bf16 v[12:15], v[148:151], v[214:217], v[12:15]
	v_mfma_f32_16x16x32_bf16 v[8:11], v[162:165], v[214:217], v[8:11]
	v_mfma_f32_16x16x32_bf16 v[52:55], v[166:169], v[182:185], v[52:55]
	v_mfma_f32_16x16x32_bf16 v[48:51], v[174:177], v[182:185], v[48:51]
	v_mfma_f32_16x16x32_bf16 v[36:39], v[166:169], v[190:193], v[36:39]
	v_mfma_f32_16x16x32_bf16 v[32:35], v[174:177], v[190:193], v[32:35]
	v_mfma_f32_16x16x32_bf16 v[20:23], v[166:169], v[198:201], v[20:23]
	v_mfma_f32_16x16x32_bf16 v[16:19], v[174:177], v[198:201], v[16:19]
	v_mfma_f32_16x16x32_bf16 v[4:7], v[166:169], v[210:213], v[4:7]
	v_mfma_f32_16x16x32_bf16 v[0:3], v[174:177], v[210:213], v[0:3]
	v_mfma_f32_16x16x32_bf16 v[52:55], v[170:173], v[186:189], v[52:55]
	v_mfma_f32_16x16x32_bf16 v[48:51], v[178:181], v[186:189], v[48:51]
	v_mfma_f32_16x16x32_bf16 v[36:39], v[170:173], v[194:197], v[36:39]
	v_mfma_f32_16x16x32_bf16 v[32:35], v[178:181], v[194:197], v[32:35]
	v_mfma_f32_16x16x32_bf16 v[20:23], v[170:173], v[202:205], v[20:23]
	v_mfma_f32_16x16x32_bf16 v[16:19], v[178:181], v[202:205], v[16:19]
	v_mfma_f32_16x16x32_bf16 v[4:7], v[170:173], v[214:217], v[4:7]
	v_mfma_f32_16x16x32_bf16 v[0:3], v[178:181], v[214:217], v[0:3]
	s_barrier
	s_add_i32 s68, s68, 2
	s_add_u32 s66, s66, 0x100
	s_addc_u32 s67, s67, 0
	s_cmp_gt_u32 s68, 5
	s_mov_b64 s[30:31], s[12:13]
	s_cbranch_scc0 .LBB0_901

.LBB0_926:
	s_ashr_i32 s25, s24, 31
	s_lshl_b64 s[28:29], s[24:25], 18
	s_add_u32 s28, s51, s28
	s_addc_u32 s29, s52, s29
	s_and_b64 s[12:13], s[12:13], exec
	s_cselect_b32 s25, s29, s41
	s_cselect_b32 s67, s28, s40
	s_add_u32 s68, s40, 0x100
	s_addc_u32 s69, s41, 0
	s_mov_b32 s70, -2
	ds_read_b128 v[128:131], v159
	ds_read_b128 v[148:151], v159 offset:1024
	ds_read_b128 v[152:155], v159 offset:2048
	ds_read_b128 v[162:165], v159 offset:3072
	ds_read_b128 v[166:169], v160
	ds_read_b128 v[170:173], v160 offset:1024
	ds_read_b128 v[174:177], v160 offset:2048
	ds_read_b128 v[178:181], v160 offset:3072
	s_add_u32 s12, s30, 0x100
	s_addc_u32 s13, s31, 0
	s_cmp_eq_u32 s70, 4
	s_cselect_b32 s43, s27, s13
	s_cselect_b32 s42, s26, s12
	s_cselect_b32 s41, s25, s69
	s_cselect_b32 s40, s67, s68
	v_lshl_add_u64 v[218:219], s[30:31], 0, v[140:141]
	s_add_i32 m0, s54, 0xc000
	ds_read_b128 v[182:185], v161
	ds_read_b128 v[186:189], v161 offset:1024
	ds_read_b128 v[190:193], v161 offset:2048
	ds_read_b128 v[194:197], v161 offset:3072
	ds_read_b128 v[198:201], v161 offset:4096
	ds_read_b128 v[202:205], v161 offset:5120
	ds_read_b128 v[210:213], v161 offset:6144
	ds_read_b128 v[214:217], v161 offset:7168
	global_load_lds_dwordx4 v[218:219], off
	v_lshl_add_u64 v[218:219], s[30:31], 0, v[142:143]
	s_add_i32 m0, s54, 0xe000
	s_nop 0
	global_load_lds_dwordx4 v[218:219], off
	s_waitcnt vmcnt(8)
	s_waitcnt lgkmcnt(0)
	s_barrier
	s_setprio 1
	s_waitcnt lgkmcnt(0)
	v_mfma_f32_16x16x32_bf16 v[124:127], v[128:131], v[182:185], 0
	v_mfma_f32_16x16x32_bf16 v[120:123], v[152:155], v[182:185], 0
	v_mfma_f32_16x16x32_bf16 v[108:111], v[128:131], v[190:193], 0
	v_mfma_f32_16x16x32_bf16 v[104:107], v[152:155], v[190:193], 0
	v_mfma_f32_16x16x32_bf16 v[92:95], v[128:131], v[198:201], 0
	v_mfma_f32_16x16x32_bf16 v[88:91], v[152:155], v[198:201], 0
	v_mfma_f32_16x16x32_bf16 v[76:79], v[128:131], v[210:213], 0
	v_mfma_f32_16x16x32_bf16 v[72:75], v[152:155], v[210:213], 0
	v_mfma_f32_16x16x32_bf16 v[124:127], v[148:151], v[186:189], v[124:127]
	v_mfma_f32_16x16x32_bf16 v[120:123], v[162:165], v[186:189], v[120:123]
	v_mfma_f32_16x16x32_bf16 v[108:111], v[148:151], v[194:197], v[108:111]
	v_mfma_f32_16x16x32_bf16 v[104:107], v[162:165], v[194:197], v[104:107]
	v_mfma_f32_16x16x32_bf16 v[92:95], v[148:151], v[202:205], v[92:95]
	v_mfma_f32_16x16x32_bf16 v[88:91], v[162:165], v[202:205], v[88:91]
	v_mfma_f32_16x16x32_bf16 v[76:79], v[148:151], v[214:217], v[76:79]
	v_mfma_f32_16x16x32_bf16 v[72:75], v[162:165], v[214:217], v[72:75]
	s_setprio 0
	s_setprio 1
	v_mfma_f32_16x16x32_bf16 v[116:119], v[166:169], v[182:185], 0
	v_mfma_f32_16x16x32_bf16 v[112:115], v[174:177], v[182:185], 0
	v_mfma_f32_16x16x32_bf16 v[100:103], v[166:169], v[190:193], 0
	v_mfma_f32_16x16x32_bf16 v[96:99], v[174:177], v[190:193], 0
	v_mfma_f32_16x16x32_bf16 v[84:87], v[166:169], v[198:201], 0
	v_mfma_f32_16x16x32_bf16 v[80:83], v[174:177], v[198:201], 0
	v_mfma_f32_16x16x32_bf16 v[68:71], v[166:169], v[210:213], 0
	v_mfma_f32_16x16x32_bf16 v[64:67], v[174:177], v[210:213], 0
	v_mfma_f32_16x16x32_bf16 v[116:119], v[170:173], v[186:189], v[116:119]
	v_mfma_f32_16x16x32_bf16 v[112:115], v[178:181], v[186:189], v[112:115]
	v_mfma_f32_16x16x32_bf16 v[100:103], v[170:173], v[194:197], v[100:103]
	v_mfma_f32_16x16x32_bf16 v[96:99], v[178:181], v[194:197], v[96:99]
	v_mfma_f32_16x16x32_bf16 v[84:87], v[170:173], v[202:205], v[84:87]
	v_mfma_f32_16x16x32_bf16 v[80:83], v[178:181], v[202:205], v[80:83]
	v_mfma_f32_16x16x32_bf16 v[68:71], v[170:173], v[214:217], v[68:71]
	v_mfma_f32_16x16x32_bf16 v[64:67], v[178:181], v[214:217], v[64:67]
	s_setprio 0
	s_barrier
	s_add_i32 s30, s61, s53
	v_lshl_add_u64 v[218:219], s[40:41], 0, v[134:135]
	s_mov_b32 m0, s30
	ds_read_b128 v[182:185], v161 offset:16384
	ds_read_b128 v[186:189], v161 offset:17408
	ds_read_b128 v[190:193], v161 offset:18432
	ds_read_b128 v[194:197], v161 offset:19456
	ds_read_b128 v[198:201], v161 offset:20480
	ds_read_b128 v[202:205], v161 offset:21504
	ds_read_b128 v[210:213], v161 offset:22528
	ds_read_b128 v[214:217], v161 offset:23552
	global_load_lds_dwordx4 v[218:219], off
	s_add_i32 m0, s30, 0x2000
	s_add_u32 s30, s40, 0x20000
	v_lshl_add_u64 v[220:221], s[40:41], 0, v[138:139]
	s_addc_u32 s31, s41, 0
	s_add_i32 s71, s62, s53
	global_load_lds_dwordx4 v[220:221], off
	v_lshl_add_u64 v[222:223], s[30:31], 0, v[134:135]
	s_mov_b32 m0, s71
	v_lshl_add_u64 v[224:225], s[42:43], 0, v[136:137]
	global_load_lds_dwordx4 v[222:223], off
	v_lshl_add_u64 v[222:223], s[30:31], 0, v[138:139]
	s_add_i32 m0, s71, 0x2000
	s_nop 0
	global_load_lds_dwordx4 v[222:223], off
	v_lshl_add_u64 v[222:223], s[42:43], 0, v[132:133]
	s_mov_b32 m0, s54
	s_nop 0
	global_load_lds_dwordx4 v[222:223], off
	s_mov_b32 m0, s55
	s_nop 0
	global_load_lds_dwordx4 v[224:225], off
	s_waitcnt vmcnt(8)
	s_waitcnt lgkmcnt(0)
	s_barrier
	s_setprio 1
	s_waitcnt lgkmcnt(0)
	v_mfma_f32_16x16x32_bf16 v[60:63], v[128:131], v[182:185], 0
	v_mfma_f32_16x16x32_bf16 v[56:59], v[152:155], v[182:185], 0
	v_mfma_f32_16x16x32_bf16 v[44:47], v[128:131], v[190:193], 0
	v_mfma_f32_16x16x32_bf16 v[40:43], v[152:155], v[190:193], 0
	v_mfma_f32_16x16x32_bf16 v[28:31], v[128:131], v[198:201], 0
	v_mfma_f32_16x16x32_bf16 v[24:27], v[152:155], v[198:201], 0
	v_mfma_f32_16x16x32_bf16 v[12:15], v[128:131], v[210:213], 0
	v_mfma_f32_16x16x32_bf16 v[8:11], v[152:155], v[210:213], 0
	v_mfma_f32_16x16x32_bf16 v[60:63], v[148:151], v[186:189], v[60:63]
	v_mfma_f32_16x16x32_bf16 v[56:59], v[162:165], v[186:189], v[56:59]
	v_mfma_f32_16x16x32_bf16 v[44:47], v[148:151], v[194:197], v[44:47]
	v_mfma_f32_16x16x32_bf16 v[40:43], v[162:165], v[194:197], v[40:43]
	v_mfma_f32_16x16x32_bf16 v[28:31], v[148:151], v[202:205], v[28:31]
	v_mfma_f32_16x16x32_bf16 v[24:27], v[162:165], v[202:205], v[24:27]
	v_mfma_f32_16x16x32_bf16 v[12:15], v[148:151], v[214:217], v[12:15]
	v_mfma_f32_16x16x32_bf16 v[8:11], v[162:165], v[214:217], v[8:11]
	s_setprio 0
	s_setprio 1
	v_mfma_f32_16x16x32_bf16 v[52:55], v[166:169], v[182:185], 0
	v_mfma_f32_16x16x32_bf16 v[48:51], v[174:177], v[182:185], 0
	v_mfma_f32_16x16x32_bf16 v[36:39], v[166:169], v[190:193], 0
	v_mfma_f32_16x16x32_bf16 v[32:35], v[174:177], v[190:193], 0
	v_mfma_f32_16x16x32_bf16 v[20:23], v[166:169], v[198:201], 0
	v_mfma_f32_16x16x32_bf16 v[16:19], v[174:177], v[198:201], 0
	v_mfma_f32_16x16x32_bf16 v[4:7], v[166:169], v[210:213], 0
	v_mfma_f32_16x16x32_bf16 v[0:3], v[174:177], v[210:213], 0
	v_mfma_f32_16x16x32_bf16 v[52:55], v[170:173], v[186:189], v[52:55]
	v_mfma_f32_16x16x32_bf16 v[48:51], v[178:181], v[186:189], v[48:51]
	v_mfma_f32_16x16x32_bf16 v[36:39], v[170:173], v[194:197], v[36:39]
	v_mfma_f32_16x16x32_bf16 v[32:35], v[178:181], v[194:197], v[32:35]
	v_mfma_f32_16x16x32_bf16 v[20:23], v[170:173], v[202:205], v[20:23]
	v_mfma_f32_16x16x32_bf16 v[16:19], v[178:181], v[202:205], v[16:19]
	v_mfma_f32_16x16x32_bf16 v[4:7], v[170:173], v[214:217], v[4:7]
	v_mfma_f32_16x16x32_bf16 v[0:3], v[178:181], v[214:217], v[0:3]
	s_setprio 0
	s_barrier
	s_add_i32 s71, 0, 0x18000
	s_add_i32 s72, 0, 0x1c000
	v_add_u32_e32 v162, s71, v157
	v_add_u32_e32 v178, s72, v157
	ds_read_b128 v[128:131], v162
	ds_read_b128 v[148:151], v162 offset:1024
	ds_read_b128 v[152:155], v162 offset:2048
	ds_read_b128 v[162:165], v162 offset:3072
	ds_read_b128 v[166:169], v178
	ds_read_b128 v[170:173], v178 offset:1024
	ds_read_b128 v[174:177], v178 offset:2048
	ds_read_b128 v[178:181], v178 offset:3072
	s_add_u32 s30, s42, 0x160000
	s_addc_u32 s31, s43, 0
	s_mov_b32 m0, s56
	v_lshl_add_u64 v[226:227], s[30:31], 0, v[132:133]
	ds_read_b128 v[182:185], v161 offset:32768
	ds_read_b128 v[186:189], v161 offset:33792
	ds_read_b128 v[190:193], v161 offset:34816
	ds_read_b128 v[194:197], v161 offset:35840
	ds_read_b128 v[198:201], v161 offset:36864
	ds_read_b128 v[202:205], v161 offset:37888
	ds_read_b128 v[210:213], v161 offset:38912
	ds_read_b128 v[214:217], v161 offset:39936
	global_load_lds_dwordx4 v[226:227], off
	v_lshl_add_u64 v[226:227], s[30:31], 0, v[136:137]
	s_mov_b32 m0, s57
	s_nop 0
	global_load_lds_dwordx4 v[226:227], off
	s_waitcnt vmcnt(8)
	s_waitcnt lgkmcnt(0)
	s_barrier
	s_setprio 1
	s_waitcnt lgkmcnt(0)
	v_mfma_f32_16x16x32_bf16 v[124:127], v[128:131], v[182:185], v[124:127]
	v_mfma_f32_16x16x32_bf16 v[120:123], v[152:155], v[182:185], v[120:123]
	v_mfma_f32_16x16x32_bf16 v[108:111], v[128:131], v[190:193], v[108:111]
	v_mfma_f32_16x16x32_bf16 v[104:107], v[152:155], v[190:193], v[104:107]
	v_mfma_f32_16x16x32_bf16 v[92:95], v[128:131], v[198:201], v[92:95]
	v_mfma_f32_16x16x32_bf16 v[88:91], v[152:155], v[198:201], v[88:91]
	v_mfma_f32_16x16x32_bf16 v[76:79], v[128:131], v[210:213], v[76:79]
	v_mfma_f32_16x16x32_bf16 v[72:75], v[152:155], v[210:213], v[72:75]
	v_mfma_f32_16x16x32_bf16 v[124:127], v[148:151], v[186:189], v[124:127]
	v_mfma_f32_16x16x32_bf16 v[120:123], v[162:165], v[186:189], v[120:123]
	v_mfma_f32_16x16x32_bf16 v[108:111], v[148:151], v[194:197], v[108:111]
	v_mfma_f32_16x16x32_bf16 v[104:107], v[162:165], v[194:197], v[104:107]
	v_mfma_f32_16x16x32_bf16 v[92:95], v[148:151], v[202:205], v[92:95]
	v_mfma_f32_16x16x32_bf16 v[88:91], v[162:165], v[202:205], v[88:91]
	v_mfma_f32_16x16x32_bf16 v[76:79], v[148:151], v[214:217], v[76:79]
	v_mfma_f32_16x16x32_bf16 v[72:75], v[162:165], v[214:217], v[72:75]
	s_setprio 0
	s_setprio 1
	v_mfma_f32_16x16x32_bf16 v[116:119], v[166:169], v[182:185], v[116:119]
	v_mfma_f32_16x16x32_bf16 v[112:115], v[174:177], v[182:185], v[112:115]
	v_mfma_f32_16x16x32_bf16 v[100:103], v[166:169], v[190:193], v[100:103]
	v_mfma_f32_16x16x32_bf16 v[96:99], v[174:177], v[190:193], v[96:99]
	v_mfma_f32_16x16x32_bf16 v[84:87], v[166:169], v[198:201], v[84:87]
	v_mfma_f32_16x16x32_bf16 v[80:83], v[174:177], v[198:201], v[80:83]
	v_mfma_f32_16x16x32_bf16 v[68:71], v[166:169], v[210:213], v[68:71]
	v_mfma_f32_16x16x32_bf16 v[64:67], v[174:177], v[210:213], v[64:67]
	v_mfma_f32_16x16x32_bf16 v[116:119], v[170:173], v[186:189], v[116:119]
	v_mfma_f32_16x16x32_bf16 v[112:115], v[178:181], v[186:189], v[112:115]
	v_mfma_f32_16x16x32_bf16 v[100:103], v[170:173], v[194:197], v[100:103]
	v_mfma_f32_16x16x32_bf16 v[96:99], v[178:181], v[194:197], v[96:99]
	v_mfma_f32_16x16x32_bf16 v[84:87], v[170:173], v[202:205], v[84:87]
	v_mfma_f32_16x16x32_bf16 v[80:83], v[178:181], v[202:205], v[80:83]
	v_mfma_f32_16x16x32_bf16 v[68:71], v[170:173], v[214:217], v[68:71]
	v_mfma_f32_16x16x32_bf16 v[64:67], v[178:181], v[214:217], v[64:67]
	s_setprio 0
	s_barrier
	s_add_i32 s30, s71, s53
	v_lshl_add_u64 v[218:219], v[218:219], 0, s[16:17]
	s_mov_b32 m0, s30
	ds_read_b128 v[182:185], v161 offset:49152
	ds_read_b128 v[186:189], v161 offset:50176
	ds_read_b128 v[190:193], v161 offset:51200
	ds_read_b128 v[194:197], v161 offset:52224
	ds_read_b128 v[198:201], v161 offset:53248
	ds_read_b128 v[202:205], v161 offset:54272
	ds_read_b128 v[210:213], v161 offset:55296
	ds_read_b128 v[214:217], v161 offset:56320
	global_load_lds_dwordx4 v[218:219], off
	s_add_i32 m0, s30, 0x2000
	s_add_u32 s30, s40, 0x20080
	v_lshl_add_u64 v[218:219], v[220:221], 0, s[16:17]
	s_addc_u32 s31, s41, 0
	s_add_i32 s40, s72, s53
	global_load_lds_dwordx4 v[218:219], off
	v_lshl_add_u64 v[218:219], s[30:31], 0, v[134:135]
	s_mov_b32 m0, s40
	s_nop 0
	global_load_lds_dwordx4 v[218:219], off
	v_lshl_add_u64 v[218:219], s[30:31], 0, v[138:139]
	s_add_i32 m0, s40, 0x2000
	s_nop 0
	global_load_lds_dwordx4 v[218:219], off
	v_lshl_add_u64 v[218:219], v[222:223], 0, s[16:17]
	s_mov_b32 m0, s59
	s_nop 0
	global_load_lds_dwordx4 v[218:219], off
	v_lshl_add_u64 v[218:219], v[224:225], 0, s[16:17]
	s_mov_b32 m0, s60
	s_nop 0
	global_load_lds_dwordx4 v[218:219], off
	s_waitcnt vmcnt(8)
	s_waitcnt lgkmcnt(0)
	s_barrier
	s_setprio 1
	s_waitcnt lgkmcnt(0)
	v_mfma_f32_16x16x32_bf16 v[60:63], v[128:131], v[182:185], v[60:63]
	v_mfma_f32_16x16x32_bf16 v[56:59], v[152:155], v[182:185], v[56:59]
	v_mfma_f32_16x16x32_bf16 v[44:47], v[128:131], v[190:193], v[44:47]
	v_mfma_f32_16x16x32_bf16 v[40:43], v[152:155], v[190:193], v[40:43]
	v_mfma_f32_16x16x32_bf16 v[28:31], v[128:131], v[198:201], v[28:31]
	v_mfma_f32_16x16x32_bf16 v[24:27], v[152:155], v[198:201], v[24:27]
	v_mfma_f32_16x16x32_bf16 v[12:15], v[128:131], v[210:213], v[12:15]
	v_mfma_f32_16x16x32_bf16 v[8:11], v[152:155], v[210:213], v[8:11]
	v_mfma_f32_16x16x32_bf16 v[60:63], v[148:151], v[186:189], v[60:63]
	v_mfma_f32_16x16x32_bf16 v[56:59], v[162:165], v[186:189], v[56:59]
	v_mfma_f32_16x16x32_bf16 v[44:47], v[148:151], v[194:197], v[44:47]
	v_mfma_f32_16x16x32_bf16 v[40:43], v[162:165], v[194:197], v[40:43]
	v_mfma_f32_16x16x32_bf16 v[28:31], v[148:151], v[202:205], v[28:31]
	v_mfma_f32_16x16x32_bf16 v[24:27], v[162:165], v[202:205], v[24:27]
	v_mfma_f32_16x16x32_bf16 v[12:15], v[148:151], v[214:217], v[12:15]
	v_mfma_f32_16x16x32_bf16 v[8:11], v[162:165], v[214:217], v[8:11]
	s_setprio 0
	s_setprio 1
	v_mfma_f32_16x16x32_bf16 v[52:55], v[166:169], v[182:185], v[52:55]
	v_mfma_f32_16x16x32_bf16 v[48:51], v[174:177], v[182:185], v[48:51]
	v_mfma_f32_16x16x32_bf16 v[36:39], v[166:169], v[190:193], v[36:39]
	v_mfma_f32_16x16x32_bf16 v[32:35], v[174:177], v[190:193], v[32:35]
	v_mfma_f32_16x16x32_bf16 v[20:23], v[166:169], v[198:201], v[20:23]
	v_mfma_f32_16x16x32_bf16 v[16:19], v[174:177], v[198:201], v[16:19]
	v_mfma_f32_16x16x32_bf16 v[4:7], v[166:169], v[210:213], v[4:7]
	v_mfma_f32_16x16x32_bf16 v[0:3], v[174:177], v[210:213], v[0:3]
	v_mfma_f32_16x16x32_bf16 v[52:55], v[170:173], v[186:189], v[52:55]
	v_mfma_f32_16x16x32_bf16 v[48:51], v[178:181], v[186:189], v[48:51]
	v_mfma_f32_16x16x32_bf16 v[36:39], v[170:173], v[194:197], v[36:39]
	v_mfma_f32_16x16x32_bf16 v[32:35], v[178:181], v[194:197], v[32:35]
	v_mfma_f32_16x16x32_bf16 v[20:23], v[170:173], v[202:205], v[20:23]
	v_mfma_f32_16x16x32_bf16 v[16:19], v[178:181], v[202:205], v[16:19]
	v_mfma_f32_16x16x32_bf16 v[4:7], v[170:173], v[214:217], v[4:7]
	v_mfma_f32_16x16x32_bf16 v[0:3], v[178:181], v[214:217], v[0:3]
	s_setprio 0
	s_barrier
	s_add_i32 s70, s70, 2
	s_add_u32 s68, s68, 0x100
	s_addc_u32 s69, s69, 0
	s_cmp_gt_u32 s70, 5
	s_mov_b64 s[30:31], s[12:13]
	s_cbranch_scc1 .Lpeel_done_27249
.LBB0_927:
	ds_read_b128 v[128:131], v159
	ds_read_b128 v[148:151], v159 offset:1024
	ds_read_b128 v[152:155], v159 offset:2048
	ds_read_b128 v[162:165], v159 offset:3072
	ds_read_b128 v[166:169], v160
	ds_read_b128 v[170:173], v160 offset:1024
	ds_read_b128 v[174:177], v160 offset:2048
	ds_read_b128 v[178:181], v160 offset:3072
	s_add_u32 s12, s30, 0x100
	s_addc_u32 s13, s31, 0
	s_cmp_eq_u32 s70, 4
	s_cselect_b32 s43, s27, s13
	s_cselect_b32 s42, s26, s12
	s_cselect_b32 s41, s25, s69
	s_cselect_b32 s40, s67, s68
	v_lshl_add_u64 v[218:219], s[30:31], 0, v[140:141]
	s_add_i32 m0, s54, 0xc000
	ds_read_b128 v[182:185], v161
	ds_read_b128 v[186:189], v161 offset:1024
	ds_read_b128 v[190:193], v161 offset:2048
	ds_read_b128 v[194:197], v161 offset:3072
	ds_read_b128 v[198:201], v161 offset:4096
	ds_read_b128 v[202:205], v161 offset:5120
	ds_read_b128 v[210:213], v161 offset:6144
	ds_read_b128 v[214:217], v161 offset:7168
	global_load_lds_dwordx4 v[218:219], off
	v_lshl_add_u64 v[218:219], s[30:31], 0, v[142:143]
	s_add_i32 m0, s54, 0xe000
	s_nop 0
	global_load_lds_dwordx4 v[218:219], off
	s_waitcnt vmcnt(8)
	s_waitcnt lgkmcnt(0)
	s_barrier
	s_waitcnt lgkmcnt(0)
	v_mfma_f32_16x16x32_bf16 v[124:127], v[128:131], v[182:185], v[124:127]
	v_mfma_f32_16x16x32_bf16 v[120:123], v[152:155], v[182:185], v[120:123]
	v_mfma_f32_16x16x32_bf16 v[108:111], v[128:131], v[190:193], v[108:111]
	v_mfma_f32_16x16x32_bf16 v[104:107], v[152:155], v[190:193], v[104:107]
	v_mfma_f32_16x16x32_bf16 v[92:95], v[128:131], v[198:201], v[92:95]
	v_mfma_f32_16x16x32_bf16 v[88:91], v[152:155], v[198:201], v[88:91]
	v_mfma_f32_16x16x32_bf16 v[76:79], v[128:131], v[210:213], v[76:79]
	v_mfma_f32_16x16x32_bf16 v[72:75], v[152:155], v[210:213], v[72:75]
	v_mfma_f32_16x16x32_bf16 v[124:127], v[148:151], v[186:189], v[124:127]
	v_mfma_f32_16x16x32_bf16 v[120:123], v[162:165], v[186:189], v[120:123]
	v_mfma_f32_16x16x32_bf16 v[108:111], v[148:151], v[194:197], v[108:111]
	v_mfma_f32_16x16x32_bf16 v[104:107], v[162:165], v[194:197], v[104:107]
	v_mfma_f32_16x16x32_bf16 v[92:95], v[148:151], v[202:205], v[92:95]
	v_mfma_f32_16x16x32_bf16 v[88:91], v[162:165], v[202:205], v[88:91]
	v_mfma_f32_16x16x32_bf16 v[76:79], v[148:151], v[214:217], v[76:79]
	v_mfma_f32_16x16x32_bf16 v[72:75], v[162:165], v[214:217], v[72:75]
	v_mfma_f32_16x16x32_bf16 v[116:119], v[166:169], v[182:185], v[116:119]
	v_mfma_f32_16x16x32_bf16 v[112:115], v[174:177], v[182:185], v[112:115]
	v_mfma_f32_16x16x32_bf16 v[100:103], v[166:169], v[190:193], v[100:103]
	v_mfma_f32_16x16x32_bf16 v[96:99], v[174:177], v[190:193], v[96:99]
	v_mfma_f32_16x16x32_bf16 v[84:87], v[166:169], v[198:201], v[84:87]
	v_mfma_f32_16x16x32_bf16 v[80:83], v[174:177], v[198:201], v[80:83]
	v_mfma_f32_16x16x32_bf16 v[68:71], v[166:169], v[210:213], v[68:71]
	v_mfma_f32_16x16x32_bf16 v[64:67], v[174:177], v[210:213], v[64:67]
	v_mfma_f32_16x16x32_bf16 v[116:119], v[170:173], v[186:189], v[116:119]
	v_mfma_f32_16x16x32_bf16 v[112:115], v[178:181], v[186:189], v[112:115]
	v_mfma_f32_16x16x32_bf16 v[100:103], v[170:173], v[194:197], v[100:103]
	v_mfma_f32_16x16x32_bf16 v[96:99], v[178:181], v[194:197], v[96:99]
	v_mfma_f32_16x16x32_bf16 v[84:87], v[170:173], v[202:205], v[84:87]
	v_mfma_f32_16x16x32_bf16 v[80:83], v[178:181], v[202:205], v[80:83]
	v_mfma_f32_16x16x32_bf16 v[68:71], v[170:173], v[214:217], v[68:71]
	v_mfma_f32_16x16x32_bf16 v[64:67], v[178:181], v[214:217], v[64:67]
	s_barrier
	s_add_i32 s30, s61, s53
	v_lshl_add_u64 v[218:219], s[40:41], 0, v[134:135]
	s_mov_b32 m0, s30
	ds_read_b128 v[182:185], v161 offset:16384
	ds_read_b128 v[186:189], v161 offset:17408
	ds_read_b128 v[190:193], v161 offset:18432
	ds_read_b128 v[194:197], v161 offset:19456
	ds_read_b128 v[198:201], v161 offset:20480
	ds_read_b128 v[202:205], v161 offset:21504
	ds_read_b128 v[210:213], v161 offset:22528
	ds_read_b128 v[214:217], v161 offset:23552
	global_load_lds_dwordx4 v[218:219], off
	s_add_i32 m0, s30, 0x2000
	s_add_u32 s30, s40, 0x20000
	v_lshl_add_u64 v[220:221], s[40:41], 0, v[138:139]
	s_addc_u32 s31, s41, 0
	s_add_i32 s71, s62, s53
	global_load_lds_dwordx4 v[220:221], off
	v_lshl_add_u64 v[222:223], s[30:31], 0, v[134:135]
	s_mov_b32 m0, s71
	v_lshl_add_u64 v[224:225], s[42:43], 0, v[136:137]
	global_load_lds_dwordx4 v[222:223], off
	v_lshl_add_u64 v[222:223], s[30:31], 0, v[138:139]
	s_add_i32 m0, s71, 0x2000
	s_nop 0
	global_load_lds_dwordx4 v[222:223], off
	v_lshl_add_u64 v[222:223], s[42:43], 0, v[132:133]
	s_mov_b32 m0, s54
	s_nop 0
	global_load_lds_dwordx4 v[222:223], off
	s_mov_b32 m0, s55
	s_nop 0
	global_load_lds_dwordx4 v[224:225], off
	s_waitcnt vmcnt(8)
	s_waitcnt lgkmcnt(0)
	s_barrier
	s_waitcnt lgkmcnt(0)
	v_mfma_f32_16x16x32_bf16 v[60:63], v[128:131], v[182:185], v[60:63]
	v_mfma_f32_16x16x32_bf16 v[56:59], v[152:155], v[182:185], v[56:59]
	v_mfma_f32_16x16x32_bf16 v[44:47], v[128:131], v[190:193], v[44:47]
	v_mfma_f32_16x16x32_bf16 v[40:43], v[152:155], v[190:193], v[40:43]
	v_mfma_f32_16x16x32_bf16 v[28:31], v[128:131], v[198:201], v[28:31]
	v_mfma_f32_16x16x32_bf16 v[24:27], v[152:155], v[198:201], v[24:27]
	v_mfma_f32_16x16x32_bf16 v[12:15], v[128:131], v[210:213], v[12:15]
	v_mfma_f32_16x16x32_bf16 v[8:11], v[152:155], v[210:213], v[8:11]
	v_mfma_f32_16x16x32_bf16 v[60:63], v[148:151], v[186:189], v[60:63]
	v_mfma_f32_16x16x32_bf16 v[56:59], v[162:165], v[186:189], v[56:59]
	v_mfma_f32_16x16x32_bf16 v[44:47], v[148:151], v[194:197], v[44:47]
	v_mfma_f32_16x16x32_bf16 v[40:43], v[162:165], v[194:197], v[40:43]
	v_mfma_f32_16x16x32_bf16 v[28:31], v[148:151], v[202:205], v[28:31]
	v_mfma_f32_16x16x32_bf16 v[24:27], v[162:165], v[202:205], v[24:27]
	v_mfma_f32_16x16x32_bf16 v[12:15], v[148:151], v[214:217], v[12:15]
	v_mfma_f32_16x16x32_bf16 v[8:11], v[162:165], v[214:217], v[8:11]
	v_mfma_f32_16x16x32_bf16 v[52:55], v[166:169], v[182:185], v[52:55]
	v_mfma_f32_16x16x32_bf16 v[48:51], v[174:177], v[182:185], v[48:51]
	v_mfma_f32_16x16x32_bf16 v[36:39], v[166:169], v[190:193], v[36:39]
	v_mfma_f32_16x16x32_bf16 v[32:35], v[174:177], v[190:193], v[32:35]
	v_mfma_f32_16x16x32_bf16 v[20:23], v[166:169], v[198:201], v[20:23]
	v_mfma_f32_16x16x32_bf16 v[16:19], v[174:177], v[198:201], v[16:19]
	v_mfma_f32_16x16x32_bf16 v[4:7], v[166:169], v[210:213], v[4:7]
	v_mfma_f32_16x16x32_bf16 v[0:3], v[174:177], v[210:213], v[0:3]
	v_mfma_f32_16x16x32_bf16 v[52:55], v[170:173], v[186:189], v[52:55]
	v_mfma_f32_16x16x32_bf16 v[48:51], v[178:181], v[186:189], v[48:51]
	v_mfma_f32_16x16x32_bf16 v[36:39], v[170:173], v[194:197], v[36:39]
	v_mfma_f32_16x16x32_bf16 v[32:35], v[178:181], v[194:197], v[32:35]
	v_mfma_f32_16x16x32_bf16 v[20:23], v[170:173], v[202:205], v[20:23]
	v_mfma_f32_16x16x32_bf16 v[16:19], v[178:181], v[202:205], v[16:19]
	v_mfma_f32_16x16x32_bf16 v[4:7], v[170:173], v[214:217], v[4:7]
	v_mfma_f32_16x16x32_bf16 v[0:3], v[178:181], v[214:217], v[0:3]
	s_barrier
	s_add_i32 s71, 0, 0x18000
	s_add_i32 s72, 0, 0x1c000
	v_add_u32_e32 v162, s71, v157
	v_add_u32_e32 v178, s72, v157
	ds_read_b128 v[128:131], v162
	ds_read_b128 v[148:151], v162 offset:1024
	ds_read_b128 v[152:155], v162 offset:2048
	ds_read_b128 v[162:165], v162 offset:3072
	ds_read_b128 v[166:169], v178
	ds_read_b128 v[170:173], v178 offset:1024
	ds_read_b128 v[174:177], v178 offset:2048
	ds_read_b128 v[178:181], v178 offset:3072
	s_add_u32 s30, s42, 0x160000
	s_addc_u32 s31, s43, 0
	s_mov_b32 m0, s56
	v_lshl_add_u64 v[226:227], s[30:31], 0, v[132:133]
	ds_read_b128 v[182:185], v161 offset:32768
	ds_read_b128 v[186:189], v161 offset:33792
	ds_read_b128 v[190:193], v161 offset:34816
	ds_read_b128 v[194:197], v161 offset:35840
	ds_read_b128 v[198:201], v161 offset:36864
	ds_read_b128 v[202:205], v161 offset:37888
	ds_read_b128 v[210:213], v161 offset:38912
	ds_read_b128 v[214:217], v161 offset:39936
	global_load_lds_dwordx4 v[226:227], off
	v_lshl_add_u64 v[226:227], s[30:31], 0, v[136:137]
	s_mov_b32 m0, s57
	s_nop 0
	global_load_lds_dwordx4 v[226:227], off
	s_waitcnt vmcnt(8)
	s_waitcnt lgkmcnt(0)
	s_barrier
	s_waitcnt lgkmcnt(0)
	v_mfma_f32_16x16x32_bf16 v[124:127], v[128:131], v[182:185], v[124:127]
	v_mfma_f32_16x16x32_bf16 v[120:123], v[152:155], v[182:185], v[120:123]
	v_mfma_f32_16x16x32_bf16 v[108:111], v[128:131], v[190:193], v[108:111]
	v_mfma_f32_16x16x32_bf16 v[104:107], v[152:155], v[190:193], v[104:107]
	v_mfma_f32_16x16x32_bf16 v[92:95], v[128:131], v[198:201], v[92:95]
	v_mfma_f32_16x16x32_bf16 v[88:91], v[152:155], v[198:201], v[88:91]
	v_mfma_f32_16x16x32_bf16 v[76:79], v[128:131], v[210:213], v[76:79]
	v_mfma_f32_16x16x32_bf16 v[72:75], v[152:155], v[210:213], v[72:75]
	v_mfma_f32_16x16x32_bf16 v[124:127], v[148:151], v[186:189], v[124:127]
	v_mfma_f32_16x16x32_bf16 v[120:123], v[162:165], v[186:189], v[120:123]
	v_mfma_f32_16x16x32_bf16 v[108:111], v[148:151], v[194:197], v[108:111]
	v_mfma_f32_16x16x32_bf16 v[104:107], v[162:165], v[194:197], v[104:107]
	v_mfma_f32_16x16x32_bf16 v[92:95], v[148:151], v[202:205], v[92:95]
	v_mfma_f32_16x16x32_bf16 v[88:91], v[162:165], v[202:205], v[88:91]
	v_mfma_f32_16x16x32_bf16 v[76:79], v[148:151], v[214:217], v[76:79]
	v_mfma_f32_16x16x32_bf16 v[72:75], v[162:165], v[214:217], v[72:75]
	v_mfma_f32_16x16x32_bf16 v[116:119], v[166:169], v[182:185], v[116:119]
	v_mfma_f32_16x16x32_bf16 v[112:115], v[174:177], v[182:185], v[112:115]
	v_mfma_f32_16x16x32_bf16 v[100:103], v[166:169], v[190:193], v[100:103]
	v_mfma_f32_16x16x32_bf16 v[96:99], v[174:177], v[190:193], v[96:99]
	v_mfma_f32_16x16x32_bf16 v[84:87], v[166:169], v[198:201], v[84:87]
	v_mfma_f32_16x16x32_bf16 v[80:83], v[174:177], v[198:201], v[80:83]
	v_mfma_f32_16x16x32_bf16 v[68:71], v[166:169], v[210:213], v[68:71]
	v_mfma_f32_16x16x32_bf16 v[64:67], v[174:177], v[210:213], v[64:67]
	v_mfma_f32_16x16x32_bf16 v[116:119], v[170:173], v[186:189], v[116:119]
	v_mfma_f32_16x16x32_bf16 v[112:115], v[178:181], v[186:189], v[112:115]
	v_mfma_f32_16x16x32_bf16 v[100:103], v[170:173], v[194:197], v[100:103]
	v_mfma_f32_16x16x32_bf16 v[96:99], v[178:181], v[194:197], v[96:99]
	v_mfma_f32_16x16x32_bf16 v[84:87], v[170:173], v[202:205], v[84:87]
	v_mfma_f32_16x16x32_bf16 v[80:83], v[178:181], v[202:205], v[80:83]
	v_mfma_f32_16x16x32_bf16 v[68:71], v[170:173], v[214:217], v[68:71]
	v_mfma_f32_16x16x32_bf16 v[64:67], v[178:181], v[214:217], v[64:67]
	s_barrier
	s_add_i32 s30, s71, s53
	v_lshl_add_u64 v[218:219], v[218:219], 0, s[16:17]
	s_mov_b32 m0, s30
	ds_read_b128 v[182:185], v161 offset:49152
	ds_read_b128 v[186:189], v161 offset:50176
	ds_read_b128 v[190:193], v161 offset:51200
	ds_read_b128 v[194:197], v161 offset:52224
	ds_read_b128 v[198:201], v161 offset:53248
	ds_read_b128 v[202:205], v161 offset:54272
	ds_read_b128 v[210:213], v161 offset:55296
	ds_read_b128 v[214:217], v161 offset:56320
	global_load_lds_dwordx4 v[218:219], off
	s_add_i32 m0, s30, 0x2000
	s_add_u32 s30, s40, 0x20080
	v_lshl_add_u64 v[218:219], v[220:221], 0, s[16:17]
	s_addc_u32 s31, s41, 0
	s_add_i32 s40, s72, s53
	global_load_lds_dwordx4 v[218:219], off
	v_lshl_add_u64 v[218:219], s[30:31], 0, v[134:135]
	s_mov_b32 m0, s40
	s_nop 0
	global_load_lds_dwordx4 v[218:219], off
	v_lshl_add_u64 v[218:219], s[30:31], 0, v[138:139]
	s_add_i32 m0, s40, 0x2000
	s_nop 0
	global_load_lds_dwordx4 v[218:219], off
	v_lshl_add_u64 v[218:219], v[222:223], 0, s[16:17]
	s_mov_b32 m0, s59
	s_nop 0
	global_load_lds_dwordx4 v[218:219], off
	v_lshl_add_u64 v[218:219], v[224:225], 0, s[16:17]
	s_mov_b32 m0, s60
	s_nop 0
	global_load_lds_dwordx4 v[218:219], off
	s_waitcnt vmcnt(8)
	s_waitcnt lgkmcnt(0)
	s_barrier
	s_waitcnt lgkmcnt(0)
	v_mfma_f32_16x16x32_bf16 v[60:63], v[128:131], v[182:185], v[60:63]
	v_mfma_f32_16x16x32_bf16 v[56:59], v[152:155], v[182:185], v[56:59]
	v_mfma_f32_16x16x32_bf16 v[44:47], v[128:131], v[190:193], v[44:47]
	v_mfma_f32_16x16x32_bf16 v[40:43], v[152:155], v[190:193], v[40:43]
	v_mfma_f32_16x16x32_bf16 v[28:31], v[128:131], v[198:201], v[28:31]
	v_mfma_f32_16x16x32_bf16 v[24:27], v[152:155], v[198:201], v[24:27]
	v_mfma_f32_16x16x32_bf16 v[12:15], v[128:131], v[210:213], v[12:15]
	v_mfma_f32_16x16x32_bf16 v[8:11], v[152:155], v[210:213], v[8:11]
	v_mfma_f32_16x16x32_bf16 v[60:63], v[148:151], v[186:189], v[60:63]
	v_mfma_f32_16x16x32_bf16 v[56:59], v[162:165], v[186:189], v[56:59]
	v_mfma_f32_16x16x32_bf16 v[44:47], v[148:151], v[194:197], v[44:47]
	v_mfma_f32_16x16x32_bf16 v[40:43], v[162:165], v[194:197], v[40:43]
	v_mfma_f32_16x16x32_bf16 v[28:31], v[148:151], v[202:205], v[28:31]
	v_mfma_f32_16x16x32_bf16 v[24:27], v[162:165], v[202:205], v[24:27]
	v_mfma_f32_16x16x32_bf16 v[12:15], v[148:151], v[214:217], v[12:15]
	v_mfma_f32_16x16x32_bf16 v[8:11], v[162:165], v[214:217], v[8:11]
	v_mfma_f32_16x16x32_bf16 v[52:55], v[166:169], v[182:185], v[52:55]
	v_mfma_f32_16x16x32_bf16 v[48:51], v[174:177], v[182:185], v[48:51]
	v_mfma_f32_16x16x32_bf16 v[36:39], v[166:169], v[190:193], v[36:39]
	v_mfma_f32_16x16x32_bf16 v[32:35], v[174:177], v[190:193], v[32:35]
	v_mfma_f32_16x16x32_bf16 v[20:23], v[166:169], v[198:201], v[20:23]
	v_mfma_f32_16x16x32_bf16 v[16:19], v[174:177], v[198:201], v[16:19]
	v_mfma_f32_16x16x32_bf16 v[4:7], v[166:169], v[210:213], v[4:7]
	v_mfma_f32_16x16x32_bf16 v[0:3], v[174:177], v[210:213], v[0:3]
	v_mfma_f32_16x16x32_bf16 v[52:55], v[170:173], v[186:189], v[52:55]
	v_mfma_f32_16x16x32_bf16 v[48:51], v[178:181], v[186:189], v[48:51]
	v_mfma_f32_16x16x32_bf16 v[36:39], v[170:173], v[194:197], v[36:39]
	v_mfma_f32_16x16x32_bf16 v[32:35], v[178:181], v[194:197], v[32:35]
	v_mfma_f32_16x16x32_bf16 v[20:23], v[170:173], v[202:205], v[20:23]
	v_mfma_f32_16x16x32_bf16 v[16:19], v[178:181], v[202:205], v[16:19]
	v_mfma_f32_16x16x32_bf16 v[4:7], v[170:173], v[214:217], v[4:7]
	v_mfma_f32_16x16x32_bf16 v[0:3], v[178:181], v[214:217], v[0:3]
	s_barrier
	s_add_i32 s70, s70, 2
	s_add_u32 s68, s68, 0x100
	s_addc_u32 s69, s69, 0
	s_cmp_gt_u32 s70, 5
	s_mov_b64 s[30:31], s[12:13]
	s_cbranch_scc0 .LBB0_927

.LBB0_1006:
	s_ashr_i32 s41, s40, 31
	s_lshl_b64 s[50:51], s[40:41], 19
	s_add_u32 s50, s59, s50
	s_addc_u32 s51, s60, s51
	s_and_b64 s[14:15], s[14:15], exec
	s_cselect_b32 s41, s51, s55
	s_cselect_b32 s78, s50, s54
	s_add_u32 s79, s54, 0x100
	s_addc_u32 s80, s55, 0
	s_mov_b32 s81, -2
	s_waitcnt lgkmcnt(0)
	ds_read_b128 v[146:149], v157
	ds_read_b128 v[150:153], v157 offset:1024
	ds_read_b128 v[160:163], v157 offset:2048
	ds_read_b128 v[164:167], v157 offset:3072
	ds_read_b128 v[168:171], v158
	ds_read_b128 v[172:175], v158 offset:1024
	ds_read_b128 v[176:179], v158 offset:2048
	ds_read_b128 v[180:183], v158 offset:3072
	s_add_u32 s14, s52, 0x100
	s_addc_u32 s15, s53, 0
	s_cmp_eq_u32 s81, 12
	s_cselect_b32 s57, s43, s15
	s_cselect_b32 s56, s42, s14
	s_cselect_b32 s55, s41, s80
	s_cselect_b32 s54, s78, s79
	v_lshl_add_u64 v[204:205], s[52:53], 0, v[138:139]
	s_add_i32 m0, s21, 0xc000
	ds_read_b128 v[184:187], v159
	ds_read_b128 v[188:191], v159 offset:1024
	ds_read_b128 v[192:195], v159 offset:2048
	ds_read_b128 v[196:199], v159 offset:3072
	ds_read_b128 v[200:203], v159 offset:4096
	ds_read_b128 v[210:213], v159 offset:5120
	ds_read_b128 v[214:217], v159 offset:6144
	ds_read_b128 v[218:221], v159 offset:7168
	global_load_lds_dwordx4 v[204:205], off
	v_lshl_add_u64 v[204:205], s[52:53], 0, v[140:141]
	s_add_i32 m0, s21, 0xe000
	s_nop 0
	global_load_lds_dwordx4 v[204:205], off
	s_waitcnt vmcnt(8)
	s_waitcnt lgkmcnt(0)
	s_barrier
	s_setprio 1
	s_waitcnt lgkmcnt(0)
	v_mfma_f32_16x16x32_bf16 v[124:127], v[146:149], v[184:187], 0
	v_mfma_f32_16x16x32_bf16 v[120:123], v[160:163], v[184:187], 0
	v_mfma_f32_16x16x32_bf16 v[108:111], v[146:149], v[192:195], 0
	v_mfma_f32_16x16x32_bf16 v[104:107], v[160:163], v[192:195], 0
	v_mfma_f32_16x16x32_bf16 v[92:95], v[146:149], v[200:203], 0
	v_mfma_f32_16x16x32_bf16 v[88:91], v[160:163], v[200:203], 0
	v_mfma_f32_16x16x32_bf16 v[76:79], v[146:149], v[214:217], 0
	v_mfma_f32_16x16x32_bf16 v[72:75], v[160:163], v[214:217], 0
	v_mfma_f32_16x16x32_bf16 v[124:127], v[150:153], v[188:191], v[124:127]
	v_mfma_f32_16x16x32_bf16 v[120:123], v[164:167], v[188:191], v[120:123]
	v_mfma_f32_16x16x32_bf16 v[108:111], v[150:153], v[196:199], v[108:111]
	v_mfma_f32_16x16x32_bf16 v[104:107], v[164:167], v[196:199], v[104:107]
	v_mfma_f32_16x16x32_bf16 v[92:95], v[150:153], v[210:213], v[92:95]
	v_mfma_f32_16x16x32_bf16 v[88:91], v[164:167], v[210:213], v[88:91]
	v_mfma_f32_16x16x32_bf16 v[76:79], v[150:153], v[218:221], v[76:79]
	v_mfma_f32_16x16x32_bf16 v[72:75], v[164:167], v[218:221], v[72:75]
	s_setprio 0
	s_setprio 1
	v_mfma_f32_16x16x32_bf16 v[116:119], v[168:171], v[184:187], 0
	v_mfma_f32_16x16x32_bf16 v[112:115], v[176:179], v[184:187], 0
	v_mfma_f32_16x16x32_bf16 v[100:103], v[168:171], v[192:195], 0
	v_mfma_f32_16x16x32_bf16 v[96:99], v[176:179], v[192:195], 0
	v_mfma_f32_16x16x32_bf16 v[84:87], v[168:171], v[200:203], 0
	v_mfma_f32_16x16x32_bf16 v[80:83], v[176:179], v[200:203], 0
	v_mfma_f32_16x16x32_bf16 v[68:71], v[168:171], v[214:217], 0
	v_mfma_f32_16x16x32_bf16 v[64:67], v[176:179], v[214:217], 0
	v_mfma_f32_16x16x32_bf16 v[116:119], v[172:175], v[188:191], v[116:119]
	v_mfma_f32_16x16x32_bf16 v[112:115], v[180:183], v[188:191], v[112:115]
	v_mfma_f32_16x16x32_bf16 v[100:103], v[172:175], v[196:199], v[100:103]
	v_mfma_f32_16x16x32_bf16 v[96:99], v[180:183], v[196:199], v[96:99]
	v_mfma_f32_16x16x32_bf16 v[84:87], v[172:175], v[210:213], v[84:87]
	v_mfma_f32_16x16x32_bf16 v[80:83], v[180:183], v[210:213], v[80:83]
	v_mfma_f32_16x16x32_bf16 v[68:71], v[172:175], v[218:221], v[68:71]
	v_mfma_f32_16x16x32_bf16 v[64:67], v[180:183], v[218:221], v[64:67]
	s_setprio 0
	s_barrier
	s_add_i32 s52, s68, s61
	v_lshl_add_u64 v[204:205], s[54:55], 0, v[130:131]
	s_mov_b32 m0, s52
	ds_read_b128 v[184:187], v159 offset:16384
	ds_read_b128 v[188:191], v159 offset:17408
	ds_read_b128 v[192:195], v159 offset:18432
	ds_read_b128 v[196:199], v159 offset:19456
	ds_read_b128 v[200:203], v159 offset:20480
	ds_read_b128 v[210:213], v159 offset:21504
	ds_read_b128 v[214:217], v159 offset:22528
	ds_read_b128 v[218:221], v159 offset:23552
	global_load_lds_dwordx4 v[204:205], off
	s_add_i32 m0, s52, 0x2000
	s_add_u32 s52, s54, 0x40000
	v_lshl_add_u64 v[222:223], s[54:55], 0, v[134:135]
	s_addc_u32 s53, s55, 0
	s_add_i32 s82, s69, s61
	global_load_lds_dwordx4 v[222:223], off
	v_lshl_add_u64 v[224:225], s[52:53], 0, v[130:131]
	s_mov_b32 m0, s82
	v_lshl_add_u64 v[226:227], s[56:57], 0, v[132:133]
	global_load_lds_dwordx4 v[224:225], off
	v_lshl_add_u64 v[224:225], s[52:53], 0, v[134:135]
	s_add_i32 m0, s82, 0x2000
	s_nop 0
	global_load_lds_dwordx4 v[224:225], off
	v_lshl_add_u64 v[224:225], s[56:57], 0, v[128:129]
	s_mov_b32 m0, s21
	s_nop 0
	global_load_lds_dwordx4 v[224:225], off
	s_mov_b32 m0, s62
	s_nop 0
	global_load_lds_dwordx4 v[226:227], off
	s_waitcnt vmcnt(8)
	s_waitcnt lgkmcnt(0)
	s_barrier
	s_setprio 1
	s_waitcnt lgkmcnt(0)
	v_mfma_f32_16x16x32_bf16 v[60:63], v[146:149], v[184:187], 0
	v_mfma_f32_16x16x32_bf16 v[56:59], v[160:163], v[184:187], 0
	v_mfma_f32_16x16x32_bf16 v[44:47], v[146:149], v[192:195], 0
	v_mfma_f32_16x16x32_bf16 v[40:43], v[160:163], v[192:195], 0
	v_mfma_f32_16x16x32_bf16 v[28:31], v[146:149], v[200:203], 0
	v_mfma_f32_16x16x32_bf16 v[24:27], v[160:163], v[200:203], 0
	v_mfma_f32_16x16x32_bf16 v[12:15], v[146:149], v[214:217], 0
	v_mfma_f32_16x16x32_bf16 v[8:11], v[160:163], v[214:217], 0
	v_mfma_f32_16x16x32_bf16 v[60:63], v[150:153], v[188:191], v[60:63]
	v_mfma_f32_16x16x32_bf16 v[56:59], v[164:167], v[188:191], v[56:59]
	v_mfma_f32_16x16x32_bf16 v[44:47], v[150:153], v[196:199], v[44:47]
	v_mfma_f32_16x16x32_bf16 v[40:43], v[164:167], v[196:199], v[40:43]
	v_mfma_f32_16x16x32_bf16 v[28:31], v[150:153], v[210:213], v[28:31]
	v_mfma_f32_16x16x32_bf16 v[24:27], v[164:167], v[210:213], v[24:27]
	v_mfma_f32_16x16x32_bf16 v[12:15], v[150:153], v[218:221], v[12:15]
	v_mfma_f32_16x16x32_bf16 v[8:11], v[164:167], v[218:221], v[8:11]
	s_setprio 0
	s_setprio 1
	v_mfma_f32_16x16x32_bf16 v[52:55], v[168:171], v[184:187], 0
	v_mfma_f32_16x16x32_bf16 v[48:51], v[176:179], v[184:187], 0
	v_mfma_f32_16x16x32_bf16 v[36:39], v[168:171], v[192:195], 0
	v_mfma_f32_16x16x32_bf16 v[32:35], v[176:179], v[192:195], 0
	v_mfma_f32_16x16x32_bf16 v[20:23], v[168:171], v[200:203], 0
	v_mfma_f32_16x16x32_bf16 v[16:19], v[176:179], v[200:203], 0
	v_mfma_f32_16x16x32_bf16 v[4:7], v[168:171], v[214:217], 0
	v_mfma_f32_16x16x32_bf16 v[0:3], v[176:179], v[214:217], 0
	v_mfma_f32_16x16x32_bf16 v[52:55], v[172:175], v[188:191], v[52:55]
	v_mfma_f32_16x16x32_bf16 v[48:51], v[180:183], v[188:191], v[48:51]
	v_mfma_f32_16x16x32_bf16 v[36:39], v[172:175], v[196:199], v[36:39]
	v_mfma_f32_16x16x32_bf16 v[32:35], v[180:183], v[196:199], v[32:35]
	v_mfma_f32_16x16x32_bf16 v[20:23], v[172:175], v[210:213], v[20:23]
	v_mfma_f32_16x16x32_bf16 v[16:19], v[180:183], v[210:213], v[16:19]
	v_mfma_f32_16x16x32_bf16 v[4:7], v[172:175], v[218:221], v[4:7]
	v_mfma_f32_16x16x32_bf16 v[0:3], v[180:183], v[218:221], v[0:3]
	s_setprio 0
	s_barrier
	s_add_i32 s82, 0, 0x18000
	v_add_u32_e32 v136, s82, v155
	s_add_i32 s83, 0, 0x1c000
	ds_read_b128 v[146:149], v136
	ds_read_b128 v[150:153], v136 offset:1024
	ds_read_b128 v[160:163], v136 offset:2048
	ds_read_b128 v[164:167], v136 offset:3072
	v_add_u32_e32 v136, s83, v155
	ds_read_b128 v[168:171], v136
	ds_read_b128 v[172:175], v136 offset:1024
	ds_read_b128 v[176:179], v136 offset:2048
	ds_read_b128 v[180:183], v136 offset:3072
	s_add_u32 s52, s56, 0x160000
	s_addc_u32 s53, s57, 0
	s_mov_b32 m0, s63
	v_lshl_add_u64 v[228:229], s[52:53], 0, v[128:129]
	ds_read_b128 v[184:187], v159 offset:32768
	ds_read_b128 v[188:191], v159 offset:33792
	ds_read_b128 v[192:195], v159 offset:34816
	ds_read_b128 v[196:199], v159 offset:35840
	ds_read_b128 v[200:203], v159 offset:36864
	ds_read_b128 v[210:213], v159 offset:37888
	ds_read_b128 v[214:217], v159 offset:38912
	ds_read_b128 v[218:221], v159 offset:39936
	global_load_lds_dwordx4 v[228:229], off
	v_lshl_add_u64 v[228:229], s[52:53], 0, v[132:133]
	s_mov_b32 m0, s64
	s_nop 0
	global_load_lds_dwordx4 v[228:229], off
	s_waitcnt vmcnt(8)
	s_waitcnt lgkmcnt(0)
	s_barrier
	s_setprio 1
	s_waitcnt lgkmcnt(0)
	v_mfma_f32_16x16x32_bf16 v[124:127], v[146:149], v[184:187], v[124:127]
	v_mfma_f32_16x16x32_bf16 v[120:123], v[160:163], v[184:187], v[120:123]
	v_mfma_f32_16x16x32_bf16 v[108:111], v[146:149], v[192:195], v[108:111]
	v_mfma_f32_16x16x32_bf16 v[104:107], v[160:163], v[192:195], v[104:107]
	v_mfma_f32_16x16x32_bf16 v[92:95], v[146:149], v[200:203], v[92:95]
	v_mfma_f32_16x16x32_bf16 v[88:91], v[160:163], v[200:203], v[88:91]
	v_mfma_f32_16x16x32_bf16 v[76:79], v[146:149], v[214:217], v[76:79]
	v_mfma_f32_16x16x32_bf16 v[72:75], v[160:163], v[214:217], v[72:75]
	v_mfma_f32_16x16x32_bf16 v[124:127], v[150:153], v[188:191], v[124:127]
	v_mfma_f32_16x16x32_bf16 v[120:123], v[164:167], v[188:191], v[120:123]
	v_mfma_f32_16x16x32_bf16 v[108:111], v[150:153], v[196:199], v[108:111]
	v_mfma_f32_16x16x32_bf16 v[104:107], v[164:167], v[196:199], v[104:107]
	v_mfma_f32_16x16x32_bf16 v[92:95], v[150:153], v[210:213], v[92:95]
	v_mfma_f32_16x16x32_bf16 v[88:91], v[164:167], v[210:213], v[88:91]
	v_mfma_f32_16x16x32_bf16 v[76:79], v[150:153], v[218:221], v[76:79]
	v_mfma_f32_16x16x32_bf16 v[72:75], v[164:167], v[218:221], v[72:75]
	s_setprio 0
	s_setprio 1
	v_mfma_f32_16x16x32_bf16 v[116:119], v[168:171], v[184:187], v[116:119]
	v_mfma_f32_16x16x32_bf16 v[112:115], v[176:179], v[184:187], v[112:115]
	v_mfma_f32_16x16x32_bf16 v[100:103], v[168:171], v[192:195], v[100:103]
	v_mfma_f32_16x16x32_bf16 v[96:99], v[176:179], v[192:195], v[96:99]
	v_mfma_f32_16x16x32_bf16 v[84:87], v[168:171], v[200:203], v[84:87]
	v_mfma_f32_16x16x32_bf16 v[80:83], v[176:179], v[200:203], v[80:83]
	v_mfma_f32_16x16x32_bf16 v[68:71], v[168:171], v[214:217], v[68:71]
	v_mfma_f32_16x16x32_bf16 v[64:67], v[176:179], v[214:217], v[64:67]
	v_mfma_f32_16x16x32_bf16 v[116:119], v[172:175], v[188:191], v[116:119]
	v_mfma_f32_16x16x32_bf16 v[112:115], v[180:183], v[188:191], v[112:115]
	v_mfma_f32_16x16x32_bf16 v[100:103], v[172:175], v[196:199], v[100:103]
	v_mfma_f32_16x16x32_bf16 v[96:99], v[180:183], v[196:199], v[96:99]
	v_mfma_f32_16x16x32_bf16 v[84:87], v[172:175], v[210:213], v[84:87]
	v_mfma_f32_16x16x32_bf16 v[80:83], v[180:183], v[210:213], v[80:83]
	v_mfma_f32_16x16x32_bf16 v[68:71], v[172:175], v[218:221], v[68:71]
	v_mfma_f32_16x16x32_bf16 v[64:67], v[180:183], v[218:221], v[64:67]
	s_setprio 0
	s_barrier
	s_add_i32 s52, s82, s61
	v_lshl_add_u64 v[204:205], v[204:205], 0, s[28:29]
	s_mov_b32 m0, s52
	ds_read_b128 v[184:187], v159 offset:49152
	ds_read_b128 v[188:191], v159 offset:50176
	ds_read_b128 v[192:195], v159 offset:51200
	ds_read_b128 v[196:199], v159 offset:52224
	ds_read_b128 v[200:203], v159 offset:53248
	ds_read_b128 v[210:213], v159 offset:54272
	ds_read_b128 v[214:217], v159 offset:55296
	ds_read_b128 v[218:221], v159 offset:56320
	global_load_lds_dwordx4 v[204:205], off
	s_add_i32 m0, s52, 0x2000
	s_add_u32 s52, s54, 0x40080
	v_lshl_add_u64 v[204:205], v[222:223], 0, s[28:29]
	s_addc_u32 s53, s55, 0
	s_add_i32 s54, s83, s61
	global_load_lds_dwordx4 v[204:205], off
	v_lshl_add_u64 v[204:205], s[52:53], 0, v[130:131]
	s_mov_b32 m0, s54
	s_nop 0
	global_load_lds_dwordx4 v[204:205], off
	v_lshl_add_u64 v[204:205], s[52:53], 0, v[134:135]
	s_add_i32 m0, s54, 0x2000
	s_nop 0
	global_load_lds_dwordx4 v[204:205], off
	v_lshl_add_u64 v[204:205], v[224:225], 0, s[28:29]
	s_mov_b32 m0, s66
	s_nop 0
	global_load_lds_dwordx4 v[204:205], off
	v_lshl_add_u64 v[204:205], v[226:227], 0, s[28:29]
	s_mov_b32 m0, s67
	s_nop 0
	global_load_lds_dwordx4 v[204:205], off
	s_waitcnt vmcnt(8)
	s_waitcnt lgkmcnt(0)
	s_barrier
	s_setprio 1
	s_waitcnt lgkmcnt(0)
	v_mfma_f32_16x16x32_bf16 v[60:63], v[146:149], v[184:187], v[60:63]
	v_mfma_f32_16x16x32_bf16 v[56:59], v[160:163], v[184:187], v[56:59]
	v_mfma_f32_16x16x32_bf16 v[44:47], v[146:149], v[192:195], v[44:47]
	v_mfma_f32_16x16x32_bf16 v[40:43], v[160:163], v[192:195], v[40:43]
	v_mfma_f32_16x16x32_bf16 v[28:31], v[146:149], v[200:203], v[28:31]
	v_mfma_f32_16x16x32_bf16 v[24:27], v[160:163], v[200:203], v[24:27]
	v_mfma_f32_16x16x32_bf16 v[12:15], v[146:149], v[214:217], v[12:15]
	v_mfma_f32_16x16x32_bf16 v[8:11], v[160:163], v[214:217], v[8:11]
	v_mfma_f32_16x16x32_bf16 v[60:63], v[150:153], v[188:191], v[60:63]
	v_mfma_f32_16x16x32_bf16 v[56:59], v[164:167], v[188:191], v[56:59]
	v_mfma_f32_16x16x32_bf16 v[44:47], v[150:153], v[196:199], v[44:47]
	v_mfma_f32_16x16x32_bf16 v[40:43], v[164:167], v[196:199], v[40:43]
	v_mfma_f32_16x16x32_bf16 v[28:31], v[150:153], v[210:213], v[28:31]
	v_mfma_f32_16x16x32_bf16 v[24:27], v[164:167], v[210:213], v[24:27]
	v_mfma_f32_16x16x32_bf16 v[12:15], v[150:153], v[218:221], v[12:15]
	v_mfma_f32_16x16x32_bf16 v[8:11], v[164:167], v[218:221], v[8:11]
	s_setprio 0
	s_setprio 1
	v_mfma_f32_16x16x32_bf16 v[52:55], v[168:171], v[184:187], v[52:55]
	v_mfma_f32_16x16x32_bf16 v[48:51], v[176:179], v[184:187], v[48:51]
	v_mfma_f32_16x16x32_bf16 v[36:39], v[168:171], v[192:195], v[36:39]
	v_mfma_f32_16x16x32_bf16 v[32:35], v[176:179], v[192:195], v[32:35]
	v_mfma_f32_16x16x32_bf16 v[20:23], v[168:171], v[200:203], v[20:23]
	v_mfma_f32_16x16x32_bf16 v[16:19], v[176:179], v[200:203], v[16:19]
	v_mfma_f32_16x16x32_bf16 v[4:7], v[168:171], v[214:217], v[4:7]
	v_mfma_f32_16x16x32_bf16 v[0:3], v[176:179], v[214:217], v[0:3]
	v_mfma_f32_16x16x32_bf16 v[52:55], v[172:175], v[188:191], v[52:55]
	v_mfma_f32_16x16x32_bf16 v[48:51], v[180:183], v[188:191], v[48:51]
	v_mfma_f32_16x16x32_bf16 v[36:39], v[172:175], v[196:199], v[36:39]
	v_mfma_f32_16x16x32_bf16 v[32:35], v[180:183], v[196:199], v[32:35]
	v_mfma_f32_16x16x32_bf16 v[20:23], v[172:175], v[210:213], v[20:23]
	v_mfma_f32_16x16x32_bf16 v[16:19], v[180:183], v[210:213], v[16:19]
	v_mfma_f32_16x16x32_bf16 v[4:7], v[172:175], v[218:221], v[4:7]
	v_mfma_f32_16x16x32_bf16 v[0:3], v[180:183], v[218:221], v[0:3]
	s_setprio 0
	s_barrier
	s_add_i32 s81, s81, 2
	s_add_u32 s79, s79, 0x100
	s_addc_u32 s80, s80, 0
	s_cmp_gt_u32 s81, 13
	s_mov_b64 s[52:53], s[14:15]
	s_cbranch_scc1 .Lpeel_done_29861
.LBB0_1007:
	ds_read_b128 v[146:149], v157
	ds_read_b128 v[150:153], v157 offset:1024
	ds_read_b128 v[160:163], v157 offset:2048
	ds_read_b128 v[164:167], v157 offset:3072
	ds_read_b128 v[168:171], v158
	ds_read_b128 v[172:175], v158 offset:1024
	ds_read_b128 v[176:179], v158 offset:2048
	ds_read_b128 v[180:183], v158 offset:3072
	s_add_u32 s14, s52, 0x100
	s_addc_u32 s15, s53, 0
	s_cmp_eq_u32 s81, 12
	s_cselect_b32 s57, s43, s15
	s_cselect_b32 s56, s42, s14
	s_cselect_b32 s55, s41, s80
	s_cselect_b32 s54, s78, s79
	v_lshl_add_u64 v[204:205], s[52:53], 0, v[138:139]
	s_add_i32 m0, s21, 0xc000
	ds_read_b128 v[184:187], v159
	ds_read_b128 v[188:191], v159 offset:1024
	ds_read_b128 v[192:195], v159 offset:2048
	ds_read_b128 v[196:199], v159 offset:3072
	ds_read_b128 v[200:203], v159 offset:4096
	ds_read_b128 v[210:213], v159 offset:5120
	ds_read_b128 v[214:217], v159 offset:6144
	ds_read_b128 v[218:221], v159 offset:7168
	global_load_lds_dwordx4 v[204:205], off
	v_lshl_add_u64 v[204:205], s[52:53], 0, v[140:141]
	s_add_i32 m0, s21, 0xe000
	s_nop 0
	global_load_lds_dwordx4 v[204:205], off
	s_waitcnt vmcnt(8)
	s_waitcnt lgkmcnt(0)
	s_barrier
	s_waitcnt lgkmcnt(0)
	v_mfma_f32_16x16x32_bf16 v[124:127], v[146:149], v[184:187], v[124:127]
	v_mfma_f32_16x16x32_bf16 v[120:123], v[160:163], v[184:187], v[120:123]
	v_mfma_f32_16x16x32_bf16 v[108:111], v[146:149], v[192:195], v[108:111]
	v_mfma_f32_16x16x32_bf16 v[104:107], v[160:163], v[192:195], v[104:107]
	v_mfma_f32_16x16x32_bf16 v[92:95], v[146:149], v[200:203], v[92:95]
	v_mfma_f32_16x16x32_bf16 v[88:91], v[160:163], v[200:203], v[88:91]
	v_mfma_f32_16x16x32_bf16 v[76:79], v[146:149], v[214:217], v[76:79]
	v_mfma_f32_16x16x32_bf16 v[72:75], v[160:163], v[214:217], v[72:75]
	v_mfma_f32_16x16x32_bf16 v[124:127], v[150:153], v[188:191], v[124:127]
	v_mfma_f32_16x16x32_bf16 v[120:123], v[164:167], v[188:191], v[120:123]
	v_mfma_f32_16x16x32_bf16 v[108:111], v[150:153], v[196:199], v[108:111]
	v_mfma_f32_16x16x32_bf16 v[104:107], v[164:167], v[196:199], v[104:107]
	v_mfma_f32_16x16x32_bf16 v[92:95], v[150:153], v[210:213], v[92:95]
	v_mfma_f32_16x16x32_bf16 v[88:91], v[164:167], v[210:213], v[88:91]
	v_mfma_f32_16x16x32_bf16 v[76:79], v[150:153], v[218:221], v[76:79]
	v_mfma_f32_16x16x32_bf16 v[72:75], v[164:167], v[218:221], v[72:75]
	v_mfma_f32_16x16x32_bf16 v[116:119], v[168:171], v[184:187], v[116:119]
	v_mfma_f32_16x16x32_bf16 v[112:115], v[176:179], v[184:187], v[112:115]
	v_mfma_f32_16x16x32_bf16 v[100:103], v[168:171], v[192:195], v[100:103]
	v_mfma_f32_16x16x32_bf16 v[96:99], v[176:179], v[192:195], v[96:99]
	v_mfma_f32_16x16x32_bf16 v[84:87], v[168:171], v[200:203], v[84:87]
	v_mfma_f32_16x16x32_bf16 v[80:83], v[176:179], v[200:203], v[80:83]
	v_mfma_f32_16x16x32_bf16 v[68:71], v[168:171], v[214:217], v[68:71]
	v_mfma_f32_16x16x32_bf16 v[64:67], v[176:179], v[214:217], v[64:67]
	v_mfma_f32_16x16x32_bf16 v[116:119], v[172:175], v[188:191], v[116:119]
	v_mfma_f32_16x16x32_bf16 v[112:115], v[180:183], v[188:191], v[112:115]
	v_mfma_f32_16x16x32_bf16 v[100:103], v[172:175], v[196:199], v[100:103]
	v_mfma_f32_16x16x32_bf16 v[96:99], v[180:183], v[196:199], v[96:99]
	v_mfma_f32_16x16x32_bf16 v[84:87], v[172:175], v[210:213], v[84:87]
	v_mfma_f32_16x16x32_bf16 v[80:83], v[180:183], v[210:213], v[80:83]
	v_mfma_f32_16x16x32_bf16 v[68:71], v[172:175], v[218:221], v[68:71]
	v_mfma_f32_16x16x32_bf16 v[64:67], v[180:183], v[218:221], v[64:67]
	s_barrier
	s_add_i32 s52, s68, s61
	v_lshl_add_u64 v[204:205], s[54:55], 0, v[130:131]
	s_mov_b32 m0, s52
	ds_read_b128 v[184:187], v159 offset:16384
	ds_read_b128 v[188:191], v159 offset:17408
	ds_read_b128 v[192:195], v159 offset:18432
	ds_read_b128 v[196:199], v159 offset:19456
	ds_read_b128 v[200:203], v159 offset:20480
	ds_read_b128 v[210:213], v159 offset:21504
	ds_read_b128 v[214:217], v159 offset:22528
	ds_read_b128 v[218:221], v159 offset:23552
	global_load_lds_dwordx4 v[204:205], off
	s_add_i32 m0, s52, 0x2000
	s_add_u32 s52, s54, 0x40000
	v_lshl_add_u64 v[222:223], s[54:55], 0, v[134:135]
	s_addc_u32 s53, s55, 0
	s_add_i32 s82, s69, s61
	global_load_lds_dwordx4 v[222:223], off
	v_lshl_add_u64 v[224:225], s[52:53], 0, v[130:131]
	s_mov_b32 m0, s82
	v_lshl_add_u64 v[226:227], s[56:57], 0, v[132:133]
	global_load_lds_dwordx4 v[224:225], off
	v_lshl_add_u64 v[224:225], s[52:53], 0, v[134:135]
	s_add_i32 m0, s82, 0x2000
	s_nop 0
	global_load_lds_dwordx4 v[224:225], off
	v_lshl_add_u64 v[224:225], s[56:57], 0, v[128:129]
	s_mov_b32 m0, s21
	s_nop 0
	global_load_lds_dwordx4 v[224:225], off
	s_mov_b32 m0, s62
	s_nop 0
	global_load_lds_dwordx4 v[226:227], off
	s_waitcnt vmcnt(8)
	s_waitcnt lgkmcnt(0)
	s_barrier
	s_waitcnt lgkmcnt(0)
	v_mfma_f32_16x16x32_bf16 v[60:63], v[146:149], v[184:187], v[60:63]
	v_mfma_f32_16x16x32_bf16 v[56:59], v[160:163], v[184:187], v[56:59]
	v_mfma_f32_16x16x32_bf16 v[44:47], v[146:149], v[192:195], v[44:47]
	v_mfma_f32_16x16x32_bf16 v[40:43], v[160:163], v[192:195], v[40:43]
	v_mfma_f32_16x16x32_bf16 v[28:31], v[146:149], v[200:203], v[28:31]
	v_mfma_f32_16x16x32_bf16 v[24:27], v[160:163], v[200:203], v[24:27]
	v_mfma_f32_16x16x32_bf16 v[12:15], v[146:149], v[214:217], v[12:15]
	v_mfma_f32_16x16x32_bf16 v[8:11], v[160:163], v[214:217], v[8:11]
	v_mfma_f32_16x16x32_bf16 v[60:63], v[150:153], v[188:191], v[60:63]
	v_mfma_f32_16x16x32_bf16 v[56:59], v[164:167], v[188:191], v[56:59]
	v_mfma_f32_16x16x32_bf16 v[44:47], v[150:153], v[196:199], v[44:47]
	v_mfma_f32_16x16x32_bf16 v[40:43], v[164:167], v[196:199], v[40:43]
	v_mfma_f32_16x16x32_bf16 v[28:31], v[150:153], v[210:213], v[28:31]
	v_mfma_f32_16x16x32_bf16 v[24:27], v[164:167], v[210:213], v[24:27]
	v_mfma_f32_16x16x32_bf16 v[12:15], v[150:153], v[218:221], v[12:15]
	v_mfma_f32_16x16x32_bf16 v[8:11], v[164:167], v[218:221], v[8:11]
	v_mfma_f32_16x16x32_bf16 v[52:55], v[168:171], v[184:187], v[52:55]
	v_mfma_f32_16x16x32_bf16 v[48:51], v[176:179], v[184:187], v[48:51]
	v_mfma_f32_16x16x32_bf16 v[36:39], v[168:171], v[192:195], v[36:39]
	v_mfma_f32_16x16x32_bf16 v[32:35], v[176:179], v[192:195], v[32:35]
	v_mfma_f32_16x16x32_bf16 v[20:23], v[168:171], v[200:203], v[20:23]
	v_mfma_f32_16x16x32_bf16 v[16:19], v[176:179], v[200:203], v[16:19]
	v_mfma_f32_16x16x32_bf16 v[4:7], v[168:171], v[214:217], v[4:7]
	v_mfma_f32_16x16x32_bf16 v[0:3], v[176:179], v[214:217], v[0:3]
	v_mfma_f32_16x16x32_bf16 v[52:55], v[172:175], v[188:191], v[52:55]
	v_mfma_f32_16x16x32_bf16 v[48:51], v[180:183], v[188:191], v[48:51]
	v_mfma_f32_16x16x32_bf16 v[36:39], v[172:175], v[196:199], v[36:39]
	v_mfma_f32_16x16x32_bf16 v[32:35], v[180:183], v[196:199], v[32:35]
	v_mfma_f32_16x16x32_bf16 v[20:23], v[172:175], v[210:213], v[20:23]
	v_mfma_f32_16x16x32_bf16 v[16:19], v[180:183], v[210:213], v[16:19]
	v_mfma_f32_16x16x32_bf16 v[4:7], v[172:175], v[218:221], v[4:7]
	v_mfma_f32_16x16x32_bf16 v[0:3], v[180:183], v[218:221], v[0:3]
	s_barrier
	s_add_i32 s82, 0, 0x18000
	v_add_u32_e32 v136, s82, v155
	s_add_i32 s83, 0, 0x1c000
	ds_read_b128 v[146:149], v136
	ds_read_b128 v[150:153], v136 offset:1024
	ds_read_b128 v[160:163], v136 offset:2048
	ds_read_b128 v[164:167], v136 offset:3072
	v_add_u32_e32 v136, s83, v155
	ds_read_b128 v[168:171], v136
	ds_read_b128 v[172:175], v136 offset:1024
	ds_read_b128 v[176:179], v136 offset:2048
	ds_read_b128 v[180:183], v136 offset:3072
	s_add_u32 s52, s56, 0x160000
	s_addc_u32 s53, s57, 0
	s_mov_b32 m0, s63
	v_lshl_add_u64 v[228:229], s[52:53], 0, v[128:129]
	ds_read_b128 v[184:187], v159 offset:32768
	ds_read_b128 v[188:191], v159 offset:33792
	ds_read_b128 v[192:195], v159 offset:34816
	ds_read_b128 v[196:199], v159 offset:35840
	ds_read_b128 v[200:203], v159 offset:36864
	ds_read_b128 v[210:213], v159 offset:37888
	ds_read_b128 v[214:217], v159 offset:38912
	ds_read_b128 v[218:221], v159 offset:39936
	global_load_lds_dwordx4 v[228:229], off
	v_lshl_add_u64 v[228:229], s[52:53], 0, v[132:133]
	s_mov_b32 m0, s64
	s_nop 0
	global_load_lds_dwordx4 v[228:229], off
	s_waitcnt vmcnt(8)
	s_waitcnt lgkmcnt(0)
	s_barrier
	s_waitcnt lgkmcnt(0)
	v_mfma_f32_16x16x32_bf16 v[124:127], v[146:149], v[184:187], v[124:127]
	v_mfma_f32_16x16x32_bf16 v[120:123], v[160:163], v[184:187], v[120:123]
	v_mfma_f32_16x16x32_bf16 v[108:111], v[146:149], v[192:195], v[108:111]
	v_mfma_f32_16x16x32_bf16 v[104:107], v[160:163], v[192:195], v[104:107]
	v_mfma_f32_16x16x32_bf16 v[92:95], v[146:149], v[200:203], v[92:95]
	v_mfma_f32_16x16x32_bf16 v[88:91], v[160:163], v[200:203], v[88:91]
	v_mfma_f32_16x16x32_bf16 v[76:79], v[146:149], v[214:217], v[76:79]
	v_mfma_f32_16x16x32_bf16 v[72:75], v[160:163], v[214:217], v[72:75]
	v_mfma_f32_16x16x32_bf16 v[124:127], v[150:153], v[188:191], v[124:127]
	v_mfma_f32_16x16x32_bf16 v[120:123], v[164:167], v[188:191], v[120:123]
	v_mfma_f32_16x16x32_bf16 v[108:111], v[150:153], v[196:199], v[108:111]
	v_mfma_f32_16x16x32_bf16 v[104:107], v[164:167], v[196:199], v[104:107]
	v_mfma_f32_16x16x32_bf16 v[92:95], v[150:153], v[210:213], v[92:95]
	v_mfma_f32_16x16x32_bf16 v[88:91], v[164:167], v[210:213], v[88:91]
	v_mfma_f32_16x16x32_bf16 v[76:79], v[150:153], v[218:221], v[76:79]
	v_mfma_f32_16x16x32_bf16 v[72:75], v[164:167], v[218:221], v[72:75]
	v_mfma_f32_16x16x32_bf16 v[116:119], v[168:171], v[184:187], v[116:119]
	v_mfma_f32_16x16x32_bf16 v[112:115], v[176:179], v[184:187], v[112:115]
	v_mfma_f32_16x16x32_bf16 v[100:103], v[168:171], v[192:195], v[100:103]
	v_mfma_f32_16x16x32_bf16 v[96:99], v[176:179], v[192:195], v[96:99]
	v_mfma_f32_16x16x32_bf16 v[84:87], v[168:171], v[200:203], v[84:87]
	v_mfma_f32_16x16x32_bf16 v[80:83], v[176:179], v[200:203], v[80:83]
	v_mfma_f32_16x16x32_bf16 v[68:71], v[168:171], v[214:217], v[68:71]
	v_mfma_f32_16x16x32_bf16 v[64:67], v[176:179], v[214:217], v[64:67]
	v_mfma_f32_16x16x32_bf16 v[116:119], v[172:175], v[188:191], v[116:119]
	v_mfma_f32_16x16x32_bf16 v[112:115], v[180:183], v[188:191], v[112:115]
	v_mfma_f32_16x16x32_bf16 v[100:103], v[172:175], v[196:199], v[100:103]
	v_mfma_f32_16x16x32_bf16 v[96:99], v[180:183], v[196:199], v[96:99]
	v_mfma_f32_16x16x32_bf16 v[84:87], v[172:175], v[210:213], v[84:87]
	v_mfma_f32_16x16x32_bf16 v[80:83], v[180:183], v[210:213], v[80:83]
	v_mfma_f32_16x16x32_bf16 v[68:71], v[172:175], v[218:221], v[68:71]
	v_mfma_f32_16x16x32_bf16 v[64:67], v[180:183], v[218:221], v[64:67]
	s_barrier
	s_add_i32 s52, s82, s61
	v_lshl_add_u64 v[204:205], v[204:205], 0, s[28:29]
	s_mov_b32 m0, s52
	ds_read_b128 v[184:187], v159 offset:49152
	ds_read_b128 v[188:191], v159 offset:50176
	ds_read_b128 v[192:195], v159 offset:51200
	ds_read_b128 v[196:199], v159 offset:52224
	ds_read_b128 v[200:203], v159 offset:53248
	ds_read_b128 v[210:213], v159 offset:54272
	ds_read_b128 v[214:217], v159 offset:55296
	ds_read_b128 v[218:221], v159 offset:56320
	global_load_lds_dwordx4 v[204:205], off
	s_add_i32 m0, s52, 0x2000
	s_add_u32 s52, s54, 0x40080
	v_lshl_add_u64 v[204:205], v[222:223], 0, s[28:29]
	s_addc_u32 s53, s55, 0
	s_add_i32 s54, s83, s61
	global_load_lds_dwordx4 v[204:205], off
	v_lshl_add_u64 v[204:205], s[52:53], 0, v[130:131]
	s_mov_b32 m0, s54
	s_nop 0
	global_load_lds_dwordx4 v[204:205], off
	v_lshl_add_u64 v[204:205], s[52:53], 0, v[134:135]
	s_add_i32 m0, s54, 0x2000
	s_nop 0
	global_load_lds_dwordx4 v[204:205], off
	v_lshl_add_u64 v[204:205], v[224:225], 0, s[28:29]
	s_mov_b32 m0, s66
	s_nop 0
	global_load_lds_dwordx4 v[204:205], off
	v_lshl_add_u64 v[204:205], v[226:227], 0, s[28:29]
	s_mov_b32 m0, s67
	s_nop 0
	global_load_lds_dwordx4 v[204:205], off
	s_waitcnt vmcnt(8)
	s_waitcnt lgkmcnt(0)
	s_barrier
	s_waitcnt lgkmcnt(0)
	v_mfma_f32_16x16x32_bf16 v[60:63], v[146:149], v[184:187], v[60:63]
	v_mfma_f32_16x16x32_bf16 v[56:59], v[160:163], v[184:187], v[56:59]
	v_mfma_f32_16x16x32_bf16 v[44:47], v[146:149], v[192:195], v[44:47]
	v_mfma_f32_16x16x32_bf16 v[40:43], v[160:163], v[192:195], v[40:43]
	v_mfma_f32_16x16x32_bf16 v[28:31], v[146:149], v[200:203], v[28:31]
	v_mfma_f32_16x16x32_bf16 v[24:27], v[160:163], v[200:203], v[24:27]
	v_mfma_f32_16x16x32_bf16 v[12:15], v[146:149], v[214:217], v[12:15]
	v_mfma_f32_16x16x32_bf16 v[8:11], v[160:163], v[214:217], v[8:11]
	v_mfma_f32_16x16x32_bf16 v[60:63], v[150:153], v[188:191], v[60:63]
	v_mfma_f32_16x16x32_bf16 v[56:59], v[164:167], v[188:191], v[56:59]
	v_mfma_f32_16x16x32_bf16 v[44:47], v[150:153], v[196:199], v[44:47]
	v_mfma_f32_16x16x32_bf16 v[40:43], v[164:167], v[196:199], v[40:43]
	v_mfma_f32_16x16x32_bf16 v[28:31], v[150:153], v[210:213], v[28:31]
	v_mfma_f32_16x16x32_bf16 v[24:27], v[164:167], v[210:213], v[24:27]
	v_mfma_f32_16x16x32_bf16 v[12:15], v[150:153], v[218:221], v[12:15]
	v_mfma_f32_16x16x32_bf16 v[8:11], v[164:167], v[218:221], v[8:11]
	v_mfma_f32_16x16x32_bf16 v[52:55], v[168:171], v[184:187], v[52:55]
	v_mfma_f32_16x16x32_bf16 v[48:51], v[176:179], v[184:187], v[48:51]
	v_mfma_f32_16x16x32_bf16 v[36:39], v[168:171], v[192:195], v[36:39]
	v_mfma_f32_16x16x32_bf16 v[32:35], v[176:179], v[192:195], v[32:35]
	v_mfma_f32_16x16x32_bf16 v[20:23], v[168:171], v[200:203], v[20:23]
	v_mfma_f32_16x16x32_bf16 v[16:19], v[176:179], v[200:203], v[16:19]
	v_mfma_f32_16x16x32_bf16 v[4:7], v[168:171], v[214:217], v[4:7]
	v_mfma_f32_16x16x32_bf16 v[0:3], v[176:179], v[214:217], v[0:3]
	v_mfma_f32_16x16x32_bf16 v[52:55], v[172:175], v[188:191], v[52:55]
	v_mfma_f32_16x16x32_bf16 v[48:51], v[180:183], v[188:191], v[48:51]
	v_mfma_f32_16x16x32_bf16 v[36:39], v[172:175], v[196:199], v[36:39]
	v_mfma_f32_16x16x32_bf16 v[32:35], v[180:183], v[196:199], v[32:35]
	v_mfma_f32_16x16x32_bf16 v[20:23], v[172:175], v[210:213], v[20:23]
	v_mfma_f32_16x16x32_bf16 v[16:19], v[180:183], v[210:213], v[16:19]
	v_mfma_f32_16x16x32_bf16 v[4:7], v[172:175], v[218:221], v[4:7]
	v_mfma_f32_16x16x32_bf16 v[0:3], v[180:183], v[218:221], v[0:3]
	s_barrier
	s_add_i32 s81, s81, 2
	s_add_u32 s79, s79, 0x100
	s_addc_u32 s80, s80, 0
	s_cmp_gt_u32 s81, 13
	s_mov_b64 s[52:53], s[14:15]
	s_cbranch_scc0 .LBB0_1007

.LBB0_1130:
	s_ashr_i32 s27, s26, 31
	s_lshl_b64 s[28:29], s[26:27], 19
	s_add_u32 s28, s48, s28
	s_addc_u32 s29, s49, s29
	s_and_b64 s[30:31], s[10:11], exec
	s_cselect_b32 s27, s29, s43
	s_cselect_b32 s66, s28, s42
	s_ashr_i32 s25, s24, 31
	s_lshl_b64 s[30:31], s[24:25], 19
	s_add_u32 s30, s35, s30
	s_addc_u32 s31, s54, s31
	s_and_b64 s[52:53], s[10:11], exec
	s_cselect_b32 s25, s31, s51
	s_cselect_b32 s67, s30, s50
	s_add_u32 s42, s42, 0x40080
	s_addc_u32 s43, s43, 0
	s_add_u32 s68, s50, 0x100
	s_addc_u32 s69, s51, 0
	s_mov_b32 s70, -2
	ds_read_b128 v[144:147], v151
	ds_read_b128 v[156:159], v151 offset:1024
	ds_read_b128 v[160:163], v151 offset:2048
	ds_read_b128 v[164:167], v151 offset:3072
	ds_read_b128 v[168:171], v152
	ds_read_b128 v[172:175], v152 offset:1024
	ds_read_b128 v[176:179], v152 offset:2048
	ds_read_b128 v[180:183], v152 offset:3072
	s_add_u32 s50, s42, 0xfffc0080
	s_addc_u32 s51, s43, -1
	s_cmp_eq_u32 s70, 12
	s_cselect_b32 s53, s27, s51
	s_cselect_b32 s52, s66, s50
	s_cselect_b32 s51, s25, s69
	s_cselect_b32 s50, s67, s68
	v_lshl_add_u64 v[204:205], s[42:43], 0, v[136:137]
	s_add_i32 m0, s41, 0xc000
	ds_read_b128 v[184:187], v153
	ds_read_b128 v[188:191], v153 offset:1024
	ds_read_b128 v[192:195], v153 offset:2048
	ds_read_b128 v[196:199], v153 offset:3072
	ds_read_b128 v[200:203], v153 offset:4096
	ds_read_b128 v[210:213], v153 offset:5120
	ds_read_b128 v[214:217], v153 offset:6144
	ds_read_b128 v[218:221], v153 offset:7168
	global_load_lds_dwordx4 v[204:205], off
	v_lshl_add_u64 v[204:205], s[42:43], 0, v[138:139]
	s_add_i32 m0, s41, 0xe000
	s_nop 0
	global_load_lds_dwordx4 v[204:205], off
	s_waitcnt vmcnt(8)
	s_waitcnt lgkmcnt(0)
	s_barrier
	s_setprio 1
	s_waitcnt lgkmcnt(0)
	v_mfma_f32_16x16x32_bf16 v[124:127], v[144:147], v[184:187], 0
	v_mfma_f32_16x16x32_bf16 v[120:123], v[160:163], v[184:187], 0
	v_mfma_f32_16x16x32_bf16 v[108:111], v[144:147], v[192:195], 0
	v_mfma_f32_16x16x32_bf16 v[104:107], v[160:163], v[192:195], 0
	v_mfma_f32_16x16x32_bf16 v[92:95], v[144:147], v[200:203], 0
	v_mfma_f32_16x16x32_bf16 v[88:91], v[160:163], v[200:203], 0
	v_mfma_f32_16x16x32_bf16 v[76:79], v[144:147], v[214:217], 0
	v_mfma_f32_16x16x32_bf16 v[72:75], v[160:163], v[214:217], 0
	v_mfma_f32_16x16x32_bf16 v[124:127], v[156:159], v[188:191], v[124:127]
	v_mfma_f32_16x16x32_bf16 v[120:123], v[164:167], v[188:191], v[120:123]
	v_mfma_f32_16x16x32_bf16 v[108:111], v[156:159], v[196:199], v[108:111]
	v_mfma_f32_16x16x32_bf16 v[104:107], v[164:167], v[196:199], v[104:107]
	v_mfma_f32_16x16x32_bf16 v[92:95], v[156:159], v[210:213], v[92:95]
	v_mfma_f32_16x16x32_bf16 v[88:91], v[164:167], v[210:213], v[88:91]
	v_mfma_f32_16x16x32_bf16 v[76:79], v[156:159], v[218:221], v[76:79]
	v_mfma_f32_16x16x32_bf16 v[72:75], v[164:167], v[218:221], v[72:75]
	s_setprio 0
	s_setprio 1
	v_mfma_f32_16x16x32_bf16 v[116:119], v[168:171], v[184:187], 0
	v_mfma_f32_16x16x32_bf16 v[112:115], v[176:179], v[184:187], 0
	v_mfma_f32_16x16x32_bf16 v[100:103], v[168:171], v[192:195], 0
	v_mfma_f32_16x16x32_bf16 v[96:99], v[176:179], v[192:195], 0
	v_mfma_f32_16x16x32_bf16 v[84:87], v[168:171], v[200:203], 0
	v_mfma_f32_16x16x32_bf16 v[80:83], v[176:179], v[200:203], 0
	v_mfma_f32_16x16x32_bf16 v[68:71], v[168:171], v[214:217], 0
	v_mfma_f32_16x16x32_bf16 v[64:67], v[176:179], v[214:217], 0
	v_mfma_f32_16x16x32_bf16 v[116:119], v[172:175], v[188:191], v[116:119]
	v_mfma_f32_16x16x32_bf16 v[112:115], v[180:183], v[188:191], v[112:115]
	v_mfma_f32_16x16x32_bf16 v[100:103], v[172:175], v[196:199], v[100:103]
	v_mfma_f32_16x16x32_bf16 v[96:99], v[180:183], v[196:199], v[96:99]
	v_mfma_f32_16x16x32_bf16 v[84:87], v[172:175], v[210:213], v[84:87]
	v_mfma_f32_16x16x32_bf16 v[80:83], v[180:183], v[210:213], v[80:83]
	v_mfma_f32_16x16x32_bf16 v[68:71], v[172:175], v[218:221], v[68:71]
	v_mfma_f32_16x16x32_bf16 v[64:67], v[180:183], v[218:221], v[64:67]
	s_setprio 0
	s_barrier
	s_add_i32 s71, s62, s55
	v_lshl_add_u64 v[204:205], s[50:51], 0, v[130:131]
	s_mov_b32 m0, s71
	ds_read_b128 v[184:187], v153 offset:16384
	ds_read_b128 v[188:191], v153 offset:17408
	ds_read_b128 v[192:195], v153 offset:18432
	ds_read_b128 v[196:199], v153 offset:19456
	ds_read_b128 v[200:203], v153 offset:20480
	ds_read_b128 v[210:213], v153 offset:21504
	ds_read_b128 v[214:217], v153 offset:22528
	ds_read_b128 v[218:221], v153 offset:23552
	global_load_lds_dwordx4 v[204:205], off
	s_add_i32 m0, s71, 0x2000
	s_add_u32 s72, s50, 0x40000
	v_lshl_add_u64 v[222:223], s[50:51], 0, v[134:135]
	s_addc_u32 s73, s51, 0
	s_add_i32 s71, s63, s55
	global_load_lds_dwordx4 v[222:223], off
	v_lshl_add_u64 v[224:225], s[72:73], 0, v[130:131]
	s_mov_b32 m0, s71
	v_lshl_add_u64 v[226:227], s[52:53], 0, v[132:133]
	global_load_lds_dwordx4 v[224:225], off
	v_lshl_add_u64 v[224:225], s[72:73], 0, v[134:135]
	s_add_i32 m0, s71, 0x2000
	s_nop 0
	global_load_lds_dwordx4 v[224:225], off
	v_lshl_add_u64 v[224:225], s[52:53], 0, v[128:129]
	s_mov_b32 m0, s41
	s_nop 0
	global_load_lds_dwordx4 v[224:225], off
	s_mov_b32 m0, s56
	s_nop 0
	global_load_lds_dwordx4 v[226:227], off
	s_waitcnt vmcnt(8)
	s_waitcnt lgkmcnt(0)
	s_barrier
	s_setprio 1
	s_waitcnt lgkmcnt(0)
	v_mfma_f32_16x16x32_bf16 v[60:63], v[144:147], v[184:187], 0
	v_mfma_f32_16x16x32_bf16 v[56:59], v[160:163], v[184:187], 0
	v_mfma_f32_16x16x32_bf16 v[44:47], v[144:147], v[192:195], 0
	v_mfma_f32_16x16x32_bf16 v[40:43], v[160:163], v[192:195], 0
	v_mfma_f32_16x16x32_bf16 v[28:31], v[144:147], v[200:203], 0
	v_mfma_f32_16x16x32_bf16 v[24:27], v[160:163], v[200:203], 0
	v_mfma_f32_16x16x32_bf16 v[12:15], v[144:147], v[214:217], 0
	v_mfma_f32_16x16x32_bf16 v[8:11], v[160:163], v[214:217], 0
	v_mfma_f32_16x16x32_bf16 v[60:63], v[156:159], v[188:191], v[60:63]
	v_mfma_f32_16x16x32_bf16 v[56:59], v[164:167], v[188:191], v[56:59]
	v_mfma_f32_16x16x32_bf16 v[44:47], v[156:159], v[196:199], v[44:47]
	v_mfma_f32_16x16x32_bf16 v[40:43], v[164:167], v[196:199], v[40:43]
	v_mfma_f32_16x16x32_bf16 v[28:31], v[156:159], v[210:213], v[28:31]
	v_mfma_f32_16x16x32_bf16 v[24:27], v[164:167], v[210:213], v[24:27]
	v_mfma_f32_16x16x32_bf16 v[12:15], v[156:159], v[218:221], v[12:15]
	v_mfma_f32_16x16x32_bf16 v[8:11], v[164:167], v[218:221], v[8:11]
	s_setprio 0
	s_setprio 1
	v_mfma_f32_16x16x32_bf16 v[52:55], v[168:171], v[184:187], 0
	v_mfma_f32_16x16x32_bf16 v[48:51], v[176:179], v[184:187], 0
	v_mfma_f32_16x16x32_bf16 v[36:39], v[168:171], v[192:195], 0
	v_mfma_f32_16x16x32_bf16 v[32:35], v[176:179], v[192:195], 0
	v_mfma_f32_16x16x32_bf16 v[20:23], v[168:171], v[200:203], 0
	v_mfma_f32_16x16x32_bf16 v[16:19], v[176:179], v[200:203], 0
	v_mfma_f32_16x16x32_bf16 v[4:7], v[168:171], v[214:217], 0
	v_mfma_f32_16x16x32_bf16 v[0:3], v[176:179], v[214:217], 0
	v_mfma_f32_16x16x32_bf16 v[52:55], v[172:175], v[188:191], v[52:55]
	v_mfma_f32_16x16x32_bf16 v[48:51], v[180:183], v[188:191], v[48:51]
	v_mfma_f32_16x16x32_bf16 v[36:39], v[172:175], v[196:199], v[36:39]
	v_mfma_f32_16x16x32_bf16 v[32:35], v[180:183], v[196:199], v[32:35]
	v_mfma_f32_16x16x32_bf16 v[20:23], v[172:175], v[210:213], v[20:23]
	v_mfma_f32_16x16x32_bf16 v[16:19], v[180:183], v[210:213], v[16:19]
	v_mfma_f32_16x16x32_bf16 v[4:7], v[172:175], v[218:221], v[4:7]
	v_mfma_f32_16x16x32_bf16 v[0:3], v[180:183], v[218:221], v[0:3]
	s_setprio 0
	s_barrier
	s_add_i32 s71, 0, 0x18000
	v_add_u32_e32 v155, s71, v149
	s_add_i32 s72, 0, 0x1c000
	ds_read_b128 v[144:147], v155
	ds_read_b128 v[156:159], v155 offset:1024
	ds_read_b128 v[160:163], v155 offset:2048
	ds_read_b128 v[164:167], v155 offset:3072
	v_add_u32_e32 v155, s72, v149
	ds_read_b128 v[168:171], v155
	ds_read_b128 v[172:175], v155 offset:1024
	ds_read_b128 v[176:179], v155 offset:2048
	ds_read_b128 v[180:183], v155 offset:3072
	s_add_u32 s52, s52, 0x40000
	s_addc_u32 s53, s53, 0
	s_mov_b32 m0, s57
	v_lshl_add_u64 v[228:229], s[52:53], 0, v[128:129]
	ds_read_b128 v[184:187], v153 offset:32768
	ds_read_b128 v[188:191], v153 offset:33792
	ds_read_b128 v[192:195], v153 offset:34816
	ds_read_b128 v[196:199], v153 offset:35840
	ds_read_b128 v[200:203], v153 offset:36864
	ds_read_b128 v[210:213], v153 offset:37888
	ds_read_b128 v[214:217], v153 offset:38912
	ds_read_b128 v[218:221], v153 offset:39936
	global_load_lds_dwordx4 v[228:229], off
	v_lshl_add_u64 v[228:229], s[52:53], 0, v[132:133]
	s_mov_b32 m0, s58
	s_nop 0
	global_load_lds_dwordx4 v[228:229], off
	s_waitcnt vmcnt(8)
	s_waitcnt lgkmcnt(0)
	s_barrier
	s_setprio 1
	s_waitcnt lgkmcnt(0)
	v_mfma_f32_16x16x32_bf16 v[124:127], v[144:147], v[184:187], v[124:127]
	v_mfma_f32_16x16x32_bf16 v[120:123], v[160:163], v[184:187], v[120:123]
	v_mfma_f32_16x16x32_bf16 v[108:111], v[144:147], v[192:195], v[108:111]
	v_mfma_f32_16x16x32_bf16 v[104:107], v[160:163], v[192:195], v[104:107]
	v_mfma_f32_16x16x32_bf16 v[92:95], v[144:147], v[200:203], v[92:95]
	v_mfma_f32_16x16x32_bf16 v[88:91], v[160:163], v[200:203], v[88:91]
	v_mfma_f32_16x16x32_bf16 v[76:79], v[144:147], v[214:217], v[76:79]
	v_mfma_f32_16x16x32_bf16 v[72:75], v[160:163], v[214:217], v[72:75]
	v_mfma_f32_16x16x32_bf16 v[124:127], v[156:159], v[188:191], v[124:127]
	v_mfma_f32_16x16x32_bf16 v[120:123], v[164:167], v[188:191], v[120:123]
	v_mfma_f32_16x16x32_bf16 v[108:111], v[156:159], v[196:199], v[108:111]
	v_mfma_f32_16x16x32_bf16 v[104:107], v[164:167], v[196:199], v[104:107]
	v_mfma_f32_16x16x32_bf16 v[92:95], v[156:159], v[210:213], v[92:95]
	v_mfma_f32_16x16x32_bf16 v[88:91], v[164:167], v[210:213], v[88:91]
	v_mfma_f32_16x16x32_bf16 v[76:79], v[156:159], v[218:221], v[76:79]
	v_mfma_f32_16x16x32_bf16 v[72:75], v[164:167], v[218:221], v[72:75]
	s_setprio 0
	s_setprio 1
	v_mfma_f32_16x16x32_bf16 v[116:119], v[168:171], v[184:187], v[116:119]
	v_mfma_f32_16x16x32_bf16 v[112:115], v[176:179], v[184:187], v[112:115]
	v_mfma_f32_16x16x32_bf16 v[100:103], v[168:171], v[192:195], v[100:103]
	v_mfma_f32_16x16x32_bf16 v[96:99], v[176:179], v[192:195], v[96:99]
	v_mfma_f32_16x16x32_bf16 v[84:87], v[168:171], v[200:203], v[84:87]
	v_mfma_f32_16x16x32_bf16 v[80:83], v[176:179], v[200:203], v[80:83]
	v_mfma_f32_16x16x32_bf16 v[68:71], v[168:171], v[214:217], v[68:71]
	v_mfma_f32_16x16x32_bf16 v[64:67], v[176:179], v[214:217], v[64:67]
	v_mfma_f32_16x16x32_bf16 v[116:119], v[172:175], v[188:191], v[116:119]
	v_mfma_f32_16x16x32_bf16 v[112:115], v[180:183], v[188:191], v[112:115]
	v_mfma_f32_16x16x32_bf16 v[100:103], v[172:175], v[196:199], v[100:103]
	v_mfma_f32_16x16x32_bf16 v[96:99], v[180:183], v[196:199], v[96:99]
	v_mfma_f32_16x16x32_bf16 v[84:87], v[172:175], v[210:213], v[84:87]
	v_mfma_f32_16x16x32_bf16 v[80:83], v[180:183], v[210:213], v[80:83]
	v_mfma_f32_16x16x32_bf16 v[68:71], v[172:175], v[218:221], v[68:71]
	v_mfma_f32_16x16x32_bf16 v[64:67], v[180:183], v[218:221], v[64:67]
	s_setprio 0
	s_barrier
	s_add_i32 s52, s71, s55
	v_lshl_add_u64 v[204:205], v[204:205], 0, s[14:15]
	s_mov_b32 m0, s52
	ds_read_b128 v[184:187], v153 offset:49152
	ds_read_b128 v[188:191], v153 offset:50176
	ds_read_b128 v[192:195], v153 offset:51200
	ds_read_b128 v[196:199], v153 offset:52224
	ds_read_b128 v[200:203], v153 offset:53248
	ds_read_b128 v[210:213], v153 offset:54272
	ds_read_b128 v[214:217], v153 offset:55296
	ds_read_b128 v[218:221], v153 offset:56320
	global_load_lds_dwordx4 v[204:205], off
	s_add_i32 m0, s52, 0x2000
	s_add_u32 s50, s50, 0x40080
	v_lshl_add_u64 v[204:205], v[222:223], 0, s[14:15]
	s_addc_u32 s51, s51, 0
	s_add_i32 s52, s72, s55
	global_load_lds_dwordx4 v[204:205], off
	v_lshl_add_u64 v[204:205], s[50:51], 0, v[130:131]
	s_mov_b32 m0, s52
	s_nop 0
	global_load_lds_dwordx4 v[204:205], off
	v_lshl_add_u64 v[204:205], s[50:51], 0, v[134:135]
	s_add_i32 m0, s52, 0x2000
	s_nop 0
	global_load_lds_dwordx4 v[204:205], off
	v_lshl_add_u64 v[204:205], v[224:225], 0, s[14:15]
	s_mov_b32 m0, s60
	s_nop 0
	global_load_lds_dwordx4 v[204:205], off
	v_lshl_add_u64 v[204:205], v[226:227], 0, s[14:15]
	s_mov_b32 m0, s61
	s_nop 0
	global_load_lds_dwordx4 v[204:205], off
	s_waitcnt vmcnt(8)
	s_waitcnt lgkmcnt(0)
	s_barrier
	s_setprio 1
	s_waitcnt lgkmcnt(0)
	v_mfma_f32_16x16x32_bf16 v[60:63], v[144:147], v[184:187], v[60:63]
	v_mfma_f32_16x16x32_bf16 v[56:59], v[160:163], v[184:187], v[56:59]
	v_mfma_f32_16x16x32_bf16 v[44:47], v[144:147], v[192:195], v[44:47]
	v_mfma_f32_16x16x32_bf16 v[40:43], v[160:163], v[192:195], v[40:43]
	v_mfma_f32_16x16x32_bf16 v[28:31], v[144:147], v[200:203], v[28:31]
	v_mfma_f32_16x16x32_bf16 v[24:27], v[160:163], v[200:203], v[24:27]
	v_mfma_f32_16x16x32_bf16 v[12:15], v[144:147], v[214:217], v[12:15]
	v_mfma_f32_16x16x32_bf16 v[8:11], v[160:163], v[214:217], v[8:11]
	v_mfma_f32_16x16x32_bf16 v[60:63], v[156:159], v[188:191], v[60:63]
	v_mfma_f32_16x16x32_bf16 v[56:59], v[164:167], v[188:191], v[56:59]
	v_mfma_f32_16x16x32_bf16 v[44:47], v[156:159], v[196:199], v[44:47]
	v_mfma_f32_16x16x32_bf16 v[40:43], v[164:167], v[196:199], v[40:43]
	v_mfma_f32_16x16x32_bf16 v[28:31], v[156:159], v[210:213], v[28:31]
	v_mfma_f32_16x16x32_bf16 v[24:27], v[164:167], v[210:213], v[24:27]
	v_mfma_f32_16x16x32_bf16 v[12:15], v[156:159], v[218:221], v[12:15]
	v_mfma_f32_16x16x32_bf16 v[8:11], v[164:167], v[218:221], v[8:11]
	s_setprio 0
	s_setprio 1
	v_mfma_f32_16x16x32_bf16 v[52:55], v[168:171], v[184:187], v[52:55]
	v_mfma_f32_16x16x32_bf16 v[48:51], v[176:179], v[184:187], v[48:51]
	v_mfma_f32_16x16x32_bf16 v[36:39], v[168:171], v[192:195], v[36:39]
	v_mfma_f32_16x16x32_bf16 v[32:35], v[176:179], v[192:195], v[32:35]
	v_mfma_f32_16x16x32_bf16 v[20:23], v[168:171], v[200:203], v[20:23]
	v_mfma_f32_16x16x32_bf16 v[16:19], v[176:179], v[200:203], v[16:19]
	v_mfma_f32_16x16x32_bf16 v[4:7], v[168:171], v[214:217], v[4:7]
	v_mfma_f32_16x16x32_bf16 v[0:3], v[176:179], v[214:217], v[0:3]
	v_mfma_f32_16x16x32_bf16 v[52:55], v[172:175], v[188:191], v[52:55]
	v_mfma_f32_16x16x32_bf16 v[48:51], v[180:183], v[188:191], v[48:51]
	v_mfma_f32_16x16x32_bf16 v[36:39], v[172:175], v[196:199], v[36:39]
	v_mfma_f32_16x16x32_bf16 v[32:35], v[180:183], v[196:199], v[32:35]
	v_mfma_f32_16x16x32_bf16 v[20:23], v[172:175], v[210:213], v[20:23]
	v_mfma_f32_16x16x32_bf16 v[16:19], v[180:183], v[210:213], v[16:19]
	v_mfma_f32_16x16x32_bf16 v[4:7], v[172:175], v[218:221], v[4:7]
	v_mfma_f32_16x16x32_bf16 v[0:3], v[180:183], v[218:221], v[0:3]
	s_setprio 0
	s_barrier
	s_add_i32 s70, s70, 2
	s_add_u32 s42, s42, 0x100
	s_addc_u32 s43, s43, 0
	s_add_u32 s68, s68, 0x100
	s_addc_u32 s69, s69, 0
	s_cmp_gt_u32 s70, 13
	s_cbranch_scc1 .Lpeel_done_32180
.LBB0_1131:
	ds_read_b128 v[144:147], v151
	ds_read_b128 v[156:159], v151 offset:1024
	ds_read_b128 v[160:163], v151 offset:2048
	ds_read_b128 v[164:167], v151 offset:3072
	ds_read_b128 v[168:171], v152
	ds_read_b128 v[172:175], v152 offset:1024
	ds_read_b128 v[176:179], v152 offset:2048
	ds_read_b128 v[180:183], v152 offset:3072
	s_add_u32 s50, s42, 0xfffc0080
	s_addc_u32 s51, s43, -1
	s_cmp_eq_u32 s70, 12
	s_cselect_b32 s53, s27, s51
	s_cselect_b32 s52, s66, s50
	s_cselect_b32 s51, s25, s69
	s_cselect_b32 s50, s67, s68
	v_lshl_add_u64 v[204:205], s[42:43], 0, v[136:137]
	s_add_i32 m0, s41, 0xc000
	ds_read_b128 v[184:187], v153
	ds_read_b128 v[188:191], v153 offset:1024
	ds_read_b128 v[192:195], v153 offset:2048
	ds_read_b128 v[196:199], v153 offset:3072
	ds_read_b128 v[200:203], v153 offset:4096
	ds_read_b128 v[210:213], v153 offset:5120
	ds_read_b128 v[214:217], v153 offset:6144
	ds_read_b128 v[218:221], v153 offset:7168
	global_load_lds_dwordx4 v[204:205], off
	v_lshl_add_u64 v[204:205], s[42:43], 0, v[138:139]
	s_add_i32 m0, s41, 0xe000
	s_nop 0
	global_load_lds_dwordx4 v[204:205], off
	s_waitcnt vmcnt(8)
	s_waitcnt lgkmcnt(0)
	s_barrier
	s_waitcnt lgkmcnt(0)
	v_mfma_f32_16x16x32_bf16 v[124:127], v[144:147], v[184:187], v[124:127]
	v_mfma_f32_16x16x32_bf16 v[120:123], v[160:163], v[184:187], v[120:123]
	v_mfma_f32_16x16x32_bf16 v[108:111], v[144:147], v[192:195], v[108:111]
	v_mfma_f32_16x16x32_bf16 v[104:107], v[160:163], v[192:195], v[104:107]
	v_mfma_f32_16x16x32_bf16 v[92:95], v[144:147], v[200:203], v[92:95]
	v_mfma_f32_16x16x32_bf16 v[88:91], v[160:163], v[200:203], v[88:91]
	v_mfma_f32_16x16x32_bf16 v[76:79], v[144:147], v[214:217], v[76:79]
	v_mfma_f32_16x16x32_bf16 v[72:75], v[160:163], v[214:217], v[72:75]
	v_mfma_f32_16x16x32_bf16 v[124:127], v[156:159], v[188:191], v[124:127]
	v_mfma_f32_16x16x32_bf16 v[120:123], v[164:167], v[188:191], v[120:123]
	v_mfma_f32_16x16x32_bf16 v[108:111], v[156:159], v[196:199], v[108:111]
	v_mfma_f32_16x16x32_bf16 v[104:107], v[164:167], v[196:199], v[104:107]
	v_mfma_f32_16x16x32_bf16 v[92:95], v[156:159], v[210:213], v[92:95]
	v_mfma_f32_16x16x32_bf16 v[88:91], v[164:167], v[210:213], v[88:91]
	v_mfma_f32_16x16x32_bf16 v[76:79], v[156:159], v[218:221], v[76:79]
	v_mfma_f32_16x16x32_bf16 v[72:75], v[164:167], v[218:221], v[72:75]
	v_mfma_f32_16x16x32_bf16 v[116:119], v[168:171], v[184:187], v[116:119]
	v_mfma_f32_16x16x32_bf16 v[112:115], v[176:179], v[184:187], v[112:115]
	v_mfma_f32_16x16x32_bf16 v[100:103], v[168:171], v[192:195], v[100:103]
	v_mfma_f32_16x16x32_bf16 v[96:99], v[176:179], v[192:195], v[96:99]
	v_mfma_f32_16x16x32_bf16 v[84:87], v[168:171], v[200:203], v[84:87]
	v_mfma_f32_16x16x32_bf16 v[80:83], v[176:179], v[200:203], v[80:83]
	v_mfma_f32_16x16x32_bf16 v[68:71], v[168:171], v[214:217], v[68:71]
	v_mfma_f32_16x16x32_bf16 v[64:67], v[176:179], v[214:217], v[64:67]
	v_mfma_f32_16x16x32_bf16 v[116:119], v[172:175], v[188:191], v[116:119]
	v_mfma_f32_16x16x32_bf16 v[112:115], v[180:183], v[188:191], v[112:115]
	v_mfma_f32_16x16x32_bf16 v[100:103], v[172:175], v[196:199], v[100:103]
	v_mfma_f32_16x16x32_bf16 v[96:99], v[180:183], v[196:199], v[96:99]
	v_mfma_f32_16x16x32_bf16 v[84:87], v[172:175], v[210:213], v[84:87]
	v_mfma_f32_16x16x32_bf16 v[80:83], v[180:183], v[210:213], v[80:83]
	v_mfma_f32_16x16x32_bf16 v[68:71], v[172:175], v[218:221], v[68:71]
	v_mfma_f32_16x16x32_bf16 v[64:67], v[180:183], v[218:221], v[64:67]
	s_barrier
	s_add_i32 s71, s62, s55
	v_lshl_add_u64 v[204:205], s[50:51], 0, v[130:131]
	s_mov_b32 m0, s71
	ds_read_b128 v[184:187], v153 offset:16384
	ds_read_b128 v[188:191], v153 offset:17408
	ds_read_b128 v[192:195], v153 offset:18432
	ds_read_b128 v[196:199], v153 offset:19456
	ds_read_b128 v[200:203], v153 offset:20480
	ds_read_b128 v[210:213], v153 offset:21504
	ds_read_b128 v[214:217], v153 offset:22528
	ds_read_b128 v[218:221], v153 offset:23552
	global_load_lds_dwordx4 v[204:205], off
	s_add_i32 m0, s71, 0x2000
	s_add_u32 s72, s50, 0x40000
	v_lshl_add_u64 v[222:223], s[50:51], 0, v[134:135]
	s_addc_u32 s73, s51, 0
	s_add_i32 s71, s63, s55
	global_load_lds_dwordx4 v[222:223], off
	v_lshl_add_u64 v[224:225], s[72:73], 0, v[130:131]
	s_mov_b32 m0, s71
	v_lshl_add_u64 v[226:227], s[52:53], 0, v[132:133]
	global_load_lds_dwordx4 v[224:225], off
	v_lshl_add_u64 v[224:225], s[72:73], 0, v[134:135]
	s_add_i32 m0, s71, 0x2000
	s_nop 0
	global_load_lds_dwordx4 v[224:225], off
	v_lshl_add_u64 v[224:225], s[52:53], 0, v[128:129]
	s_mov_b32 m0, s41
	s_nop 0
	global_load_lds_dwordx4 v[224:225], off
	s_mov_b32 m0, s56
	s_nop 0
	global_load_lds_dwordx4 v[226:227], off
	s_waitcnt vmcnt(8)
	s_waitcnt lgkmcnt(0)
	s_barrier
	s_waitcnt lgkmcnt(0)
	v_mfma_f32_16x16x32_bf16 v[60:63], v[144:147], v[184:187], v[60:63]
	v_mfma_f32_16x16x32_bf16 v[56:59], v[160:163], v[184:187], v[56:59]
	v_mfma_f32_16x16x32_bf16 v[44:47], v[144:147], v[192:195], v[44:47]
	v_mfma_f32_16x16x32_bf16 v[40:43], v[160:163], v[192:195], v[40:43]
	v_mfma_f32_16x16x32_bf16 v[28:31], v[144:147], v[200:203], v[28:31]
	v_mfma_f32_16x16x32_bf16 v[24:27], v[160:163], v[200:203], v[24:27]
	v_mfma_f32_16x16x32_bf16 v[12:15], v[144:147], v[214:217], v[12:15]
	v_mfma_f32_16x16x32_bf16 v[8:11], v[160:163], v[214:217], v[8:11]
	v_mfma_f32_16x16x32_bf16 v[60:63], v[156:159], v[188:191], v[60:63]
	v_mfma_f32_16x16x32_bf16 v[56:59], v[164:167], v[188:191], v[56:59]
	v_mfma_f32_16x16x32_bf16 v[44:47], v[156:159], v[196:199], v[44:47]
	v_mfma_f32_16x16x32_bf16 v[40:43], v[164:167], v[196:199], v[40:43]
	v_mfma_f32_16x16x32_bf16 v[28:31], v[156:159], v[210:213], v[28:31]
	v_mfma_f32_16x16x32_bf16 v[24:27], v[164:167], v[210:213], v[24:27]
	v_mfma_f32_16x16x32_bf16 v[12:15], v[156:159], v[218:221], v[12:15]
	v_mfma_f32_16x16x32_bf16 v[8:11], v[164:167], v[218:221], v[8:11]
	v_mfma_f32_16x16x32_bf16 v[52:55], v[168:171], v[184:187], v[52:55]
	v_mfma_f32_16x16x32_bf16 v[48:51], v[176:179], v[184:187], v[48:51]
	v_mfma_f32_16x16x32_bf16 v[36:39], v[168:171], v[192:195], v[36:39]
	v_mfma_f32_16x16x32_bf16 v[32:35], v[176:179], v[192:195], v[32:35]
	v_mfma_f32_16x16x32_bf16 v[20:23], v[168:171], v[200:203], v[20:23]
	v_mfma_f32_16x16x32_bf16 v[16:19], v[176:179], v[200:203], v[16:19]
	v_mfma_f32_16x16x32_bf16 v[4:7], v[168:171], v[214:217], v[4:7]
	v_mfma_f32_16x16x32_bf16 v[0:3], v[176:179], v[214:217], v[0:3]
	v_mfma_f32_16x16x32_bf16 v[52:55], v[172:175], v[188:191], v[52:55]
	v_mfma_f32_16x16x32_bf16 v[48:51], v[180:183], v[188:191], v[48:51]
	v_mfma_f32_16x16x32_bf16 v[36:39], v[172:175], v[196:199], v[36:39]
	v_mfma_f32_16x16x32_bf16 v[32:35], v[180:183], v[196:199], v[32:35]
	v_mfma_f32_16x16x32_bf16 v[20:23], v[172:175], v[210:213], v[20:23]
	v_mfma_f32_16x16x32_bf16 v[16:19], v[180:183], v[210:213], v[16:19]
	v_mfma_f32_16x16x32_bf16 v[4:7], v[172:175], v[218:221], v[4:7]
	v_mfma_f32_16x16x32_bf16 v[0:3], v[180:183], v[218:221], v[0:3]
	s_barrier
	s_add_i32 s71, 0, 0x18000
	v_add_u32_e32 v155, s71, v149
	s_add_i32 s72, 0, 0x1c000
	ds_read_b128 v[144:147], v155
	ds_read_b128 v[156:159], v155 offset:1024
	ds_read_b128 v[160:163], v155 offset:2048
	ds_read_b128 v[164:167], v155 offset:3072
	v_add_u32_e32 v155, s72, v149
	ds_read_b128 v[168:171], v155
	ds_read_b128 v[172:175], v155 offset:1024
	ds_read_b128 v[176:179], v155 offset:2048
	ds_read_b128 v[180:183], v155 offset:3072
	s_add_u32 s52, s52, 0x40000
	s_addc_u32 s53, s53, 0
	s_mov_b32 m0, s57
	v_lshl_add_u64 v[228:229], s[52:53], 0, v[128:129]
	ds_read_b128 v[184:187], v153 offset:32768
	ds_read_b128 v[188:191], v153 offset:33792
	ds_read_b128 v[192:195], v153 offset:34816
	ds_read_b128 v[196:199], v153 offset:35840
	ds_read_b128 v[200:203], v153 offset:36864
	ds_read_b128 v[210:213], v153 offset:37888
	ds_read_b128 v[214:217], v153 offset:38912
	ds_read_b128 v[218:221], v153 offset:39936
	global_load_lds_dwordx4 v[228:229], off
	v_lshl_add_u64 v[228:229], s[52:53], 0, v[132:133]
	s_mov_b32 m0, s58
	s_nop 0
	global_load_lds_dwordx4 v[228:229], off
	s_waitcnt vmcnt(8)
	s_waitcnt lgkmcnt(0)
	s_barrier
	s_waitcnt lgkmcnt(0)
	v_mfma_f32_16x16x32_bf16 v[124:127], v[144:147], v[184:187], v[124:127]
	v_mfma_f32_16x16x32_bf16 v[120:123], v[160:163], v[184:187], v[120:123]
	v_mfma_f32_16x16x32_bf16 v[108:111], v[144:147], v[192:195], v[108:111]
	v_mfma_f32_16x16x32_bf16 v[104:107], v[160:163], v[192:195], v[104:107]
	v_mfma_f32_16x16x32_bf16 v[92:95], v[144:147], v[200:203], v[92:95]
	v_mfma_f32_16x16x32_bf16 v[88:91], v[160:163], v[200:203], v[88:91]
	v_mfma_f32_16x16x32_bf16 v[76:79], v[144:147], v[214:217], v[76:79]
	v_mfma_f32_16x16x32_bf16 v[72:75], v[160:163], v[214:217], v[72:75]
	v_mfma_f32_16x16x32_bf16 v[124:127], v[156:159], v[188:191], v[124:127]
	v_mfma_f32_16x16x32_bf16 v[120:123], v[164:167], v[188:191], v[120:123]
	v_mfma_f32_16x16x32_bf16 v[108:111], v[156:159], v[196:199], v[108:111]
	v_mfma_f32_16x16x32_bf16 v[104:107], v[164:167], v[196:199], v[104:107]
	v_mfma_f32_16x16x32_bf16 v[92:95], v[156:159], v[210:213], v[92:95]
	v_mfma_f32_16x16x32_bf16 v[88:91], v[164:167], v[210:213], v[88:91]
	v_mfma_f32_16x16x32_bf16 v[76:79], v[156:159], v[218:221], v[76:79]
	v_mfma_f32_16x16x32_bf16 v[72:75], v[164:167], v[218:221], v[72:75]
	v_mfma_f32_16x16x32_bf16 v[116:119], v[168:171], v[184:187], v[116:119]
	v_mfma_f32_16x16x32_bf16 v[112:115], v[176:179], v[184:187], v[112:115]
	v_mfma_f32_16x16x32_bf16 v[100:103], v[168:171], v[192:195], v[100:103]
	v_mfma_f32_16x16x32_bf16 v[96:99], v[176:179], v[192:195], v[96:99]
	v_mfma_f32_16x16x32_bf16 v[84:87], v[168:171], v[200:203], v[84:87]
	v_mfma_f32_16x16x32_bf16 v[80:83], v[176:179], v[200:203], v[80:83]
	v_mfma_f32_16x16x32_bf16 v[68:71], v[168:171], v[214:217], v[68:71]
	v_mfma_f32_16x16x32_bf16 v[64:67], v[176:179], v[214:217], v[64:67]
	v_mfma_f32_16x16x32_bf16 v[116:119], v[172:175], v[188:191], v[116:119]
	v_mfma_f32_16x16x32_bf16 v[112:115], v[180:183], v[188:191], v[112:115]
	v_mfma_f32_16x16x32_bf16 v[100:103], v[172:175], v[196:199], v[100:103]
	v_mfma_f32_16x16x32_bf16 v[96:99], v[180:183], v[196:199], v[96:99]
	v_mfma_f32_16x16x32_bf16 v[84:87], v[172:175], v[210:213], v[84:87]
	v_mfma_f32_16x16x32_bf16 v[80:83], v[180:183], v[210:213], v[80:83]
	v_mfma_f32_16x16x32_bf16 v[68:71], v[172:175], v[218:221], v[68:71]
	v_mfma_f32_16x16x32_bf16 v[64:67], v[180:183], v[218:221], v[64:67]
	s_barrier
	s_add_i32 s52, s71, s55
	v_lshl_add_u64 v[204:205], v[204:205], 0, s[14:15]
	s_mov_b32 m0, s52
	ds_read_b128 v[184:187], v153 offset:49152
	ds_read_b128 v[188:191], v153 offset:50176
	ds_read_b128 v[192:195], v153 offset:51200
	ds_read_b128 v[196:199], v153 offset:52224
	ds_read_b128 v[200:203], v153 offset:53248
	ds_read_b128 v[210:213], v153 offset:54272
	ds_read_b128 v[214:217], v153 offset:55296
	ds_read_b128 v[218:221], v153 offset:56320
	global_load_lds_dwordx4 v[204:205], off
	s_add_i32 m0, s52, 0x2000
	s_add_u32 s50, s50, 0x40080
	v_lshl_add_u64 v[204:205], v[222:223], 0, s[14:15]
	s_addc_u32 s51, s51, 0
	s_add_i32 s52, s72, s55
	global_load_lds_dwordx4 v[204:205], off
	v_lshl_add_u64 v[204:205], s[50:51], 0, v[130:131]
	s_mov_b32 m0, s52
	s_nop 0
	global_load_lds_dwordx4 v[204:205], off
	v_lshl_add_u64 v[204:205], s[50:51], 0, v[134:135]
	s_add_i32 m0, s52, 0x2000
	s_nop 0
	global_load_lds_dwordx4 v[204:205], off
	v_lshl_add_u64 v[204:205], v[224:225], 0, s[14:15]
	s_mov_b32 m0, s60
	s_nop 0
	global_load_lds_dwordx4 v[204:205], off
	v_lshl_add_u64 v[204:205], v[226:227], 0, s[14:15]
	s_mov_b32 m0, s61
	s_nop 0
	global_load_lds_dwordx4 v[204:205], off
	s_waitcnt vmcnt(8)
	s_waitcnt lgkmcnt(0)
	s_barrier
	s_waitcnt lgkmcnt(0)
	v_mfma_f32_16x16x32_bf16 v[60:63], v[144:147], v[184:187], v[60:63]
	v_mfma_f32_16x16x32_bf16 v[56:59], v[160:163], v[184:187], v[56:59]
	v_mfma_f32_16x16x32_bf16 v[44:47], v[144:147], v[192:195], v[44:47]
	v_mfma_f32_16x16x32_bf16 v[40:43], v[160:163], v[192:195], v[40:43]
	v_mfma_f32_16x16x32_bf16 v[28:31], v[144:147], v[200:203], v[28:31]
	v_mfma_f32_16x16x32_bf16 v[24:27], v[160:163], v[200:203], v[24:27]
	v_mfma_f32_16x16x32_bf16 v[12:15], v[144:147], v[214:217], v[12:15]
	v_mfma_f32_16x16x32_bf16 v[8:11], v[160:163], v[214:217], v[8:11]
	v_mfma_f32_16x16x32_bf16 v[60:63], v[156:159], v[188:191], v[60:63]
	v_mfma_f32_16x16x32_bf16 v[56:59], v[164:167], v[188:191], v[56:59]
	v_mfma_f32_16x16x32_bf16 v[44:47], v[156:159], v[196:199], v[44:47]
	v_mfma_f32_16x16x32_bf16 v[40:43], v[164:167], v[196:199], v[40:43]
	v_mfma_f32_16x16x32_bf16 v[28:31], v[156:159], v[210:213], v[28:31]
	v_mfma_f32_16x16x32_bf16 v[24:27], v[164:167], v[210:213], v[24:27]
	v_mfma_f32_16x16x32_bf16 v[12:15], v[156:159], v[218:221], v[12:15]
	v_mfma_f32_16x16x32_bf16 v[8:11], v[164:167], v[218:221], v[8:11]
	v_mfma_f32_16x16x32_bf16 v[52:55], v[168:171], v[184:187], v[52:55]
	v_mfma_f32_16x16x32_bf16 v[48:51], v[176:179], v[184:187], v[48:51]
	v_mfma_f32_16x16x32_bf16 v[36:39], v[168:171], v[192:195], v[36:39]
	v_mfma_f32_16x16x32_bf16 v[32:35], v[176:179], v[192:195], v[32:35]
	v_mfma_f32_16x16x32_bf16 v[20:23], v[168:171], v[200:203], v[20:23]
	v_mfma_f32_16x16x32_bf16 v[16:19], v[176:179], v[200:203], v[16:19]
	v_mfma_f32_16x16x32_bf16 v[4:7], v[168:171], v[214:217], v[4:7]
	v_mfma_f32_16x16x32_bf16 v[0:3], v[176:179], v[214:217], v[0:3]
	v_mfma_f32_16x16x32_bf16 v[52:55], v[172:175], v[188:191], v[52:55]
	v_mfma_f32_16x16x32_bf16 v[48:51], v[180:183], v[188:191], v[48:51]
	v_mfma_f32_16x16x32_bf16 v[36:39], v[172:175], v[196:199], v[36:39]
	v_mfma_f32_16x16x32_bf16 v[32:35], v[180:183], v[196:199], v[32:35]
	v_mfma_f32_16x16x32_bf16 v[20:23], v[172:175], v[210:213], v[20:23]
	v_mfma_f32_16x16x32_bf16 v[16:19], v[180:183], v[210:213], v[16:19]
	v_mfma_f32_16x16x32_bf16 v[4:7], v[172:175], v[218:221], v[4:7]
	v_mfma_f32_16x16x32_bf16 v[0:3], v[180:183], v[218:221], v[0:3]
	s_barrier
	s_add_i32 s70, s70, 2
	s_add_u32 s42, s42, 0x100
	s_addc_u32 s43, s43, 0
	s_add_u32 s68, s68, 0x100
	s_addc_u32 s69, s69, 0
	s_cmp_gt_u32 s70, 13
	s_cbranch_scc0 .LBB0_1131
.Lpeel_done_32180:
	s_and_b64 vcc, exec, s[20:21]
	s_cbranch_vccz .LBB0_1134
	s_barrier

.LBB0_1282:
	s_ashr_i32 s43, s42, 31
	s_lshl_b64 s[50:51], s[42:43], 19
	s_add_u32 s50, s14, s50
	s_addc_u32 s51, s15, s51
	s_and_b64 s[52:53], s[12:13], exec
	s_cselect_b32 s43, s51, s55
	s_cselect_b32 s77, s50, s54
	s_ashr_i32 s41, s40, 31
	s_lshl_b64 s[52:53], s[40:41], 19
	s_add_u32 s52, s35, s52
	s_addc_u32 s53, s60, s53
	s_and_b64 s[58:59], s[12:13], exec
	s_cselect_b32 s41, s53, s57
	s_cselect_b32 s78, s52, s56
	s_add_u32 s54, s54, 0x40080
	s_addc_u32 s55, s55, 0
	s_add_u32 s79, s56, 0x100
	s_addc_u32 s80, s57, 0
	s_mov_b32 s81, -2
	s_waitcnt lgkmcnt(0)
	ds_read_b128 v[142:145], v153
	ds_read_b128 v[146:149], v153 offset:1024
	ds_read_b128 v[156:159], v153 offset:2048
	ds_read_b128 v[160:163], v153 offset:3072
	ds_read_b128 v[164:167], v154
	ds_read_b128 v[168:171], v154 offset:1024
	ds_read_b128 v[172:175], v154 offset:2048
	ds_read_b128 v[176:179], v154 offset:3072
	s_add_u32 s56, s54, 0xfffc0080
	s_addc_u32 s57, s55, -1
	s_cmp_eq_u32 s81, 12
	s_cselect_b32 s59, s43, s57
	s_cselect_b32 s58, s77, s56
	s_cselect_b32 s57, s41, s80
	s_cselect_b32 s56, s78, s79
	v_lshl_add_u64 v[204:205], s[54:55], 0, v[134:135]
	s_add_i32 m0, s21, 0xc000
	ds_read_b128 v[180:183], v155
	ds_read_b128 v[184:187], v155 offset:1024
	ds_read_b128 v[188:191], v155 offset:2048
	ds_read_b128 v[192:195], v155 offset:3072
	ds_read_b128 v[196:199], v155 offset:4096
	ds_read_b128 v[200:203], v155 offset:5120
	ds_read_b128 v[210:213], v155 offset:6144
	ds_read_b128 v[214:217], v155 offset:7168
	global_load_lds_dwordx4 v[204:205], off
	v_lshl_add_u64 v[204:205], s[54:55], 0, v[136:137]
	s_add_i32 m0, s21, 0xe000
	s_nop 0
	global_load_lds_dwordx4 v[204:205], off
	s_waitcnt vmcnt(8)
	s_waitcnt lgkmcnt(0)
	s_barrier
	s_setprio 1
	s_waitcnt lgkmcnt(0)
	v_mfma_f32_16x16x32_bf16 v[124:127], v[142:145], v[180:183], 0
	v_mfma_f32_16x16x32_bf16 v[120:123], v[156:159], v[180:183], 0
	v_mfma_f32_16x16x32_bf16 v[108:111], v[142:145], v[188:191], 0
	v_mfma_f32_16x16x32_bf16 v[104:107], v[156:159], v[188:191], 0
	v_mfma_f32_16x16x32_bf16 v[92:95], v[142:145], v[196:199], 0
	v_mfma_f32_16x16x32_bf16 v[88:91], v[156:159], v[196:199], 0
	v_mfma_f32_16x16x32_bf16 v[76:79], v[142:145], v[210:213], 0
	v_mfma_f32_16x16x32_bf16 v[72:75], v[156:159], v[210:213], 0
	v_mfma_f32_16x16x32_bf16 v[124:127], v[146:149], v[184:187], v[124:127]
	v_mfma_f32_16x16x32_bf16 v[120:123], v[160:163], v[184:187], v[120:123]
	v_mfma_f32_16x16x32_bf16 v[108:111], v[146:149], v[192:195], v[108:111]
	v_mfma_f32_16x16x32_bf16 v[104:107], v[160:163], v[192:195], v[104:107]
	v_mfma_f32_16x16x32_bf16 v[92:95], v[146:149], v[200:203], v[92:95]
	v_mfma_f32_16x16x32_bf16 v[88:91], v[160:163], v[200:203], v[88:91]
	v_mfma_f32_16x16x32_bf16 v[76:79], v[146:149], v[214:217], v[76:79]
	v_mfma_f32_16x16x32_bf16 v[72:75], v[160:163], v[214:217], v[72:75]
	s_setprio 0
	s_setprio 1
	v_mfma_f32_16x16x32_bf16 v[116:119], v[164:167], v[180:183], 0
	v_mfma_f32_16x16x32_bf16 v[112:115], v[172:175], v[180:183], 0
	v_mfma_f32_16x16x32_bf16 v[100:103], v[164:167], v[188:191], 0
	v_mfma_f32_16x16x32_bf16 v[96:99], v[172:175], v[188:191], 0
	v_mfma_f32_16x16x32_bf16 v[84:87], v[164:167], v[196:199], 0
	v_mfma_f32_16x16x32_bf16 v[80:83], v[172:175], v[196:199], 0
	v_mfma_f32_16x16x32_bf16 v[68:71], v[164:167], v[210:213], 0
	v_mfma_f32_16x16x32_bf16 v[64:67], v[172:175], v[210:213], 0
	v_mfma_f32_16x16x32_bf16 v[116:119], v[168:171], v[184:187], v[116:119]
	v_mfma_f32_16x16x32_bf16 v[112:115], v[176:179], v[184:187], v[112:115]
	v_mfma_f32_16x16x32_bf16 v[100:103], v[168:171], v[192:195], v[100:103]
	v_mfma_f32_16x16x32_bf16 v[96:99], v[176:179], v[192:195], v[96:99]
	v_mfma_f32_16x16x32_bf16 v[84:87], v[168:171], v[200:203], v[84:87]
	v_mfma_f32_16x16x32_bf16 v[80:83], v[176:179], v[200:203], v[80:83]
	v_mfma_f32_16x16x32_bf16 v[68:71], v[168:171], v[214:217], v[68:71]
	v_mfma_f32_16x16x32_bf16 v[64:67], v[176:179], v[214:217], v[64:67]
	s_setprio 0
	s_barrier
	s_add_i32 s82, s68, s61
	v_lshl_add_u64 v[204:205], s[56:57], 0, v[128:129]
	s_mov_b32 m0, s82
	ds_read_b128 v[180:183], v155 offset:16384
	ds_read_b128 v[184:187], v155 offset:17408
	ds_read_b128 v[188:191], v155 offset:18432
	ds_read_b128 v[192:195], v155 offset:19456
	ds_read_b128 v[196:199], v155 offset:20480
	ds_read_b128 v[200:203], v155 offset:21504
	ds_read_b128 v[210:213], v155 offset:22528
	ds_read_b128 v[214:217], v155 offset:23552
	global_load_lds_dwordx4 v[204:205], off
	s_add_i32 m0, s82, 0x2000
	s_add_u32 s82, s56, 0x40000
	v_lshl_add_u64 v[218:219], s[56:57], 0, v[130:131]
	s_addc_u32 s83, s57, 0
	s_add_i32 s86, s69, s61
	global_load_lds_dwordx4 v[218:219], off
	v_lshl_add_u64 v[220:221], s[82:83], 0, v[128:129]
	s_mov_b32 m0, s86
	v_lshl_add_u64 v[222:223], s[58:59], 0, v[130:131]
	global_load_lds_dwordx4 v[220:221], off
	v_lshl_add_u64 v[220:221], s[82:83], 0, v[130:131]
	s_add_i32 m0, s86, 0x2000
	s_nop 0
	global_load_lds_dwordx4 v[220:221], off
	v_lshl_add_u64 v[220:221], s[58:59], 0, v[128:129]
	s_mov_b32 m0, s21
	s_nop 0
	global_load_lds_dwordx4 v[220:221], off
	s_mov_b32 m0, s62
	s_nop 0
	global_load_lds_dwordx4 v[222:223], off
	s_waitcnt vmcnt(8)
	s_waitcnt lgkmcnt(0)
	s_barrier
	s_setprio 1
	s_waitcnt lgkmcnt(0)
	v_mfma_f32_16x16x32_bf16 v[60:63], v[142:145], v[180:183], 0
	v_mfma_f32_16x16x32_bf16 v[56:59], v[156:159], v[180:183], 0
	v_mfma_f32_16x16x32_bf16 v[44:47], v[142:145], v[188:191], 0
	v_mfma_f32_16x16x32_bf16 v[40:43], v[156:159], v[188:191], 0
	v_mfma_f32_16x16x32_bf16 v[28:31], v[142:145], v[196:199], 0
	v_mfma_f32_16x16x32_bf16 v[24:27], v[156:159], v[196:199], 0
	v_mfma_f32_16x16x32_bf16 v[12:15], v[142:145], v[210:213], 0
	v_mfma_f32_16x16x32_bf16 v[8:11], v[156:159], v[210:213], 0
	v_mfma_f32_16x16x32_bf16 v[60:63], v[146:149], v[184:187], v[60:63]
	v_mfma_f32_16x16x32_bf16 v[56:59], v[160:163], v[184:187], v[56:59]
	v_mfma_f32_16x16x32_bf16 v[44:47], v[146:149], v[192:195], v[44:47]
	v_mfma_f32_16x16x32_bf16 v[40:43], v[160:163], v[192:195], v[40:43]
	v_mfma_f32_16x16x32_bf16 v[28:31], v[146:149], v[200:203], v[28:31]
	v_mfma_f32_16x16x32_bf16 v[24:27], v[160:163], v[200:203], v[24:27]
	v_mfma_f32_16x16x32_bf16 v[12:15], v[146:149], v[214:217], v[12:15]
	v_mfma_f32_16x16x32_bf16 v[8:11], v[160:163], v[214:217], v[8:11]
	s_setprio 0
	s_setprio 1
	v_mfma_f32_16x16x32_bf16 v[52:55], v[164:167], v[180:183], 0
	v_mfma_f32_16x16x32_bf16 v[48:51], v[172:175], v[180:183], 0
	v_mfma_f32_16x16x32_bf16 v[36:39], v[164:167], v[188:191], 0
	v_mfma_f32_16x16x32_bf16 v[32:35], v[172:175], v[188:191], 0
	v_mfma_f32_16x16x32_bf16 v[20:23], v[164:167], v[196:199], 0
	v_mfma_f32_16x16x32_bf16 v[16:19], v[172:175], v[196:199], 0
	v_mfma_f32_16x16x32_bf16 v[4:7], v[164:167], v[210:213], 0
	v_mfma_f32_16x16x32_bf16 v[0:3], v[172:175], v[210:213], 0
	v_mfma_f32_16x16x32_bf16 v[52:55], v[168:171], v[184:187], v[52:55]
	v_mfma_f32_16x16x32_bf16 v[48:51], v[176:179], v[184:187], v[48:51]
	v_mfma_f32_16x16x32_bf16 v[36:39], v[168:171], v[192:195], v[36:39]
	v_mfma_f32_16x16x32_bf16 v[32:35], v[176:179], v[192:195], v[32:35]
	v_mfma_f32_16x16x32_bf16 v[20:23], v[168:171], v[200:203], v[20:23]
	v_mfma_f32_16x16x32_bf16 v[16:19], v[176:179], v[200:203], v[16:19]
	v_mfma_f32_16x16x32_bf16 v[4:7], v[168:171], v[214:217], v[4:7]
	v_mfma_f32_16x16x32_bf16 v[0:3], v[176:179], v[214:217], v[0:3]
	s_setprio 0
	s_barrier
	s_add_i32 s82, 0, 0x18000
	v_add_u32_e32 v132, s82, v151
	s_add_i32 s83, 0, 0x1c000
	ds_read_b128 v[142:145], v132
	ds_read_b128 v[146:149], v132 offset:1024
	ds_read_b128 v[156:159], v132 offset:2048
	ds_read_b128 v[160:163], v132 offset:3072
	v_add_u32_e32 v132, s83, v151
	ds_read_b128 v[164:167], v132
	ds_read_b128 v[168:171], v132 offset:1024
	ds_read_b128 v[172:175], v132 offset:2048
	ds_read_b128 v[176:179], v132 offset:3072
	s_add_u32 s58, s58, 0x40000
	s_addc_u32 s59, s59, 0
	s_mov_b32 m0, s63
	v_lshl_add_u64 v[224:225], s[58:59], 0, v[128:129]
	ds_read_b128 v[180:183], v155 offset:32768
	ds_read_b128 v[184:187], v155 offset:33792
	ds_read_b128 v[188:191], v155 offset:34816
	ds_read_b128 v[192:195], v155 offset:35840
	ds_read_b128 v[196:199], v155 offset:36864
	ds_read_b128 v[200:203], v155 offset:37888
	ds_read_b128 v[210:213], v155 offset:38912
	ds_read_b128 v[214:217], v155 offset:39936
	global_load_lds_dwordx4 v[224:225], off
	v_lshl_add_u64 v[224:225], s[58:59], 0, v[130:131]
	s_mov_b32 m0, s64
	s_nop 0
	global_load_lds_dwordx4 v[224:225], off
	s_waitcnt vmcnt(8)
	s_waitcnt lgkmcnt(0)
	s_barrier
	s_setprio 1
	s_waitcnt lgkmcnt(0)
	v_mfma_f32_16x16x32_bf16 v[124:127], v[142:145], v[180:183], v[124:127]
	v_mfma_f32_16x16x32_bf16 v[120:123], v[156:159], v[180:183], v[120:123]
	v_mfma_f32_16x16x32_bf16 v[108:111], v[142:145], v[188:191], v[108:111]
	v_mfma_f32_16x16x32_bf16 v[104:107], v[156:159], v[188:191], v[104:107]
	v_mfma_f32_16x16x32_bf16 v[92:95], v[142:145], v[196:199], v[92:95]
	v_mfma_f32_16x16x32_bf16 v[88:91], v[156:159], v[196:199], v[88:91]
	v_mfma_f32_16x16x32_bf16 v[76:79], v[142:145], v[210:213], v[76:79]
	v_mfma_f32_16x16x32_bf16 v[72:75], v[156:159], v[210:213], v[72:75]
	v_mfma_f32_16x16x32_bf16 v[124:127], v[146:149], v[184:187], v[124:127]
	v_mfma_f32_16x16x32_bf16 v[120:123], v[160:163], v[184:187], v[120:123]
	v_mfma_f32_16x16x32_bf16 v[108:111], v[146:149], v[192:195], v[108:111]
	v_mfma_f32_16x16x32_bf16 v[104:107], v[160:163], v[192:195], v[104:107]
	v_mfma_f32_16x16x32_bf16 v[92:95], v[146:149], v[200:203], v[92:95]
	v_mfma_f32_16x16x32_bf16 v[88:91], v[160:163], v[200:203], v[88:91]
	v_mfma_f32_16x16x32_bf16 v[76:79], v[146:149], v[214:217], v[76:79]
	v_mfma_f32_16x16x32_bf16 v[72:75], v[160:163], v[214:217], v[72:75]
	s_setprio 0
	s_setprio 1
	v_mfma_f32_16x16x32_bf16 v[116:119], v[164:167], v[180:183], v[116:119]
	v_mfma_f32_16x16x32_bf16 v[112:115], v[172:175], v[180:183], v[112:115]
	v_mfma_f32_16x16x32_bf16 v[100:103], v[164:167], v[188:191], v[100:103]
	v_mfma_f32_16x16x32_bf16 v[96:99], v[172:175], v[188:191], v[96:99]
	v_mfma_f32_16x16x32_bf16 v[84:87], v[164:167], v[196:199], v[84:87]
	v_mfma_f32_16x16x32_bf16 v[80:83], v[172:175], v[196:199], v[80:83]
	v_mfma_f32_16x16x32_bf16 v[68:71], v[164:167], v[210:213], v[68:71]
	v_mfma_f32_16x16x32_bf16 v[64:67], v[172:175], v[210:213], v[64:67]
	v_mfma_f32_16x16x32_bf16 v[116:119], v[168:171], v[184:187], v[116:119]
	v_mfma_f32_16x16x32_bf16 v[112:115], v[176:179], v[184:187], v[112:115]
	v_mfma_f32_16x16x32_bf16 v[100:103], v[168:171], v[192:195], v[100:103]
	v_mfma_f32_16x16x32_bf16 v[96:99], v[176:179], v[192:195], v[96:99]
	v_mfma_f32_16x16x32_bf16 v[84:87], v[168:171], v[200:203], v[84:87]
	v_mfma_f32_16x16x32_bf16 v[80:83], v[176:179], v[200:203], v[80:83]
	v_mfma_f32_16x16x32_bf16 v[68:71], v[168:171], v[214:217], v[68:71]
	v_mfma_f32_16x16x32_bf16 v[64:67], v[176:179], v[214:217], v[64:67]
	s_setprio 0
	s_barrier
	s_add_i32 s58, s82, s61
	v_lshl_add_u64 v[204:205], v[204:205], 0, s[28:29]
	s_mov_b32 m0, s58
	ds_read_b128 v[180:183], v155 offset:49152
	ds_read_b128 v[184:187], v155 offset:50176
	ds_read_b128 v[188:191], v155 offset:51200
	ds_read_b128 v[192:195], v155 offset:52224
	ds_read_b128 v[196:199], v155 offset:53248
	ds_read_b128 v[200:203], v155 offset:54272
	ds_read_b128 v[210:213], v155 offset:55296
	ds_read_b128 v[214:217], v155 offset:56320
	global_load_lds_dwordx4 v[204:205], off
	s_add_i32 m0, s58, 0x2000
	s_add_u32 s56, s56, 0x40080
	v_lshl_add_u64 v[204:205], v[218:219], 0, s[28:29]
	s_addc_u32 s57, s57, 0
	s_add_i32 s58, s83, s61
	global_load_lds_dwordx4 v[204:205], off
	v_lshl_add_u64 v[204:205], s[56:57], 0, v[128:129]
	s_mov_b32 m0, s58
	s_nop 0
	global_load_lds_dwordx4 v[204:205], off
	v_lshl_add_u64 v[204:205], s[56:57], 0, v[130:131]
	s_add_i32 m0, s58, 0x2000
	s_nop 0
	global_load_lds_dwordx4 v[204:205], off
	v_lshl_add_u64 v[204:205], v[220:221], 0, s[28:29]
	s_mov_b32 m0, s66
	s_nop 0
	global_load_lds_dwordx4 v[204:205], off
	v_lshl_add_u64 v[204:205], v[222:223], 0, s[28:29]
	s_mov_b32 m0, s67
	s_nop 0
	global_load_lds_dwordx4 v[204:205], off
	s_waitcnt vmcnt(8)
	s_waitcnt lgkmcnt(0)
	s_barrier
	s_setprio 1
	s_waitcnt lgkmcnt(0)
	v_mfma_f32_16x16x32_bf16 v[60:63], v[142:145], v[180:183], v[60:63]
	v_mfma_f32_16x16x32_bf16 v[56:59], v[156:159], v[180:183], v[56:59]
	v_mfma_f32_16x16x32_bf16 v[44:47], v[142:145], v[188:191], v[44:47]
	v_mfma_f32_16x16x32_bf16 v[40:43], v[156:159], v[188:191], v[40:43]
	v_mfma_f32_16x16x32_bf16 v[28:31], v[142:145], v[196:199], v[28:31]
	v_mfma_f32_16x16x32_bf16 v[24:27], v[156:159], v[196:199], v[24:27]
	v_mfma_f32_16x16x32_bf16 v[12:15], v[142:145], v[210:213], v[12:15]
	v_mfma_f32_16x16x32_bf16 v[8:11], v[156:159], v[210:213], v[8:11]
	v_mfma_f32_16x16x32_bf16 v[60:63], v[146:149], v[184:187], v[60:63]
	v_mfma_f32_16x16x32_bf16 v[56:59], v[160:163], v[184:187], v[56:59]
	v_mfma_f32_16x16x32_bf16 v[44:47], v[146:149], v[192:195], v[44:47]
	v_mfma_f32_16x16x32_bf16 v[40:43], v[160:163], v[192:195], v[40:43]
	v_mfma_f32_16x16x32_bf16 v[28:31], v[146:149], v[200:203], v[28:31]
	v_mfma_f32_16x16x32_bf16 v[24:27], v[160:163], v[200:203], v[24:27]
	v_mfma_f32_16x16x32_bf16 v[12:15], v[146:149], v[214:217], v[12:15]
	v_mfma_f32_16x16x32_bf16 v[8:11], v[160:163], v[214:217], v[8:11]
	s_setprio 0
	s_setprio 1
	v_mfma_f32_16x16x32_bf16 v[52:55], v[164:167], v[180:183], v[52:55]
	v_mfma_f32_16x16x32_bf16 v[48:51], v[172:175], v[180:183], v[48:51]
	v_mfma_f32_16x16x32_bf16 v[36:39], v[164:167], v[188:191], v[36:39]
	v_mfma_f32_16x16x32_bf16 v[32:35], v[172:175], v[188:191], v[32:35]
	v_mfma_f32_16x16x32_bf16 v[20:23], v[164:167], v[196:199], v[20:23]
	v_mfma_f32_16x16x32_bf16 v[16:19], v[172:175], v[196:199], v[16:19]
	v_mfma_f32_16x16x32_bf16 v[4:7], v[164:167], v[210:213], v[4:7]
	v_mfma_f32_16x16x32_bf16 v[0:3], v[172:175], v[210:213], v[0:3]
	v_mfma_f32_16x16x32_bf16 v[52:55], v[168:171], v[184:187], v[52:55]
	v_mfma_f32_16x16x32_bf16 v[48:51], v[176:179], v[184:187], v[48:51]
	v_mfma_f32_16x16x32_bf16 v[36:39], v[168:171], v[192:195], v[36:39]
	v_mfma_f32_16x16x32_bf16 v[32:35], v[176:179], v[192:195], v[32:35]
	v_mfma_f32_16x16x32_bf16 v[20:23], v[168:171], v[200:203], v[20:23]
	v_mfma_f32_16x16x32_bf16 v[16:19], v[176:179], v[200:203], v[16:19]
	v_mfma_f32_16x16x32_bf16 v[4:7], v[168:171], v[214:217], v[4:7]
	v_mfma_f32_16x16x32_bf16 v[0:3], v[176:179], v[214:217], v[0:3]
	s_setprio 0
	s_barrier
	s_add_i32 s81, s81, 2
	s_add_u32 s54, s54, 0x100
	s_addc_u32 s55, s55, 0
	s_add_u32 s79, s79, 0x100
	s_addc_u32 s80, s80, 0
	s_cmp_gt_u32 s81, 13
	s_cbranch_scc1 .Lpeel_done_38108
.LBB0_1283:
	ds_read_b128 v[142:145], v153
	ds_read_b128 v[146:149], v153 offset:1024
	ds_read_b128 v[156:159], v153 offset:2048
	ds_read_b128 v[160:163], v153 offset:3072
	ds_read_b128 v[164:167], v154
	ds_read_b128 v[168:171], v154 offset:1024
	ds_read_b128 v[172:175], v154 offset:2048
	ds_read_b128 v[176:179], v154 offset:3072
	s_add_u32 s56, s54, 0xfffc0080
	s_addc_u32 s57, s55, -1
	s_cmp_eq_u32 s81, 12
	s_cselect_b32 s59, s43, s57
	s_cselect_b32 s58, s77, s56
	s_cselect_b32 s57, s41, s80
	s_cselect_b32 s56, s78, s79
	v_lshl_add_u64 v[204:205], s[54:55], 0, v[134:135]
	s_add_i32 m0, s21, 0xc000
	ds_read_b128 v[180:183], v155
	ds_read_b128 v[184:187], v155 offset:1024
	ds_read_b128 v[188:191], v155 offset:2048
	ds_read_b128 v[192:195], v155 offset:3072
	ds_read_b128 v[196:199], v155 offset:4096
	ds_read_b128 v[200:203], v155 offset:5120
	ds_read_b128 v[210:213], v155 offset:6144
	ds_read_b128 v[214:217], v155 offset:7168
	global_load_lds_dwordx4 v[204:205], off
	v_lshl_add_u64 v[204:205], s[54:55], 0, v[136:137]
	s_add_i32 m0, s21, 0xe000
	s_nop 0
	global_load_lds_dwordx4 v[204:205], off
	s_waitcnt vmcnt(8)
	s_waitcnt lgkmcnt(0)
	s_barrier
	s_waitcnt lgkmcnt(0)
	v_mfma_f32_16x16x32_bf16 v[124:127], v[142:145], v[180:183], v[124:127]
	v_mfma_f32_16x16x32_bf16 v[120:123], v[156:159], v[180:183], v[120:123]
	v_mfma_f32_16x16x32_bf16 v[108:111], v[142:145], v[188:191], v[108:111]
	v_mfma_f32_16x16x32_bf16 v[104:107], v[156:159], v[188:191], v[104:107]
	v_mfma_f32_16x16x32_bf16 v[92:95], v[142:145], v[196:199], v[92:95]
	v_mfma_f32_16x16x32_bf16 v[88:91], v[156:159], v[196:199], v[88:91]
	v_mfma_f32_16x16x32_bf16 v[76:79], v[142:145], v[210:213], v[76:79]
	v_mfma_f32_16x16x32_bf16 v[72:75], v[156:159], v[210:213], v[72:75]
	v_mfma_f32_16x16x32_bf16 v[124:127], v[146:149], v[184:187], v[124:127]
	v_mfma_f32_16x16x32_bf16 v[120:123], v[160:163], v[184:187], v[120:123]
	v_mfma_f32_16x16x32_bf16 v[108:111], v[146:149], v[192:195], v[108:111]
	v_mfma_f32_16x16x32_bf16 v[104:107], v[160:163], v[192:195], v[104:107]
	v_mfma_f32_16x16x32_bf16 v[92:95], v[146:149], v[200:203], v[92:95]
	v_mfma_f32_16x16x32_bf16 v[88:91], v[160:163], v[200:203], v[88:91]
	v_mfma_f32_16x16x32_bf16 v[76:79], v[146:149], v[214:217], v[76:79]
	v_mfma_f32_16x16x32_bf16 v[72:75], v[160:163], v[214:217], v[72:75]
	v_mfma_f32_16x16x32_bf16 v[116:119], v[164:167], v[180:183], v[116:119]
	v_mfma_f32_16x16x32_bf16 v[112:115], v[172:175], v[180:183], v[112:115]
	v_mfma_f32_16x16x32_bf16 v[100:103], v[164:167], v[188:191], v[100:103]
	v_mfma_f32_16x16x32_bf16 v[96:99], v[172:175], v[188:191], v[96:99]
	v_mfma_f32_16x16x32_bf16 v[84:87], v[164:167], v[196:199], v[84:87]
	v_mfma_f32_16x16x32_bf16 v[80:83], v[172:175], v[196:199], v[80:83]
	v_mfma_f32_16x16x32_bf16 v[68:71], v[164:167], v[210:213], v[68:71]
	v_mfma_f32_16x16x32_bf16 v[64:67], v[172:175], v[210:213], v[64:67]
	v_mfma_f32_16x16x32_bf16 v[116:119], v[168:171], v[184:187], v[116:119]
	v_mfma_f32_16x16x32_bf16 v[112:115], v[176:179], v[184:187], v[112:115]
	v_mfma_f32_16x16x32_bf16 v[100:103], v[168:171], v[192:195], v[100:103]
	v_mfma_f32_16x16x32_bf16 v[96:99], v[176:179], v[192:195], v[96:99]
	v_mfma_f32_16x16x32_bf16 v[84:87], v[168:171], v[200:203], v[84:87]
	v_mfma_f32_16x16x32_bf16 v[80:83], v[176:179], v[200:203], v[80:83]
	v_mfma_f32_16x16x32_bf16 v[68:71], v[168:171], v[214:217], v[68:71]
	v_mfma_f32_16x16x32_bf16 v[64:67], v[176:179], v[214:217], v[64:67]
	s_barrier
	s_add_i32 s82, s68, s61
	v_lshl_add_u64 v[204:205], s[56:57], 0, v[128:129]
	s_mov_b32 m0, s82
	ds_read_b128 v[180:183], v155 offset:16384
	ds_read_b128 v[184:187], v155 offset:17408
	ds_read_b128 v[188:191], v155 offset:18432
	ds_read_b128 v[192:195], v155 offset:19456
	ds_read_b128 v[196:199], v155 offset:20480
	ds_read_b128 v[200:203], v155 offset:21504
	ds_read_b128 v[210:213], v155 offset:22528
	ds_read_b128 v[214:217], v155 offset:23552
	global_load_lds_dwordx4 v[204:205], off
	s_add_i32 m0, s82, 0x2000
	s_add_u32 s82, s56, 0x40000
	v_lshl_add_u64 v[218:219], s[56:57], 0, v[130:131]
	s_addc_u32 s83, s57, 0
	s_add_i32 s86, s69, s61
	global_load_lds_dwordx4 v[218:219], off
	v_lshl_add_u64 v[220:221], s[82:83], 0, v[128:129]
	s_mov_b32 m0, s86
	v_lshl_add_u64 v[222:223], s[58:59], 0, v[130:131]
	global_load_lds_dwordx4 v[220:221], off
	v_lshl_add_u64 v[220:221], s[82:83], 0, v[130:131]
	s_add_i32 m0, s86, 0x2000
	s_nop 0
	global_load_lds_dwordx4 v[220:221], off
	v_lshl_add_u64 v[220:221], s[58:59], 0, v[128:129]
	s_mov_b32 m0, s21
	s_nop 0
	global_load_lds_dwordx4 v[220:221], off
	s_mov_b32 m0, s62
	s_nop 0
	global_load_lds_dwordx4 v[222:223], off
	s_waitcnt vmcnt(8)
	s_waitcnt lgkmcnt(0)
	s_barrier
	s_waitcnt lgkmcnt(0)
	v_mfma_f32_16x16x32_bf16 v[60:63], v[142:145], v[180:183], v[60:63]
	v_mfma_f32_16x16x32_bf16 v[56:59], v[156:159], v[180:183], v[56:59]
	v_mfma_f32_16x16x32_bf16 v[44:47], v[142:145], v[188:191], v[44:47]
	v_mfma_f32_16x16x32_bf16 v[40:43], v[156:159], v[188:191], v[40:43]
	v_mfma_f32_16x16x32_bf16 v[28:31], v[142:145], v[196:199], v[28:31]
	v_mfma_f32_16x16x32_bf16 v[24:27], v[156:159], v[196:199], v[24:27]
	v_mfma_f32_16x16x32_bf16 v[12:15], v[142:145], v[210:213], v[12:15]
	v_mfma_f32_16x16x32_bf16 v[8:11], v[156:159], v[210:213], v[8:11]
	v_mfma_f32_16x16x32_bf16 v[60:63], v[146:149], v[184:187], v[60:63]
	v_mfma_f32_16x16x32_bf16 v[56:59], v[160:163], v[184:187], v[56:59]
	v_mfma_f32_16x16x32_bf16 v[44:47], v[146:149], v[192:195], v[44:47]
	v_mfma_f32_16x16x32_bf16 v[40:43], v[160:163], v[192:195], v[40:43]
	v_mfma_f32_16x16x32_bf16 v[28:31], v[146:149], v[200:203], v[28:31]
	v_mfma_f32_16x16x32_bf16 v[24:27], v[160:163], v[200:203], v[24:27]
	v_mfma_f32_16x16x32_bf16 v[12:15], v[146:149], v[214:217], v[12:15]
	v_mfma_f32_16x16x32_bf16 v[8:11], v[160:163], v[214:217], v[8:11]
	v_mfma_f32_16x16x32_bf16 v[52:55], v[164:167], v[180:183], v[52:55]
	v_mfma_f32_16x16x32_bf16 v[48:51], v[172:175], v[180:183], v[48:51]
	v_mfma_f32_16x16x32_bf16 v[36:39], v[164:167], v[188:191], v[36:39]
	v_mfma_f32_16x16x32_bf16 v[32:35], v[172:175], v[188:191], v[32:35]
	v_mfma_f32_16x16x32_bf16 v[20:23], v[164:167], v[196:199], v[20:23]
	v_mfma_f32_16x16x32_bf16 v[16:19], v[172:175], v[196:199], v[16:19]
	v_mfma_f32_16x16x32_bf16 v[4:7], v[164:167], v[210:213], v[4:7]
	v_mfma_f32_16x16x32_bf16 v[0:3], v[172:175], v[210:213], v[0:3]
	v_mfma_f32_16x16x32_bf16 v[52:55], v[168:171], v[184:187], v[52:55]
	v_mfma_f32_16x16x32_bf16 v[48:51], v[176:179], v[184:187], v[48:51]
	v_mfma_f32_16x16x32_bf16 v[36:39], v[168:171], v[192:195], v[36:39]
	v_mfma_f32_16x16x32_bf16 v[32:35], v[176:179], v[192:195], v[32:35]
	v_mfma_f32_16x16x32_bf16 v[20:23], v[168:171], v[200:203], v[20:23]
	v_mfma_f32_16x16x32_bf16 v[16:19], v[176:179], v[200:203], v[16:19]
	v_mfma_f32_16x16x32_bf16 v[4:7], v[168:171], v[214:217], v[4:7]
	v_mfma_f32_16x16x32_bf16 v[0:3], v[176:179], v[214:217], v[0:3]
	s_barrier
	s_add_i32 s82, 0, 0x18000
	v_add_u32_e32 v132, s82, v151
	s_add_i32 s83, 0, 0x1c000
	ds_read_b128 v[142:145], v132
	ds_read_b128 v[146:149], v132 offset:1024
	ds_read_b128 v[156:159], v132 offset:2048
	ds_read_b128 v[160:163], v132 offset:3072
	v_add_u32_e32 v132, s83, v151
	ds_read_b128 v[164:167], v132
	ds_read_b128 v[168:171], v132 offset:1024
	ds_read_b128 v[172:175], v132 offset:2048
	ds_read_b128 v[176:179], v132 offset:3072
	s_add_u32 s58, s58, 0x40000
	s_addc_u32 s59, s59, 0
	s_mov_b32 m0, s63
	v_lshl_add_u64 v[224:225], s[58:59], 0, v[128:129]
	ds_read_b128 v[180:183], v155 offset:32768
	ds_read_b128 v[184:187], v155 offset:33792
	ds_read_b128 v[188:191], v155 offset:34816
	ds_read_b128 v[192:195], v155 offset:35840
	ds_read_b128 v[196:199], v155 offset:36864
	ds_read_b128 v[200:203], v155 offset:37888
	ds_read_b128 v[210:213], v155 offset:38912
	ds_read_b128 v[214:217], v155 offset:39936
	global_load_lds_dwordx4 v[224:225], off
	v_lshl_add_u64 v[224:225], s[58:59], 0, v[130:131]
	s_mov_b32 m0, s64
	s_nop 0
	global_load_lds_dwordx4 v[224:225], off
	s_waitcnt vmcnt(8)
	s_waitcnt lgkmcnt(0)
	s_barrier
	s_waitcnt lgkmcnt(0)
	v_mfma_f32_16x16x32_bf16 v[124:127], v[142:145], v[180:183], v[124:127]
	v_mfma_f32_16x16x32_bf16 v[120:123], v[156:159], v[180:183], v[120:123]
	v_mfma_f32_16x16x32_bf16 v[108:111], v[142:145], v[188:191], v[108:111]
	v_mfma_f32_16x16x32_bf16 v[104:107], v[156:159], v[188:191], v[104:107]
	v_mfma_f32_16x16x32_bf16 v[92:95], v[142:145], v[196:199], v[92:95]
	v_mfma_f32_16x16x32_bf16 v[88:91], v[156:159], v[196:199], v[88:91]
	v_mfma_f32_16x16x32_bf16 v[76:79], v[142:145], v[210:213], v[76:79]
	v_mfma_f32_16x16x32_bf16 v[72:75], v[156:159], v[210:213], v[72:75]
	v_mfma_f32_16x16x32_bf16 v[124:127], v[146:149], v[184:187], v[124:127]
	v_mfma_f32_16x16x32_bf16 v[120:123], v[160:163], v[184:187], v[120:123]
	v_mfma_f32_16x16x32_bf16 v[108:111], v[146:149], v[192:195], v[108:111]
	v_mfma_f32_16x16x32_bf16 v[104:107], v[160:163], v[192:195], v[104:107]
	v_mfma_f32_16x16x32_bf16 v[92:95], v[146:149], v[200:203], v[92:95]
	v_mfma_f32_16x16x32_bf16 v[88:91], v[160:163], v[200:203], v[88:91]
	v_mfma_f32_16x16x32_bf16 v[76:79], v[146:149], v[214:217], v[76:79]
	v_mfma_f32_16x16x32_bf16 v[72:75], v[160:163], v[214:217], v[72:75]
	v_mfma_f32_16x16x32_bf16 v[116:119], v[164:167], v[180:183], v[116:119]
	v_mfma_f32_16x16x32_bf16 v[112:115], v[172:175], v[180:183], v[112:115]
	v_mfma_f32_16x16x32_bf16 v[100:103], v[164:167], v[188:191], v[100:103]
	v_mfma_f32_16x16x32_bf16 v[96:99], v[172:175], v[188:191], v[96:99]
	v_mfma_f32_16x16x32_bf16 v[84:87], v[164:167], v[196:199], v[84:87]
	v_mfma_f32_16x16x32_bf16 v[80:83], v[172:175], v[196:199], v[80:83]
	v_mfma_f32_16x16x32_bf16 v[68:71], v[164:167], v[210:213], v[68:71]
	v_mfma_f32_16x16x32_bf16 v[64:67], v[172:175], v[210:213], v[64:67]
	v_mfma_f32_16x16x32_bf16 v[116:119], v[168:171], v[184:187], v[116:119]
	v_mfma_f32_16x16x32_bf16 v[112:115], v[176:179], v[184:187], v[112:115]
	v_mfma_f32_16x16x32_bf16 v[100:103], v[168:171], v[192:195], v[100:103]
	v_mfma_f32_16x16x32_bf16 v[96:99], v[176:179], v[192:195], v[96:99]
	v_mfma_f32_16x16x32_bf16 v[84:87], v[168:171], v[200:203], v[84:87]
	v_mfma_f32_16x16x32_bf16 v[80:83], v[176:179], v[200:203], v[80:83]
	v_mfma_f32_16x16x32_bf16 v[68:71], v[168:171], v[214:217], v[68:71]
	v_mfma_f32_16x16x32_bf16 v[64:67], v[176:179], v[214:217], v[64:67]
	s_barrier
	s_add_i32 s58, s82, s61
	v_lshl_add_u64 v[204:205], v[204:205], 0, s[28:29]
	s_mov_b32 m0, s58
	ds_read_b128 v[180:183], v155 offset:49152
	ds_read_b128 v[184:187], v155 offset:50176
	ds_read_b128 v[188:191], v155 offset:51200
	ds_read_b128 v[192:195], v155 offset:52224
	ds_read_b128 v[196:199], v155 offset:53248
	ds_read_b128 v[200:203], v155 offset:54272
	ds_read_b128 v[210:213], v155 offset:55296
	ds_read_b128 v[214:217], v155 offset:56320
	global_load_lds_dwordx4 v[204:205], off
	s_add_i32 m0, s58, 0x2000
	s_add_u32 s56, s56, 0x40080
	v_lshl_add_u64 v[204:205], v[218:219], 0, s[28:29]
	s_addc_u32 s57, s57, 0
	s_add_i32 s58, s83, s61
	global_load_lds_dwordx4 v[204:205], off
	v_lshl_add_u64 v[204:205], s[56:57], 0, v[128:129]
	s_mov_b32 m0, s58
	s_nop 0
	global_load_lds_dwordx4 v[204:205], off
	v_lshl_add_u64 v[204:205], s[56:57], 0, v[130:131]
	s_add_i32 m0, s58, 0x2000
	s_nop 0
	global_load_lds_dwordx4 v[204:205], off
	v_lshl_add_u64 v[204:205], v[220:221], 0, s[28:29]
	s_mov_b32 m0, s66
	s_nop 0
	global_load_lds_dwordx4 v[204:205], off
	v_lshl_add_u64 v[204:205], v[222:223], 0, s[28:29]
	s_mov_b32 m0, s67
	s_nop 0
	global_load_lds_dwordx4 v[204:205], off
	s_waitcnt vmcnt(8)
	s_waitcnt lgkmcnt(0)
	s_barrier
	s_waitcnt lgkmcnt(0)
	v_mfma_f32_16x16x32_bf16 v[60:63], v[142:145], v[180:183], v[60:63]
	v_mfma_f32_16x16x32_bf16 v[56:59], v[156:159], v[180:183], v[56:59]
	v_mfma_f32_16x16x32_bf16 v[44:47], v[142:145], v[188:191], v[44:47]
	v_mfma_f32_16x16x32_bf16 v[40:43], v[156:159], v[188:191], v[40:43]
	v_mfma_f32_16x16x32_bf16 v[28:31], v[142:145], v[196:199], v[28:31]
	v_mfma_f32_16x16x32_bf16 v[24:27], v[156:159], v[196:199], v[24:27]
	v_mfma_f32_16x16x32_bf16 v[12:15], v[142:145], v[210:213], v[12:15]
	v_mfma_f32_16x16x32_bf16 v[8:11], v[156:159], v[210:213], v[8:11]
	v_mfma_f32_16x16x32_bf16 v[60:63], v[146:149], v[184:187], v[60:63]
	v_mfma_f32_16x16x32_bf16 v[56:59], v[160:163], v[184:187], v[56:59]
	v_mfma_f32_16x16x32_bf16 v[44:47], v[146:149], v[192:195], v[44:47]
	v_mfma_f32_16x16x32_bf16 v[40:43], v[160:163], v[192:195], v[40:43]
	v_mfma_f32_16x16x32_bf16 v[28:31], v[146:149], v[200:203], v[28:31]
	v_mfma_f32_16x16x32_bf16 v[24:27], v[160:163], v[200:203], v[24:27]
	v_mfma_f32_16x16x32_bf16 v[12:15], v[146:149], v[214:217], v[12:15]
	v_mfma_f32_16x16x32_bf16 v[8:11], v[160:163], v[214:217], v[8:11]
	v_mfma_f32_16x16x32_bf16 v[52:55], v[164:167], v[180:183], v[52:55]
	v_mfma_f32_16x16x32_bf16 v[48:51], v[172:175], v[180:183], v[48:51]
	v_mfma_f32_16x16x32_bf16 v[36:39], v[164:167], v[188:191], v[36:39]
	v_mfma_f32_16x16x32_bf16 v[32:35], v[172:175], v[188:191], v[32:35]
	v_mfma_f32_16x16x32_bf16 v[20:23], v[164:167], v[196:199], v[20:23]
	v_mfma_f32_16x16x32_bf16 v[16:19], v[172:175], v[196:199], v[16:19]
	v_mfma_f32_16x16x32_bf16 v[4:7], v[164:167], v[210:213], v[4:7]
	v_mfma_f32_16x16x32_bf16 v[0:3], v[172:175], v[210:213], v[0:3]
	v_mfma_f32_16x16x32_bf16 v[52:55], v[168:171], v[184:187], v[52:55]
	v_mfma_f32_16x16x32_bf16 v[48:51], v[176:179], v[184:187], v[48:51]
	v_mfma_f32_16x16x32_bf16 v[36:39], v[168:171], v[192:195], v[36:39]
	v_mfma_f32_16x16x32_bf16 v[32:35], v[176:179], v[192:195], v[32:35]
	v_mfma_f32_16x16x32_bf16 v[20:23], v[168:171], v[200:203], v[20:23]
	v_mfma_f32_16x16x32_bf16 v[16:19], v[176:179], v[200:203], v[16:19]
	v_mfma_f32_16x16x32_bf16 v[4:7], v[168:171], v[214:217], v[4:7]
	v_mfma_f32_16x16x32_bf16 v[0:3], v[176:179], v[214:217], v[0:3]
	s_barrier
	s_add_i32 s81, s81, 2
	s_add_u32 s54, s54, 0x100
	s_addc_u32 s55, s55, 0
	s_add_u32 s79, s79, 0x100
	s_addc_u32 s80, s80, 0
	s_cmp_gt_u32 s81, 13
	s_cbranch_scc0 .LBB0_1283

.LBB0_1406:
	s_ashr_i32 s25, s24, 31
	s_lshl_b64 s[26:27], s[24:25], 19
	s_add_u32 s26, s48, s26
	s_addc_u32 s27, s49, s27
	s_and_b64 s[28:29], s[8:9], exec
	s_cselect_b32 s25, s27, s41
	s_cselect_b32 s65, s26, s40
	s_ashr_i32 s21, s20, 31
	s_lshl_b64 s[28:29], s[20:21], 19
	s_add_u32 s28, s35, s28
	s_addc_u32 s29, s52, s29
	s_and_b64 s[50:51], s[8:9], exec
	s_cselect_b32 s21, s29, s43
	s_cselect_b32 s66, s28, s42
	s_add_u32 s40, s40, 0x40080
	s_addc_u32 s41, s41, 0
	s_add_u32 s67, s42, 0x100
	s_addc_u32 s68, s43, 0
	s_mov_b32 s69, -2
	ds_read_b128 v[154:157], v149
	ds_read_b128 v[158:161], v149 offset:1024
	ds_read_b128 v[162:165], v149 offset:2048
	ds_read_b128 v[166:169], v149 offset:3072
	ds_read_b128 v[170:173], v150
	ds_read_b128 v[174:177], v150 offset:1024
	ds_read_b128 v[178:181], v150 offset:2048
	ds_read_b128 v[182:185], v150 offset:3072
	s_add_u32 s42, s40, 0xfffc0080
	s_addc_u32 s43, s41, -1
	s_cmp_eq_u32 s69, 12
	s_cselect_b32 s51, s25, s43
	s_cselect_b32 s50, s65, s42
	s_cselect_b32 s43, s21, s68
	s_cselect_b32 s42, s66, s67
	v_lshl_add_u64 v[144:145], s[40:41], 0, v[136:137]
	s_add_i32 m0, s31, 0xc000
	ds_read_b128 v[186:189], v151
	ds_read_b128 v[190:193], v151 offset:1024
	ds_read_b128 v[194:197], v151 offset:2048
	ds_read_b128 v[198:201], v151 offset:3072
	ds_read_b128 v[202:205], v151 offset:4096
	ds_read_b128 v[210:213], v151 offset:5120
	ds_read_b128 v[214:217], v151 offset:6144
	ds_read_b128 v[218:221], v151 offset:7168
	global_load_lds_dwordx4 v[144:145], off
	v_lshl_add_u64 v[144:145], s[40:41], 0, v[138:139]
	s_add_i32 m0, s31, 0xe000
	s_nop 0
	global_load_lds_dwordx4 v[144:145], off
	s_waitcnt vmcnt(8)
	s_waitcnt lgkmcnt(0)
	s_barrier
	s_setprio 1
	s_waitcnt lgkmcnt(0)
	v_mfma_f32_16x16x32_bf16 v[116:119], v[154:157], v[186:189], 0
	v_mfma_f32_16x16x32_bf16 v[112:115], v[162:165], v[186:189], 0
	v_mfma_f32_16x16x32_bf16 v[104:107], v[154:157], v[194:197], 0
	v_mfma_f32_16x16x32_bf16 v[100:103], v[162:165], v[194:197], 0
	v_mfma_f32_16x16x32_bf16 v[88:91], v[154:157], v[202:205], 0
	v_mfma_f32_16x16x32_bf16 v[84:87], v[162:165], v[202:205], 0
	v_mfma_f32_16x16x32_bf16 v[72:75], v[154:157], v[214:217], 0
	v_mfma_f32_16x16x32_bf16 v[68:71], v[162:165], v[214:217], 0
	v_mfma_f32_16x16x32_bf16 v[116:119], v[158:161], v[190:193], v[116:119]
	v_mfma_f32_16x16x32_bf16 v[112:115], v[166:169], v[190:193], v[112:115]
	v_mfma_f32_16x16x32_bf16 v[104:107], v[158:161], v[198:201], v[104:107]
	v_mfma_f32_16x16x32_bf16 v[100:103], v[166:169], v[198:201], v[100:103]
	v_mfma_f32_16x16x32_bf16 v[88:91], v[158:161], v[210:213], v[88:91]
	v_mfma_f32_16x16x32_bf16 v[84:87], v[166:169], v[210:213], v[84:87]
	v_mfma_f32_16x16x32_bf16 v[72:75], v[158:161], v[218:221], v[72:75]
	v_mfma_f32_16x16x32_bf16 v[68:71], v[166:169], v[218:221], v[68:71]
	s_setprio 0
	s_setprio 1
	v_mfma_f32_16x16x32_bf16 v[124:127], v[170:173], v[186:189], 0
	v_mfma_f32_16x16x32_bf16 v[120:123], v[178:181], v[186:189], 0
	v_mfma_f32_16x16x32_bf16 v[108:111], v[170:173], v[194:197], 0
	v_mfma_f32_16x16x32_bf16 v[96:99], v[178:181], v[194:197], 0
	v_mfma_f32_16x16x32_bf16 v[92:95], v[170:173], v[202:205], 0
	v_mfma_f32_16x16x32_bf16 v[80:83], v[178:181], v[202:205], 0
	v_mfma_f32_16x16x32_bf16 v[76:79], v[170:173], v[214:217], 0
	v_mfma_f32_16x16x32_bf16 v[64:67], v[178:181], v[214:217], 0
	v_mfma_f32_16x16x32_bf16 v[124:127], v[174:177], v[190:193], v[124:127]
	v_mfma_f32_16x16x32_bf16 v[120:123], v[182:185], v[190:193], v[120:123]
	v_mfma_f32_16x16x32_bf16 v[108:111], v[174:177], v[198:201], v[108:111]
	v_mfma_f32_16x16x32_bf16 v[96:99], v[182:185], v[198:201], v[96:99]
	v_mfma_f32_16x16x32_bf16 v[92:95], v[174:177], v[210:213], v[92:95]
	v_mfma_f32_16x16x32_bf16 v[80:83], v[182:185], v[210:213], v[80:83]
	v_mfma_f32_16x16x32_bf16 v[76:79], v[174:177], v[218:221], v[76:79]
	v_mfma_f32_16x16x32_bf16 v[64:67], v[182:185], v[218:221], v[64:67]
	s_setprio 0
	s_barrier
	s_add_i32 s70, s60, s53
	v_lshl_add_u64 v[144:145], s[42:43], 0, v[130:131]
	s_mov_b32 m0, s70
	ds_read_b128 v[186:189], v151 offset:16384
	ds_read_b128 v[190:193], v151 offset:17408
	ds_read_b128 v[194:197], v151 offset:18432
	ds_read_b128 v[198:201], v151 offset:19456
	ds_read_b128 v[202:205], v151 offset:20480
	ds_read_b128 v[210:213], v151 offset:21504
	ds_read_b128 v[214:217], v151 offset:22528
	ds_read_b128 v[218:221], v151 offset:23552
	global_load_lds_dwordx4 v[144:145], off
	s_add_i32 m0, s70, 0x2000
	s_add_u32 s70, s42, 0x40000
	v_lshl_add_u64 v[222:223], s[42:43], 0, v[134:135]
	s_addc_u32 s71, s43, 0
	s_add_i32 s72, s61, s53
	global_load_lds_dwordx4 v[222:223], off
	v_lshl_add_u64 v[224:225], s[70:71], 0, v[130:131]
	s_mov_b32 m0, s72
	v_lshl_add_u64 v[226:227], s[50:51], 0, v[132:133]
	global_load_lds_dwordx4 v[224:225], off
	v_lshl_add_u64 v[224:225], s[70:71], 0, v[134:135]
	s_add_i32 m0, s72, 0x2000
	s_nop 0
	global_load_lds_dwordx4 v[224:225], off
	v_lshl_add_u64 v[224:225], s[50:51], 0, v[128:129]
	s_mov_b32 m0, s31
	s_nop 0
	global_load_lds_dwordx4 v[224:225], off
	s_mov_b32 m0, s54
	s_nop 0
	global_load_lds_dwordx4 v[226:227], off
	s_waitcnt vmcnt(8)
	s_waitcnt lgkmcnt(0)
	s_barrier
	s_setprio 1
	s_waitcnt lgkmcnt(0)
	v_mfma_f32_16x16x32_bf16 v[56:59], v[154:157], v[186:189], 0
	v_mfma_f32_16x16x32_bf16 v[52:55], v[162:165], v[186:189], 0
	v_mfma_f32_16x16x32_bf16 v[40:43], v[154:157], v[194:197], 0
	v_mfma_f32_16x16x32_bf16 v[36:39], v[162:165], v[194:197], 0
	v_mfma_f32_16x16x32_bf16 v[24:27], v[154:157], v[202:205], 0
	v_mfma_f32_16x16x32_bf16 v[20:23], v[162:165], v[202:205], 0
	v_mfma_f32_16x16x32_bf16 v[8:11], v[154:157], v[214:217], 0
	v_mfma_f32_16x16x32_bf16 v[4:7], v[162:165], v[214:217], 0
	v_mfma_f32_16x16x32_bf16 v[56:59], v[158:161], v[190:193], v[56:59]
	v_mfma_f32_16x16x32_bf16 v[52:55], v[166:169], v[190:193], v[52:55]
	v_mfma_f32_16x16x32_bf16 v[40:43], v[158:161], v[198:201], v[40:43]
	v_mfma_f32_16x16x32_bf16 v[36:39], v[166:169], v[198:201], v[36:39]
	v_mfma_f32_16x16x32_bf16 v[24:27], v[158:161], v[210:213], v[24:27]
	v_mfma_f32_16x16x32_bf16 v[20:23], v[166:169], v[210:213], v[20:23]
	v_mfma_f32_16x16x32_bf16 v[8:11], v[158:161], v[218:221], v[8:11]
	v_mfma_f32_16x16x32_bf16 v[4:7], v[166:169], v[218:221], v[4:7]
	s_setprio 0
	s_setprio 1
	v_mfma_f32_16x16x32_bf16 v[60:63], v[170:173], v[186:189], 0
	v_mfma_f32_16x16x32_bf16 v[48:51], v[178:181], v[186:189], 0
	v_mfma_f32_16x16x32_bf16 v[44:47], v[170:173], v[194:197], 0
	v_mfma_f32_16x16x32_bf16 v[32:35], v[178:181], v[194:197], 0
	v_mfma_f32_16x16x32_bf16 v[28:31], v[170:173], v[202:205], 0
	v_mfma_f32_16x16x32_bf16 v[16:19], v[178:181], v[202:205], 0
	v_mfma_f32_16x16x32_bf16 v[12:15], v[170:173], v[214:217], 0
	v_mfma_f32_16x16x32_bf16 v[0:3], v[178:181], v[214:217], 0
	v_mfma_f32_16x16x32_bf16 v[60:63], v[174:177], v[190:193], v[60:63]
	v_mfma_f32_16x16x32_bf16 v[48:51], v[182:185], v[190:193], v[48:51]
	v_mfma_f32_16x16x32_bf16 v[44:47], v[174:177], v[198:201], v[44:47]
	v_mfma_f32_16x16x32_bf16 v[32:35], v[182:185], v[198:201], v[32:35]
	v_mfma_f32_16x16x32_bf16 v[28:31], v[174:177], v[210:213], v[28:31]
	v_mfma_f32_16x16x32_bf16 v[16:19], v[182:185], v[210:213], v[16:19]
	v_mfma_f32_16x16x32_bf16 v[12:15], v[174:177], v[218:221], v[12:15]
	v_mfma_f32_16x16x32_bf16 v[0:3], v[182:185], v[218:221], v[0:3]
	s_setprio 0
	s_barrier
	s_add_i32 s70, 0, 0x18000
	v_add_u32_e32 v153, s70, v147
	s_add_i32 s71, 0, 0x1c000
	ds_read_b128 v[154:157], v153
	ds_read_b128 v[158:161], v153 offset:1024
	ds_read_b128 v[162:165], v153 offset:2048
	ds_read_b128 v[166:169], v153 offset:3072
	v_add_u32_e32 v153, s71, v147
	ds_read_b128 v[170:173], v153
	ds_read_b128 v[174:177], v153 offset:1024
	ds_read_b128 v[178:181], v153 offset:2048
	ds_read_b128 v[182:185], v153 offset:3072
	s_add_u32 s50, s50, 0x40000
	s_addc_u32 s51, s51, 0
	s_mov_b32 m0, s55
	v_lshl_add_u64 v[228:229], s[50:51], 0, v[128:129]
	ds_read_b128 v[186:189], v151 offset:32768
	ds_read_b128 v[190:193], v151 offset:33792
	ds_read_b128 v[194:197], v151 offset:34816
	ds_read_b128 v[198:201], v151 offset:35840
	ds_read_b128 v[202:205], v151 offset:36864
	ds_read_b128 v[210:213], v151 offset:37888
	ds_read_b128 v[214:217], v151 offset:38912
	ds_read_b128 v[218:221], v151 offset:39936
	global_load_lds_dwordx4 v[228:229], off
	v_lshl_add_u64 v[228:229], s[50:51], 0, v[132:133]
	s_mov_b32 m0, s56
	s_nop 0
	global_load_lds_dwordx4 v[228:229], off
	s_waitcnt vmcnt(8)
	s_waitcnt lgkmcnt(0)
	s_barrier
	s_setprio 1
	s_waitcnt lgkmcnt(0)
	v_mfma_f32_16x16x32_bf16 v[116:119], v[154:157], v[186:189], v[116:119]
	v_mfma_f32_16x16x32_bf16 v[112:115], v[162:165], v[186:189], v[112:115]
	v_mfma_f32_16x16x32_bf16 v[104:107], v[154:157], v[194:197], v[104:107]
	v_mfma_f32_16x16x32_bf16 v[100:103], v[162:165], v[194:197], v[100:103]
	v_mfma_f32_16x16x32_bf16 v[88:91], v[154:157], v[202:205], v[88:91]
	v_mfma_f32_16x16x32_bf16 v[84:87], v[162:165], v[202:205], v[84:87]
	v_mfma_f32_16x16x32_bf16 v[72:75], v[154:157], v[214:217], v[72:75]
	v_mfma_f32_16x16x32_bf16 v[68:71], v[162:165], v[214:217], v[68:71]
	v_mfma_f32_16x16x32_bf16 v[116:119], v[158:161], v[190:193], v[116:119]
	v_mfma_f32_16x16x32_bf16 v[112:115], v[166:169], v[190:193], v[112:115]
	v_mfma_f32_16x16x32_bf16 v[104:107], v[158:161], v[198:201], v[104:107]
	v_mfma_f32_16x16x32_bf16 v[100:103], v[166:169], v[198:201], v[100:103]
	v_mfma_f32_16x16x32_bf16 v[88:91], v[158:161], v[210:213], v[88:91]
	v_mfma_f32_16x16x32_bf16 v[84:87], v[166:169], v[210:213], v[84:87]
	v_mfma_f32_16x16x32_bf16 v[72:75], v[158:161], v[218:221], v[72:75]
	v_mfma_f32_16x16x32_bf16 v[68:71], v[166:169], v[218:221], v[68:71]
	s_setprio 0
	s_setprio 1
	v_mfma_f32_16x16x32_bf16 v[124:127], v[170:173], v[186:189], v[124:127]
	v_mfma_f32_16x16x32_bf16 v[120:123], v[178:181], v[186:189], v[120:123]
	v_mfma_f32_16x16x32_bf16 v[108:111], v[170:173], v[194:197], v[108:111]
	v_mfma_f32_16x16x32_bf16 v[96:99], v[178:181], v[194:197], v[96:99]
	v_mfma_f32_16x16x32_bf16 v[92:95], v[170:173], v[202:205], v[92:95]
	v_mfma_f32_16x16x32_bf16 v[80:83], v[178:181], v[202:205], v[80:83]
	v_mfma_f32_16x16x32_bf16 v[76:79], v[170:173], v[214:217], v[76:79]
	v_mfma_f32_16x16x32_bf16 v[64:67], v[178:181], v[214:217], v[64:67]
	v_mfma_f32_16x16x32_bf16 v[124:127], v[174:177], v[190:193], v[124:127]
	v_mfma_f32_16x16x32_bf16 v[120:123], v[182:185], v[190:193], v[120:123]
	v_mfma_f32_16x16x32_bf16 v[108:111], v[174:177], v[198:201], v[108:111]
	v_mfma_f32_16x16x32_bf16 v[96:99], v[182:185], v[198:201], v[96:99]
	v_mfma_f32_16x16x32_bf16 v[92:95], v[174:177], v[210:213], v[92:95]
	v_mfma_f32_16x16x32_bf16 v[80:83], v[182:185], v[210:213], v[80:83]
	v_mfma_f32_16x16x32_bf16 v[76:79], v[174:177], v[218:221], v[76:79]
	v_mfma_f32_16x16x32_bf16 v[64:67], v[182:185], v[218:221], v[64:67]
	s_setprio 0
	s_barrier
	s_add_i32 s50, s70, s53
	v_lshl_add_u64 v[144:145], v[144:145], 0, s[12:13]
	s_mov_b32 m0, s50
	ds_read_b128 v[186:189], v151 offset:49152
	ds_read_b128 v[190:193], v151 offset:50176
	ds_read_b128 v[194:197], v151 offset:51200
	ds_read_b128 v[198:201], v151 offset:52224
	ds_read_b128 v[202:205], v151 offset:53248
	ds_read_b128 v[210:213], v151 offset:54272
	ds_read_b128 v[214:217], v151 offset:55296
	ds_read_b128 v[218:221], v151 offset:56320
	global_load_lds_dwordx4 v[144:145], off
	s_add_i32 m0, s50, 0x2000
	s_add_u32 s42, s42, 0x40080
	v_lshl_add_u64 v[144:145], v[222:223], 0, s[12:13]
	s_addc_u32 s43, s43, 0
	s_add_i32 s50, s71, s53
	global_load_lds_dwordx4 v[144:145], off
	v_lshl_add_u64 v[144:145], s[42:43], 0, v[130:131]
	s_mov_b32 m0, s50
	s_nop 0
	global_load_lds_dwordx4 v[144:145], off
	v_lshl_add_u64 v[144:145], s[42:43], 0, v[134:135]
	s_add_i32 m0, s50, 0x2000
	s_nop 0
	global_load_lds_dwordx4 v[144:145], off
	v_lshl_add_u64 v[144:145], v[224:225], 0, s[12:13]
	s_mov_b32 m0, s58
	s_nop 0
	global_load_lds_dwordx4 v[144:145], off
	v_lshl_add_u64 v[144:145], v[226:227], 0, s[12:13]
	s_mov_b32 m0, s59
	s_nop 0
	global_load_lds_dwordx4 v[144:145], off
	s_waitcnt vmcnt(8)
	s_waitcnt lgkmcnt(0)
	s_barrier
	s_setprio 1
	s_waitcnt lgkmcnt(0)
	v_mfma_f32_16x16x32_bf16 v[56:59], v[154:157], v[186:189], v[56:59]
	v_mfma_f32_16x16x32_bf16 v[52:55], v[162:165], v[186:189], v[52:55]
	v_mfma_f32_16x16x32_bf16 v[40:43], v[154:157], v[194:197], v[40:43]
	v_mfma_f32_16x16x32_bf16 v[36:39], v[162:165], v[194:197], v[36:39]
	v_mfma_f32_16x16x32_bf16 v[24:27], v[154:157], v[202:205], v[24:27]
	v_mfma_f32_16x16x32_bf16 v[20:23], v[162:165], v[202:205], v[20:23]
	v_mfma_f32_16x16x32_bf16 v[8:11], v[154:157], v[214:217], v[8:11]
	v_mfma_f32_16x16x32_bf16 v[4:7], v[162:165], v[214:217], v[4:7]
	v_mfma_f32_16x16x32_bf16 v[56:59], v[158:161], v[190:193], v[56:59]
	v_mfma_f32_16x16x32_bf16 v[52:55], v[166:169], v[190:193], v[52:55]
	v_mfma_f32_16x16x32_bf16 v[40:43], v[158:161], v[198:201], v[40:43]
	v_mfma_f32_16x16x32_bf16 v[36:39], v[166:169], v[198:201], v[36:39]
	v_mfma_f32_16x16x32_bf16 v[24:27], v[158:161], v[210:213], v[24:27]
	v_mfma_f32_16x16x32_bf16 v[20:23], v[166:169], v[210:213], v[20:23]
	v_mfma_f32_16x16x32_bf16 v[8:11], v[158:161], v[218:221], v[8:11]
	v_mfma_f32_16x16x32_bf16 v[4:7], v[166:169], v[218:221], v[4:7]
	s_setprio 0
	s_setprio 1
	v_mfma_f32_16x16x32_bf16 v[60:63], v[170:173], v[186:189], v[60:63]
	v_mfma_f32_16x16x32_bf16 v[48:51], v[178:181], v[186:189], v[48:51]
	v_mfma_f32_16x16x32_bf16 v[44:47], v[170:173], v[194:197], v[44:47]
	v_mfma_f32_16x16x32_bf16 v[32:35], v[178:181], v[194:197], v[32:35]
	v_mfma_f32_16x16x32_bf16 v[28:31], v[170:173], v[202:205], v[28:31]
	v_mfma_f32_16x16x32_bf16 v[16:19], v[178:181], v[202:205], v[16:19]
	v_mfma_f32_16x16x32_bf16 v[12:15], v[170:173], v[214:217], v[12:15]
	v_mfma_f32_16x16x32_bf16 v[0:3], v[178:181], v[214:217], v[0:3]
	v_mfma_f32_16x16x32_bf16 v[60:63], v[174:177], v[190:193], v[60:63]
	v_mfma_f32_16x16x32_bf16 v[48:51], v[182:185], v[190:193], v[48:51]
	v_mfma_f32_16x16x32_bf16 v[44:47], v[174:177], v[198:201], v[44:47]
	v_mfma_f32_16x16x32_bf16 v[32:35], v[182:185], v[198:201], v[32:35]
	v_mfma_f32_16x16x32_bf16 v[28:31], v[174:177], v[210:213], v[28:31]
	v_mfma_f32_16x16x32_bf16 v[16:19], v[182:185], v[210:213], v[16:19]
	v_mfma_f32_16x16x32_bf16 v[12:15], v[174:177], v[218:221], v[12:15]
	v_mfma_f32_16x16x32_bf16 v[0:3], v[182:185], v[218:221], v[0:3]
	s_setprio 0
	s_barrier
	s_add_i32 s69, s69, 2
	s_add_u32 s40, s40, 0x100
	s_addc_u32 s41, s41, 0
	s_add_u32 s67, s67, 0x100
	s_addc_u32 s68, s68, 0
	s_cmp_gt_u32 s69, 13
	s_cbranch_scc1 .Lpeel_done_40429
.LBB0_1407:
	ds_read_b128 v[154:157], v149
	ds_read_b128 v[158:161], v149 offset:1024
	ds_read_b128 v[162:165], v149 offset:2048
	ds_read_b128 v[166:169], v149 offset:3072
	ds_read_b128 v[170:173], v150
	ds_read_b128 v[174:177], v150 offset:1024
	ds_read_b128 v[178:181], v150 offset:2048
	ds_read_b128 v[182:185], v150 offset:3072
	s_add_u32 s42, s40, 0xfffc0080
	s_addc_u32 s43, s41, -1
	s_cmp_eq_u32 s69, 12
	s_cselect_b32 s51, s25, s43
	s_cselect_b32 s50, s65, s42
	s_cselect_b32 s43, s21, s68
	s_cselect_b32 s42, s66, s67
	v_lshl_add_u64 v[144:145], s[40:41], 0, v[136:137]
	s_add_i32 m0, s31, 0xc000
	ds_read_b128 v[186:189], v151
	ds_read_b128 v[190:193], v151 offset:1024
	ds_read_b128 v[194:197], v151 offset:2048
	ds_read_b128 v[198:201], v151 offset:3072
	ds_read_b128 v[202:205], v151 offset:4096
	ds_read_b128 v[210:213], v151 offset:5120
	ds_read_b128 v[214:217], v151 offset:6144
	ds_read_b128 v[218:221], v151 offset:7168
	global_load_lds_dwordx4 v[144:145], off
	v_lshl_add_u64 v[144:145], s[40:41], 0, v[138:139]
	s_add_i32 m0, s31, 0xe000
	s_nop 0
	global_load_lds_dwordx4 v[144:145], off
	s_waitcnt vmcnt(8)
	s_waitcnt lgkmcnt(0)
	s_barrier
	s_waitcnt lgkmcnt(0)
	v_mfma_f32_16x16x32_bf16 v[116:119], v[154:157], v[186:189], v[116:119]
	v_mfma_f32_16x16x32_bf16 v[112:115], v[162:165], v[186:189], v[112:115]
	v_mfma_f32_16x16x32_bf16 v[104:107], v[154:157], v[194:197], v[104:107]
	v_mfma_f32_16x16x32_bf16 v[100:103], v[162:165], v[194:197], v[100:103]
	v_mfma_f32_16x16x32_bf16 v[88:91], v[154:157], v[202:205], v[88:91]
	v_mfma_f32_16x16x32_bf16 v[84:87], v[162:165], v[202:205], v[84:87]
	v_mfma_f32_16x16x32_bf16 v[72:75], v[154:157], v[214:217], v[72:75]
	v_mfma_f32_16x16x32_bf16 v[68:71], v[162:165], v[214:217], v[68:71]
	v_mfma_f32_16x16x32_bf16 v[116:119], v[158:161], v[190:193], v[116:119]
	v_mfma_f32_16x16x32_bf16 v[112:115], v[166:169], v[190:193], v[112:115]
	v_mfma_f32_16x16x32_bf16 v[104:107], v[158:161], v[198:201], v[104:107]
	v_mfma_f32_16x16x32_bf16 v[100:103], v[166:169], v[198:201], v[100:103]
	v_mfma_f32_16x16x32_bf16 v[88:91], v[158:161], v[210:213], v[88:91]
	v_mfma_f32_16x16x32_bf16 v[84:87], v[166:169], v[210:213], v[84:87]
	v_mfma_f32_16x16x32_bf16 v[72:75], v[158:161], v[218:221], v[72:75]
	v_mfma_f32_16x16x32_bf16 v[68:71], v[166:169], v[218:221], v[68:71]
	v_mfma_f32_16x16x32_bf16 v[124:127], v[170:173], v[186:189], v[124:127]
	v_mfma_f32_16x16x32_bf16 v[120:123], v[178:181], v[186:189], v[120:123]
	v_mfma_f32_16x16x32_bf16 v[108:111], v[170:173], v[194:197], v[108:111]
	v_mfma_f32_16x16x32_bf16 v[96:99], v[178:181], v[194:197], v[96:99]
	v_mfma_f32_16x16x32_bf16 v[92:95], v[170:173], v[202:205], v[92:95]
	v_mfma_f32_16x16x32_bf16 v[80:83], v[178:181], v[202:205], v[80:83]
	v_mfma_f32_16x16x32_bf16 v[76:79], v[170:173], v[214:217], v[76:79]
	v_mfma_f32_16x16x32_bf16 v[64:67], v[178:181], v[214:217], v[64:67]
	v_mfma_f32_16x16x32_bf16 v[124:127], v[174:177], v[190:193], v[124:127]
	v_mfma_f32_16x16x32_bf16 v[120:123], v[182:185], v[190:193], v[120:123]
	v_mfma_f32_16x16x32_bf16 v[108:111], v[174:177], v[198:201], v[108:111]
	v_mfma_f32_16x16x32_bf16 v[96:99], v[182:185], v[198:201], v[96:99]
	v_mfma_f32_16x16x32_bf16 v[92:95], v[174:177], v[210:213], v[92:95]
	v_mfma_f32_16x16x32_bf16 v[80:83], v[182:185], v[210:213], v[80:83]
	v_mfma_f32_16x16x32_bf16 v[76:79], v[174:177], v[218:221], v[76:79]
	v_mfma_f32_16x16x32_bf16 v[64:67], v[182:185], v[218:221], v[64:67]
	s_barrier
	s_add_i32 s70, s60, s53
	v_lshl_add_u64 v[144:145], s[42:43], 0, v[130:131]
	s_mov_b32 m0, s70
	ds_read_b128 v[186:189], v151 offset:16384
	ds_read_b128 v[190:193], v151 offset:17408
	ds_read_b128 v[194:197], v151 offset:18432
	ds_read_b128 v[198:201], v151 offset:19456
	ds_read_b128 v[202:205], v151 offset:20480
	ds_read_b128 v[210:213], v151 offset:21504
	ds_read_b128 v[214:217], v151 offset:22528
	ds_read_b128 v[218:221], v151 offset:23552
	global_load_lds_dwordx4 v[144:145], off
	s_add_i32 m0, s70, 0x2000
	s_add_u32 s70, s42, 0x40000
	v_lshl_add_u64 v[222:223], s[42:43], 0, v[134:135]
	s_addc_u32 s71, s43, 0
	s_add_i32 s72, s61, s53
	global_load_lds_dwordx4 v[222:223], off
	v_lshl_add_u64 v[224:225], s[70:71], 0, v[130:131]
	s_mov_b32 m0, s72
	v_lshl_add_u64 v[226:227], s[50:51], 0, v[132:133]
	global_load_lds_dwordx4 v[224:225], off
	v_lshl_add_u64 v[224:225], s[70:71], 0, v[134:135]
	s_add_i32 m0, s72, 0x2000
	s_nop 0
	global_load_lds_dwordx4 v[224:225], off
	v_lshl_add_u64 v[224:225], s[50:51], 0, v[128:129]
	s_mov_b32 m0, s31
	s_nop 0
	global_load_lds_dwordx4 v[224:225], off
	s_mov_b32 m0, s54
	s_nop 0
	global_load_lds_dwordx4 v[226:227], off
	s_waitcnt vmcnt(8)
	s_waitcnt lgkmcnt(0)
	s_barrier
	s_waitcnt lgkmcnt(0)
	v_mfma_f32_16x16x32_bf16 v[56:59], v[154:157], v[186:189], v[56:59]
	v_mfma_f32_16x16x32_bf16 v[52:55], v[162:165], v[186:189], v[52:55]
	v_mfma_f32_16x16x32_bf16 v[40:43], v[154:157], v[194:197], v[40:43]
	v_mfma_f32_16x16x32_bf16 v[36:39], v[162:165], v[194:197], v[36:39]
	v_mfma_f32_16x16x32_bf16 v[24:27], v[154:157], v[202:205], v[24:27]
	v_mfma_f32_16x16x32_bf16 v[20:23], v[162:165], v[202:205], v[20:23]
	v_mfma_f32_16x16x32_bf16 v[8:11], v[154:157], v[214:217], v[8:11]
	v_mfma_f32_16x16x32_bf16 v[4:7], v[162:165], v[214:217], v[4:7]
	v_mfma_f32_16x16x32_bf16 v[56:59], v[158:161], v[190:193], v[56:59]
	v_mfma_f32_16x16x32_bf16 v[52:55], v[166:169], v[190:193], v[52:55]
	v_mfma_f32_16x16x32_bf16 v[40:43], v[158:161], v[198:201], v[40:43]
	v_mfma_f32_16x16x32_bf16 v[36:39], v[166:169], v[198:201], v[36:39]
	v_mfma_f32_16x16x32_bf16 v[24:27], v[158:161], v[210:213], v[24:27]
	v_mfma_f32_16x16x32_bf16 v[20:23], v[166:169], v[210:213], v[20:23]
	v_mfma_f32_16x16x32_bf16 v[8:11], v[158:161], v[218:221], v[8:11]
	v_mfma_f32_16x16x32_bf16 v[4:7], v[166:169], v[218:221], v[4:7]
	v_mfma_f32_16x16x32_bf16 v[60:63], v[170:173], v[186:189], v[60:63]
	v_mfma_f32_16x16x32_bf16 v[48:51], v[178:181], v[186:189], v[48:51]
	v_mfma_f32_16x16x32_bf16 v[44:47], v[170:173], v[194:197], v[44:47]
	v_mfma_f32_16x16x32_bf16 v[32:35], v[178:181], v[194:197], v[32:35]
	v_mfma_f32_16x16x32_bf16 v[28:31], v[170:173], v[202:205], v[28:31]
	v_mfma_f32_16x16x32_bf16 v[16:19], v[178:181], v[202:205], v[16:19]
	v_mfma_f32_16x16x32_bf16 v[12:15], v[170:173], v[214:217], v[12:15]
	v_mfma_f32_16x16x32_bf16 v[0:3], v[178:181], v[214:217], v[0:3]
	v_mfma_f32_16x16x32_bf16 v[60:63], v[174:177], v[190:193], v[60:63]
	v_mfma_f32_16x16x32_bf16 v[48:51], v[182:185], v[190:193], v[48:51]
	v_mfma_f32_16x16x32_bf16 v[44:47], v[174:177], v[198:201], v[44:47]
	v_mfma_f32_16x16x32_bf16 v[32:35], v[182:185], v[198:201], v[32:35]
	v_mfma_f32_16x16x32_bf16 v[28:31], v[174:177], v[210:213], v[28:31]
	v_mfma_f32_16x16x32_bf16 v[16:19], v[182:185], v[210:213], v[16:19]
	v_mfma_f32_16x16x32_bf16 v[12:15], v[174:177], v[218:221], v[12:15]
	v_mfma_f32_16x16x32_bf16 v[0:3], v[182:185], v[218:221], v[0:3]
	s_barrier
	s_add_i32 s70, 0, 0x18000
	v_add_u32_e32 v153, s70, v147
	s_add_i32 s71, 0, 0x1c000
	ds_read_b128 v[154:157], v153
	ds_read_b128 v[158:161], v153 offset:1024
	ds_read_b128 v[162:165], v153 offset:2048
	ds_read_b128 v[166:169], v153 offset:3072
	v_add_u32_e32 v153, s71, v147
	ds_read_b128 v[170:173], v153
	ds_read_b128 v[174:177], v153 offset:1024
	ds_read_b128 v[178:181], v153 offset:2048
	ds_read_b128 v[182:185], v153 offset:3072
	s_add_u32 s50, s50, 0x40000
	s_addc_u32 s51, s51, 0
	s_mov_b32 m0, s55
	v_lshl_add_u64 v[228:229], s[50:51], 0, v[128:129]
	ds_read_b128 v[186:189], v151 offset:32768
	ds_read_b128 v[190:193], v151 offset:33792
	ds_read_b128 v[194:197], v151 offset:34816
	ds_read_b128 v[198:201], v151 offset:35840
	ds_read_b128 v[202:205], v151 offset:36864
	ds_read_b128 v[210:213], v151 offset:37888
	ds_read_b128 v[214:217], v151 offset:38912
	ds_read_b128 v[218:221], v151 offset:39936
	global_load_lds_dwordx4 v[228:229], off
	v_lshl_add_u64 v[228:229], s[50:51], 0, v[132:133]
	s_mov_b32 m0, s56
	s_nop 0
	global_load_lds_dwordx4 v[228:229], off
	s_waitcnt vmcnt(8)
	s_waitcnt lgkmcnt(0)
	s_barrier
	s_waitcnt lgkmcnt(0)
	v_mfma_f32_16x16x32_bf16 v[116:119], v[154:157], v[186:189], v[116:119]
	v_mfma_f32_16x16x32_bf16 v[112:115], v[162:165], v[186:189], v[112:115]
	v_mfma_f32_16x16x32_bf16 v[104:107], v[154:157], v[194:197], v[104:107]
	v_mfma_f32_16x16x32_bf16 v[100:103], v[162:165], v[194:197], v[100:103]
	v_mfma_f32_16x16x32_bf16 v[88:91], v[154:157], v[202:205], v[88:91]
	v_mfma_f32_16x16x32_bf16 v[84:87], v[162:165], v[202:205], v[84:87]
	v_mfma_f32_16x16x32_bf16 v[72:75], v[154:157], v[214:217], v[72:75]
	v_mfma_f32_16x16x32_bf16 v[68:71], v[162:165], v[214:217], v[68:71]
	v_mfma_f32_16x16x32_bf16 v[116:119], v[158:161], v[190:193], v[116:119]
	v_mfma_f32_16x16x32_bf16 v[112:115], v[166:169], v[190:193], v[112:115]
	v_mfma_f32_16x16x32_bf16 v[104:107], v[158:161], v[198:201], v[104:107]
	v_mfma_f32_16x16x32_bf16 v[100:103], v[166:169], v[198:201], v[100:103]
	v_mfma_f32_16x16x32_bf16 v[88:91], v[158:161], v[210:213], v[88:91]
	v_mfma_f32_16x16x32_bf16 v[84:87], v[166:169], v[210:213], v[84:87]
	v_mfma_f32_16x16x32_bf16 v[72:75], v[158:161], v[218:221], v[72:75]
	v_mfma_f32_16x16x32_bf16 v[68:71], v[166:169], v[218:221], v[68:71]
	v_mfma_f32_16x16x32_bf16 v[124:127], v[170:173], v[186:189], v[124:127]
	v_mfma_f32_16x16x32_bf16 v[120:123], v[178:181], v[186:189], v[120:123]
	v_mfma_f32_16x16x32_bf16 v[108:111], v[170:173], v[194:197], v[108:111]
	v_mfma_f32_16x16x32_bf16 v[96:99], v[178:181], v[194:197], v[96:99]
	v_mfma_f32_16x16x32_bf16 v[92:95], v[170:173], v[202:205], v[92:95]
	v_mfma_f32_16x16x32_bf16 v[80:83], v[178:181], v[202:205], v[80:83]
	v_mfma_f32_16x16x32_bf16 v[76:79], v[170:173], v[214:217], v[76:79]
	v_mfma_f32_16x16x32_bf16 v[64:67], v[178:181], v[214:217], v[64:67]
	v_mfma_f32_16x16x32_bf16 v[124:127], v[174:177], v[190:193], v[124:127]
	v_mfma_f32_16x16x32_bf16 v[120:123], v[182:185], v[190:193], v[120:123]
	v_mfma_f32_16x16x32_bf16 v[108:111], v[174:177], v[198:201], v[108:111]
	v_mfma_f32_16x16x32_bf16 v[96:99], v[182:185], v[198:201], v[96:99]
	v_mfma_f32_16x16x32_bf16 v[92:95], v[174:177], v[210:213], v[92:95]
	v_mfma_f32_16x16x32_bf16 v[80:83], v[182:185], v[210:213], v[80:83]
	v_mfma_f32_16x16x32_bf16 v[76:79], v[174:177], v[218:221], v[76:79]
	v_mfma_f32_16x16x32_bf16 v[64:67], v[182:185], v[218:221], v[64:67]
	s_barrier
	s_add_i32 s50, s70, s53
	v_lshl_add_u64 v[144:145], v[144:145], 0, s[12:13]
	s_mov_b32 m0, s50
	ds_read_b128 v[186:189], v151 offset:49152
	ds_read_b128 v[190:193], v151 offset:50176
	ds_read_b128 v[194:197], v151 offset:51200
	ds_read_b128 v[198:201], v151 offset:52224
	ds_read_b128 v[202:205], v151 offset:53248
	ds_read_b128 v[210:213], v151 offset:54272
	ds_read_b128 v[214:217], v151 offset:55296
	ds_read_b128 v[218:221], v151 offset:56320
	global_load_lds_dwordx4 v[144:145], off
	s_add_i32 m0, s50, 0x2000
	s_add_u32 s42, s42, 0x40080
	v_lshl_add_u64 v[144:145], v[222:223], 0, s[12:13]
	s_addc_u32 s43, s43, 0
	s_add_i32 s50, s71, s53
	global_load_lds_dwordx4 v[144:145], off
	v_lshl_add_u64 v[144:145], s[42:43], 0, v[130:131]
	s_mov_b32 m0, s50
	s_nop 0
	global_load_lds_dwordx4 v[144:145], off
	v_lshl_add_u64 v[144:145], s[42:43], 0, v[134:135]
	s_add_i32 m0, s50, 0x2000
	s_nop 0
	global_load_lds_dwordx4 v[144:145], off
	v_lshl_add_u64 v[144:145], v[224:225], 0, s[12:13]
	s_mov_b32 m0, s58
	s_nop 0
	global_load_lds_dwordx4 v[144:145], off
	v_lshl_add_u64 v[144:145], v[226:227], 0, s[12:13]
	s_mov_b32 m0, s59
	s_nop 0
	global_load_lds_dwordx4 v[144:145], off
	s_waitcnt vmcnt(8)
	s_waitcnt lgkmcnt(0)
	s_barrier
	s_waitcnt lgkmcnt(0)
	v_mfma_f32_16x16x32_bf16 v[56:59], v[154:157], v[186:189], v[56:59]
	v_mfma_f32_16x16x32_bf16 v[52:55], v[162:165], v[186:189], v[52:55]
	v_mfma_f32_16x16x32_bf16 v[40:43], v[154:157], v[194:197], v[40:43]
	v_mfma_f32_16x16x32_bf16 v[36:39], v[162:165], v[194:197], v[36:39]
	v_mfma_f32_16x16x32_bf16 v[24:27], v[154:157], v[202:205], v[24:27]
	v_mfma_f32_16x16x32_bf16 v[20:23], v[162:165], v[202:205], v[20:23]
	v_mfma_f32_16x16x32_bf16 v[8:11], v[154:157], v[214:217], v[8:11]
	v_mfma_f32_16x16x32_bf16 v[4:7], v[162:165], v[214:217], v[4:7]
	v_mfma_f32_16x16x32_bf16 v[56:59], v[158:161], v[190:193], v[56:59]
	v_mfma_f32_16x16x32_bf16 v[52:55], v[166:169], v[190:193], v[52:55]
	v_mfma_f32_16x16x32_bf16 v[40:43], v[158:161], v[198:201], v[40:43]
	v_mfma_f32_16x16x32_bf16 v[36:39], v[166:169], v[198:201], v[36:39]
	v_mfma_f32_16x16x32_bf16 v[24:27], v[158:161], v[210:213], v[24:27]
	v_mfma_f32_16x16x32_bf16 v[20:23], v[166:169], v[210:213], v[20:23]
	v_mfma_f32_16x16x32_bf16 v[8:11], v[158:161], v[218:221], v[8:11]
	v_mfma_f32_16x16x32_bf16 v[4:7], v[166:169], v[218:221], v[4:7]
	v_mfma_f32_16x16x32_bf16 v[60:63], v[170:173], v[186:189], v[60:63]
	v_mfma_f32_16x16x32_bf16 v[48:51], v[178:181], v[186:189], v[48:51]
	v_mfma_f32_16x16x32_bf16 v[44:47], v[170:173], v[194:197], v[44:47]
	v_mfma_f32_16x16x32_bf16 v[32:35], v[178:181], v[194:197], v[32:35]
	v_mfma_f32_16x16x32_bf16 v[28:31], v[170:173], v[202:205], v[28:31]
	v_mfma_f32_16x16x32_bf16 v[16:19], v[178:181], v[202:205], v[16:19]
	v_mfma_f32_16x16x32_bf16 v[12:15], v[170:173], v[214:217], v[12:15]
	v_mfma_f32_16x16x32_bf16 v[0:3], v[178:181], v[214:217], v[0:3]
	v_mfma_f32_16x16x32_bf16 v[60:63], v[174:177], v[190:193], v[60:63]
	v_mfma_f32_16x16x32_bf16 v[48:51], v[182:185], v[190:193], v[48:51]
	v_mfma_f32_16x16x32_bf16 v[44:47], v[174:177], v[198:201], v[44:47]
	v_mfma_f32_16x16x32_bf16 v[32:35], v[182:185], v[198:201], v[32:35]
	v_mfma_f32_16x16x32_bf16 v[28:31], v[174:177], v[210:213], v[28:31]
	v_mfma_f32_16x16x32_bf16 v[16:19], v[182:185], v[210:213], v[16:19]
	v_mfma_f32_16x16x32_bf16 v[12:15], v[174:177], v[218:221], v[12:15]
	v_mfma_f32_16x16x32_bf16 v[0:3], v[182:185], v[218:221], v[0:3]
	s_barrier
	s_add_i32 s69, s69, 2
	s_add_u32 s40, s40, 0x100
	s_addc_u32 s41, s41, 0
	s_add_u32 s67, s67, 0x100
	s_addc_u32 s68, s68, 0
	s_cmp_gt_u32 s69, 13
	s_cbranch_scc0 .LBB0_1407
.Lpeel_done_40429:
	s_and_b64 vcc, exec, s[14:15]
	s_cbranch_vccz .LBB0_1410
	s_barrier

.LBB0_1488:
	s_add_u32 s68, s30, 0x100
	s_addc_u32 s69, s31, 0
	s_mov_b32 s70, -2
	s_waitcnt lgkmcnt(0)
	ds_read_b128 v[142:145], v153
	ds_read_b128 v[146:149], v153 offset:1024
	ds_read_b128 v[156:159], v153 offset:2048
	ds_read_b128 v[160:163], v153 offset:3072
	ds_read_b128 v[164:167], v154
	ds_read_b128 v[168:171], v154 offset:1024
	ds_read_b128 v[172:175], v154 offset:2048
	ds_read_b128 v[176:179], v154 offset:3072
	s_add_u32 s30, s28, 0x100
	s_addc_u32 s31, s29, 0
	s_cmp_eq_u32 s70, 40
	s_cselect_b32 s43, s11, s31
	s_cselect_b32 s42, s10, s30
	s_cselect_b32 s41, s27, s69
	s_cselect_b32 s40, s26, s68
	v_lshl_add_u64 v[204:205], s[28:29], 0, v[134:135]
	s_add_i32 m0, s51, 0xc000
	ds_read_b128 v[180:183], v155
	ds_read_b128 v[184:187], v155 offset:1024
	ds_read_b128 v[188:191], v155 offset:2048
	ds_read_b128 v[192:195], v155 offset:3072
	ds_read_b128 v[196:199], v155 offset:4096
	ds_read_b128 v[200:203], v155 offset:5120
	ds_read_b128 v[210:213], v155 offset:6144
	ds_read_b128 v[214:217], v155 offset:7168
	global_load_lds_dwordx4 v[204:205], off
	v_lshl_add_u64 v[204:205], s[28:29], 0, v[136:137]
	s_add_i32 m0, s51, 0xe000
	s_nop 0
	global_load_lds_dwordx4 v[204:205], off
	s_waitcnt vmcnt(8)
	s_waitcnt lgkmcnt(0)
	s_barrier
	s_setprio 1
	s_waitcnt lgkmcnt(0)
	v_mfma_f32_16x16x32_bf16 v[124:127], v[142:145], v[180:183], 0
	v_mfma_f32_16x16x32_bf16 v[120:123], v[156:159], v[180:183], 0
	v_mfma_f32_16x16x32_bf16 v[108:111], v[142:145], v[188:191], 0
	v_mfma_f32_16x16x32_bf16 v[104:107], v[156:159], v[188:191], 0
	v_mfma_f32_16x16x32_bf16 v[92:95], v[142:145], v[196:199], 0
	v_mfma_f32_16x16x32_bf16 v[88:91], v[156:159], v[196:199], 0
	v_mfma_f32_16x16x32_bf16 v[76:79], v[142:145], v[210:213], 0
	v_mfma_f32_16x16x32_bf16 v[72:75], v[156:159], v[210:213], 0
	v_mfma_f32_16x16x32_bf16 v[124:127], v[146:149], v[184:187], v[124:127]
	v_mfma_f32_16x16x32_bf16 v[120:123], v[160:163], v[184:187], v[120:123]
	v_mfma_f32_16x16x32_bf16 v[108:111], v[146:149], v[192:195], v[108:111]
	v_mfma_f32_16x16x32_bf16 v[104:107], v[160:163], v[192:195], v[104:107]
	v_mfma_f32_16x16x32_bf16 v[92:95], v[146:149], v[200:203], v[92:95]
	v_mfma_f32_16x16x32_bf16 v[88:91], v[160:163], v[200:203], v[88:91]
	v_mfma_f32_16x16x32_bf16 v[76:79], v[146:149], v[214:217], v[76:79]
	v_mfma_f32_16x16x32_bf16 v[72:75], v[160:163], v[214:217], v[72:75]
	s_setprio 0
	s_setprio 1
	v_mfma_f32_16x16x32_bf16 v[116:119], v[164:167], v[180:183], 0
	v_mfma_f32_16x16x32_bf16 v[112:115], v[172:175], v[180:183], 0
	v_mfma_f32_16x16x32_bf16 v[100:103], v[164:167], v[188:191], 0
	v_mfma_f32_16x16x32_bf16 v[96:99], v[172:175], v[188:191], 0
	v_mfma_f32_16x16x32_bf16 v[84:87], v[164:167], v[196:199], 0
	v_mfma_f32_16x16x32_bf16 v[80:83], v[172:175], v[196:199], 0
	v_mfma_f32_16x16x32_bf16 v[68:71], v[164:167], v[210:213], 0
	v_mfma_f32_16x16x32_bf16 v[64:67], v[172:175], v[210:213], 0
	v_mfma_f32_16x16x32_bf16 v[116:119], v[168:171], v[184:187], v[116:119]
	v_mfma_f32_16x16x32_bf16 v[112:115], v[176:179], v[184:187], v[112:115]
	v_mfma_f32_16x16x32_bf16 v[100:103], v[168:171], v[192:195], v[100:103]
	v_mfma_f32_16x16x32_bf16 v[96:99], v[176:179], v[192:195], v[96:99]
	v_mfma_f32_16x16x32_bf16 v[84:87], v[168:171], v[200:203], v[84:87]
	v_mfma_f32_16x16x32_bf16 v[80:83], v[176:179], v[200:203], v[80:83]
	v_mfma_f32_16x16x32_bf16 v[68:71], v[168:171], v[214:217], v[68:71]
	v_mfma_f32_16x16x32_bf16 v[64:67], v[176:179], v[214:217], v[64:67]
	s_setprio 0
	s_barrier
	s_add_i32 s28, s58, s50
	v_lshl_add_u64 v[204:205], s[40:41], 0, v[128:129]
	s_mov_b32 m0, s28
	ds_read_b128 v[180:183], v155 offset:16384
	ds_read_b128 v[184:187], v155 offset:17408
	ds_read_b128 v[188:191], v155 offset:18432
	ds_read_b128 v[192:195], v155 offset:19456
	ds_read_b128 v[196:199], v155 offset:20480
	ds_read_b128 v[200:203], v155 offset:21504
	ds_read_b128 v[210:213], v155 offset:22528
	ds_read_b128 v[214:217], v155 offset:23552
	global_load_lds_dwordx4 v[204:205], off
	s_add_i32 m0, s28, 0x2000
	s_add_u32 s28, s40, 0xb0000
	v_lshl_add_u64 v[218:219], s[40:41], 0, v[130:131]
	s_addc_u32 s29, s41, 0
	s_add_i32 s71, s59, s50
	global_load_lds_dwordx4 v[218:219], off
	v_lshl_add_u64 v[220:221], s[28:29], 0, v[128:129]
	s_mov_b32 m0, s71
	v_lshl_add_u64 v[222:223], s[42:43], 0, v[130:131]
	global_load_lds_dwordx4 v[220:221], off
	v_lshl_add_u64 v[220:221], s[28:29], 0, v[130:131]
	s_add_i32 m0, s71, 0x2000
	s_nop 0
	global_load_lds_dwordx4 v[220:221], off
	v_lshl_add_u64 v[220:221], s[42:43], 0, v[128:129]
	s_mov_b32 m0, s51
	s_nop 0
	global_load_lds_dwordx4 v[220:221], off
	s_mov_b32 m0, s52
	s_nop 0
	global_load_lds_dwordx4 v[222:223], off
	s_waitcnt vmcnt(8)
	s_waitcnt lgkmcnt(0)
	s_barrier
	s_setprio 1
	s_waitcnt lgkmcnt(0)
	v_mfma_f32_16x16x32_bf16 v[60:63], v[142:145], v[180:183], 0
	v_mfma_f32_16x16x32_bf16 v[56:59], v[156:159], v[180:183], 0
	v_mfma_f32_16x16x32_bf16 v[44:47], v[142:145], v[188:191], 0
	v_mfma_f32_16x16x32_bf16 v[40:43], v[156:159], v[188:191], 0
	v_mfma_f32_16x16x32_bf16 v[28:31], v[142:145], v[196:199], 0
	v_mfma_f32_16x16x32_bf16 v[24:27], v[156:159], v[196:199], 0
	v_mfma_f32_16x16x32_bf16 v[12:15], v[142:145], v[210:213], 0
	v_mfma_f32_16x16x32_bf16 v[8:11], v[156:159], v[210:213], 0
	v_mfma_f32_16x16x32_bf16 v[60:63], v[146:149], v[184:187], v[60:63]
	v_mfma_f32_16x16x32_bf16 v[56:59], v[160:163], v[184:187], v[56:59]
	v_mfma_f32_16x16x32_bf16 v[44:47], v[146:149], v[192:195], v[44:47]
	v_mfma_f32_16x16x32_bf16 v[40:43], v[160:163], v[192:195], v[40:43]
	v_mfma_f32_16x16x32_bf16 v[28:31], v[146:149], v[200:203], v[28:31]
	v_mfma_f32_16x16x32_bf16 v[24:27], v[160:163], v[200:203], v[24:27]
	v_mfma_f32_16x16x32_bf16 v[12:15], v[146:149], v[214:217], v[12:15]
	v_mfma_f32_16x16x32_bf16 v[8:11], v[160:163], v[214:217], v[8:11]
	s_setprio 0
	s_setprio 1
	v_mfma_f32_16x16x32_bf16 v[52:55], v[164:167], v[180:183], 0
	v_mfma_f32_16x16x32_bf16 v[48:51], v[172:175], v[180:183], 0
	v_mfma_f32_16x16x32_bf16 v[36:39], v[164:167], v[188:191], 0
	v_mfma_f32_16x16x32_bf16 v[32:35], v[172:175], v[188:191], 0
	v_mfma_f32_16x16x32_bf16 v[20:23], v[164:167], v[196:199], 0
	v_mfma_f32_16x16x32_bf16 v[16:19], v[172:175], v[196:199], 0
	v_mfma_f32_16x16x32_bf16 v[4:7], v[164:167], v[210:213], 0
	v_mfma_f32_16x16x32_bf16 v[0:3], v[172:175], v[210:213], 0
	v_mfma_f32_16x16x32_bf16 v[52:55], v[168:171], v[184:187], v[52:55]
	v_mfma_f32_16x16x32_bf16 v[48:51], v[176:179], v[184:187], v[48:51]
	v_mfma_f32_16x16x32_bf16 v[36:39], v[168:171], v[192:195], v[36:39]
	v_mfma_f32_16x16x32_bf16 v[32:35], v[176:179], v[192:195], v[32:35]
	v_mfma_f32_16x16x32_bf16 v[20:23], v[168:171], v[200:203], v[20:23]
	v_mfma_f32_16x16x32_bf16 v[16:19], v[176:179], v[200:203], v[16:19]
	v_mfma_f32_16x16x32_bf16 v[4:7], v[168:171], v[214:217], v[4:7]
	v_mfma_f32_16x16x32_bf16 v[0:3], v[176:179], v[214:217], v[0:3]
	s_setprio 0
	s_barrier
	s_add_i32 s71, 0, 0x18000
	v_add_u32_e32 v132, s71, v151
	s_add_i32 s72, 0, 0x1c000
	ds_read_b128 v[142:145], v132
	ds_read_b128 v[146:149], v132 offset:1024
	ds_read_b128 v[156:159], v132 offset:2048
	ds_read_b128 v[160:163], v132 offset:3072
	v_add_u32_e32 v132, s72, v151
	ds_read_b128 v[164:167], v132
	ds_read_b128 v[168:171], v132 offset:1024
	ds_read_b128 v[172:175], v132 offset:2048
	ds_read_b128 v[176:179], v132 offset:3072
	s_add_u32 s28, s42, 0xb0000
	s_addc_u32 s29, s43, 0
	s_mov_b32 m0, s53
	v_lshl_add_u64 v[224:225], s[28:29], 0, v[128:129]
	ds_read_b128 v[180:183], v155 offset:32768
	ds_read_b128 v[184:187], v155 offset:33792
	ds_read_b128 v[188:191], v155 offset:34816
	ds_read_b128 v[192:195], v155 offset:35840
	ds_read_b128 v[196:199], v155 offset:36864
	ds_read_b128 v[200:203], v155 offset:37888
	ds_read_b128 v[210:213], v155 offset:38912
	ds_read_b128 v[214:217], v155 offset:39936
	global_load_lds_dwordx4 v[224:225], off
	v_lshl_add_u64 v[224:225], s[28:29], 0, v[130:131]
	s_mov_b32 m0, s54
	s_nop 0
	global_load_lds_dwordx4 v[224:225], off
	s_waitcnt vmcnt(8)
	s_waitcnt lgkmcnt(0)
	s_barrier
	s_setprio 1
	s_waitcnt lgkmcnt(0)
	v_mfma_f32_16x16x32_bf16 v[124:127], v[142:145], v[180:183], v[124:127]
	v_mfma_f32_16x16x32_bf16 v[120:123], v[156:159], v[180:183], v[120:123]
	v_mfma_f32_16x16x32_bf16 v[108:111], v[142:145], v[188:191], v[108:111]
	v_mfma_f32_16x16x32_bf16 v[104:107], v[156:159], v[188:191], v[104:107]
	v_mfma_f32_16x16x32_bf16 v[92:95], v[142:145], v[196:199], v[92:95]
	v_mfma_f32_16x16x32_bf16 v[88:91], v[156:159], v[196:199], v[88:91]
	v_mfma_f32_16x16x32_bf16 v[76:79], v[142:145], v[210:213], v[76:79]
	v_mfma_f32_16x16x32_bf16 v[72:75], v[156:159], v[210:213], v[72:75]
	v_mfma_f32_16x16x32_bf16 v[124:127], v[146:149], v[184:187], v[124:127]
	v_mfma_f32_16x16x32_bf16 v[120:123], v[160:163], v[184:187], v[120:123]
	v_mfma_f32_16x16x32_bf16 v[108:111], v[146:149], v[192:195], v[108:111]
	v_mfma_f32_16x16x32_bf16 v[104:107], v[160:163], v[192:195], v[104:107]
	v_mfma_f32_16x16x32_bf16 v[92:95], v[146:149], v[200:203], v[92:95]
	v_mfma_f32_16x16x32_bf16 v[88:91], v[160:163], v[200:203], v[88:91]
	v_mfma_f32_16x16x32_bf16 v[76:79], v[146:149], v[214:217], v[76:79]
	v_mfma_f32_16x16x32_bf16 v[72:75], v[160:163], v[214:217], v[72:75]
	s_setprio 0
	s_setprio 1
	v_mfma_f32_16x16x32_bf16 v[116:119], v[164:167], v[180:183], v[116:119]
	v_mfma_f32_16x16x32_bf16 v[112:115], v[172:175], v[180:183], v[112:115]
	v_mfma_f32_16x16x32_bf16 v[100:103], v[164:167], v[188:191], v[100:103]
	v_mfma_f32_16x16x32_bf16 v[96:99], v[172:175], v[188:191], v[96:99]
	v_mfma_f32_16x16x32_bf16 v[84:87], v[164:167], v[196:199], v[84:87]
	v_mfma_f32_16x16x32_bf16 v[80:83], v[172:175], v[196:199], v[80:83]
	v_mfma_f32_16x16x32_bf16 v[68:71], v[164:167], v[210:213], v[68:71]
	v_mfma_f32_16x16x32_bf16 v[64:67], v[172:175], v[210:213], v[64:67]
	v_mfma_f32_16x16x32_bf16 v[116:119], v[168:171], v[184:187], v[116:119]
	v_mfma_f32_16x16x32_bf16 v[112:115], v[176:179], v[184:187], v[112:115]
	v_mfma_f32_16x16x32_bf16 v[100:103], v[168:171], v[192:195], v[100:103]
	v_mfma_f32_16x16x32_bf16 v[96:99], v[176:179], v[192:195], v[96:99]
	v_mfma_f32_16x16x32_bf16 v[84:87], v[168:171], v[200:203], v[84:87]
	v_mfma_f32_16x16x32_bf16 v[80:83], v[176:179], v[200:203], v[80:83]
	v_mfma_f32_16x16x32_bf16 v[68:71], v[168:171], v[214:217], v[68:71]
	v_mfma_f32_16x16x32_bf16 v[64:67], v[176:179], v[214:217], v[64:67]
	s_setprio 0
	s_barrier
	s_add_i32 s28, s71, s50
	v_lshl_add_u64 v[204:205], v[204:205], 0, s[20:21]
	s_mov_b32 m0, s28
	ds_read_b128 v[180:183], v155 offset:49152
	ds_read_b128 v[184:187], v155 offset:50176
	ds_read_b128 v[188:191], v155 offset:51200
	ds_read_b128 v[192:195], v155 offset:52224
	ds_read_b128 v[196:199], v155 offset:53248
	ds_read_b128 v[200:203], v155 offset:54272
	ds_read_b128 v[210:213], v155 offset:55296
	ds_read_b128 v[214:217], v155 offset:56320
	global_load_lds_dwordx4 v[204:205], off
	s_add_i32 m0, s28, 0x2000
	s_add_u32 s28, s40, 0xb0080
	v_lshl_add_u64 v[204:205], v[218:219], 0, s[20:21]
	s_addc_u32 s29, s41, 0
	s_add_i32 s40, s72, s50
	global_load_lds_dwordx4 v[204:205], off
	v_lshl_add_u64 v[204:205], s[28:29], 0, v[128:129]
	s_mov_b32 m0, s40
	s_nop 0
	global_load_lds_dwordx4 v[204:205], off
	v_lshl_add_u64 v[204:205], s[28:29], 0, v[130:131]
	s_add_i32 m0, s40, 0x2000
	s_nop 0
	global_load_lds_dwordx4 v[204:205], off
	v_lshl_add_u64 v[204:205], v[220:221], 0, s[20:21]
	s_mov_b32 m0, s56
	s_nop 0
	global_load_lds_dwordx4 v[204:205], off
	v_lshl_add_u64 v[204:205], v[222:223], 0, s[20:21]
	s_mov_b32 m0, s57
	s_nop 0
	global_load_lds_dwordx4 v[204:205], off
	s_waitcnt vmcnt(8)
	s_waitcnt lgkmcnt(0)
	s_barrier
	s_setprio 1
	s_waitcnt lgkmcnt(0)
	v_mfma_f32_16x16x32_bf16 v[60:63], v[142:145], v[180:183], v[60:63]
	v_mfma_f32_16x16x32_bf16 v[56:59], v[156:159], v[180:183], v[56:59]
	v_mfma_f32_16x16x32_bf16 v[44:47], v[142:145], v[188:191], v[44:47]
	v_mfma_f32_16x16x32_bf16 v[40:43], v[156:159], v[188:191], v[40:43]
	v_mfma_f32_16x16x32_bf16 v[28:31], v[142:145], v[196:199], v[28:31]
	v_mfma_f32_16x16x32_bf16 v[24:27], v[156:159], v[196:199], v[24:27]
	v_mfma_f32_16x16x32_bf16 v[12:15], v[142:145], v[210:213], v[12:15]
	v_mfma_f32_16x16x32_bf16 v[8:11], v[156:159], v[210:213], v[8:11]
	v_mfma_f32_16x16x32_bf16 v[60:63], v[146:149], v[184:187], v[60:63]
	v_mfma_f32_16x16x32_bf16 v[56:59], v[160:163], v[184:187], v[56:59]
	v_mfma_f32_16x16x32_bf16 v[44:47], v[146:149], v[192:195], v[44:47]
	v_mfma_f32_16x16x32_bf16 v[40:43], v[160:163], v[192:195], v[40:43]
	v_mfma_f32_16x16x32_bf16 v[28:31], v[146:149], v[200:203], v[28:31]
	v_mfma_f32_16x16x32_bf16 v[24:27], v[160:163], v[200:203], v[24:27]
	v_mfma_f32_16x16x32_bf16 v[12:15], v[146:149], v[214:217], v[12:15]
	v_mfma_f32_16x16x32_bf16 v[8:11], v[160:163], v[214:217], v[8:11]
	s_setprio 0
	s_setprio 1
	v_mfma_f32_16x16x32_bf16 v[52:55], v[164:167], v[180:183], v[52:55]
	v_mfma_f32_16x16x32_bf16 v[48:51], v[172:175], v[180:183], v[48:51]
	v_mfma_f32_16x16x32_bf16 v[36:39], v[164:167], v[188:191], v[36:39]
	v_mfma_f32_16x16x32_bf16 v[32:35], v[172:175], v[188:191], v[32:35]
	v_mfma_f32_16x16x32_bf16 v[20:23], v[164:167], v[196:199], v[20:23]
	v_mfma_f32_16x16x32_bf16 v[16:19], v[172:175], v[196:199], v[16:19]
	v_mfma_f32_16x16x32_bf16 v[4:7], v[164:167], v[210:213], v[4:7]
	v_mfma_f32_16x16x32_bf16 v[0:3], v[172:175], v[210:213], v[0:3]
	v_mfma_f32_16x16x32_bf16 v[52:55], v[168:171], v[184:187], v[52:55]
	v_mfma_f32_16x16x32_bf16 v[48:51], v[176:179], v[184:187], v[48:51]
	v_mfma_f32_16x16x32_bf16 v[36:39], v[168:171], v[192:195], v[36:39]
	v_mfma_f32_16x16x32_bf16 v[32:35], v[176:179], v[192:195], v[32:35]
	v_mfma_f32_16x16x32_bf16 v[20:23], v[168:171], v[200:203], v[20:23]
	v_mfma_f32_16x16x32_bf16 v[16:19], v[176:179], v[200:203], v[16:19]
	v_mfma_f32_16x16x32_bf16 v[4:7], v[168:171], v[214:217], v[4:7]
	v_mfma_f32_16x16x32_bf16 v[0:3], v[176:179], v[214:217], v[0:3]
	s_setprio 0
	s_barrier
	s_add_i32 s70, s70, 2
	s_add_u32 s68, s68, 0x100
	s_addc_u32 s69, s69, 0
	s_cmp_gt_u32 s70, 41
	s_mov_b64 s[28:29], s[30:31]
	s_cbranch_scc1 .Lpeel_done_42822
.LBB0_1489:
	ds_read_b128 v[142:145], v153
	ds_read_b128 v[146:149], v153 offset:1024
	ds_read_b128 v[156:159], v153 offset:2048
	ds_read_b128 v[160:163], v153 offset:3072
	ds_read_b128 v[164:167], v154
	ds_read_b128 v[168:171], v154 offset:1024
	ds_read_b128 v[172:175], v154 offset:2048
	ds_read_b128 v[176:179], v154 offset:3072
	s_add_u32 s30, s28, 0x100
	s_addc_u32 s31, s29, 0
	s_cmp_eq_u32 s70, 40
	s_cselect_b32 s43, s11, s31
	s_cselect_b32 s42, s10, s30
	s_cselect_b32 s41, s27, s69
	s_cselect_b32 s40, s26, s68
	v_lshl_add_u64 v[204:205], s[28:29], 0, v[134:135]
	s_add_i32 m0, s51, 0xc000
	ds_read_b128 v[180:183], v155
	ds_read_b128 v[184:187], v155 offset:1024
	ds_read_b128 v[188:191], v155 offset:2048
	ds_read_b128 v[192:195], v155 offset:3072
	ds_read_b128 v[196:199], v155 offset:4096
	ds_read_b128 v[200:203], v155 offset:5120
	ds_read_b128 v[210:213], v155 offset:6144
	ds_read_b128 v[214:217], v155 offset:7168
	global_load_lds_dwordx4 v[204:205], off
	v_lshl_add_u64 v[204:205], s[28:29], 0, v[136:137]
	s_add_i32 m0, s51, 0xe000
	s_nop 0
	global_load_lds_dwordx4 v[204:205], off
	s_waitcnt vmcnt(8)
	s_waitcnt lgkmcnt(0)
	s_barrier
	s_waitcnt lgkmcnt(0)
	v_mfma_f32_16x16x32_bf16 v[124:127], v[142:145], v[180:183], v[124:127]
	v_mfma_f32_16x16x32_bf16 v[120:123], v[156:159], v[180:183], v[120:123]
	v_mfma_f32_16x16x32_bf16 v[108:111], v[142:145], v[188:191], v[108:111]
	v_mfma_f32_16x16x32_bf16 v[104:107], v[156:159], v[188:191], v[104:107]
	v_mfma_f32_16x16x32_bf16 v[92:95], v[142:145], v[196:199], v[92:95]
	v_mfma_f32_16x16x32_bf16 v[88:91], v[156:159], v[196:199], v[88:91]
	v_mfma_f32_16x16x32_bf16 v[76:79], v[142:145], v[210:213], v[76:79]
	v_mfma_f32_16x16x32_bf16 v[72:75], v[156:159], v[210:213], v[72:75]
	v_mfma_f32_16x16x32_bf16 v[124:127], v[146:149], v[184:187], v[124:127]
	v_mfma_f32_16x16x32_bf16 v[120:123], v[160:163], v[184:187], v[120:123]
	v_mfma_f32_16x16x32_bf16 v[108:111], v[146:149], v[192:195], v[108:111]
	v_mfma_f32_16x16x32_bf16 v[104:107], v[160:163], v[192:195], v[104:107]
	v_mfma_f32_16x16x32_bf16 v[92:95], v[146:149], v[200:203], v[92:95]
	v_mfma_f32_16x16x32_bf16 v[88:91], v[160:163], v[200:203], v[88:91]
	v_mfma_f32_16x16x32_bf16 v[76:79], v[146:149], v[214:217], v[76:79]
	v_mfma_f32_16x16x32_bf16 v[72:75], v[160:163], v[214:217], v[72:75]
	v_mfma_f32_16x16x32_bf16 v[116:119], v[164:167], v[180:183], v[116:119]
	v_mfma_f32_16x16x32_bf16 v[112:115], v[172:175], v[180:183], v[112:115]
	v_mfma_f32_16x16x32_bf16 v[100:103], v[164:167], v[188:191], v[100:103]
	v_mfma_f32_16x16x32_bf16 v[96:99], v[172:175], v[188:191], v[96:99]
	v_mfma_f32_16x16x32_bf16 v[84:87], v[164:167], v[196:199], v[84:87]
	v_mfma_f32_16x16x32_bf16 v[80:83], v[172:175], v[196:199], v[80:83]
	v_mfma_f32_16x16x32_bf16 v[68:71], v[164:167], v[210:213], v[68:71]
	v_mfma_f32_16x16x32_bf16 v[64:67], v[172:175], v[210:213], v[64:67]
	v_mfma_f32_16x16x32_bf16 v[116:119], v[168:171], v[184:187], v[116:119]
	v_mfma_f32_16x16x32_bf16 v[112:115], v[176:179], v[184:187], v[112:115]
	v_mfma_f32_16x16x32_bf16 v[100:103], v[168:171], v[192:195], v[100:103]
	v_mfma_f32_16x16x32_bf16 v[96:99], v[176:179], v[192:195], v[96:99]
	v_mfma_f32_16x16x32_bf16 v[84:87], v[168:171], v[200:203], v[84:87]
	v_mfma_f32_16x16x32_bf16 v[80:83], v[176:179], v[200:203], v[80:83]
	v_mfma_f32_16x16x32_bf16 v[68:71], v[168:171], v[214:217], v[68:71]
	v_mfma_f32_16x16x32_bf16 v[64:67], v[176:179], v[214:217], v[64:67]
	s_barrier
	s_add_i32 s28, s58, s50
	v_lshl_add_u64 v[204:205], s[40:41], 0, v[128:129]
	s_mov_b32 m0, s28
	ds_read_b128 v[180:183], v155 offset:16384
	ds_read_b128 v[184:187], v155 offset:17408
	ds_read_b128 v[188:191], v155 offset:18432
	ds_read_b128 v[192:195], v155 offset:19456
	ds_read_b128 v[196:199], v155 offset:20480
	ds_read_b128 v[200:203], v155 offset:21504
	ds_read_b128 v[210:213], v155 offset:22528
	ds_read_b128 v[214:217], v155 offset:23552
	global_load_lds_dwordx4 v[204:205], off
	s_add_i32 m0, s28, 0x2000
	s_add_u32 s28, s40, 0xb0000
	v_lshl_add_u64 v[218:219], s[40:41], 0, v[130:131]
	s_addc_u32 s29, s41, 0
	s_add_i32 s71, s59, s50
	global_load_lds_dwordx4 v[218:219], off
	v_lshl_add_u64 v[220:221], s[28:29], 0, v[128:129]
	s_mov_b32 m0, s71
	v_lshl_add_u64 v[222:223], s[42:43], 0, v[130:131]
	global_load_lds_dwordx4 v[220:221], off
	v_lshl_add_u64 v[220:221], s[28:29], 0, v[130:131]
	s_add_i32 m0, s71, 0x2000
	s_nop 0
	global_load_lds_dwordx4 v[220:221], off
	v_lshl_add_u64 v[220:221], s[42:43], 0, v[128:129]
	s_mov_b32 m0, s51
	s_nop 0
	global_load_lds_dwordx4 v[220:221], off
	s_mov_b32 m0, s52
	s_nop 0
	global_load_lds_dwordx4 v[222:223], off
	s_waitcnt vmcnt(8)
	s_waitcnt lgkmcnt(0)
	s_barrier
	s_waitcnt lgkmcnt(0)
	v_mfma_f32_16x16x32_bf16 v[60:63], v[142:145], v[180:183], v[60:63]
	v_mfma_f32_16x16x32_bf16 v[56:59], v[156:159], v[180:183], v[56:59]
	v_mfma_f32_16x16x32_bf16 v[44:47], v[142:145], v[188:191], v[44:47]
	v_mfma_f32_16x16x32_bf16 v[40:43], v[156:159], v[188:191], v[40:43]
	v_mfma_f32_16x16x32_bf16 v[28:31], v[142:145], v[196:199], v[28:31]
	v_mfma_f32_16x16x32_bf16 v[24:27], v[156:159], v[196:199], v[24:27]
	v_mfma_f32_16x16x32_bf16 v[12:15], v[142:145], v[210:213], v[12:15]
	v_mfma_f32_16x16x32_bf16 v[8:11], v[156:159], v[210:213], v[8:11]
	v_mfma_f32_16x16x32_bf16 v[60:63], v[146:149], v[184:187], v[60:63]
	v_mfma_f32_16x16x32_bf16 v[56:59], v[160:163], v[184:187], v[56:59]
	v_mfma_f32_16x16x32_bf16 v[44:47], v[146:149], v[192:195], v[44:47]
	v_mfma_f32_16x16x32_bf16 v[40:43], v[160:163], v[192:195], v[40:43]
	v_mfma_f32_16x16x32_bf16 v[28:31], v[146:149], v[200:203], v[28:31]
	v_mfma_f32_16x16x32_bf16 v[24:27], v[160:163], v[200:203], v[24:27]
	v_mfma_f32_16x16x32_bf16 v[12:15], v[146:149], v[214:217], v[12:15]
	v_mfma_f32_16x16x32_bf16 v[8:11], v[160:163], v[214:217], v[8:11]
	v_mfma_f32_16x16x32_bf16 v[52:55], v[164:167], v[180:183], v[52:55]
	v_mfma_f32_16x16x32_bf16 v[48:51], v[172:175], v[180:183], v[48:51]
	v_mfma_f32_16x16x32_bf16 v[36:39], v[164:167], v[188:191], v[36:39]
	v_mfma_f32_16x16x32_bf16 v[32:35], v[172:175], v[188:191], v[32:35]
	v_mfma_f32_16x16x32_bf16 v[20:23], v[164:167], v[196:199], v[20:23]
	v_mfma_f32_16x16x32_bf16 v[16:19], v[172:175], v[196:199], v[16:19]
	v_mfma_f32_16x16x32_bf16 v[4:7], v[164:167], v[210:213], v[4:7]
	v_mfma_f32_16x16x32_bf16 v[0:3], v[172:175], v[210:213], v[0:3]
	v_mfma_f32_16x16x32_bf16 v[52:55], v[168:171], v[184:187], v[52:55]
	v_mfma_f32_16x16x32_bf16 v[48:51], v[176:179], v[184:187], v[48:51]
	v_mfma_f32_16x16x32_bf16 v[36:39], v[168:171], v[192:195], v[36:39]
	v_mfma_f32_16x16x32_bf16 v[32:35], v[176:179], v[192:195], v[32:35]
	v_mfma_f32_16x16x32_bf16 v[20:23], v[168:171], v[200:203], v[20:23]
	v_mfma_f32_16x16x32_bf16 v[16:19], v[176:179], v[200:203], v[16:19]
	v_mfma_f32_16x16x32_bf16 v[4:7], v[168:171], v[214:217], v[4:7]
	v_mfma_f32_16x16x32_bf16 v[0:3], v[176:179], v[214:217], v[0:3]
	s_barrier
	s_add_i32 s71, 0, 0x18000
	v_add_u32_e32 v132, s71, v151
	s_add_i32 s72, 0, 0x1c000
	ds_read_b128 v[142:145], v132
	ds_read_b128 v[146:149], v132 offset:1024
	ds_read_b128 v[156:159], v132 offset:2048
	ds_read_b128 v[160:163], v132 offset:3072
	v_add_u32_e32 v132, s72, v151
	ds_read_b128 v[164:167], v132
	ds_read_b128 v[168:171], v132 offset:1024
	ds_read_b128 v[172:175], v132 offset:2048
	ds_read_b128 v[176:179], v132 offset:3072
	s_add_u32 s28, s42, 0xb0000
	s_addc_u32 s29, s43, 0
	s_mov_b32 m0, s53
	v_lshl_add_u64 v[224:225], s[28:29], 0, v[128:129]
	ds_read_b128 v[180:183], v155 offset:32768
	ds_read_b128 v[184:187], v155 offset:33792
	ds_read_b128 v[188:191], v155 offset:34816
	ds_read_b128 v[192:195], v155 offset:35840
	ds_read_b128 v[196:199], v155 offset:36864
	ds_read_b128 v[200:203], v155 offset:37888
	ds_read_b128 v[210:213], v155 offset:38912
	ds_read_b128 v[214:217], v155 offset:39936
	global_load_lds_dwordx4 v[224:225], off
	v_lshl_add_u64 v[224:225], s[28:29], 0, v[130:131]
	s_mov_b32 m0, s54
	s_nop 0
	global_load_lds_dwordx4 v[224:225], off
	s_waitcnt vmcnt(8)
	s_waitcnt lgkmcnt(0)
	s_barrier
	s_waitcnt lgkmcnt(0)
	v_mfma_f32_16x16x32_bf16 v[124:127], v[142:145], v[180:183], v[124:127]
	v_mfma_f32_16x16x32_bf16 v[120:123], v[156:159], v[180:183], v[120:123]
	v_mfma_f32_16x16x32_bf16 v[108:111], v[142:145], v[188:191], v[108:111]
	v_mfma_f32_16x16x32_bf16 v[104:107], v[156:159], v[188:191], v[104:107]
	v_mfma_f32_16x16x32_bf16 v[92:95], v[142:145], v[196:199], v[92:95]
	v_mfma_f32_16x16x32_bf16 v[88:91], v[156:159], v[196:199], v[88:91]
	v_mfma_f32_16x16x32_bf16 v[76:79], v[142:145], v[210:213], v[76:79]
	v_mfma_f32_16x16x32_bf16 v[72:75], v[156:159], v[210:213], v[72:75]
	v_mfma_f32_16x16x32_bf16 v[124:127], v[146:149], v[184:187], v[124:127]
	v_mfma_f32_16x16x32_bf16 v[120:123], v[160:163], v[184:187], v[120:123]
	v_mfma_f32_16x16x32_bf16 v[108:111], v[146:149], v[192:195], v[108:111]
	v_mfma_f32_16x16x32_bf16 v[104:107], v[160:163], v[192:195], v[104:107]
	v_mfma_f32_16x16x32_bf16 v[92:95], v[146:149], v[200:203], v[92:95]
	v_mfma_f32_16x16x32_bf16 v[88:91], v[160:163], v[200:203], v[88:91]
	v_mfma_f32_16x16x32_bf16 v[76:79], v[146:149], v[214:217], v[76:79]
	v_mfma_f32_16x16x32_bf16 v[72:75], v[160:163], v[214:217], v[72:75]
	v_mfma_f32_16x16x32_bf16 v[116:119], v[164:167], v[180:183], v[116:119]
	v_mfma_f32_16x16x32_bf16 v[112:115], v[172:175], v[180:183], v[112:115]
	v_mfma_f32_16x16x32_bf16 v[100:103], v[164:167], v[188:191], v[100:103]
	v_mfma_f32_16x16x32_bf16 v[96:99], v[172:175], v[188:191], v[96:99]
	v_mfma_f32_16x16x32_bf16 v[84:87], v[164:167], v[196:199], v[84:87]
	v_mfma_f32_16x16x32_bf16 v[80:83], v[172:175], v[196:199], v[80:83]
	v_mfma_f32_16x16x32_bf16 v[68:71], v[164:167], v[210:213], v[68:71]
	v_mfma_f32_16x16x32_bf16 v[64:67], v[172:175], v[210:213], v[64:67]
	v_mfma_f32_16x16x32_bf16 v[116:119], v[168:171], v[184:187], v[116:119]
	v_mfma_f32_16x16x32_bf16 v[112:115], v[176:179], v[184:187], v[112:115]
	v_mfma_f32_16x16x32_bf16 v[100:103], v[168:171], v[192:195], v[100:103]
	v_mfma_f32_16x16x32_bf16 v[96:99], v[176:179], v[192:195], v[96:99]
	v_mfma_f32_16x16x32_bf16 v[84:87], v[168:171], v[200:203], v[84:87]
	v_mfma_f32_16x16x32_bf16 v[80:83], v[176:179], v[200:203], v[80:83]
	v_mfma_f32_16x16x32_bf16 v[68:71], v[168:171], v[214:217], v[68:71]
	v_mfma_f32_16x16x32_bf16 v[64:67], v[176:179], v[214:217], v[64:67]
	s_barrier
	s_add_i32 s28, s71, s50
	v_lshl_add_u64 v[204:205], v[204:205], 0, s[20:21]
	s_mov_b32 m0, s28
	ds_read_b128 v[180:183], v155 offset:49152
	ds_read_b128 v[184:187], v155 offset:50176
	ds_read_b128 v[188:191], v155 offset:51200
	ds_read_b128 v[192:195], v155 offset:52224
	ds_read_b128 v[196:199], v155 offset:53248
	ds_read_b128 v[200:203], v155 offset:54272
	ds_read_b128 v[210:213], v155 offset:55296
	ds_read_b128 v[214:217], v155 offset:56320
	global_load_lds_dwordx4 v[204:205], off
	s_add_i32 m0, s28, 0x2000
	s_add_u32 s28, s40, 0xb0080
	v_lshl_add_u64 v[204:205], v[218:219], 0, s[20:21]
	s_addc_u32 s29, s41, 0
	s_add_i32 s40, s72, s50
	global_load_lds_dwordx4 v[204:205], off
	v_lshl_add_u64 v[204:205], s[28:29], 0, v[128:129]
	s_mov_b32 m0, s40
	s_nop 0
	global_load_lds_dwordx4 v[204:205], off
	v_lshl_add_u64 v[204:205], s[28:29], 0, v[130:131]
	s_add_i32 m0, s40, 0x2000
	s_nop 0
	global_load_lds_dwordx4 v[204:205], off
	v_lshl_add_u64 v[204:205], v[220:221], 0, s[20:21]
	s_mov_b32 m0, s56
	s_nop 0
	global_load_lds_dwordx4 v[204:205], off
	v_lshl_add_u64 v[204:205], v[222:223], 0, s[20:21]
	s_mov_b32 m0, s57
	s_nop 0
	global_load_lds_dwordx4 v[204:205], off
	s_waitcnt vmcnt(8)
	s_waitcnt lgkmcnt(0)
	s_barrier
	s_waitcnt lgkmcnt(0)
	v_mfma_f32_16x16x32_bf16 v[60:63], v[142:145], v[180:183], v[60:63]
	v_mfma_f32_16x16x32_bf16 v[56:59], v[156:159], v[180:183], v[56:59]
	v_mfma_f32_16x16x32_bf16 v[44:47], v[142:145], v[188:191], v[44:47]
	v_mfma_f32_16x16x32_bf16 v[40:43], v[156:159], v[188:191], v[40:43]
	v_mfma_f32_16x16x32_bf16 v[28:31], v[142:145], v[196:199], v[28:31]
	v_mfma_f32_16x16x32_bf16 v[24:27], v[156:159], v[196:199], v[24:27]
	v_mfma_f32_16x16x32_bf16 v[12:15], v[142:145], v[210:213], v[12:15]
	v_mfma_f32_16x16x32_bf16 v[8:11], v[156:159], v[210:213], v[8:11]
	v_mfma_f32_16x16x32_bf16 v[60:63], v[146:149], v[184:187], v[60:63]
	v_mfma_f32_16x16x32_bf16 v[56:59], v[160:163], v[184:187], v[56:59]
	v_mfma_f32_16x16x32_bf16 v[44:47], v[146:149], v[192:195], v[44:47]
	v_mfma_f32_16x16x32_bf16 v[40:43], v[160:163], v[192:195], v[40:43]
	v_mfma_f32_16x16x32_bf16 v[28:31], v[146:149], v[200:203], v[28:31]
	v_mfma_f32_16x16x32_bf16 v[24:27], v[160:163], v[200:203], v[24:27]
	v_mfma_f32_16x16x32_bf16 v[12:15], v[146:149], v[214:217], v[12:15]
	v_mfma_f32_16x16x32_bf16 v[8:11], v[160:163], v[214:217], v[8:11]
	v_mfma_f32_16x16x32_bf16 v[52:55], v[164:167], v[180:183], v[52:55]
	v_mfma_f32_16x16x32_bf16 v[48:51], v[172:175], v[180:183], v[48:51]
	v_mfma_f32_16x16x32_bf16 v[36:39], v[164:167], v[188:191], v[36:39]
	v_mfma_f32_16x16x32_bf16 v[32:35], v[172:175], v[188:191], v[32:35]
	v_mfma_f32_16x16x32_bf16 v[20:23], v[164:167], v[196:199], v[20:23]
	v_mfma_f32_16x16x32_bf16 v[16:19], v[172:175], v[196:199], v[16:19]
	v_mfma_f32_16x16x32_bf16 v[4:7], v[164:167], v[210:213], v[4:7]
	v_mfma_f32_16x16x32_bf16 v[0:3], v[172:175], v[210:213], v[0:3]
	v_mfma_f32_16x16x32_bf16 v[52:55], v[168:171], v[184:187], v[52:55]
	v_mfma_f32_16x16x32_bf16 v[48:51], v[176:179], v[184:187], v[48:51]
	v_mfma_f32_16x16x32_bf16 v[36:39], v[168:171], v[192:195], v[36:39]
	v_mfma_f32_16x16x32_bf16 v[32:35], v[176:179], v[192:195], v[32:35]
	v_mfma_f32_16x16x32_bf16 v[20:23], v[168:171], v[200:203], v[20:23]
	v_mfma_f32_16x16x32_bf16 v[16:19], v[176:179], v[200:203], v[16:19]
	v_mfma_f32_16x16x32_bf16 v[4:7], v[168:171], v[214:217], v[4:7]
	v_mfma_f32_16x16x32_bf16 v[0:3], v[176:179], v[214:217], v[0:3]
	s_barrier
	s_add_i32 s70, s70, 2
	s_add_u32 s68, s68, 0x100
	s_addc_u32 s69, s69, 0
	s_cmp_gt_u32 s70, 41
	s_mov_b64 s[28:29], s[30:31]
	s_cbranch_scc0 .LBB0_1489
.Lpeel_done_42822:
	s_and_b64 vcc, exec, s[24:25]
	s_cbranch_vccz .LBB0_1492
	s_barrier
